# packed-f32 math in the hand-written epilogues (UP, GLU, IN, fused last epilogue); hand-written deferred-row fix-up before both down-projections: all halo rows loaded up front, next task's loads in fli
# speedup vs baseline: 1.0104x; 1.0051x over previous
; #define PG8_STAGE(bufoff, gbase, voff) do { const __amdgpu_buffer_rsrc_t _r = __builtin_amdgcn_make_buffer_rsrc((void*)(gbase), (short)0, 0x7fffffff, 0x00020000); _Pragma("unroll") for (int _i = 0; _i < 2; ++_i) \
;         __builtin_amdgcn_raw_ptr_buffer_load_lds(_r, (LAS unsigned*)(lds + (bufoff) + ldsw + _i * 8192), 16, (int)(voff)[_i], 0, 0, 0); } while (0)
; #define PG8_LDA(dst, b, h) do { _Pragma("unroll") for (int m = 0; m < 4; ++m) _Pragma("unroll") for (int k = 0; k < 2; ++k) dst[m][k] = *(const LAS bf16x8*)(lds + PG8_SA(b, h) + aoff + m * 2048 + k * 1024); } while (0)
; #define PG8_LDB(dst, b, h) do { _Pragma("unroll") for (int n = 0; n < 2; ++n) _Pragma("unroll") for (int k = 0; k < 2; ++k) dst[n][k] = *(const LAS bf16x8*)(lds + PG8_SB(b, h) + boff + n * 2048 + k * 1024); } while (0)
; #define PG8_MMA(ai, bj, At, Bt) do { __builtin_amdgcn_s_setprio(1); _Pragma("unroll") for (int k = 0; k < 2; ++k) _Pragma("unroll") for (int m = 0; m < 4; ++m) _Pragma("unroll") for (int n = 0; n < ((bj) == 1 ? NB1 : 2); ++n) \
;         acc[ai][bj][m][n] = __builtin_amdgcn_mfma_f32_16x16x32_bf16(Bt[n][k], At[m][k], acc[ai][bj][m][n], 0, 0, 0); __builtin_amdgcn_s_setprio(0); } while (0)
; #define PG8_WAIT_V(n) asm volatile("s_waitcnt vmcnt(" #n ")" ::: "memory")
; #define PG8_WAIT_L(n) asm volatile("s_waitcnt lgkmcnt(" #n ")" ::: "memory")
; #define PG8_BAR __builtin_amdgcn_s_barrier()
; #define PG8_SCHED __builtin_amdgcn_sched_barrier(0)
;     ...
;             PG8_LDB(B0, 1, 0); PG8_SCHED; PG8_LDA(At, 1, 0); PG8_STAGE(PG8_SA(0, 1), a2 + hstepA, voffA);
;             PG8_WAIT_L(8); PG8_BAR; PG8_WAIT_L(0); PG8_MMA(0, 0, At, B0); PG8_BAR; PG8_SCHED;
;             PG8_LDB(B1, 1, 1); PG8_STAGE(PG8_SB(1, 0), b3, voffB);
;             PG8_BAR; PG8_WAIT_L(0); PG8_MMA(0, 1, At, B1); PG8_BAR;
;             PG8_LDA(At, 1, 1); PG8_STAGE(PG8_SA(1, 0), a3, voffA);
;             PG8_BAR; PG8_WAIT_L(0); PG8_MMA(1, 0, At, B0); PG8_BAR; PG8_SCHED;
;             PG8_STAGE(PG8_SB(1, 1), b3 + hstepB, voffB);
;             PG8_WAIT_V(6); PG8_BAR; PG8_MMA(1, 1, At, B1); PG8_BAR;
;     ...
; #pragma unroll
;         for (int a = 0; a < 2; ++a)
; #pragma unroll
;             for (int b = 0; b < 2; ++b)
; #pragma unroll
;                 for (int m = 0; m < 4; ++m)
; #pragma unroll
;                     for (int n = 0; n < 2; ++n) acc[a][b][m][n] = (f32x4){0.f, 0.f, 0.f, 0.f};
.Lkmid_507:
	ds_read_b128 v[76:79], v75
	ds_read_b128 v[80:83], v75 offset:1024
	ds_read_b128 v[84:87], v75 offset:2048
	ds_read_b128 v[88:91], v75 offset:3072
	s_add_u32 s64, s64, s6
	s_addc_u32 s9, s26, s7
	s_and_b32 s65, s9, 0xffff
	s_mov_b32 m0, s83
	ds_read_b128 v[92:95], v74 offset:32768
	ds_read_b128 v[96:99], v74 offset:33792
	ds_read_b128 v[100:103], v74 offset:34816
	ds_read_b128 v[104:107], v74 offset:35840
	ds_read_b128 v[108:111], v74 offset:36864
	ds_read_b128 v[112:115], v74 offset:37888
	ds_read_b128 v[116:119], v74 offset:38912
	ds_read_b128 v[120:123], v74 offset:39936
	buffer_load_dwordx4 v67, s[64:67], 0 offen lds
	s_mov_b32 m0, s90
	s_nop 0
	buffer_load_dwordx4 v71, s[64:67], 0 offen lds
	s_waitcnt lgkmcnt(8)
	s_barrier
	s_waitcnt lgkmcnt(0)
	s_setprio 1
	s_waitcnt lgkmcnt(7)
	v_mfma_f32_16x16x32_bf16 v[60:63], v[76:79], v[92:95], v[60:63]
	v_mfma_f32_16x16x32_bf16 v[56:59], v[84:87], v[92:95], v[56:59]
	s_waitcnt lgkmcnt(5)
	v_mfma_f32_16x16x32_bf16 v[52:55], v[76:79], v[100:103], v[52:55]
	v_mfma_f32_16x16x32_bf16 v[48:51], v[84:87], v[100:103], v[48:51]
	s_waitcnt lgkmcnt(3)
	v_mfma_f32_16x16x32_bf16 v[44:47], v[76:79], v[108:111], v[44:47]
	v_mfma_f32_16x16x32_bf16 v[40:43], v[84:87], v[108:111], v[40:43]
	s_waitcnt lgkmcnt(1)
	v_mfma_f32_16x16x32_bf16 v[36:39], v[76:79], v[116:119], v[36:39]
	v_mfma_f32_16x16x32_bf16 v[32:35], v[84:87], v[116:119], v[32:35]
	v_mfma_f32_16x16x32_bf16 v[60:63], v[80:83], v[96:99], v[60:63]
	v_mfma_f32_16x16x32_bf16 v[56:59], v[88:91], v[96:99], v[56:59]
	v_mfma_f32_16x16x32_bf16 v[52:55], v[80:83], v[104:107], v[52:55]
	v_mfma_f32_16x16x32_bf16 v[48:51], v[88:91], v[104:107], v[48:51]
	v_mfma_f32_16x16x32_bf16 v[44:47], v[80:83], v[112:115], v[44:47]
	v_mfma_f32_16x16x32_bf16 v[40:43], v[88:91], v[112:115], v[40:43]
	s_waitcnt lgkmcnt(0)
	v_mfma_f32_16x16x32_bf16 v[36:39], v[80:83], v[120:123], v[36:39]
	v_mfma_f32_16x16x32_bf16 v[32:35], v[88:91], v[120:123], v[32:35]
	s_setprio 0
	s_barrier
	s_add_u32 s44, s44, 0x80
	s_addc_u32 s9, s27, 0
	s_and_b32 s45, s9, 0xffff
	s_mov_b32 m0, s92
	s_nop 0
	buffer_load_dwordx4 v70, s[44:47], 0 offen lds
	s_mov_b32 m0, s97
	s_nop 0
	buffer_load_dwordx4 v72, s[44:47], 0 offen lds
	s_barrier
	s_waitcnt lgkmcnt(0)
	s_setprio 1
	s_setprio 0
	s_and_b32 s37, s29, 0xffff
	s_mov_b32 s38, s10
	s_mov_b32 s39, s11
	s_mov_b32 m0, s94
	s_barrier
	ds_read_b128 v[92:95], v74 offset:49152
	ds_read_b128 v[96:99], v74 offset:50176
	ds_read_b128 v[100:103], v74 offset:51200
	ds_read_b128 v[104:107], v74 offset:52224
	ds_read_b128 v[108:111], v74 offset:53248
	ds_read_b128 v[112:115], v74 offset:54272
	ds_read_b128 v[116:119], v74 offset:55296
	ds_read_b128 v[120:123], v74 offset:56320
	buffer_load_dwordx4 v67, s[36:39], 0 offen lds
	s_mov_b32 m0, s3
	s_nop 0
	buffer_load_dwordx4 v71, s[36:39], 0 offen lds
	s_barrier
	s_waitcnt lgkmcnt(0)
	s_setprio 1
	s_waitcnt lgkmcnt(7)
	v_mfma_f32_16x16x32_bf16 v[28:31], v[76:79], v[92:95], v[28:31]
	v_mfma_f32_16x16x32_bf16 v[24:27], v[84:87], v[92:95], v[24:27]
	s_waitcnt lgkmcnt(5)
	v_mfma_f32_16x16x32_bf16 v[20:23], v[76:79], v[100:103], v[20:23]
	v_mfma_f32_16x16x32_bf16 v[16:19], v[84:87], v[100:103], v[16:19]
	s_waitcnt lgkmcnt(3)
	v_mfma_f32_16x16x32_bf16 v[12:15], v[76:79], v[108:111], v[12:15]
	v_mfma_f32_16x16x32_bf16 v[8:11], v[84:87], v[108:111], v[8:11]
	s_waitcnt lgkmcnt(1)
	v_mfma_f32_16x16x32_bf16 v[4:7], v[76:79], v[116:119], v[4:7]
	v_mfma_f32_16x16x32_bf16 v[0:3], v[84:87], v[116:119], v[0:3]
	v_mfma_f32_16x16x32_bf16 v[28:31], v[80:83], v[96:99], v[28:31]
	v_mfma_f32_16x16x32_bf16 v[24:27], v[88:91], v[96:99], v[24:27]
	v_mfma_f32_16x16x32_bf16 v[20:23], v[80:83], v[104:107], v[20:23]
	v_mfma_f32_16x16x32_bf16 v[16:19], v[88:91], v[104:107], v[16:19]
	v_mfma_f32_16x16x32_bf16 v[12:15], v[80:83], v[112:115], v[12:15]
	v_mfma_f32_16x16x32_bf16 v[8:11], v[88:91], v[112:115], v[8:11]
	s_waitcnt lgkmcnt(0)
	v_mfma_f32_16x16x32_bf16 v[4:7], v[80:83], v[120:123], v[4:7]
	v_mfma_f32_16x16x32_bf16 v[0:3], v[88:91], v[120:123], v[0:3]
	s_setprio 0
	s_barrier
	s_add_u32 s8, s8, 0x80
	s_addc_u32 s9, s28, 0
	s_and_b32 s9, s9, 0xffff
	s_mov_b32 m0, s13
	s_nop 0
	buffer_load_dwordx4 v70, s[8:11], 0 offen lds
	s_mov_b32 m0, s14
	s_nop 0
	buffer_load_dwordx4 v72, s[8:11], 0 offen lds
	s_waitcnt vmcnt(6)
	s_barrier
	s_setprio 1
	s_setprio 0
	s_cmp_ge_i32 s25, s33
	s_mov_b64 s[8:9], s[72:73]
	s_mov_b32 s26, s25
	s_barrier
	s_cbranch_scc0 .LBB0_507
	s_branch .LBB0_502
.Lkzero_507:
	v_mov_b32_e32 v63, 0
	v_mov_b32_e32 v62, v63
	v_mov_b32_e32 v61, v63
	v_mov_b32_e32 v60, v63
	v_mov_b32_e32 v59, v63
	v_mov_b32_e32 v58, v63
	v_mov_b32_e32 v57, v63
	v_mov_b32_e32 v56, v63
	v_mov_b32_e32 v55, v63
	v_mov_b32_e32 v54, v63
	v_mov_b32_e32 v53, v63
	v_mov_b32_e32 v52, v63
	v_mov_b32_e32 v51, v63
	v_mov_b32_e32 v50, v63
	v_mov_b32_e32 v49, v63
	v_mov_b32_e32 v48, v63
	v_mov_b32_e32 v47, v63
	v_mov_b32_e32 v46, v63
	v_mov_b32_e32 v45, v63
	v_mov_b32_e32 v44, v63
	v_mov_b32_e32 v43, v63
	v_mov_b32_e32 v42, v63
	v_mov_b32_e32 v41, v63
	v_mov_b32_e32 v40, v63
	v_mov_b32_e32 v39, v63
	v_mov_b32_e32 v38, v63
	v_mov_b32_e32 v37, v63
	v_mov_b32_e32 v36, v63
	v_mov_b32_e32 v35, v63
	v_mov_b32_e32 v34, v63
	v_mov_b32_e32 v33, v63
	v_mov_b32_e32 v32, v63
	v_mov_b32_e32 v31, v63
	v_mov_b32_e32 v30, v63
	v_mov_b32_e32 v29, v63
	v_mov_b32_e32 v28, v63
	v_mov_b32_e32 v27, v63
	v_mov_b32_e32 v26, v63
	v_mov_b32_e32 v25, v63
	v_mov_b32_e32 v24, v63
	v_mov_b32_e32 v23, v63
	v_mov_b32_e32 v22, v63
	v_mov_b32_e32 v21, v63
	v_mov_b32_e32 v20, v63
	v_mov_b32_e32 v19, v63
	v_mov_b32_e32 v18, v63
	v_mov_b32_e32 v17, v63
	v_mov_b32_e32 v16, v63
	v_mov_b32_e32 v15, v63
	v_mov_b32_e32 v14, v63
	v_mov_b32_e32 v13, v63
	v_mov_b32_e32 v12, v63
	v_mov_b32_e32 v11, v63
	v_mov_b32_e32 v10, v63
	v_mov_b32_e32 v9, v63
	v_mov_b32_e32 v8, v63
	v_mov_b32_e32 v7, v63
	v_mov_b32_e32 v6, v63
	v_mov_b32_e32 v5, v63
	v_mov_b32_e32 v4, v63
	v_mov_b32_e32 v3, v63
	v_mov_b32_e32 v2, v63
	v_mov_b32_e32 v1, v63
	v_mov_b32_e32 v0, v63
	s_branch .LBB0_502
.LBB0_508:
	s_waitcnt vmcnt(0)
	s_cmpk_gt_u32 s81, 0xff
	s_cbranch_scc1 .LBB0_510
	s_barrier

; __device__ __forceinline__ float fast_sigmoid(float x) { return __builtin_amdgcn_rcpf(1.0f + __builtin_amdgcn_exp2f(x * -1.44269504f)); }
;     __device__ __forceinline__ void operator()(const Acc& acc, const Unit& u, int wr, int wc, int fr, int fq, LAS unsigned char* lds, f32x4 epar) const {
;     ...
; #pragma unroll
;         for (int ai = 0; ai < 2; ++ai)
; #pragma unroll
;             for (int m = 0; m < 4; ++m) { const int r = u.pm * BM + ai * HALF + wr * 64 + m * 16 + fr; const size_t off = (size_t)r * DM + c0;
;                 xv[ai][m][0] = __builtin_nontemporal_load((const f32x4*)(x + off)); xv[ai][m][1] = __builtin_nontemporal_load((const f32x4*)(x + off + 4)); }
; #pragma unroll
;         for (int ai = 0; ai < 2; ++ai)
; #pragma unroll
;             for (int m = 0; m < 4; ++m) { const int r = u.pm * BM + ai * HALF + wr * 64 + m * 16 + fr; const size_t off = (size_t)r * DM + c0;
;                 f32x4 v0 = xv[ai][m][0], v1 = xv[ai][m][1];
;                 const f32x4 za0 = acc[ai][0][m][0], za1 = acc[ai][0][m][1], zg0 = acc[ai][1][m][0], zg1 = acc[ai][1][m][1];
; #pragma unroll
;                 for (int j = 0; j < 4; ++j) { v0[j] += za0[j] * fast_sigmoid(zg0[j]); v1[j] += za1[j] * fast_sigmoid(zg1[j]); }
.LBB0_629:
	s_mov_b32 s101, 1.0
	s_mov_b32 s100, 0xbfb8aa3b
	v_readlane_b32 s44, v252, 6
	v_readlane_b32 s45, v252, 7
	v_readlane_b32 s46, v252, 8
	v_readlane_b32 s47, v252, 9
	v_readlane_b32 s48, v252, 10
	v_readlane_b32 s49, v252, 11
	v_readlane_b32 s50, v252, 12
	v_readlane_b32 s51, v252, 13
	v_readlane_b32 s52, v252, 14
	v_readlane_b32 s53, v252, 15
	v_readlane_b32 s54, v252, 16
	v_readlane_b32 s55, v252, 17
	v_readlane_b32 s56, v252, 18
	v_readlane_b32 s57, v252, 19
	v_readlane_b32 s58, v252, 20
	v_readlane_b32 s59, v252, 21
	s_mov_b64 s[0:1], exec
	v_lshl_add_u32 v188, s66, 8, v210
	v_lshl_or_b32 v189, s64, 7, v211
	v_lshlrev_b32_e32 v190, 12, v188
	v_lshlrev_b32_e32 v191, 11, v188
	v_lshlrev_b32_e32 v192, 2, v188
	v_lshl_add_u32 v190, v189, 2, v190
	v_lshl_add_u32 v191, v189, 1, v191
	global_load_dwordx4 v[222:225], v190, s[44:45] nt
	global_load_dwordx4 v[218:221], v190, s[44:45] offset:16 nt
	v_add_u32_e32 v193, 0x10000, v190
	global_load_dwordx4 v[180:183], v193, s[44:45] nt
	global_load_dwordx4 v[176:179], v193, s[44:45] offset:16 nt
	v_add_u32_e32 v193, 0x20000, v190
	global_load_dwordx4 v[172:175], v193, s[44:45] nt
	global_load_dwordx4 v[168:171], v193, s[44:45] offset:16 nt
	v_add_u32_e32 v193, 0x30000, v190
	global_load_dwordx4 v[164:167], v193, s[44:45] nt
	global_load_dwordx4 v[160:163], v193, s[44:45] offset:16 nt
	v_add_u32_e32 v193, 0x80000, v190
	global_load_dwordx4 v[156:159], v193, s[44:45] nt
	global_load_dwordx4 v[152:155], v193, s[44:45] offset:16 nt
	v_add_u32_e32 v193, 0x90000, v190
	global_load_dwordx4 v[148:151], v193, s[44:45] nt
	global_load_dwordx4 v[144:147], v193, s[44:45] offset:16 nt
	v_add_u32_e32 v193, 0xa0000, v190
	global_load_dwordx4 v[140:143], v193, s[44:45] nt
	global_load_dwordx4 v[136:139], v193, s[44:45] offset:16 nt
	v_add_u32_e32 v193, 0xb0000, v190
	global_load_dwordx4 v[132:135], v193, s[44:45] nt
	global_load_dwordx4 v[128:131], v193, s[44:45] offset:16 nt
	v_pk_mul_f32 v[124:125], s[100:101], v[124:125] op_sel_hi:[0,1]
	v_pk_mul_f32 v[126:127], s[100:101], v[126:127] op_sel_hi:[0,1]
	v_pk_mul_f32 v[120:121], s[100:101], v[120:121] op_sel_hi:[0,1]
	v_pk_mul_f32 v[122:123], s[100:101], v[122:123] op_sel_hi:[0,1]
	v_exp_f32_e32 v124, v124
	v_exp_f32_e32 v125, v125
	v_exp_f32_e32 v126, v126
	v_exp_f32_e32 v127, v127
	v_exp_f32_e32 v120, v120
	v_exp_f32_e32 v121, v121
	v_exp_f32_e32 v122, v122
	v_exp_f32_e32 v123, v123
	v_pk_add_f32 v[124:125], s[100:101], v[124:125] op_sel:[1,0]
	v_pk_add_f32 v[126:127], s[100:101], v[126:127] op_sel:[1,0]
	v_pk_add_f32 v[120:121], s[100:101], v[120:121] op_sel:[1,0]
	v_pk_add_f32 v[122:123], s[100:101], v[122:123] op_sel:[1,0]
	v_rcp_f32_e32 v124, v124
	v_rcp_f32_e32 v125, v125
	v_rcp_f32_e32 v126, v126
	v_rcp_f32_e32 v127, v127
	v_rcp_f32_e32 v120, v120
	v_rcp_f32_e32 v121, v121
	v_rcp_f32_e32 v122, v122
	v_rcp_f32_e32 v123, v123
	v_pk_mul_f32 v[108:109], s[100:101], v[108:109] op_sel_hi:[0,1]
	v_pk_mul_f32 v[110:111], s[100:101], v[110:111] op_sel_hi:[0,1]
	v_pk_mul_f32 v[104:105], s[100:101], v[104:105] op_sel_hi:[0,1]
	v_pk_mul_f32 v[106:107], s[100:101], v[106:107] op_sel_hi:[0,1]
	v_exp_f32_e32 v108, v108
	v_exp_f32_e32 v109, v109
	v_exp_f32_e32 v110, v110
	v_exp_f32_e32 v111, v111
	v_exp_f32_e32 v104, v104
	v_exp_f32_e32 v105, v105
	v_exp_f32_e32 v106, v106
	v_exp_f32_e32 v107, v107
	v_pk_add_f32 v[108:109], s[100:101], v[108:109] op_sel:[1,0]
	v_pk_add_f32 v[110:111], s[100:101], v[110:111] op_sel:[1,0]
	v_pk_add_f32 v[104:105], s[100:101], v[104:105] op_sel:[1,0]
	v_pk_add_f32 v[106:107], s[100:101], v[106:107] op_sel:[1,0]
	v_rcp_f32_e32 v108, v108
	v_rcp_f32_e32 v109, v109
	v_rcp_f32_e32 v110, v110
	v_rcp_f32_e32 v111, v111
	v_rcp_f32_e32 v104, v104
	v_rcp_f32_e32 v105, v105
	v_rcp_f32_e32 v106, v106
	v_rcp_f32_e32 v107, v107
	v_pk_mul_f32 v[92:93], s[100:101], v[92:93] op_sel_hi:[0,1]
	v_pk_mul_f32 v[94:95], s[100:101], v[94:95] op_sel_hi:[0,1]
	v_pk_mul_f32 v[88:89], s[100:101], v[88:89] op_sel_hi:[0,1]
	v_pk_mul_f32 v[90:91], s[100:101], v[90:91] op_sel_hi:[0,1]
	v_exp_f32_e32 v92, v92
	v_exp_f32_e32 v93, v93
	v_exp_f32_e32 v94, v94
	v_exp_f32_e32 v95, v95
	v_exp_f32_e32 v88, v88
	v_exp_f32_e32 v89, v89
	v_exp_f32_e32 v90, v90
	v_exp_f32_e32 v91, v91
	v_pk_add_f32 v[92:93], s[100:101], v[92:93] op_sel:[1,0]
	v_pk_add_f32 v[94:95], s[100:101], v[94:95] op_sel:[1,0]
	v_pk_add_f32 v[88:89], s[100:101], v[88:89] op_sel:[1,0]
	v_pk_add_f32 v[90:91], s[100:101], v[90:91] op_sel:[1,0]
	v_rcp_f32_e32 v92, v92
	v_rcp_f32_e32 v93, v93
	v_rcp_f32_e32 v94, v94
	v_rcp_f32_e32 v95, v95
	v_rcp_f32_e32 v88, v88
	v_rcp_f32_e32 v89, v89
	v_rcp_f32_e32 v90, v90
	v_rcp_f32_e32 v91, v91
	v_pk_mul_f32 v[76:77], s[100:101], v[76:77] op_sel_hi:[0,1]
	v_pk_mul_f32 v[78:79], s[100:101], v[78:79] op_sel_hi:[0,1]
	v_pk_mul_f32 v[72:73], s[100:101], v[72:73] op_sel_hi:[0,1]
	v_pk_mul_f32 v[74:75], s[100:101], v[74:75] op_sel_hi:[0,1]
	v_exp_f32_e32 v76, v76
	v_exp_f32_e32 v77, v77
	v_exp_f32_e32 v78, v78
	v_exp_f32_e32 v79, v79
	v_exp_f32_e32 v72, v72
	v_exp_f32_e32 v73, v73
	v_exp_f32_e32 v74, v74
	v_exp_f32_e32 v75, v75
	v_pk_add_f32 v[76:77], s[100:101], v[76:77] op_sel:[1,0]
	v_pk_add_f32 v[78:79], s[100:101], v[78:79] op_sel:[1,0]
	v_pk_add_f32 v[72:73], s[100:101], v[72:73] op_sel:[1,0]
	v_pk_add_f32 v[74:75], s[100:101], v[74:75] op_sel:[1,0]
	v_rcp_f32_e32 v76, v76
	v_rcp_f32_e32 v77, v77
	v_rcp_f32_e32 v78, v78
	v_rcp_f32_e32 v79, v79
	v_rcp_f32_e32 v72, v72
	v_rcp_f32_e32 v73, v73
	v_rcp_f32_e32 v74, v74
	v_rcp_f32_e32 v75, v75
	v_pk_mul_f32 v[60:61], s[100:101], v[60:61] op_sel_hi:[0,1]
	v_pk_mul_f32 v[62:63], s[100:101], v[62:63] op_sel_hi:[0,1]
; __device__ __forceinline__ unsigned cvt_pk_bf16(float lo, float hi) { unsigned r; asm volatile("v_cvt_pk_bf16_f32 %0, %1, %2" : "=v"(r) : "v"(lo), "v"(hi)); return r; }
; __device__ __forceinline__ float fast_sigmoid(float x) { return __builtin_amdgcn_rcpf(1.0f + __builtin_amdgcn_exp2f(x * -1.44269504f)); }
;     __device__ __forceinline__ void operator()(const Acc& acc, const Unit& u, int wr, int wc, int fr, int fq, LAS unsigned char* lds, f32x4 epar) const {
;     ...
;             for (int m = 0; m < 4; ++m) { const int r = u.pm * BM + ai * HALF + wr * 64 + m * 16 + fr; const size_t off = (size_t)r * DM + c0;
;                 f32x4 v0 = xv[ai][m][0], v1 = xv[ai][m][1];
;                 const f32x4 za0 = acc[ai][0][m][0], za1 = acc[ai][0][m][1], zg0 = acc[ai][1][m][0], zg1 = acc[ai][1][m][1];
; #pragma unroll
;                 for (int j = 0; j < 4; ++j) { v0[j] += za0[j] * fast_sigmoid(zg0[j]); v1[j] += za1[j] * fast_sigmoid(zg1[j]); }
;                 u32x4 w; w.x = cvt_pk_bf16(v0[0], v0[1]); w.y = cvt_pk_bf16(v0[2], v0[3]); w.z = cvt_pk_bf16(v1[0], v1[1]); w.w = cvt_pk_bf16(v1[2], v1[3]);
;                 *(u32x4*)(HB + off) = w;
;                 float s = (v0[0] * v0[0] + v0[1] * v0[1]) + (v0[2] * v0[2] + v0[3] * v0[3]) + (v1[0] * v1[0] + v1[1] * v1[1]) + (v1[2] * v1[2] + v1[3] * v1[3]);
;                 s += __shfl_xor(s, 16); s += __shfl_xor(s, 32);
;                 if (fq == 0) unsafeAtomicAdd(ssq + r, s); }
	v_pk_mul_f32 v[56:57], s[100:101], v[56:57] op_sel_hi:[0,1]
	v_pk_mul_f32 v[58:59], s[100:101], v[58:59] op_sel_hi:[0,1]
	v_exp_f32_e32 v60, v60
	v_exp_f32_e32 v61, v61
	v_exp_f32_e32 v62, v62
	v_exp_f32_e32 v63, v63
	v_exp_f32_e32 v56, v56
	v_exp_f32_e32 v57, v57
	v_exp_f32_e32 v58, v58
	v_exp_f32_e32 v59, v59
	v_pk_add_f32 v[60:61], s[100:101], v[60:61] op_sel:[1,0]
	v_pk_add_f32 v[62:63], s[100:101], v[62:63] op_sel:[1,0]
	v_pk_add_f32 v[56:57], s[100:101], v[56:57] op_sel:[1,0]
	v_pk_add_f32 v[58:59], s[100:101], v[58:59] op_sel:[1,0]
	v_rcp_f32_e32 v60, v60
	v_rcp_f32_e32 v61, v61
	v_rcp_f32_e32 v62, v62
	v_rcp_f32_e32 v63, v63
	v_rcp_f32_e32 v56, v56
	v_rcp_f32_e32 v57, v57
	v_rcp_f32_e32 v58, v58
	v_rcp_f32_e32 v59, v59
	v_pk_mul_f32 v[44:45], s[100:101], v[44:45] op_sel_hi:[0,1]
	v_pk_mul_f32 v[46:47], s[100:101], v[46:47] op_sel_hi:[0,1]
	v_pk_mul_f32 v[40:41], s[100:101], v[40:41] op_sel_hi:[0,1]
	v_pk_mul_f32 v[42:43], s[100:101], v[42:43] op_sel_hi:[0,1]
	v_exp_f32_e32 v44, v44
	v_exp_f32_e32 v45, v45
	v_exp_f32_e32 v46, v46
	v_exp_f32_e32 v47, v47
	v_exp_f32_e32 v40, v40
	v_exp_f32_e32 v41, v41
	v_exp_f32_e32 v42, v42
	v_exp_f32_e32 v43, v43
	v_pk_add_f32 v[44:45], s[100:101], v[44:45] op_sel:[1,0]
	v_pk_add_f32 v[46:47], s[100:101], v[46:47] op_sel:[1,0]
	v_pk_add_f32 v[40:41], s[100:101], v[40:41] op_sel:[1,0]
	v_pk_add_f32 v[42:43], s[100:101], v[42:43] op_sel:[1,0]
	v_rcp_f32_e32 v44, v44
	v_rcp_f32_e32 v45, v45
	v_rcp_f32_e32 v46, v46
	v_rcp_f32_e32 v47, v47
	v_rcp_f32_e32 v40, v40
	v_rcp_f32_e32 v41, v41
	v_rcp_f32_e32 v42, v42
	v_rcp_f32_e32 v43, v43
	v_pk_mul_f32 v[28:29], s[100:101], v[28:29] op_sel_hi:[0,1]
	v_pk_mul_f32 v[30:31], s[100:101], v[30:31] op_sel_hi:[0,1]
	v_pk_mul_f32 v[24:25], s[100:101], v[24:25] op_sel_hi:[0,1]
	v_pk_mul_f32 v[26:27], s[100:101], v[26:27] op_sel_hi:[0,1]
	v_exp_f32_e32 v28, v28
	v_exp_f32_e32 v29, v29
	v_exp_f32_e32 v30, v30
	v_exp_f32_e32 v31, v31
	v_exp_f32_e32 v24, v24
	v_exp_f32_e32 v25, v25
	v_exp_f32_e32 v26, v26
	v_exp_f32_e32 v27, v27
	v_pk_add_f32 v[28:29], s[100:101], v[28:29] op_sel:[1,0]
	v_pk_add_f32 v[30:31], s[100:101], v[30:31] op_sel:[1,0]
	v_pk_add_f32 v[24:25], s[100:101], v[24:25] op_sel:[1,0]
	v_pk_add_f32 v[26:27], s[100:101], v[26:27] op_sel:[1,0]
	v_rcp_f32_e32 v28, v28
	v_rcp_f32_e32 v29, v29
	v_rcp_f32_e32 v30, v30
	v_rcp_f32_e32 v31, v31
	v_rcp_f32_e32 v24, v24
	v_rcp_f32_e32 v25, v25
	v_rcp_f32_e32 v26, v26
	v_rcp_f32_e32 v27, v27
	v_pk_mul_f32 v[12:13], s[100:101], v[12:13] op_sel_hi:[0,1]
	v_pk_mul_f32 v[14:15], s[100:101], v[14:15] op_sel_hi:[0,1]
	v_pk_mul_f32 v[8:9], s[100:101], v[8:9] op_sel_hi:[0,1]
	v_pk_mul_f32 v[10:11], s[100:101], v[10:11] op_sel_hi:[0,1]
	v_exp_f32_e32 v12, v12
	v_exp_f32_e32 v13, v13
	v_exp_f32_e32 v14, v14
	v_exp_f32_e32 v15, v15
	v_exp_f32_e32 v8, v8
	v_exp_f32_e32 v9, v9
	v_exp_f32_e32 v10, v10
	v_exp_f32_e32 v11, v11
	v_pk_add_f32 v[12:13], s[100:101], v[12:13] op_sel:[1,0]
	v_pk_add_f32 v[14:15], s[100:101], v[14:15] op_sel:[1,0]
	v_pk_add_f32 v[8:9], s[100:101], v[8:9] op_sel:[1,0]
	v_pk_add_f32 v[10:11], s[100:101], v[10:11] op_sel:[1,0]
	v_rcp_f32_e32 v12, v12
	v_rcp_f32_e32 v13, v13
	v_rcp_f32_e32 v14, v14
	v_rcp_f32_e32 v15, v15
	v_rcp_f32_e32 v8, v8
	v_rcp_f32_e32 v9, v9
	v_rcp_f32_e32 v10, v10
	v_rcp_f32_e32 v11, v11
	s_nop 0
	s_waitcnt vmcnt(14)
	v_pk_fma_f32 v[222:223], v[124:125], v[112:113], v[222:223]
	v_pk_fma_f32 v[224:225], v[126:127], v[114:115], v[224:225]
	v_pk_fma_f32 v[218:219], v[120:121], v[116:117], v[218:219]
	v_pk_fma_f32 v[220:221], v[122:123], v[118:119], v[220:221]
	v_mul_f32_e32 v124, v222, v222
	v_mul_f32_e32 v125, v224, v224
	v_mul_f32_e32 v126, v218, v218
	v_mul_f32_e32 v127, v220, v220
	v_fmac_f32_e32 v124, v223, v223
	v_fmac_f32_e32 v125, v225, v225
	v_fmac_f32_e32 v126, v219, v219
	v_fmac_f32_e32 v127, v221, v221
	v_cvt_pk_bf16_f32 v112, v222, v223
	v_cvt_pk_bf16_f32 v113, v224, v225
	v_cvt_pk_bf16_f32 v114, v218, v219
	v_cvt_pk_bf16_f32 v115, v220, v221
	v_add_f32_e32 v124, v124, v125
	v_add_f32_e32 v126, v126, v127
	v_add_f32_e32 v194, v124, v126
	global_store_dwordx4 v191, v[112:115], s[20:21]
	v_mov_b32_e32 v202, v194
	s_nop 0
	s_nop 0
	v_permlane16_swap_b32_e32 v194, v202
	v_add_f32_e32 v194, v194, v202
	v_mov_b32_e32 v202, v194
	s_nop 1
	v_permlane32_swap_b32_e32 v194, v202
	v_add_f32_e32 v194, v194, v202
	s_and_b64 exec, exec, s[4:5]
	global_atomic_add_f32 v192, v194, s[60:61]
	s_mov_b64 exec, s[0:1]
	s_waitcnt vmcnt(14)
	v_pk_fma_f32 v[180:181], v[108:109], v[100:101], v[180:181]
	v_pk_fma_f32 v[182:183], v[110:111], v[102:103], v[182:183]
	v_pk_fma_f32 v[176:177], v[104:105], v[96:97], v[176:177]
	v_pk_fma_f32 v[178:179], v[106:107], v[98:99], v[178:179]
	v_mul_f32_e32 v108, v180, v180
	v_mul_f32_e32 v109, v182, v182
	v_mul_f32_e32 v110, v176, v176
	v_mul_f32_e32 v111, v178, v178
	v_fmac_f32_e32 v108, v181, v181
	v_fmac_f32_e32 v109, v183, v183
	v_fmac_f32_e32 v110, v177, v177
	v_fmac_f32_e32 v111, v179, v179
	v_cvt_pk_bf16_f32 v100, v180, v181
	v_cvt_pk_bf16_f32 v101, v182, v183
	v_cvt_pk_bf16_f32 v102, v176, v177
	v_cvt_pk_bf16_f32 v103, v178, v179
	v_add_f32_e32 v108, v108, v109
	v_add_f32_e32 v110, v110, v111
	v_add_u32_e32 v193, 0x8000, v191
	v_add_f32_e32 v195, v108, v110
	global_store_dwordx4 v193, v[100:103], s[20:21]
	v_mov_b32_e32 v203, v195
	v_add_u32_e32 v193, 0x40, v192
	s_nop 0
	v_permlane16_swap_b32_e32 v195, v203
	v_add_f32_e32 v195, v195, v203
	v_mov_b32_e32 v203, v195
	s_nop 1
	v_permlane32_swap_b32_e32 v195, v203
	v_add_f32_e32 v195, v195, v203
	s_and_b64 exec, exec, s[4:5]
	global_atomic_add_f32 v193, v195, s[60:61]
	s_mov_b64 exec, s[0:1]
	s_waitcnt vmcnt(14)
; __device__ __forceinline__ unsigned cvt_pk_bf16(float lo, float hi) { unsigned r; asm volatile("v_cvt_pk_bf16_f32 %0, %1, %2" : "=v"(r) : "v"(lo), "v"(hi)); return r; }
; __device__ __forceinline__ float fast_sigmoid(float x) { return __builtin_amdgcn_rcpf(1.0f + __builtin_amdgcn_exp2f(x * -1.44269504f)); }
;     __device__ __forceinline__ void operator()(const Acc& acc, const Unit& u, int wr, int wc, int fr, int fq, LAS unsigned char* lds, f32x4 epar) const {
;     ...
;             for (int m = 0; m < 4; ++m) { const int r = u.pm * BM + ai * HALF + wr * 64 + m * 16 + fr; const size_t off = (size_t)r * DM + c0;
;                 f32x4 v0 = xv[ai][m][0], v1 = xv[ai][m][1];
;                 const f32x4 za0 = acc[ai][0][m][0], za1 = acc[ai][0][m][1], zg0 = acc[ai][1][m][0], zg1 = acc[ai][1][m][1];
; #pragma unroll
;                 for (int j = 0; j < 4; ++j) { v0[j] += za0[j] * fast_sigmoid(zg0[j]); v1[j] += za1[j] * fast_sigmoid(zg1[j]); }
;                 u32x4 w; w.x = cvt_pk_bf16(v0[0], v0[1]); w.y = cvt_pk_bf16(v0[2], v0[3]); w.z = cvt_pk_bf16(v1[0], v1[1]); w.w = cvt_pk_bf16(v1[2], v1[3]);
;                 *(u32x4*)(HB + off) = w;
;                 float s = (v0[0] * v0[0] + v0[1] * v0[1]) + (v0[2] * v0[2] + v0[3] * v0[3]) + (v1[0] * v1[0] + v1[1] * v1[1]) + (v1[2] * v1[2] + v1[3] * v1[3]);
;                 s += __shfl_xor(s, 16); s += __shfl_xor(s, 32);
;                 if (fq == 0) unsafeAtomicAdd(ssq + r, s); }
	v_pk_fma_f32 v[172:173], v[92:93], v[84:85], v[172:173]
	v_pk_fma_f32 v[174:175], v[94:95], v[86:87], v[174:175]
	v_pk_fma_f32 v[168:169], v[88:89], v[80:81], v[168:169]
	v_pk_fma_f32 v[170:171], v[90:91], v[82:83], v[170:171]
	v_mul_f32_e32 v92, v172, v172
	v_mul_f32_e32 v93, v174, v174
	v_mul_f32_e32 v94, v168, v168
	v_mul_f32_e32 v95, v170, v170
	v_fmac_f32_e32 v92, v173, v173
	v_fmac_f32_e32 v93, v175, v175
	v_fmac_f32_e32 v94, v169, v169
	v_fmac_f32_e32 v95, v171, v171
	v_cvt_pk_bf16_f32 v84, v172, v173
	v_cvt_pk_bf16_f32 v85, v174, v175
	v_cvt_pk_bf16_f32 v86, v168, v169
	v_cvt_pk_bf16_f32 v87, v170, v171
	v_add_f32_e32 v92, v92, v93
	v_add_f32_e32 v94, v94, v95
	v_add_u32_e32 v193, 0x10000, v191
	v_add_f32_e32 v196, v92, v94
	global_store_dwordx4 v193, v[84:87], s[20:21]
	v_mov_b32_e32 v204, v196
	v_add_u32_e32 v193, 0x80, v192
	s_nop 0
	v_permlane16_swap_b32_e32 v196, v204
	v_add_f32_e32 v196, v196, v204
	v_mov_b32_e32 v204, v196
	s_nop 1
	v_permlane32_swap_b32_e32 v196, v204
	v_add_f32_e32 v196, v196, v204
	s_and_b64 exec, exec, s[4:5]
	global_atomic_add_f32 v193, v196, s[60:61]
	s_mov_b64 exec, s[0:1]
	s_waitcnt vmcnt(14)
	v_pk_fma_f32 v[164:165], v[76:77], v[68:69], v[164:165]
	v_pk_fma_f32 v[166:167], v[78:79], v[70:71], v[166:167]
	v_pk_fma_f32 v[160:161], v[72:73], v[64:65], v[160:161]
	v_pk_fma_f32 v[162:163], v[74:75], v[66:67], v[162:163]
	v_mul_f32_e32 v76, v164, v164
	v_mul_f32_e32 v77, v166, v166
	v_mul_f32_e32 v78, v160, v160
	v_mul_f32_e32 v79, v162, v162
	v_fmac_f32_e32 v76, v165, v165
	v_fmac_f32_e32 v77, v167, v167
	v_fmac_f32_e32 v78, v161, v161
	v_fmac_f32_e32 v79, v163, v163
	v_cvt_pk_bf16_f32 v68, v164, v165
	v_cvt_pk_bf16_f32 v69, v166, v167
	v_cvt_pk_bf16_f32 v70, v160, v161
	v_cvt_pk_bf16_f32 v71, v162, v163
	v_add_f32_e32 v76, v76, v77
	v_add_f32_e32 v78, v78, v79
	v_add_u32_e32 v193, 0x18000, v191
	v_add_f32_e32 v197, v76, v78
	global_store_dwordx4 v193, v[68:71], s[20:21]
	v_mov_b32_e32 v205, v197
	v_add_u32_e32 v193, 0xc0, v192
	s_nop 0
	v_permlane16_swap_b32_e32 v197, v205
	v_add_f32_e32 v197, v197, v205
	v_mov_b32_e32 v205, v197
	s_nop 1
	v_permlane32_swap_b32_e32 v197, v205
	v_add_f32_e32 v197, v197, v205
	s_and_b64 exec, exec, s[4:5]
	global_atomic_add_f32 v193, v197, s[60:61]
	s_mov_b64 exec, s[0:1]
	s_waitcnt vmcnt(14)
	v_pk_fma_f32 v[156:157], v[60:61], v[52:53], v[156:157]
	v_pk_fma_f32 v[158:159], v[62:63], v[54:55], v[158:159]
	v_pk_fma_f32 v[152:153], v[56:57], v[48:49], v[152:153]
	v_pk_fma_f32 v[154:155], v[58:59], v[50:51], v[154:155]
	v_mul_f32_e32 v60, v156, v156
	v_mul_f32_e32 v61, v158, v158
	v_mul_f32_e32 v62, v152, v152
	v_mul_f32_e32 v63, v154, v154
	v_fmac_f32_e32 v60, v157, v157
	v_fmac_f32_e32 v61, v159, v159
	v_fmac_f32_e32 v62, v153, v153
	v_fmac_f32_e32 v63, v155, v155
	v_cvt_pk_bf16_f32 v52, v156, v157
	v_cvt_pk_bf16_f32 v53, v158, v159
	v_cvt_pk_bf16_f32 v54, v152, v153
	v_cvt_pk_bf16_f32 v55, v154, v155
	v_add_f32_e32 v60, v60, v61
	v_add_f32_e32 v62, v62, v63
	v_add_u32_e32 v193, 0x40000, v191
	v_add_f32_e32 v198, v60, v62
	global_store_dwordx4 v193, v[52:55], s[20:21]
	v_mov_b32_e32 v124, v198
	v_add_u32_e32 v193, 0x200, v192
	s_nop 0
	v_permlane16_swap_b32_e32 v198, v124
	v_add_f32_e32 v198, v198, v124
	v_mov_b32_e32 v124, v198
	s_nop 1
	v_permlane32_swap_b32_e32 v198, v124
	v_add_f32_e32 v198, v198, v124
	s_and_b64 exec, exec, s[4:5]
	global_atomic_add_f32 v193, v198, s[60:61]
	s_mov_b64 exec, s[0:1]
	s_waitcnt vmcnt(14)
	v_pk_fma_f32 v[148:149], v[44:45], v[36:37], v[148:149]
	v_pk_fma_f32 v[150:151], v[46:47], v[38:39], v[150:151]
	v_pk_fma_f32 v[144:145], v[40:41], v[32:33], v[144:145]
	v_pk_fma_f32 v[146:147], v[42:43], v[34:35], v[146:147]
	v_mul_f32_e32 v44, v148, v148
	v_mul_f32_e32 v45, v150, v150
	v_mul_f32_e32 v46, v144, v144
	v_mul_f32_e32 v47, v146, v146
	v_fmac_f32_e32 v44, v149, v149
	v_fmac_f32_e32 v45, v151, v151
	v_fmac_f32_e32 v46, v145, v145
	v_fmac_f32_e32 v47, v147, v147
	v_cvt_pk_bf16_f32 v36, v148, v149
	v_cvt_pk_bf16_f32 v37, v150, v151
	v_cvt_pk_bf16_f32 v38, v144, v145
	v_cvt_pk_bf16_f32 v39, v146, v147
	v_add_f32_e32 v44, v44, v45
	v_add_f32_e32 v46, v46, v47
	v_add_u32_e32 v193, 0x48000, v191
	v_add_f32_e32 v199, v44, v46
	global_store_dwordx4 v193, v[36:39], s[20:21]
	v_mov_b32_e32 v125, v199
	v_add_u32_e32 v193, 0x240, v192
	s_nop 0
	v_permlane16_swap_b32_e32 v199, v125
	v_add_f32_e32 v199, v199, v125
	v_mov_b32_e32 v125, v199
	s_nop 1
	v_permlane32_swap_b32_e32 v199, v125
	v_add_f32_e32 v199, v199, v125
	s_and_b64 exec, exec, s[4:5]
	global_atomic_add_f32 v193, v199, s[60:61]
	s_mov_b64 exec, s[0:1]
	s_waitcnt vmcnt(14)
	v_pk_fma_f32 v[140:141], v[28:29], v[20:21], v[140:141]
	v_pk_fma_f32 v[142:143], v[30:31], v[22:23], v[142:143]
	v_pk_fma_f32 v[136:137], v[24:25], v[16:17], v[136:137]
	v_pk_fma_f32 v[138:139], v[26:27], v[18:19], v[138:139]
	v_mul_f32_e32 v28, v140, v140
	v_mul_f32_e32 v29, v142, v142
	v_mul_f32_e32 v30, v136, v136
	v_mul_f32_e32 v31, v138, v138
	v_fmac_f32_e32 v28, v141, v141
	v_fmac_f32_e32 v29, v143, v143
	v_fmac_f32_e32 v30, v137, v137
	v_fmac_f32_e32 v31, v139, v139
	v_cvt_pk_bf16_f32 v20, v140, v141
	v_cvt_pk_bf16_f32 v21, v142, v143
	v_cvt_pk_bf16_f32 v22, v136, v137
	v_cvt_pk_bf16_f32 v23, v138, v139
	v_add_f32_e32 v28, v28, v29
	v_add_f32_e32 v30, v30, v31
	v_add_u32_e32 v193, 0x50000, v191
	v_add_f32_e32 v200, v28, v30
	global_store_dwordx4 v193, v[20:23], s[20:21]
	v_mov_b32_e32 v126, v200
	v_add_u32_e32 v193, 0x280, v192
	s_nop 0
	v_permlane16_swap_b32_e32 v200, v126
	v_add_f32_e32 v200, v200, v126
	v_mov_b32_e32 v126, v200
	s_nop 1
	v_permlane32_swap_b32_e32 v200, v126
	v_add_f32_e32 v200, v200, v126
	s_and_b64 exec, exec, s[4:5]
	global_atomic_add_f32 v193, v200, s[60:61]
	s_mov_b64 exec, s[0:1]
	s_waitcnt vmcnt(14)
	v_pk_fma_f32 v[132:133], v[12:13], v[4:5], v[132:133]
	v_pk_fma_f32 v[134:135], v[14:15], v[6:7], v[134:135]
	v_pk_fma_f32 v[128:129], v[8:9], v[0:1], v[128:129]
	v_pk_fma_f32 v[130:131], v[10:11], v[2:3], v[130:131]
	v_mul_f32_e32 v12, v132, v132
	v_mul_f32_e32 v13, v134, v134
	v_mul_f32_e32 v14, v128, v128
	v_mul_f32_e32 v15, v130, v130
	v_fmac_f32_e32 v12, v133, v133
	v_fmac_f32_e32 v13, v135, v135
	v_fmac_f32_e32 v14, v129, v129
	v_fmac_f32_e32 v15, v131, v131
	v_cvt_pk_bf16_f32 v4, v132, v133
	v_cvt_pk_bf16_f32 v5, v134, v135
	v_cvt_pk_bf16_f32 v6, v128, v129
	v_cvt_pk_bf16_f32 v7, v130, v131
	v_add_f32_e32 v12, v12, v13
	v_add_f32_e32 v14, v14, v15
	v_add_u32_e32 v193, 0x58000, v191
	v_add_f32_e32 v201, v12, v14
	global_store_dwordx4 v193, v[4:7], s[20:21]
	v_mov_b32_e32 v127, v201
	v_add_u32_e32 v193, 0x2c0, v192
	s_nop 0
	v_permlane16_swap_b32_e32 v201, v127
	v_add_f32_e32 v201, v201, v127
	v_mov_b32_e32 v127, v201
	s_nop 1
	v_permlane32_swap_b32_e32 v201, v127
	v_add_f32_e32 v201, v201, v127
	s_and_b64 exec, exec, s[4:5]
	global_atomic_add_f32 v193, v201, s[60:61]
	s_mov_b64 exec, s[0:1]
	s_branch .LBB0_618

;     __device__ __forceinline__ void operator()(const Acc& acc, const Unit& u, int wr, int wc, int fr, int fq, LAS unsigned char* lds, f32x4 epar) const {
;     ...
;         LAS float* pw = (LAS float*)(lds + STAGE_BYTES + 64 + (wr * 4 + wc) * 1024);
;         *(LAS f32x4*)(pw + (fq * 16 + fr) * 4) = epar;
;         asm volatile("s_waitcnt lgkmcnt(0)" ::: "memory");
;         float w0[NV], w1[NV], w2[NV], bb[NV];
; #pragma unroll
;         for (int i = 0; i < NV; i += 4) { const f32x4 a = *(const LAS f32x4*)(pw + NV * fq + i), b = *(const LAS f32x4*)(pw + 32 + NV * fq + i), c = *(const LAS f32x4*)(pw + 64 + NV * fq + i);
;             f32x4 d = (f32x4){0.f, 0.f, 0.f, 0.f}; if (MODE == 0) d = *(const LAS f32x4*)(pw + 96 + NV * fq + i);
; #pragma unroll
;             for (int j = 0; j < 4; ++j) { w0[i + j] = a[j]; w1[i + j] = b[j]; w2[i + j] = c[j]; bb[i + j] = d[j]; } }
;         float sq[2][4];
; #pragma unroll
;         for (int ai = 0; ai < 2; ++ai)
; #pragma unroll
;             for (int m = 0; m < 4; ++m) sq[ai][m] = pw[128 + ai * 64 + m * 16 + fr];
; #pragma unroll
;         for (int ai = 0; ai < 2; ++ai) {
;             const int strip = u.pm * 4 + ai * 2 + wr;
;             float p1prev[NV], p2prev[NV];
; #pragma unroll
;             for (int i = 0; i < NV; ++i) { p1prev[i] = 0.f; p2prev[i] = 0.f; }
; #pragma unroll
;             for (int m = 0; m < 4; ++m) {
;                 const int r = u.pm * BM + ai * HALF + wr * 64 + m * 16 + fr;
;                 const float rs = __builtin_amdgcn_rsqf(sq[ai][m] * (1.0f / DM) + RMS_EPS);
;                 float X[NV], Y[NV], o[NV];
;                 if (MODE == 0) {
; #pragma unroll
;                     for (int n = 0; n < 2; ++n)
; #pragma unroll
;                         for (int j = 0; j < 4; ++j) { X[n * 4 + j] = acc[ai][0][m][n][j] * rs; Y[n * 4 + j] = acc[ai][1][m][n][j] * rs; }
;                 } else {
; #pragma unroll
;                     for (int j = 0; j < 4; ++j) { X[j] = (acc[ai][0][m][1][j] * rs) * (acc[ai][1][m][0][j] * rs); Y[j] = acc[ai][0][m][0][j] * rs; }
;                 }
; #pragma unroll
;                 for (int i = 0; i < NV; ++i) {
;                     const float a1 = dpp_rot<0x121>(X[i]), a2 = dpp_rot<0x122>(X[i]);
;                     const float q1 = fr >= 1 ? a1 : p1prev[i], q2 = fr >= 2 ? a2 : p2prev[i];
;                     p1prev[i] = a1; p2prev[i] = a2;
.LBB0_692:
	s_mov_b32 s100, 0xbfb8aa3b
	ds_write_b128 v198, v[72:75]
	s_mov_b64 s[24:25], exec
	s_waitcnt lgkmcnt(0)
	ds_read_b128 v[88:91], v199
	ds_read_b128 v[92:95], v199 offset:16
	ds_read_b128 v[128:131], v199 offset:128
	ds_read_b128 v[132:135], v199 offset:144
	ds_read_b128 v[136:139], v199 offset:256
	ds_read_b128 v[140:143], v199 offset:272
	ds_read_b128 v[174:177], v199 offset:384
	ds_read_b128 v[178:181], v199 offset:400
	ds_read2_b32 v[182:183], v191 offset0:128 offset1:144
	ds_read2_b32 v[184:185], v191 offset0:160 offset1:176
	ds_read2_b32 v[76:77], v191 offset0:192 offset1:208
	ds_read2_b32 v[78:79], v191 offset0:224 offset1:240
	v_lshl_add_u32 v230, s70, 8, v190
	v_lshl_or_b32 v231, s72, 7, v192
	v_mul_u32_u24_e32 v230, 0x1600, v230
	s_lshl_b32 s26, s70, 2
	s_add_i32 s26, s26, s14
	s_mul_i32 s16, s26, 6
	v_and_b32_e32 v233, 15, v190
	v_lshl_add_u32 v230, v231, 1, v230
	v_add_u32_e32 v233, s16, v233
	v_mul_u32_u24_e32 v233, 0x1600, v233
	s_nop 0
	v_lshl_add_u32 v233, v231, 1, v233
	s_waitcnt lgkmcnt(0)
	v_pk_mul_f32 v[88:89], s[100:101], v[88:89] op_sel_hi:[0,1]
	v_pk_mul_f32 v[90:91], s[100:101], v[90:91] op_sel_hi:[0,1]
	v_pk_mul_f32 v[92:93], s[100:101], v[92:93] op_sel_hi:[0,1]
	v_pk_mul_f32 v[94:95], s[100:101], v[94:95] op_sel_hi:[0,1]
	v_pk_mul_f32 v[128:129], s[100:101], v[128:129] op_sel_hi:[0,1]
	v_pk_mul_f32 v[130:131], s[100:101], v[130:131] op_sel_hi:[0,1]
	v_pk_mul_f32 v[132:133], s[100:101], v[132:133] op_sel_hi:[0,1]
	v_pk_mul_f32 v[134:135], s[100:101], v[134:135] op_sel_hi:[0,1]
	v_pk_mul_f32 v[136:137], s[100:101], v[136:137] op_sel_hi:[0,1]
	v_pk_mul_f32 v[138:139], s[100:101], v[138:139] op_sel_hi:[0,1]
	v_pk_mul_f32 v[140:141], s[100:101], v[140:141] op_sel_hi:[0,1]
	v_pk_mul_f32 v[142:143], s[100:101], v[142:143] op_sel_hi:[0,1]
	v_pk_mul_f32 v[174:175], s[100:101], v[174:175] op_sel_hi:[0,1]
	v_pk_mul_f32 v[176:177], s[100:101], v[176:177] op_sel_hi:[0,1]
	v_pk_mul_f32 v[178:179], s[100:101], v[178:179] op_sel_hi:[0,1]
	v_pk_mul_f32 v[180:181], s[100:101], v[180:181] op_sel_hi:[0,1]
	v_fmamk_f32 v182, v182, 0x3a800000, v200
	v_fmamk_f32 v183, v183, 0x3a800000, v200
	v_fmamk_f32 v184, v184, 0x3a800000, v200
	v_fmamk_f32 v185, v185, 0x3a800000, v200
	v_fmamk_f32 v76, v76, 0x3a800000, v200
	v_fmamk_f32 v77, v77, 0x3a800000, v200
	v_fmamk_f32 v78, v78, 0x3a800000, v200
	v_fmamk_f32 v79, v79, 0x3a800000, v200
	v_pk_mul_f32 v[202:203], s[100:101], v[182:183] op_sel_hi:[0,1]
	v_pk_mul_f32 v[204:205], s[100:101], v[184:185] op_sel_hi:[0,1]
	v_pk_mul_f32 v[206:207], s[100:101], v[76:77] op_sel_hi:[0,1]
	v_pk_mul_f32 v[208:209], s[100:101], v[78:79] op_sel_hi:[0,1]
	v_rsq_f32_e32 v182, v182
	v_rsq_f32_e32 v183, v183
	v_rsq_f32_e32 v184, v184
	v_rsq_f32_e32 v185, v185
	v_rsq_f32_e32 v76, v76
	v_rsq_f32_e32 v77, v77
	v_rsq_f32_e32 v78, v78
	v_rsq_f32_e32 v79, v79
	s_nop 0
	v_pk_mul_f32 v[202:203], v[202:203], v[182:183]
	v_pk_mul_f32 v[204:205], v[204:205], v[184:185]
	v_pk_mul_f32 v[206:207], v[206:207], v[76:77]
	v_pk_mul_f32 v[208:209], v[208:209], v[78:79]
	v_pk_mul_f32 v[152:153], v[152:153], v[182:183] op_sel_hi:[1,0]
	v_pk_mul_f32 v[154:155], v[154:155], v[182:183] op_sel_hi:[1,0]
	v_pk_mul_f32 v[144:145], v[144:145], v[182:183] op_sel_hi:[1,0]
	v_pk_mul_f32 v[146:147], v[146:147], v[182:183] op_sel_hi:[1,0]
	v_pk_fma_f32 v[210:211], v[152:153], v[136:137], v[174:175]
	v_pk_fma_f32 v[212:213], v[154:155], v[138:139], v[176:177]
	v_pk_fma_f32 v[214:215], v[144:145], v[140:141], v[178:179]
	v_pk_fma_f32 v[216:217], v[146:147], v[142:143], v[180:181]
	v_pk_mul_f32 v[218:219], v[156:157], v[182:183] op_sel_hi:[1,0]
	v_pk_mul_f32 v[220:221], v[158:159], v[182:183] op_sel_hi:[1,0]
	v_pk_mul_f32 v[222:223], v[148:149], v[182:183] op_sel_hi:[1,0]
	v_pk_mul_f32 v[224:225], v[150:151], v[182:183] op_sel_hi:[1,0]
	v_cvt_pk_bf16_f32 v236, v152, v153
	v_cvt_pk_bf16_f32 v237, v154, v155
	v_cvt_pk_bf16_f32 v238, v144, v145
	v_cvt_pk_bf16_f32 v239, v146, v147
	v_cvt_pk_bf16_f32 v240, v218, v219
	v_cvt_pk_bf16_f32 v241, v220, v221
	v_cvt_pk_bf16_f32 v242, v222, v223
	v_cvt_pk_bf16_f32 v243, v224, v225
	v_add_u32_e32 v234, 0x2c00, v233
	v_add_u32_e32 v235, 0x5800, v233
	s_andn2_b64 exec, exec, s[8:9]
	global_store_dwordx4 v234, v[236:239], s[42:43]
	global_store_dwordx4 v235, v[240:243], s[42:43]
	s_mov_b64 exec, s[24:25]
	v_fmac_f32_dpp v210, v152, v128 row_shr:1 row_mask:0xf bank_mask:0xf
	v_fmac_f32_dpp v211, v153, v129 row_shr:1 row_mask:0xf bank_mask:0xf
	v_fmac_f32_dpp v212, v154, v130 row_shr:1 row_mask:0xf bank_mask:0xf
	v_fmac_f32_dpp v213, v155, v131 row_shr:1 row_mask:0xf bank_mask:0xf
	v_fmac_f32_dpp v214, v144, v132 row_shr:1 row_mask:0xf bank_mask:0xf
	v_fmac_f32_dpp v215, v145, v133 row_shr:1 row_mask:0xf bank_mask:0xf
	v_fmac_f32_dpp v216, v146, v134 row_shr:1 row_mask:0xf bank_mask:0xf
	v_fmac_f32_dpp v217, v147, v135 row_shr:1 row_mask:0xf bank_mask:0xf
	v_fmac_f32_dpp v210, v152, v88 row_shr:2 row_mask:0xf bank_mask:0xf
	v_fmac_f32_dpp v211, v153, v89 row_shr:2 row_mask:0xf bank_mask:0xf
	v_fmac_f32_dpp v212, v154, v90 row_shr:2 row_mask:0xf bank_mask:0xf
	v_fmac_f32_dpp v213, v155, v91 row_shr:2 row_mask:0xf bank_mask:0xf
	v_fmac_f32_dpp v214, v144, v92 row_shr:2 row_mask:0xf bank_mask:0xf
	v_fmac_f32_dpp v215, v145, v93 row_shr:2 row_mask:0xf bank_mask:0xf
	v_fmac_f32_dpp v216, v146, v94 row_shr:2 row_mask:0xf bank_mask:0xf
	v_fmac_f32_dpp v217, v147, v95 row_shr:2 row_mask:0xf bank_mask:0xf
	v_exp_f32_e32 v218, v210
	v_exp_f32_e32 v219, v211
	v_exp_f32_e32 v220, v212
	v_exp_f32_e32 v221, v213
	v_exp_f32_e32 v222, v214
	v_exp_f32_e32 v223, v215
	v_exp_f32_e32 v224, v216
	v_exp_f32_e32 v225, v217
;     __device__ __forceinline__ void operator()(const Acc& acc, const Unit& u, int wr, int wc, int fr, int fq, LAS unsigned char* lds, f32x4 epar) const {
;     ...
;             for (int m = 0; m < 4; ++m) {
;                 const int r = u.pm * BM + ai * HALF + wr * 64 + m * 16 + fr;
;                 const float rs = __builtin_amdgcn_rsqf(sq[ai][m] * (1.0f / DM) + RMS_EPS);
;                 float X[NV], Y[NV], o[NV];
;                 if (MODE == 0) {
; #pragma unroll
;                     for (int n = 0; n < 2; ++n)
; #pragma unroll
;                         for (int j = 0; j < 4; ++j) { X[n * 4 + j] = acc[ai][0][m][n][j] * rs; Y[n * 4 + j] = acc[ai][1][m][n][j] * rs; }
;                 } else {
; #pragma unroll
;                     for (int j = 0; j < 4; ++j) { X[j] = (acc[ai][0][m][1][j] * rs) * (acc[ai][1][m][0][j] * rs); Y[j] = acc[ai][0][m][0][j] * rs; }
;                 }
; #pragma unroll
;                 for (int i = 0; i < NV; ++i) {
;                     const float a1 = dpp_rot<0x121>(X[i]), a2 = dpp_rot<0x122>(X[i]);
;                     const float q1 = fr >= 1 ? a1 : p1prev[i], q2 = fr >= 2 ? a2 : p2prev[i];
;                     p1prev[i] = a1; p2prev[i] = a2;
;                     const float cv = w2[i] * X[i] + w1[i] * q1 + w0[i] * q2 + bb[i];
;                     o[i] = MODE == 0 ? silu_f(cv) * Y[i] : cv * Y[i];
;                 }
;                 if (m == 0 && fr < 2) {
;                     bf16_t* hx = halo + ((size_t)strip * 6 + 2 + fr) * C + c0; bf16_t* hy = halo + ((size_t)strip * 6 + 4 + fr) * C + c0;
;                     u32x4 px, py; px.x = cvt_pk_bf16(X[0], X[1]); px.y = cvt_pk_bf16(X[2], X[3]); px.z = cvt_pk_bf16(X[4 % NV], X[5 % NV]); px.w = cvt_pk_bf16(X[6 % NV], X[7 % NV]);
;                     py.x = cvt_pk_bf16(Y[0], Y[1]); py.y = cvt_pk_bf16(Y[2], Y[3]); py.z = cvt_pk_bf16(Y[4 % NV], Y[5 % NV]); py.w = cvt_pk_bf16(Y[6 % NV], Y[7 % NV]);
;                     if (MODE == 0) { *(u32x4*)hx = px; *(u32x4*)hy = py; } else { u32x2 a; a.x = px.x; a.y = px.y; *(u32x2*)hx = a; u32x2 b; b.x = py.x; b.y = py.y; *(u32x2*)hy = b; }
;                 } else {
;                     if (MODE == 0) { u32x4 w; w.x = cvt_pk_bf16(o[0], o[1]); w.y = cvt_pk_bf16(o[2], o[3]); w.z = cvt_pk_bf16(o[4 % NV], o[5 % NV]); w.w = cvt_pk_bf16(o[6 % NV], o[7 % NV]);
	v_pk_fma_f32 v[218:219], v[218:219], v[202:203], v[202:203] op_sel_hi:[1,0,0]
	v_pk_fma_f32 v[220:221], v[220:221], v[202:203], v[202:203] op_sel_hi:[1,0,0]
	v_pk_fma_f32 v[222:223], v[222:223], v[202:203], v[202:203] op_sel_hi:[1,0,0]
	v_pk_fma_f32 v[224:225], v[224:225], v[202:203], v[202:203] op_sel_hi:[1,0,0]
	v_rcp_f32_e32 v218, v218
	v_rcp_f32_e32 v219, v219
	v_rcp_f32_e32 v220, v220
	v_rcp_f32_e32 v221, v221
	v_rcp_f32_e32 v222, v222
	v_rcp_f32_e32 v223, v223
	v_rcp_f32_e32 v224, v224
	v_rcp_f32_e32 v225, v225
	v_pk_mul_f32 v[210:211], v[210:211], v[218:219]
	v_pk_mul_f32 v[212:213], v[212:213], v[220:221]
	v_pk_mul_f32 v[214:215], v[214:215], v[222:223]
	v_pk_mul_f32 v[216:217], v[216:217], v[224:225]
	v_pk_mul_f32 v[156:157], v[210:211], v[156:157]
	v_pk_mul_f32 v[158:159], v[212:213], v[158:159]
	v_pk_mul_f32 v[148:149], v[214:215], v[148:149]
	v_pk_mul_f32 v[150:151], v[216:217], v[150:151]
	v_cvt_pk_bf16_f32 v226, v156, v157
	v_cvt_pk_bf16_f32 v227, v158, v159
	v_cvt_pk_bf16_f32 v228, v148, v149
	v_cvt_pk_bf16_f32 v229, v150, v151
	v_add_u32_e32 v234, 0x0, v230
	s_and_b64 exec, exec, s[8:9]
	global_store_dwordx4 v234, v[226:229], s[96:97] nt
	s_mov_b64 exec, s[24:25]
	v_pk_mul_f32 v[124:125], v[124:125], v[182:183] op_sel:[0,1]
	v_pk_mul_f32 v[126:127], v[126:127], v[182:183] op_sel:[0,1]
	v_pk_mul_f32 v[120:121], v[120:121], v[182:183] op_sel:[0,1]
	v_pk_mul_f32 v[122:123], v[122:123], v[182:183] op_sel:[0,1]
	v_pk_fma_f32 v[210:211], v[124:125], v[136:137], v[174:175]
	v_pk_fma_f32 v[212:213], v[126:127], v[138:139], v[176:177]
	v_pk_fma_f32 v[214:215], v[120:121], v[140:141], v[178:179]
	v_pk_fma_f32 v[216:217], v[122:123], v[142:143], v[180:181]
	v_fmac_f32_dpp v210, v124, v128 row_shr:1 row_mask:0xf bank_mask:0xf
	v_fmac_f32_dpp v211, v125, v129 row_shr:1 row_mask:0xf bank_mask:0xf
	v_fmac_f32_dpp v212, v126, v130 row_shr:1 row_mask:0xf bank_mask:0xf
	v_fmac_f32_dpp v213, v127, v131 row_shr:1 row_mask:0xf bank_mask:0xf
	v_fmac_f32_dpp v214, v120, v132 row_shr:1 row_mask:0xf bank_mask:0xf
	v_fmac_f32_dpp v215, v121, v133 row_shr:1 row_mask:0xf bank_mask:0xf
	v_fmac_f32_dpp v216, v122, v134 row_shr:1 row_mask:0xf bank_mask:0xf
	v_fmac_f32_dpp v217, v123, v135 row_shr:1 row_mask:0xf bank_mask:0xf
	v_fmac_f32_dpp v210, v124, v88 row_shr:2 row_mask:0xf bank_mask:0xf
	v_fmac_f32_dpp v211, v125, v89 row_shr:2 row_mask:0xf bank_mask:0xf
	v_fmac_f32_dpp v212, v126, v90 row_shr:2 row_mask:0xf bank_mask:0xf
	v_fmac_f32_dpp v213, v127, v91 row_shr:2 row_mask:0xf bank_mask:0xf
	v_fmac_f32_dpp v214, v120, v92 row_shr:2 row_mask:0xf bank_mask:0xf
	v_fmac_f32_dpp v215, v121, v93 row_shr:2 row_mask:0xf bank_mask:0xf
	v_fmac_f32_dpp v216, v122, v94 row_shr:2 row_mask:0xf bank_mask:0xf
	v_fmac_f32_dpp v217, v123, v95 row_shr:2 row_mask:0xf bank_mask:0xf
	v_fmac_f32_dpp v210, v152, v128 row_shl:15 row_mask:0xf bank_mask:0xf
	v_fmac_f32_dpp v211, v153, v129 row_shl:15 row_mask:0xf bank_mask:0xf
	v_fmac_f32_dpp v212, v154, v130 row_shl:15 row_mask:0xf bank_mask:0xf
	v_fmac_f32_dpp v213, v155, v131 row_shl:15 row_mask:0xf bank_mask:0xf
	v_fmac_f32_dpp v214, v144, v132 row_shl:15 row_mask:0xf bank_mask:0xf
	v_fmac_f32_dpp v215, v145, v133 row_shl:15 row_mask:0xf bank_mask:0xf
	v_fmac_f32_dpp v216, v146, v134 row_shl:15 row_mask:0xf bank_mask:0xf
	v_fmac_f32_dpp v217, v147, v135 row_shl:15 row_mask:0xf bank_mask:0xf
	v_fmac_f32_dpp v210, v152, v88 row_shl:14 row_mask:0xf bank_mask:0xf
	v_fmac_f32_dpp v211, v153, v89 row_shl:14 row_mask:0xf bank_mask:0xf
	v_fmac_f32_dpp v212, v154, v90 row_shl:14 row_mask:0xf bank_mask:0xf
	v_fmac_f32_dpp v213, v155, v91 row_shl:14 row_mask:0xf bank_mask:0xf
	v_fmac_f32_dpp v214, v144, v92 row_shl:14 row_mask:0xf bank_mask:0xf
	v_fmac_f32_dpp v215, v145, v93 row_shl:14 row_mask:0xf bank_mask:0xf
	v_fmac_f32_dpp v216, v146, v94 row_shl:14 row_mask:0xf bank_mask:0xf
	v_fmac_f32_dpp v217, v147, v95 row_shl:14 row_mask:0xf bank_mask:0xf
	v_exp_f32_e32 v218, v210
	v_exp_f32_e32 v219, v211
	v_exp_f32_e32 v220, v212
	v_exp_f32_e32 v221, v213
	v_exp_f32_e32 v222, v214
	v_exp_f32_e32 v223, v215
	v_exp_f32_e32 v224, v216
	v_exp_f32_e32 v225, v217
	v_pk_fma_f32 v[218:219], v[218:219], v[202:203], v[202:203] op_sel:[0,1,1]
	v_pk_fma_f32 v[220:221], v[220:221], v[202:203], v[202:203] op_sel:[0,1,1]
	v_pk_fma_f32 v[222:223], v[222:223], v[202:203], v[202:203] op_sel:[0,1,1]
	v_pk_fma_f32 v[224:225], v[224:225], v[202:203], v[202:203] op_sel:[0,1,1]
	v_rcp_f32_e32 v218, v218
	v_rcp_f32_e32 v219, v219
	v_rcp_f32_e32 v220, v220
	v_rcp_f32_e32 v221, v221
	v_rcp_f32_e32 v222, v222
	v_rcp_f32_e32 v223, v223
	v_rcp_f32_e32 v224, v224
	v_rcp_f32_e32 v225, v225
	v_pk_mul_f32 v[210:211], v[210:211], v[218:219]
	v_pk_mul_f32 v[212:213], v[212:213], v[220:221]
	v_pk_mul_f32 v[214:215], v[214:215], v[222:223]
	v_pk_mul_f32 v[216:217], v[216:217], v[224:225]
	v_pk_mul_f32 v[116:117], v[210:211], v[116:117]
	v_pk_mul_f32 v[118:119], v[212:213], v[118:119]
	v_pk_mul_f32 v[112:113], v[214:215], v[112:113]
	v_pk_mul_f32 v[114:115], v[216:217], v[114:115]
	v_cvt_pk_bf16_f32 v226, v116, v117
	v_cvt_pk_bf16_f32 v227, v118, v119
	v_cvt_pk_bf16_f32 v228, v112, v113
	v_cvt_pk_bf16_f32 v229, v114, v115
	v_add_u32_e32 v234, 0x16000, v230
	global_store_dwordx4 v234, v[226:229], s[96:97] nt
	v_pk_mul_f32 v[108:109], v[108:109], v[184:185] op_sel_hi:[1,0]
	v_pk_mul_f32 v[110:111], v[110:111], v[184:185] op_sel_hi:[1,0]
	v_pk_mul_f32 v[104:105], v[104:105], v[184:185] op_sel_hi:[1,0]
	v_pk_mul_f32 v[106:107], v[106:107], v[184:185] op_sel_hi:[1,0]
	v_pk_fma_f32 v[210:211], v[108:109], v[136:137], v[174:175]
	v_pk_fma_f32 v[212:213], v[110:111], v[138:139], v[176:177]
;     __device__ __forceinline__ void operator()(const Acc& acc, const Unit& u, int wr, int wc, int fr, int fq, LAS unsigned char* lds, f32x4 epar) const {
;     ...
;             for (int m = 0; m < 4; ++m) {
;                 const int r = u.pm * BM + ai * HALF + wr * 64 + m * 16 + fr;
;                 const float rs = __builtin_amdgcn_rsqf(sq[ai][m] * (1.0f / DM) + RMS_EPS);
;                 float X[NV], Y[NV], o[NV];
;                 if (MODE == 0) {
; #pragma unroll
;                     for (int n = 0; n < 2; ++n)
; #pragma unroll
;                         for (int j = 0; j < 4; ++j) { X[n * 4 + j] = acc[ai][0][m][n][j] * rs; Y[n * 4 + j] = acc[ai][1][m][n][j] * rs; }
;                 } else {
; #pragma unroll
;                     for (int j = 0; j < 4; ++j) { X[j] = (acc[ai][0][m][1][j] * rs) * (acc[ai][1][m][0][j] * rs); Y[j] = acc[ai][0][m][0][j] * rs; }
;                 }
; #pragma unroll
;                 for (int i = 0; i < NV; ++i) {
;                     const float a1 = dpp_rot<0x121>(X[i]), a2 = dpp_rot<0x122>(X[i]);
;                     const float q1 = fr >= 1 ? a1 : p1prev[i], q2 = fr >= 2 ? a2 : p2prev[i];
;                     p1prev[i] = a1; p2prev[i] = a2;
;                     const float cv = w2[i] * X[i] + w1[i] * q1 + w0[i] * q2 + bb[i];
;                     o[i] = MODE == 0 ? silu_f(cv) * Y[i] : cv * Y[i];
;                 }
;                 if (m == 0 && fr < 2) {
;                     bf16_t* hx = halo + ((size_t)strip * 6 + 2 + fr) * C + c0; bf16_t* hy = halo + ((size_t)strip * 6 + 4 + fr) * C + c0;
;                     u32x4 px, py; px.x = cvt_pk_bf16(X[0], X[1]); px.y = cvt_pk_bf16(X[2], X[3]); px.z = cvt_pk_bf16(X[4 % NV], X[5 % NV]); px.w = cvt_pk_bf16(X[6 % NV], X[7 % NV]);
;                     py.x = cvt_pk_bf16(Y[0], Y[1]); py.y = cvt_pk_bf16(Y[2], Y[3]); py.z = cvt_pk_bf16(Y[4 % NV], Y[5 % NV]); py.w = cvt_pk_bf16(Y[6 % NV], Y[7 % NV]);
;                     if (MODE == 0) { *(u32x4*)hx = px; *(u32x4*)hy = py; } else { u32x2 a; a.x = px.x; a.y = px.y; *(u32x2*)hx = a; u32x2 b; b.x = py.x; b.y = py.y; *(u32x2*)hy = b; }
;                 } else {
;                     if (MODE == 0) { u32x4 w; w.x = cvt_pk_bf16(o[0], o[1]); w.y = cvt_pk_bf16(o[2], o[3]); w.z = cvt_pk_bf16(o[4 % NV], o[5 % NV]); w.w = cvt_pk_bf16(o[6 % NV], o[7 % NV]);
	v_pk_fma_f32 v[214:215], v[104:105], v[140:141], v[178:179]
	v_pk_fma_f32 v[216:217], v[106:107], v[142:143], v[180:181]
	v_fmac_f32_dpp v210, v108, v128 row_shr:1 row_mask:0xf bank_mask:0xf
	v_fmac_f32_dpp v211, v109, v129 row_shr:1 row_mask:0xf bank_mask:0xf
	v_fmac_f32_dpp v212, v110, v130 row_shr:1 row_mask:0xf bank_mask:0xf
	v_fmac_f32_dpp v213, v111, v131 row_shr:1 row_mask:0xf bank_mask:0xf
	v_fmac_f32_dpp v214, v104, v132 row_shr:1 row_mask:0xf bank_mask:0xf
	v_fmac_f32_dpp v215, v105, v133 row_shr:1 row_mask:0xf bank_mask:0xf
	v_fmac_f32_dpp v216, v106, v134 row_shr:1 row_mask:0xf bank_mask:0xf
	v_fmac_f32_dpp v217, v107, v135 row_shr:1 row_mask:0xf bank_mask:0xf
	v_fmac_f32_dpp v210, v108, v88 row_shr:2 row_mask:0xf bank_mask:0xf
	v_fmac_f32_dpp v211, v109, v89 row_shr:2 row_mask:0xf bank_mask:0xf
	v_fmac_f32_dpp v212, v110, v90 row_shr:2 row_mask:0xf bank_mask:0xf
	v_fmac_f32_dpp v213, v111, v91 row_shr:2 row_mask:0xf bank_mask:0xf
	v_fmac_f32_dpp v214, v104, v92 row_shr:2 row_mask:0xf bank_mask:0xf
	v_fmac_f32_dpp v215, v105, v93 row_shr:2 row_mask:0xf bank_mask:0xf
	v_fmac_f32_dpp v216, v106, v94 row_shr:2 row_mask:0xf bank_mask:0xf
	v_fmac_f32_dpp v217, v107, v95 row_shr:2 row_mask:0xf bank_mask:0xf
	v_fmac_f32_dpp v210, v124, v128 row_shl:15 row_mask:0xf bank_mask:0xf
	v_fmac_f32_dpp v211, v125, v129 row_shl:15 row_mask:0xf bank_mask:0xf
	v_fmac_f32_dpp v212, v126, v130 row_shl:15 row_mask:0xf bank_mask:0xf
	v_fmac_f32_dpp v213, v127, v131 row_shl:15 row_mask:0xf bank_mask:0xf
	v_fmac_f32_dpp v214, v120, v132 row_shl:15 row_mask:0xf bank_mask:0xf
	v_fmac_f32_dpp v215, v121, v133 row_shl:15 row_mask:0xf bank_mask:0xf
	v_fmac_f32_dpp v216, v122, v134 row_shl:15 row_mask:0xf bank_mask:0xf
	v_fmac_f32_dpp v217, v123, v135 row_shl:15 row_mask:0xf bank_mask:0xf
	v_fmac_f32_dpp v210, v124, v88 row_shl:14 row_mask:0xf bank_mask:0xf
	v_fmac_f32_dpp v211, v125, v89 row_shl:14 row_mask:0xf bank_mask:0xf
	v_fmac_f32_dpp v212, v126, v90 row_shl:14 row_mask:0xf bank_mask:0xf
	v_fmac_f32_dpp v213, v127, v91 row_shl:14 row_mask:0xf bank_mask:0xf
	v_fmac_f32_dpp v214, v120, v92 row_shl:14 row_mask:0xf bank_mask:0xf
	v_fmac_f32_dpp v215, v121, v93 row_shl:14 row_mask:0xf bank_mask:0xf
	v_fmac_f32_dpp v216, v122, v94 row_shl:14 row_mask:0xf bank_mask:0xf
	v_fmac_f32_dpp v217, v123, v95 row_shl:14 row_mask:0xf bank_mask:0xf
	v_exp_f32_e32 v218, v210
	v_exp_f32_e32 v219, v211
	v_exp_f32_e32 v220, v212
	v_exp_f32_e32 v221, v213
	v_exp_f32_e32 v222, v214
	v_exp_f32_e32 v223, v215
	v_exp_f32_e32 v224, v216
	v_exp_f32_e32 v225, v217
	v_pk_fma_f32 v[218:219], v[218:219], v[204:205], v[204:205] op_sel_hi:[1,0,0]
	v_pk_fma_f32 v[220:221], v[220:221], v[204:205], v[204:205] op_sel_hi:[1,0,0]
	v_pk_fma_f32 v[222:223], v[222:223], v[204:205], v[204:205] op_sel_hi:[1,0,0]
	v_pk_fma_f32 v[224:225], v[224:225], v[204:205], v[204:205] op_sel_hi:[1,0,0]
	v_rcp_f32_e32 v218, v218
	v_rcp_f32_e32 v219, v219
	v_rcp_f32_e32 v220, v220
	v_rcp_f32_e32 v221, v221
	v_rcp_f32_e32 v222, v222
	v_rcp_f32_e32 v223, v223
	v_rcp_f32_e32 v224, v224
	v_rcp_f32_e32 v225, v225
	v_pk_mul_f32 v[210:211], v[210:211], v[218:219]
	v_pk_mul_f32 v[212:213], v[212:213], v[220:221]
	v_pk_mul_f32 v[214:215], v[214:215], v[222:223]
	v_pk_mul_f32 v[216:217], v[216:217], v[224:225]
	v_pk_mul_f32 v[100:101], v[210:211], v[100:101]
	v_pk_mul_f32 v[102:103], v[212:213], v[102:103]
	v_pk_mul_f32 v[96:97], v[214:215], v[96:97]
	v_pk_mul_f32 v[98:99], v[216:217], v[98:99]
	v_cvt_pk_bf16_f32 v226, v100, v101
	v_cvt_pk_bf16_f32 v227, v102, v103
	v_cvt_pk_bf16_f32 v228, v96, v97
	v_cvt_pk_bf16_f32 v229, v98, v99
	v_add_u32_e32 v234, 0x2c000, v230
	global_store_dwordx4 v234, v[226:229], s[96:97] nt
	v_pk_mul_f32 v[84:85], v[84:85], v[184:185] op_sel:[0,1]
	v_pk_mul_f32 v[86:87], v[86:87], v[184:185] op_sel:[0,1]
	v_pk_mul_f32 v[80:81], v[80:81], v[184:185] op_sel:[0,1]
	v_pk_mul_f32 v[82:83], v[82:83], v[184:185] op_sel:[0,1]
	v_pk_fma_f32 v[210:211], v[84:85], v[136:137], v[174:175]
	v_pk_fma_f32 v[212:213], v[86:87], v[138:139], v[176:177]
	v_pk_fma_f32 v[214:215], v[80:81], v[140:141], v[178:179]
	v_pk_fma_f32 v[216:217], v[82:83], v[142:143], v[180:181]
	v_cvt_pk_bf16_f32 v236, v84, v85
	v_cvt_pk_bf16_f32 v237, v86, v87
	v_cvt_pk_bf16_f32 v238, v80, v81
	v_cvt_pk_bf16_f32 v239, v82, v83
	v_add_u32_e32 v235, 0xfffecc00, v233
	s_and_b64 exec, exec, s[10:11]
	global_store_dwordx4 v235, v[236:239], s[42:43]
	s_mov_b64 exec, s[24:25]
	v_fmac_f32_dpp v210, v84, v128 row_shr:1 row_mask:0xf bank_mask:0xf
	v_fmac_f32_dpp v211, v85, v129 row_shr:1 row_mask:0xf bank_mask:0xf
	v_fmac_f32_dpp v212, v86, v130 row_shr:1 row_mask:0xf bank_mask:0xf
	v_fmac_f32_dpp v213, v87, v131 row_shr:1 row_mask:0xf bank_mask:0xf
	v_fmac_f32_dpp v214, v80, v132 row_shr:1 row_mask:0xf bank_mask:0xf
	v_fmac_f32_dpp v215, v81, v133 row_shr:1 row_mask:0xf bank_mask:0xf
	v_fmac_f32_dpp v216, v82, v134 row_shr:1 row_mask:0xf bank_mask:0xf
	v_fmac_f32_dpp v217, v83, v135 row_shr:1 row_mask:0xf bank_mask:0xf
	v_fmac_f32_dpp v210, v84, v88 row_shr:2 row_mask:0xf bank_mask:0xf
	v_fmac_f32_dpp v211, v85, v89 row_shr:2 row_mask:0xf bank_mask:0xf
	v_fmac_f32_dpp v212, v86, v90 row_shr:2 row_mask:0xf bank_mask:0xf
	v_fmac_f32_dpp v213, v87, v91 row_shr:2 row_mask:0xf bank_mask:0xf
	v_fmac_f32_dpp v214, v80, v92 row_shr:2 row_mask:0xf bank_mask:0xf
	v_fmac_f32_dpp v215, v81, v93 row_shr:2 row_mask:0xf bank_mask:0xf
	v_fmac_f32_dpp v216, v82, v94 row_shr:2 row_mask:0xf bank_mask:0xf
	v_fmac_f32_dpp v217, v83, v95 row_shr:2 row_mask:0xf bank_mask:0xf
	v_fmac_f32_dpp v210, v108, v128 row_shl:15 row_mask:0xf bank_mask:0xf
; __device__ __forceinline__ unsigned cvt_pk_bf16(float lo, float hi) { unsigned r; asm volatile("v_cvt_pk_bf16_f32 %0, %1, %2" : "=v"(r) : "v"(lo), "v"(hi)); return r; }
;     __device__ __forceinline__ void operator()(const Acc& acc, const Unit& u, int wr, int wc, int fr, int fq, LAS unsigned char* lds, f32x4 epar) const {
;     ...
;             for (int m = 0; m < 4; ++m) {
;                 const int r = u.pm * BM + ai * HALF + wr * 64 + m * 16 + fr;
;                 const float rs = __builtin_amdgcn_rsqf(sq[ai][m] * (1.0f / DM) + RMS_EPS);
;                 float X[NV], Y[NV], o[NV];
;                 if (MODE == 0) {
; #pragma unroll
;                     for (int n = 0; n < 2; ++n)
; #pragma unroll
;                         for (int j = 0; j < 4; ++j) { X[n * 4 + j] = acc[ai][0][m][n][j] * rs; Y[n * 4 + j] = acc[ai][1][m][n][j] * rs; }
;                 } else {
; #pragma unroll
;                     for (int j = 0; j < 4; ++j) { X[j] = (acc[ai][0][m][1][j] * rs) * (acc[ai][1][m][0][j] * rs); Y[j] = acc[ai][0][m][0][j] * rs; }
;                 }
; #pragma unroll
;                 for (int i = 0; i < NV; ++i) {
;                     const float a1 = dpp_rot<0x121>(X[i]), a2 = dpp_rot<0x122>(X[i]);
;                     const float q1 = fr >= 1 ? a1 : p1prev[i], q2 = fr >= 2 ? a2 : p2prev[i];
;                     p1prev[i] = a1; p2prev[i] = a2;
;                     const float cv = w2[i] * X[i] + w1[i] * q1 + w0[i] * q2 + bb[i];
;                     o[i] = MODE == 0 ? silu_f(cv) * Y[i] : cv * Y[i];
;                 }
;                 if (m == 0 && fr < 2) {
;                     bf16_t* hx = halo + ((size_t)strip * 6 + 2 + fr) * C + c0; bf16_t* hy = halo + ((size_t)strip * 6 + 4 + fr) * C + c0;
;                     u32x4 px, py; px.x = cvt_pk_bf16(X[0], X[1]); px.y = cvt_pk_bf16(X[2], X[3]); px.z = cvt_pk_bf16(X[4 % NV], X[5 % NV]); px.w = cvt_pk_bf16(X[6 % NV], X[7 % NV]);
;                     py.x = cvt_pk_bf16(Y[0], Y[1]); py.y = cvt_pk_bf16(Y[2], Y[3]); py.z = cvt_pk_bf16(Y[4 % NV], Y[5 % NV]); py.w = cvt_pk_bf16(Y[6 % NV], Y[7 % NV]);
;                     if (MODE == 0) { *(u32x4*)hx = px; *(u32x4*)hy = py; } else { u32x2 a; a.x = px.x; a.y = px.y; *(u32x2*)hx = a; u32x2 b; b.x = py.x; b.y = py.y; *(u32x2*)hy = b; }
	v_fmac_f32_dpp v211, v109, v129 row_shl:15 row_mask:0xf bank_mask:0xf
	v_fmac_f32_dpp v212, v110, v130 row_shl:15 row_mask:0xf bank_mask:0xf
	v_fmac_f32_dpp v213, v111, v131 row_shl:15 row_mask:0xf bank_mask:0xf
	v_fmac_f32_dpp v214, v104, v132 row_shl:15 row_mask:0xf bank_mask:0xf
	v_fmac_f32_dpp v215, v105, v133 row_shl:15 row_mask:0xf bank_mask:0xf
	v_fmac_f32_dpp v216, v106, v134 row_shl:15 row_mask:0xf bank_mask:0xf
	v_fmac_f32_dpp v217, v107, v135 row_shl:15 row_mask:0xf bank_mask:0xf
	v_fmac_f32_dpp v210, v108, v88 row_shl:14 row_mask:0xf bank_mask:0xf
	v_fmac_f32_dpp v211, v109, v89 row_shl:14 row_mask:0xf bank_mask:0xf
	v_fmac_f32_dpp v212, v110, v90 row_shl:14 row_mask:0xf bank_mask:0xf
	v_fmac_f32_dpp v213, v111, v91 row_shl:14 row_mask:0xf bank_mask:0xf
	v_fmac_f32_dpp v214, v104, v92 row_shl:14 row_mask:0xf bank_mask:0xf
	v_fmac_f32_dpp v215, v105, v93 row_shl:14 row_mask:0xf bank_mask:0xf
	v_fmac_f32_dpp v216, v106, v94 row_shl:14 row_mask:0xf bank_mask:0xf
	v_fmac_f32_dpp v217, v107, v95 row_shl:14 row_mask:0xf bank_mask:0xf
	v_exp_f32_e32 v218, v210
	v_exp_f32_e32 v219, v211
	v_exp_f32_e32 v220, v212
	v_exp_f32_e32 v221, v213
	v_exp_f32_e32 v222, v214
	v_exp_f32_e32 v223, v215
	v_exp_f32_e32 v224, v216
	v_exp_f32_e32 v225, v217
	v_pk_fma_f32 v[218:219], v[218:219], v[204:205], v[204:205] op_sel:[0,1,1]
	v_pk_fma_f32 v[220:221], v[220:221], v[204:205], v[204:205] op_sel:[0,1,1]
	v_pk_fma_f32 v[222:223], v[222:223], v[204:205], v[204:205] op_sel:[0,1,1]
	v_pk_fma_f32 v[224:225], v[224:225], v[204:205], v[204:205] op_sel:[0,1,1]
	v_rcp_f32_e32 v218, v218
	v_rcp_f32_e32 v219, v219
	v_rcp_f32_e32 v220, v220
	v_rcp_f32_e32 v221, v221
	v_rcp_f32_e32 v222, v222
	v_rcp_f32_e32 v223, v223
	v_rcp_f32_e32 v224, v224
	v_rcp_f32_e32 v225, v225
	v_pk_mul_f32 v[210:211], v[210:211], v[218:219]
	v_pk_mul_f32 v[212:213], v[212:213], v[220:221]
	v_pk_mul_f32 v[214:215], v[214:215], v[222:223]
	v_pk_mul_f32 v[216:217], v[216:217], v[224:225]
	v_pk_mul_f32 v[68:69], v[210:211], v[68:69]
	v_pk_mul_f32 v[70:71], v[212:213], v[70:71]
	v_pk_mul_f32 v[64:65], v[214:215], v[64:65]
	v_pk_mul_f32 v[66:67], v[216:217], v[66:67]
	v_cvt_pk_bf16_f32 v226, v68, v69
	v_cvt_pk_bf16_f32 v227, v70, v71
	v_cvt_pk_bf16_f32 v228, v64, v65
	v_cvt_pk_bf16_f32 v229, v66, v67
	v_add_u32_e32 v234, 0x42000, v230
	global_store_dwordx4 v234, v[226:229], s[96:97] nt
	v_pk_mul_f32 v[60:61], v[60:61], v[76:77] op_sel_hi:[1,0]
	v_pk_mul_f32 v[62:63], v[62:63], v[76:77] op_sel_hi:[1,0]
	v_pk_mul_f32 v[52:53], v[52:53], v[76:77] op_sel_hi:[1,0]
	v_pk_mul_f32 v[54:55], v[54:55], v[76:77] op_sel_hi:[1,0]
	v_pk_fma_f32 v[210:211], v[60:61], v[136:137], v[174:175]
	v_pk_fma_f32 v[212:213], v[62:63], v[138:139], v[176:177]
	v_pk_fma_f32 v[214:215], v[52:53], v[140:141], v[178:179]
	v_pk_fma_f32 v[216:217], v[54:55], v[142:143], v[180:181]
	v_pk_mul_f32 v[218:219], v[56:57], v[76:77] op_sel_hi:[1,0]
	v_pk_mul_f32 v[220:221], v[58:59], v[76:77] op_sel_hi:[1,0]
	v_pk_mul_f32 v[222:223], v[48:49], v[76:77] op_sel_hi:[1,0]
	v_pk_mul_f32 v[224:225], v[50:51], v[76:77] op_sel_hi:[1,0]
	v_cvt_pk_bf16_f32 v236, v60, v61
	v_cvt_pk_bf16_f32 v237, v62, v63
	v_cvt_pk_bf16_f32 v238, v52, v53
	v_cvt_pk_bf16_f32 v239, v54, v55
	v_cvt_pk_bf16_f32 v240, v218, v219
	v_cvt_pk_bf16_f32 v241, v220, v221
	v_cvt_pk_bf16_f32 v242, v222, v223
	v_cvt_pk_bf16_f32 v243, v224, v225
	v_add_u32_e32 v234, 0x13400, v233
	v_add_u32_e32 v235, 0x16000, v233
	s_andn2_b64 exec, exec, s[8:9]
	global_store_dwordx4 v234, v[236:239], s[42:43]
	global_store_dwordx4 v235, v[240:243], s[42:43]
	s_mov_b64 exec, s[24:25]
	v_fmac_f32_dpp v210, v60, v128 row_shr:1 row_mask:0xf bank_mask:0xf
	v_fmac_f32_dpp v211, v61, v129 row_shr:1 row_mask:0xf bank_mask:0xf
	v_fmac_f32_dpp v212, v62, v130 row_shr:1 row_mask:0xf bank_mask:0xf
	v_fmac_f32_dpp v213, v63, v131 row_shr:1 row_mask:0xf bank_mask:0xf
	v_fmac_f32_dpp v214, v52, v132 row_shr:1 row_mask:0xf bank_mask:0xf
	v_fmac_f32_dpp v215, v53, v133 row_shr:1 row_mask:0xf bank_mask:0xf
	v_fmac_f32_dpp v216, v54, v134 row_shr:1 row_mask:0xf bank_mask:0xf
	v_fmac_f32_dpp v217, v55, v135 row_shr:1 row_mask:0xf bank_mask:0xf
	v_fmac_f32_dpp v210, v60, v88 row_shr:2 row_mask:0xf bank_mask:0xf
	v_fmac_f32_dpp v211, v61, v89 row_shr:2 row_mask:0xf bank_mask:0xf
	v_fmac_f32_dpp v212, v62, v90 row_shr:2 row_mask:0xf bank_mask:0xf
	v_fmac_f32_dpp v213, v63, v91 row_shr:2 row_mask:0xf bank_mask:0xf
	v_fmac_f32_dpp v214, v52, v92 row_shr:2 row_mask:0xf bank_mask:0xf
	v_fmac_f32_dpp v215, v53, v93 row_shr:2 row_mask:0xf bank_mask:0xf
	v_fmac_f32_dpp v216, v54, v94 row_shr:2 row_mask:0xf bank_mask:0xf
	v_fmac_f32_dpp v217, v55, v95 row_shr:2 row_mask:0xf bank_mask:0xf
	v_exp_f32_e32 v218, v210
	v_exp_f32_e32 v219, v211
	v_exp_f32_e32 v220, v212
	v_exp_f32_e32 v221, v213
	v_exp_f32_e32 v222, v214
	v_exp_f32_e32 v223, v215
	v_exp_f32_e32 v224, v216
	v_exp_f32_e32 v225, v217
	v_pk_fma_f32 v[218:219], v[218:219], v[206:207], v[206:207] op_sel_hi:[1,0,0]
	v_pk_fma_f32 v[220:221], v[220:221], v[206:207], v[206:207] op_sel_hi:[1,0,0]
	v_pk_fma_f32 v[222:223], v[222:223], v[206:207], v[206:207] op_sel_hi:[1,0,0]
	v_pk_fma_f32 v[224:225], v[224:225], v[206:207], v[206:207] op_sel_hi:[1,0,0]
	v_rcp_f32_e32 v218, v218
	v_rcp_f32_e32 v219, v219
	v_rcp_f32_e32 v220, v220
	v_rcp_f32_e32 v221, v221
	v_rcp_f32_e32 v222, v222
	v_rcp_f32_e32 v223, v223
	v_rcp_f32_e32 v224, v224
	v_rcp_f32_e32 v225, v225
	v_pk_mul_f32 v[210:211], v[210:211], v[218:219]
	v_pk_mul_f32 v[212:213], v[212:213], v[220:221]
	v_pk_mul_f32 v[214:215], v[214:215], v[222:223]
	v_pk_mul_f32 v[216:217], v[216:217], v[224:225]
;     __device__ __forceinline__ void operator()(const Acc& acc, const Unit& u, int wr, int wc, int fr, int fq, LAS unsigned char* lds, f32x4 epar) const {
;     ...
;             for (int m = 0; m < 4; ++m) {
;                 const int r = u.pm * BM + ai * HALF + wr * 64 + m * 16 + fr;
;                 const float rs = __builtin_amdgcn_rsqf(sq[ai][m] * (1.0f / DM) + RMS_EPS);
;                 float X[NV], Y[NV], o[NV];
;                 if (MODE == 0) {
; #pragma unroll
;                     for (int n = 0; n < 2; ++n)
; #pragma unroll
;                         for (int j = 0; j < 4; ++j) { X[n * 4 + j] = acc[ai][0][m][n][j] * rs; Y[n * 4 + j] = acc[ai][1][m][n][j] * rs; }
;                 } else {
; #pragma unroll
;                     for (int j = 0; j < 4; ++j) { X[j] = (acc[ai][0][m][1][j] * rs) * (acc[ai][1][m][0][j] * rs); Y[j] = acc[ai][0][m][0][j] * rs; }
;                 }
; #pragma unroll
;                 for (int i = 0; i < NV; ++i) {
;                     const float a1 = dpp_rot<0x121>(X[i]), a2 = dpp_rot<0x122>(X[i]);
;                     const float q1 = fr >= 1 ? a1 : p1prev[i], q2 = fr >= 2 ? a2 : p2prev[i];
;                     p1prev[i] = a1; p2prev[i] = a2;
;                     const float cv = w2[i] * X[i] + w1[i] * q1 + w0[i] * q2 + bb[i];
;                     o[i] = MODE == 0 ? silu_f(cv) * Y[i] : cv * Y[i];
;                 }
;                 if (m == 0 && fr < 2) {
;                     bf16_t* hx = halo + ((size_t)strip * 6 + 2 + fr) * C + c0; bf16_t* hy = halo + ((size_t)strip * 6 + 4 + fr) * C + c0;
;                     u32x4 px, py; px.x = cvt_pk_bf16(X[0], X[1]); px.y = cvt_pk_bf16(X[2], X[3]); px.z = cvt_pk_bf16(X[4 % NV], X[5 % NV]); px.w = cvt_pk_bf16(X[6 % NV], X[7 % NV]);
;                     py.x = cvt_pk_bf16(Y[0], Y[1]); py.y = cvt_pk_bf16(Y[2], Y[3]); py.z = cvt_pk_bf16(Y[4 % NV], Y[5 % NV]); py.w = cvt_pk_bf16(Y[6 % NV], Y[7 % NV]);
;                     if (MODE == 0) { *(u32x4*)hx = px; *(u32x4*)hy = py; } else { u32x2 a; a.x = px.x; a.y = px.y; *(u32x2*)hx = a; u32x2 b; b.x = py.x; b.y = py.y; *(u32x2*)hy = b; }
;                 } else {
;                     if (MODE == 0) { u32x4 w; w.x = cvt_pk_bf16(o[0], o[1]); w.y = cvt_pk_bf16(o[2], o[3]); w.z = cvt_pk_bf16(o[4 % NV], o[5 % NV]); w.w = cvt_pk_bf16(o[6 % NV], o[7 % NV]);
	v_pk_mul_f32 v[56:57], v[210:211], v[56:57]
	v_pk_mul_f32 v[58:59], v[212:213], v[58:59]
	v_pk_mul_f32 v[48:49], v[214:215], v[48:49]
	v_pk_mul_f32 v[50:51], v[216:217], v[50:51]
	v_cvt_pk_bf16_f32 v226, v56, v57
	v_cvt_pk_bf16_f32 v227, v58, v59
	v_cvt_pk_bf16_f32 v228, v48, v49
	v_cvt_pk_bf16_f32 v229, v50, v51
	v_add_u32_e32 v234, 0xb0000, v230
	s_and_b64 exec, exec, s[8:9]
	global_store_dwordx4 v234, v[226:229], s[96:97] nt
	s_mov_b64 exec, s[24:25]
	v_pk_mul_f32 v[44:45], v[44:45], v[76:77] op_sel:[0,1]
	v_pk_mul_f32 v[46:47], v[46:47], v[76:77] op_sel:[0,1]
	v_pk_mul_f32 v[40:41], v[40:41], v[76:77] op_sel:[0,1]
	v_pk_mul_f32 v[42:43], v[42:43], v[76:77] op_sel:[0,1]
	v_pk_fma_f32 v[210:211], v[44:45], v[136:137], v[174:175]
	v_pk_fma_f32 v[212:213], v[46:47], v[138:139], v[176:177]
	v_pk_fma_f32 v[214:215], v[40:41], v[140:141], v[178:179]
	v_pk_fma_f32 v[216:217], v[42:43], v[142:143], v[180:181]
	v_fmac_f32_dpp v210, v44, v128 row_shr:1 row_mask:0xf bank_mask:0xf
	v_fmac_f32_dpp v211, v45, v129 row_shr:1 row_mask:0xf bank_mask:0xf
	v_fmac_f32_dpp v212, v46, v130 row_shr:1 row_mask:0xf bank_mask:0xf
	v_fmac_f32_dpp v213, v47, v131 row_shr:1 row_mask:0xf bank_mask:0xf
	v_fmac_f32_dpp v214, v40, v132 row_shr:1 row_mask:0xf bank_mask:0xf
	v_fmac_f32_dpp v215, v41, v133 row_shr:1 row_mask:0xf bank_mask:0xf
	v_fmac_f32_dpp v216, v42, v134 row_shr:1 row_mask:0xf bank_mask:0xf
	v_fmac_f32_dpp v217, v43, v135 row_shr:1 row_mask:0xf bank_mask:0xf
	v_fmac_f32_dpp v210, v44, v88 row_shr:2 row_mask:0xf bank_mask:0xf
	v_fmac_f32_dpp v211, v45, v89 row_shr:2 row_mask:0xf bank_mask:0xf
	v_fmac_f32_dpp v212, v46, v90 row_shr:2 row_mask:0xf bank_mask:0xf
	v_fmac_f32_dpp v213, v47, v91 row_shr:2 row_mask:0xf bank_mask:0xf
	v_fmac_f32_dpp v214, v40, v92 row_shr:2 row_mask:0xf bank_mask:0xf
	v_fmac_f32_dpp v215, v41, v93 row_shr:2 row_mask:0xf bank_mask:0xf
	v_fmac_f32_dpp v216, v42, v94 row_shr:2 row_mask:0xf bank_mask:0xf
	v_fmac_f32_dpp v217, v43, v95 row_shr:2 row_mask:0xf bank_mask:0xf
	v_fmac_f32_dpp v210, v60, v128 row_shl:15 row_mask:0xf bank_mask:0xf
	v_fmac_f32_dpp v211, v61, v129 row_shl:15 row_mask:0xf bank_mask:0xf
	v_fmac_f32_dpp v212, v62, v130 row_shl:15 row_mask:0xf bank_mask:0xf
	v_fmac_f32_dpp v213, v63, v131 row_shl:15 row_mask:0xf bank_mask:0xf
	v_fmac_f32_dpp v214, v52, v132 row_shl:15 row_mask:0xf bank_mask:0xf
	v_fmac_f32_dpp v215, v53, v133 row_shl:15 row_mask:0xf bank_mask:0xf
	v_fmac_f32_dpp v216, v54, v134 row_shl:15 row_mask:0xf bank_mask:0xf
	v_fmac_f32_dpp v217, v55, v135 row_shl:15 row_mask:0xf bank_mask:0xf
	v_fmac_f32_dpp v210, v60, v88 row_shl:14 row_mask:0xf bank_mask:0xf
	v_fmac_f32_dpp v211, v61, v89 row_shl:14 row_mask:0xf bank_mask:0xf
	v_fmac_f32_dpp v212, v62, v90 row_shl:14 row_mask:0xf bank_mask:0xf
	v_fmac_f32_dpp v213, v63, v91 row_shl:14 row_mask:0xf bank_mask:0xf
	v_fmac_f32_dpp v214, v52, v92 row_shl:14 row_mask:0xf bank_mask:0xf
	v_fmac_f32_dpp v215, v53, v93 row_shl:14 row_mask:0xf bank_mask:0xf
	v_fmac_f32_dpp v216, v54, v94 row_shl:14 row_mask:0xf bank_mask:0xf
	v_fmac_f32_dpp v217, v55, v95 row_shl:14 row_mask:0xf bank_mask:0xf
	v_exp_f32_e32 v218, v210
	v_exp_f32_e32 v219, v211
	v_exp_f32_e32 v220, v212
	v_exp_f32_e32 v221, v213
	v_exp_f32_e32 v222, v214
	v_exp_f32_e32 v223, v215
	v_exp_f32_e32 v224, v216
	v_exp_f32_e32 v225, v217
	v_pk_fma_f32 v[218:219], v[218:219], v[206:207], v[206:207] op_sel:[0,1,1]
	v_pk_fma_f32 v[220:221], v[220:221], v[206:207], v[206:207] op_sel:[0,1,1]
	v_pk_fma_f32 v[222:223], v[222:223], v[206:207], v[206:207] op_sel:[0,1,1]
	v_pk_fma_f32 v[224:225], v[224:225], v[206:207], v[206:207] op_sel:[0,1,1]
	v_rcp_f32_e32 v218, v218
	v_rcp_f32_e32 v219, v219
	v_rcp_f32_e32 v220, v220
	v_rcp_f32_e32 v221, v221
	v_rcp_f32_e32 v222, v222
	v_rcp_f32_e32 v223, v223
	v_rcp_f32_e32 v224, v224
	v_rcp_f32_e32 v225, v225
	v_pk_mul_f32 v[210:211], v[210:211], v[218:219]
	v_pk_mul_f32 v[212:213], v[212:213], v[220:221]
	v_pk_mul_f32 v[214:215], v[214:215], v[222:223]
	v_pk_mul_f32 v[216:217], v[216:217], v[224:225]
	v_pk_mul_f32 v[36:37], v[210:211], v[36:37]
	v_pk_mul_f32 v[38:39], v[212:213], v[38:39]
	v_pk_mul_f32 v[32:33], v[214:215], v[32:33]
	v_pk_mul_f32 v[34:35], v[216:217], v[34:35]
	v_cvt_pk_bf16_f32 v226, v36, v37
	v_cvt_pk_bf16_f32 v227, v38, v39
	v_cvt_pk_bf16_f32 v228, v32, v33
	v_cvt_pk_bf16_f32 v229, v34, v35
	v_add_u32_e32 v234, 0xc6000, v230
	global_store_dwordx4 v234, v[226:229], s[96:97] nt
	v_pk_mul_f32 v[28:29], v[28:29], v[78:79] op_sel_hi:[1,0]
	v_pk_mul_f32 v[30:31], v[30:31], v[78:79] op_sel_hi:[1,0]
	v_pk_mul_f32 v[24:25], v[24:25], v[78:79] op_sel_hi:[1,0]
	v_pk_mul_f32 v[26:27], v[26:27], v[78:79] op_sel_hi:[1,0]
	v_pk_fma_f32 v[210:211], v[28:29], v[136:137], v[174:175]
	v_pk_fma_f32 v[212:213], v[30:31], v[138:139], v[176:177]
	v_pk_fma_f32 v[214:215], v[24:25], v[140:141], v[178:179]
	v_pk_fma_f32 v[216:217], v[26:27], v[142:143], v[180:181]
	v_fmac_f32_dpp v210, v28, v128 row_shr:1 row_mask:0xf bank_mask:0xf
	v_fmac_f32_dpp v211, v29, v129 row_shr:1 row_mask:0xf bank_mask:0xf
	v_fmac_f32_dpp v212, v30, v130 row_shr:1 row_mask:0xf bank_mask:0xf
	v_fmac_f32_dpp v213, v31, v131 row_shr:1 row_mask:0xf bank_mask:0xf
	v_fmac_f32_dpp v214, v24, v132 row_shr:1 row_mask:0xf bank_mask:0xf
	v_fmac_f32_dpp v215, v25, v133 row_shr:1 row_mask:0xf bank_mask:0xf
	v_fmac_f32_dpp v216, v26, v134 row_shr:1 row_mask:0xf bank_mask:0xf
	v_fmac_f32_dpp v217, v27, v135 row_shr:1 row_mask:0xf bank_mask:0xf
	v_fmac_f32_dpp v210, v28, v88 row_shr:2 row_mask:0xf bank_mask:0xf
	v_fmac_f32_dpp v211, v29, v89 row_shr:2 row_mask:0xf bank_mask:0xf
;     __device__ __forceinline__ void operator()(const Acc& acc, const Unit& u, int wr, int wc, int fr, int fq, LAS unsigned char* lds, f32x4 epar) const {
;     ...
;             for (int m = 0; m < 4; ++m) {
;                 const int r = u.pm * BM + ai * HALF + wr * 64 + m * 16 + fr;
;                 const float rs = __builtin_amdgcn_rsqf(sq[ai][m] * (1.0f / DM) + RMS_EPS);
;                 float X[NV], Y[NV], o[NV];
;                 if (MODE == 0) {
; #pragma unroll
;                     for (int n = 0; n < 2; ++n)
; #pragma unroll
;                         for (int j = 0; j < 4; ++j) { X[n * 4 + j] = acc[ai][0][m][n][j] * rs; Y[n * 4 + j] = acc[ai][1][m][n][j] * rs; }
;                 } else {
; #pragma unroll
;                     for (int j = 0; j < 4; ++j) { X[j] = (acc[ai][0][m][1][j] * rs) * (acc[ai][1][m][0][j] * rs); Y[j] = acc[ai][0][m][0][j] * rs; }
;                 }
; #pragma unroll
;                 for (int i = 0; i < NV; ++i) {
;                     const float a1 = dpp_rot<0x121>(X[i]), a2 = dpp_rot<0x122>(X[i]);
;                     const float q1 = fr >= 1 ? a1 : p1prev[i], q2 = fr >= 2 ? a2 : p2prev[i];
;                     p1prev[i] = a1; p2prev[i] = a2;
;                     const float cv = w2[i] * X[i] + w1[i] * q1 + w0[i] * q2 + bb[i];
;                     o[i] = MODE == 0 ? silu_f(cv) * Y[i] : cv * Y[i];
;                 }
;                 if (m == 0 && fr < 2) {
;                     bf16_t* hx = halo + ((size_t)strip * 6 + 2 + fr) * C + c0; bf16_t* hy = halo + ((size_t)strip * 6 + 4 + fr) * C + c0;
;                     u32x4 px, py; px.x = cvt_pk_bf16(X[0], X[1]); px.y = cvt_pk_bf16(X[2], X[3]); px.z = cvt_pk_bf16(X[4 % NV], X[5 % NV]); px.w = cvt_pk_bf16(X[6 % NV], X[7 % NV]);
;                     py.x = cvt_pk_bf16(Y[0], Y[1]); py.y = cvt_pk_bf16(Y[2], Y[3]); py.z = cvt_pk_bf16(Y[4 % NV], Y[5 % NV]); py.w = cvt_pk_bf16(Y[6 % NV], Y[7 % NV]);
;                     if (MODE == 0) { *(u32x4*)hx = px; *(u32x4*)hy = py; } else { u32x2 a; a.x = px.x; a.y = px.y; *(u32x2*)hx = a; u32x2 b; b.x = py.x; b.y = py.y; *(u32x2*)hy = b; }
;                 } else {
;                     if (MODE == 0) { u32x4 w; w.x = cvt_pk_bf16(o[0], o[1]); w.y = cvt_pk_bf16(o[2], o[3]); w.z = cvt_pk_bf16(o[4 % NV], o[5 % NV]); w.w = cvt_pk_bf16(o[6 % NV], o[7 % NV]);
	v_fmac_f32_dpp v212, v30, v90 row_shr:2 row_mask:0xf bank_mask:0xf
	v_fmac_f32_dpp v213, v31, v91 row_shr:2 row_mask:0xf bank_mask:0xf
	v_fmac_f32_dpp v214, v24, v92 row_shr:2 row_mask:0xf bank_mask:0xf
	v_fmac_f32_dpp v215, v25, v93 row_shr:2 row_mask:0xf bank_mask:0xf
	v_fmac_f32_dpp v216, v26, v94 row_shr:2 row_mask:0xf bank_mask:0xf
	v_fmac_f32_dpp v217, v27, v95 row_shr:2 row_mask:0xf bank_mask:0xf
	v_fmac_f32_dpp v210, v44, v128 row_shl:15 row_mask:0xf bank_mask:0xf
	v_fmac_f32_dpp v211, v45, v129 row_shl:15 row_mask:0xf bank_mask:0xf
	v_fmac_f32_dpp v212, v46, v130 row_shl:15 row_mask:0xf bank_mask:0xf
	v_fmac_f32_dpp v213, v47, v131 row_shl:15 row_mask:0xf bank_mask:0xf
	v_fmac_f32_dpp v214, v40, v132 row_shl:15 row_mask:0xf bank_mask:0xf
	v_fmac_f32_dpp v215, v41, v133 row_shl:15 row_mask:0xf bank_mask:0xf
	v_fmac_f32_dpp v216, v42, v134 row_shl:15 row_mask:0xf bank_mask:0xf
	v_fmac_f32_dpp v217, v43, v135 row_shl:15 row_mask:0xf bank_mask:0xf
	v_fmac_f32_dpp v210, v44, v88 row_shl:14 row_mask:0xf bank_mask:0xf
	v_fmac_f32_dpp v211, v45, v89 row_shl:14 row_mask:0xf bank_mask:0xf
	v_fmac_f32_dpp v212, v46, v90 row_shl:14 row_mask:0xf bank_mask:0xf
	v_fmac_f32_dpp v213, v47, v91 row_shl:14 row_mask:0xf bank_mask:0xf
	v_fmac_f32_dpp v214, v40, v92 row_shl:14 row_mask:0xf bank_mask:0xf
	v_fmac_f32_dpp v215, v41, v93 row_shl:14 row_mask:0xf bank_mask:0xf
	v_fmac_f32_dpp v216, v42, v94 row_shl:14 row_mask:0xf bank_mask:0xf
	v_fmac_f32_dpp v217, v43, v95 row_shl:14 row_mask:0xf bank_mask:0xf
	v_exp_f32_e32 v218, v210
	v_exp_f32_e32 v219, v211
	v_exp_f32_e32 v220, v212
	v_exp_f32_e32 v221, v213
	v_exp_f32_e32 v222, v214
	v_exp_f32_e32 v223, v215
	v_exp_f32_e32 v224, v216
	v_exp_f32_e32 v225, v217
	v_pk_fma_f32 v[218:219], v[218:219], v[208:209], v[208:209] op_sel_hi:[1,0,0]
	v_pk_fma_f32 v[220:221], v[220:221], v[208:209], v[208:209] op_sel_hi:[1,0,0]
	v_pk_fma_f32 v[222:223], v[222:223], v[208:209], v[208:209] op_sel_hi:[1,0,0]
	v_pk_fma_f32 v[224:225], v[224:225], v[208:209], v[208:209] op_sel_hi:[1,0,0]
	v_rcp_f32_e32 v218, v218
	v_rcp_f32_e32 v219, v219
	v_rcp_f32_e32 v220, v220
	v_rcp_f32_e32 v221, v221
	v_rcp_f32_e32 v222, v222
	v_rcp_f32_e32 v223, v223
	v_rcp_f32_e32 v224, v224
	v_rcp_f32_e32 v225, v225
	v_pk_mul_f32 v[210:211], v[210:211], v[218:219]
	v_pk_mul_f32 v[212:213], v[212:213], v[220:221]
	v_pk_mul_f32 v[214:215], v[214:215], v[222:223]
	v_pk_mul_f32 v[216:217], v[216:217], v[224:225]
	v_pk_mul_f32 v[20:21], v[210:211], v[20:21]
	v_pk_mul_f32 v[22:23], v[212:213], v[22:23]
	v_pk_mul_f32 v[16:17], v[214:215], v[16:17]
	v_pk_mul_f32 v[18:19], v[216:217], v[18:19]
	v_cvt_pk_bf16_f32 v226, v20, v21
	v_cvt_pk_bf16_f32 v227, v22, v23
	v_cvt_pk_bf16_f32 v228, v16, v17
	v_cvt_pk_bf16_f32 v229, v18, v19
	v_add_u32_e32 v234, 0xdc000, v230
	global_store_dwordx4 v234, v[226:229], s[96:97] nt
	v_pk_mul_f32 v[12:13], v[12:13], v[78:79] op_sel:[0,1]
	v_pk_mul_f32 v[14:15], v[14:15], v[78:79] op_sel:[0,1]
	v_pk_mul_f32 v[8:9], v[8:9], v[78:79] op_sel:[0,1]
	v_pk_mul_f32 v[10:11], v[10:11], v[78:79] op_sel:[0,1]
	v_pk_fma_f32 v[210:211], v[12:13], v[136:137], v[174:175]
	v_pk_fma_f32 v[212:213], v[14:15], v[138:139], v[176:177]
	v_pk_fma_f32 v[214:215], v[8:9], v[140:141], v[178:179]
	v_pk_fma_f32 v[216:217], v[10:11], v[142:143], v[180:181]
	v_cvt_pk_bf16_f32 v236, v12, v13
	v_cvt_pk_bf16_f32 v237, v14, v15
	v_cvt_pk_bf16_f32 v238, v8, v9
	v_cvt_pk_bf16_f32 v239, v10, v11
	v_add_u32_e32 v235, 0xffffd400, v233
	s_and_b64 exec, exec, s[10:11]
	global_store_dwordx4 v235, v[236:239], s[42:43]
; __device__ __forceinline__ unsigned cvt_pk_bf16(float lo, float hi) { unsigned r; asm volatile("v_cvt_pk_bf16_f32 %0, %1, %2" : "=v"(r) : "v"(lo), "v"(hi)); return r; }
; __device__ __forceinline__ float silu_f(float x) { return x * __builtin_amdgcn_rcpf(1.0f + __builtin_amdgcn_exp2f(x * -1.44269504f)); }
; template <int CTRL> __device__ __forceinline__ float dpp_rot(float x) { return __int_as_float(__builtin_amdgcn_mov_dpp(__float_as_int(x), CTRL, 0xf, 0xf, false)); }
;     __device__ __forceinline__ void operator()(const Acc& acc, const Unit& u, int wr, int wc, int fr, int fq, LAS unsigned char* lds, f32x4 epar) const {
;     ...
; #pragma unroll
;                 for (int i = 0; i < NV; ++i) {
;                     const float a1 = dpp_rot<0x121>(X[i]), a2 = dpp_rot<0x122>(X[i]);
;                     const float q1 = fr >= 1 ? a1 : p1prev[i], q2 = fr >= 2 ? a2 : p2prev[i];
;                     p1prev[i] = a1; p2prev[i] = a2;
;                     const float cv = w2[i] * X[i] + w1[i] * q1 + w0[i] * q2 + bb[i];
;                     o[i] = MODE == 0 ? silu_f(cv) * Y[i] : cv * Y[i];
;                 }
;                 if (m == 0 && fr < 2) {
;                     bf16_t* hx = halo + ((size_t)strip * 6 + 2 + fr) * C + c0; bf16_t* hy = halo + ((size_t)strip * 6 + 4 + fr) * C + c0;
;                     u32x4 px, py; px.x = cvt_pk_bf16(X[0], X[1]); px.y = cvt_pk_bf16(X[2], X[3]); px.z = cvt_pk_bf16(X[4 % NV], X[5 % NV]); px.w = cvt_pk_bf16(X[6 % NV], X[7 % NV]);
;                     py.x = cvt_pk_bf16(Y[0], Y[1]); py.y = cvt_pk_bf16(Y[2], Y[3]); py.z = cvt_pk_bf16(Y[4 % NV], Y[5 % NV]); py.w = cvt_pk_bf16(Y[6 % NV], Y[7 % NV]);
;                     if (MODE == 0) { *(u32x4*)hx = px; *(u32x4*)hy = py; } else { u32x2 a; a.x = px.x; a.y = px.y; *(u32x2*)hx = a; u32x2 b; b.x = py.x; b.y = py.y; *(u32x2*)hy = b; }
;                 } else {
;                     if (MODE == 0) { u32x4 w; w.x = cvt_pk_bf16(o[0], o[1]); w.y = cvt_pk_bf16(o[2], o[3]); w.z = cvt_pk_bf16(o[4 % NV], o[5 % NV]); w.w = cvt_pk_bf16(o[6 % NV], o[7 % NV]);
;                         __builtin_nontemporal_store(w, (u32x4*)(out + (size_t)r * C + c0)); }
	s_mov_b64 exec, s[24:25]
	v_fmac_f32_dpp v210, v12, v128 row_shr:1 row_mask:0xf bank_mask:0xf
	v_fmac_f32_dpp v211, v13, v129 row_shr:1 row_mask:0xf bank_mask:0xf
	v_fmac_f32_dpp v212, v14, v130 row_shr:1 row_mask:0xf bank_mask:0xf
	v_fmac_f32_dpp v213, v15, v131 row_shr:1 row_mask:0xf bank_mask:0xf
	v_fmac_f32_dpp v214, v8, v132 row_shr:1 row_mask:0xf bank_mask:0xf
	v_fmac_f32_dpp v215, v9, v133 row_shr:1 row_mask:0xf bank_mask:0xf
	v_fmac_f32_dpp v216, v10, v134 row_shr:1 row_mask:0xf bank_mask:0xf
	v_fmac_f32_dpp v217, v11, v135 row_shr:1 row_mask:0xf bank_mask:0xf
	v_fmac_f32_dpp v210, v12, v88 row_shr:2 row_mask:0xf bank_mask:0xf
	v_fmac_f32_dpp v211, v13, v89 row_shr:2 row_mask:0xf bank_mask:0xf
	v_fmac_f32_dpp v212, v14, v90 row_shr:2 row_mask:0xf bank_mask:0xf
	v_fmac_f32_dpp v213, v15, v91 row_shr:2 row_mask:0xf bank_mask:0xf
	v_fmac_f32_dpp v214, v8, v92 row_shr:2 row_mask:0xf bank_mask:0xf
	v_fmac_f32_dpp v215, v9, v93 row_shr:2 row_mask:0xf bank_mask:0xf
	v_fmac_f32_dpp v216, v10, v94 row_shr:2 row_mask:0xf bank_mask:0xf
	v_fmac_f32_dpp v217, v11, v95 row_shr:2 row_mask:0xf bank_mask:0xf
	v_fmac_f32_dpp v210, v28, v128 row_shl:15 row_mask:0xf bank_mask:0xf
	v_fmac_f32_dpp v211, v29, v129 row_shl:15 row_mask:0xf bank_mask:0xf
	v_fmac_f32_dpp v212, v30, v130 row_shl:15 row_mask:0xf bank_mask:0xf
	v_fmac_f32_dpp v213, v31, v131 row_shl:15 row_mask:0xf bank_mask:0xf
	v_fmac_f32_dpp v214, v24, v132 row_shl:15 row_mask:0xf bank_mask:0xf
	v_fmac_f32_dpp v215, v25, v133 row_shl:15 row_mask:0xf bank_mask:0xf
	v_fmac_f32_dpp v216, v26, v134 row_shl:15 row_mask:0xf bank_mask:0xf
	v_fmac_f32_dpp v217, v27, v135 row_shl:15 row_mask:0xf bank_mask:0xf
	v_fmac_f32_dpp v210, v28, v88 row_shl:14 row_mask:0xf bank_mask:0xf
	v_fmac_f32_dpp v211, v29, v89 row_shl:14 row_mask:0xf bank_mask:0xf
	v_fmac_f32_dpp v212, v30, v90 row_shl:14 row_mask:0xf bank_mask:0xf
	v_fmac_f32_dpp v213, v31, v91 row_shl:14 row_mask:0xf bank_mask:0xf
	v_fmac_f32_dpp v214, v24, v92 row_shl:14 row_mask:0xf bank_mask:0xf
	v_fmac_f32_dpp v215, v25, v93 row_shl:14 row_mask:0xf bank_mask:0xf
	v_fmac_f32_dpp v216, v26, v94 row_shl:14 row_mask:0xf bank_mask:0xf
	v_fmac_f32_dpp v217, v27, v95 row_shl:14 row_mask:0xf bank_mask:0xf
	v_exp_f32_e32 v218, v210
	v_exp_f32_e32 v219, v211
	v_exp_f32_e32 v220, v212
	v_exp_f32_e32 v221, v213
	v_exp_f32_e32 v222, v214
	v_exp_f32_e32 v223, v215
	v_exp_f32_e32 v224, v216
	v_exp_f32_e32 v225, v217
	v_pk_fma_f32 v[218:219], v[218:219], v[208:209], v[208:209] op_sel:[0,1,1]
	v_pk_fma_f32 v[220:221], v[220:221], v[208:209], v[208:209] op_sel:[0,1,1]
	v_pk_fma_f32 v[222:223], v[222:223], v[208:209], v[208:209] op_sel:[0,1,1]
	v_pk_fma_f32 v[224:225], v[224:225], v[208:209], v[208:209] op_sel:[0,1,1]
	v_rcp_f32_e32 v218, v218
	v_rcp_f32_e32 v219, v219
	v_rcp_f32_e32 v220, v220
	v_rcp_f32_e32 v221, v221
	v_rcp_f32_e32 v222, v222
	v_rcp_f32_e32 v223, v223
	v_rcp_f32_e32 v224, v224
	v_rcp_f32_e32 v225, v225
	v_pk_mul_f32 v[210:211], v[210:211], v[218:219]
	v_pk_mul_f32 v[212:213], v[212:213], v[220:221]
	v_pk_mul_f32 v[214:215], v[214:215], v[222:223]
	v_pk_mul_f32 v[216:217], v[216:217], v[224:225]
	v_pk_mul_f32 v[4:5], v[210:211], v[4:5]
	v_pk_mul_f32 v[6:7], v[212:213], v[6:7]
	v_pk_mul_f32 v[0:1], v[214:215], v[0:1]
	v_pk_mul_f32 v[2:3], v[216:217], v[2:3]
	v_cvt_pk_bf16_f32 v226, v4, v5
	v_cvt_pk_bf16_f32 v227, v6, v7
	v_cvt_pk_bf16_f32 v228, v0, v1
	v_cvt_pk_bf16_f32 v229, v2, v3
	v_add_u32_e32 v234, 0xf2000, v230
	global_store_dwordx4 v234, v[226:229], s[96:97] nt

; __device__ __forceinline__ float bf_lo(unsigned w) { return __uint_as_float(w << 16); }
; __device__ __forceinline__ float bf_hi(unsigned w) { return __uint_as_float(w & 0xffff0000u); }
; __device__ __forceinline__ int otid() { int t = threadIdx.x; asm volatile("" : "+v"(t)); return t; }
;     __device__ __forceinline__ bool next(int i, Unit& u) const { const long L = (long)i * G + c; if (L >= NG * 8) return false; u.g = (int)(L >> 3); u.pm = (int)(L & 7); u.pn = 0; return true; }
;     __device__ __forceinline__ bool next(int i, Unit& u) const { if (i >= 2) return false; u.g = g; u.pm = 2 * b + i; u.pn = 0; return true; }
; template <int MODE, class Sched> __device__ __forceinline__ void fixup_local(const bf16_t* halo, const float* cw, const float* cb, bf16_t* out, int C, const Sched& S) {
;     const int C4 = C >> 2, tid = otid(); Unit u;
;     for (int i = 0; S.next(i, u); ++i)
;         for (int c4 = tid; c4 < C4; c4 += 512) {
;             const int c = c4 * 4;
;             const f32x4 w0 = *(const f32x4*)(cw + c), w1 = *(const f32x4*)(cw + C + c), w2 = *(const f32x4*)(cw + 2 * C + c);
;             f32x4 bb = (f32x4){0.f, 0.f, 0.f, 0.f}; if (MODE == 0) bb = *(const f32x4*)(cb + c);
;             f32x4 t0[4], t1[4], h0[4], h1[4], y0[4], y1[4];
; #pragma unroll
;             for (int k = 0; k < 4; ++k) { const int s = 4 * u.pm + k; const bf16_t* hb = halo + (size_t)s * 6 * C + c; const bool first = (s & 127) == 0;
;                 const f32x4 z = (f32x4){0.f, 0.f, 0.f, 0.f};
;                 auto ld4 = [](const bf16_t* ptr) { const u32x2 w = *(const u32x2*)ptr; return (f32x4){bf_lo(w.x), bf_hi(w.x), bf_lo(w.y), bf_hi(w.y)}; };
;                 t0[k] = ld4(first ? hb : hb - (size_t)6 * C); t1[k] = ld4(first ? hb : hb - (size_t)5 * C);
;                 if (first) { t0[k] = z; t1[k] = z; }
;                 h0[k] = ld4(hb + (size_t)2 * C); h1[k] = ld4(hb + (size_t)3 * C);
;                 y0[k] = ld4(hb + (size_t)4 * C); y1[k] = ld4(hb + (size_t)5 * C); }
.LBB0_738:
	s_or_b64 exec, exec, s[0:1]
	v_readlane_b32 s0, v252, 48
	v_readlane_b32 s1, v252, 49
	s_mov_b32 s2, s0
	s_add_u32 s0, s54, 0x2c00
	s_addc_u32 s1, s55, 0
	s_mov_b32 s8, 4
	s_add_u32 s6, s54, 0x5800
	s_waitcnt lgkmcnt(0)
	s_barrier
	s_addc_u32 s7, s55, 0
	s_lshl_b32 s14, s8, 3
	s_abs_i32 s15, s14
	v_cvt_f32_u32_e32 v0, s15
	s_bfe_i32 s35, s8, 0x1001c
	s_sub_i32 s8, 0, s15
	v_mov_b32_e32 v1, v232
	v_rcp_iflag_f32_e32 v0, v0
	s_movk_i32 s3, 0x2c0
	s_ashr_i32 s33, s2, 31
	v_mul_f32_e32 v0, 0x4f7ffffe, v0
	v_cvt_u32_f32_e32 v0, v0
	v_cmp_gt_i32_e64 s[4:5], s3, v1
	s_ashr_i32 s3, s34, 31
	s_mov_b32 s67, 0
	v_readfirstlane_b32 s9, v0
	s_mul_i32 s8, s8, s9
	s_mul_hi_u32 s8, s9, s8
	s_add_i32 s66, s9, s8
	v_add_u32_e32 v60, 0xfffffe00, v1
	v_lshlrev_b32_e32 v61, 2, v1
	v_mov_b64_e32 v[16:17], 0x1ff
	s_movk_i32 s70, 0x2000
	s_movk_i32 s71, 0x4000
	s_movk_i32 s72, 0x5000
	s_movk_i32 s73, 0x6000
	s_movk_i32 s74, 0x8000
	s_movk_i32 s75, 0xa000
	s_movk_i32 s76, 0xbf
	s_cmp_lg_u32 s34, 0x100
	s_cbranch_scc1 .Lfix0_generic
	s_mov_b64 s[10:11], exec
	s_mov_b32 s12, 0xbfb8aa3b
	s_mov_b32 s13, 1.0
	v_lshlrev_b32_e32 v1, 3, v232
	v_add_u32_e32 v2, 0x1000, v1
	v_lshlrev_b32_e32 v3, 4, v232
	v_add_u32_e32 v4, 0x2000, v3
	v_mov_b32_e32 v5, 0xc0
	v_cmp_gt_u32_e64 s[30:31], v5, v232
	s_and_b32 s16, s2, 7
	s_lshl_b32 s16, s16, 4
	s_bfe_u32 s17, s2, 0x30003
	s_add_i32 s16, s16, s17
	global_load_dwordx4 v[8:11], v3, s[54:55]
	global_load_dwordx4 v[12:15], v3, s[0:1]
	global_load_dwordx4 v[16:19], v3, s[6:7]
	global_load_dwordx4 v[20:23], v3, s[56:57]
	s_add_i32 s17, s16, 0
	s_lshl_b32 s17, s17, 2
	s_mul_i32 s17, s17, 0x8400
	s_add_u32 s18, s42, s17
	s_addc_u32 s19, s43, 0
	s_add_i32 s17, s16, 0
	s_and_b32 s17, s17, 31
	s_cmp_eq_u32 s17, 0
	s_cselect_b32 s26, 0, 0x8400
	s_cselect_b32 s27, 0, 0x6e00
	s_sub_u32 s24, s18, s26
	s_subb_u32 s25, s19, 0
	global_load_dwordx2 v[40:41], v1, s[24:25]
	s_sub_u32 s24, s18, s27
	s_subb_u32 s25, s19, 0
	global_load_dwordx2 v[42:43], v1, s[24:25]
	s_add_u32 s24, s18, 0x2c00
	s_addc_u32 s25, s19, 0
	global_load_dwordx2 v[44:45], v1, s[24:25]
	s_add_u32 s24, s18, 0x4200
	s_addc_u32 s25, s19, 0
	global_load_dwordx2 v[46:47], v1, s[24:25]
	s_add_u32 s24, s18, 0x5800
	s_addc_u32 s25, s19, 0
	global_load_dwordx2 v[48:49], v1, s[24:25]
	s_add_u32 s24, s18, 0x6e00
	s_addc_u32 s25, s19, 0
	global_load_dwordx2 v[50:51], v1, s[24:25]
	s_add_i32 s17, s16, 0
	s_lshl_b32 s17, s17, 2
	s_add_i32 s17, s17, 1
	s_mul_i32 s17, s17, 0x8400
	s_add_u32 s18, s42, s17
	s_addc_u32 s19, s43, 0
	s_mov_b32 s26, 0x8400
	s_mov_b32 s27, 0x6e00
	s_sub_u32 s24, s18, s26
	s_subb_u32 s25, s19, 0
	global_load_dwordx2 v[52:53], v1, s[24:25]
	s_sub_u32 s24, s18, s27
	s_subb_u32 s25, s19, 0
	global_load_dwordx2 v[54:55], v1, s[24:25]
	s_add_u32 s24, s18, 0x2c00
	s_addc_u32 s25, s19, 0
	global_load_dwordx2 v[56:57], v1, s[24:25]
	s_add_u32 s24, s18, 0x4200
	s_addc_u32 s25, s19, 0
	global_load_dwordx2 v[58:59], v1, s[24:25]
	s_add_u32 s24, s18, 0x5800
	s_addc_u32 s25, s19, 0
	global_load_dwordx2 v[60:61], v1, s[24:25]
	s_add_u32 s24, s18, 0x6e00
	s_addc_u32 s25, s19, 0
	global_load_dwordx2 v[62:63], v1, s[24:25]
	s_add_i32 s17, s16, 0
	s_lshl_b32 s17, s17, 2
	s_add_i32 s17, s17, 2
	s_mul_i32 s17, s17, 0x8400
	s_add_u32 s18, s42, s17
	s_addc_u32 s19, s43, 0
	s_mov_b32 s26, 0x8400
	s_mov_b32 s27, 0x6e00
	s_sub_u32 s24, s18, s26
	s_subb_u32 s25, s19, 0
	global_load_dwordx2 v[64:65], v1, s[24:25]
	s_sub_u32 s24, s18, s27
	s_subb_u32 s25, s19, 0
	global_load_dwordx2 v[66:67], v1, s[24:25]
	s_add_u32 s24, s18, 0x2c00
	s_addc_u32 s25, s19, 0
	global_load_dwordx2 v[68:69], v1, s[24:25]
	s_add_u32 s24, s18, 0x4200
	s_addc_u32 s25, s19, 0
	global_load_dwordx2 v[70:71], v1, s[24:25]
	s_add_u32 s24, s18, 0x5800
	s_addc_u32 s25, s19, 0
	global_load_dwordx2 v[72:73], v1, s[24:25]
	s_add_u32 s24, s18, 0x6e00
	s_addc_u32 s25, s19, 0
	global_load_dwordx2 v[74:75], v1, s[24:25]
	s_add_i32 s17, s16, 0
	s_lshl_b32 s17, s17, 2
	s_add_i32 s17, s17, 3
	s_mul_i32 s17, s17, 0x8400
	s_add_u32 s18, s42, s17
	s_addc_u32 s19, s43, 0
	s_mov_b32 s26, 0x8400
	s_mov_b32 s27, 0x6e00
	s_sub_u32 s24, s18, s26
	s_subb_u32 s25, s19, 0
	global_load_dwordx2 v[76:77], v1, s[24:25]
	s_sub_u32 s24, s18, s27
	s_subb_u32 s25, s19, 0
	global_load_dwordx2 v[78:79], v1, s[24:25]
	s_add_u32 s24, s18, 0x2c00
	s_addc_u32 s25, s19, 0
	global_load_dwordx2 v[80:81], v1, s[24:25]
	s_add_u32 s24, s18, 0x4200
	s_addc_u32 s25, s19, 0
	global_load_dwordx2 v[82:83], v1, s[24:25]
	s_add_u32 s24, s18, 0x5800
	s_addc_u32 s25, s19, 0
	global_load_dwordx2 v[84:85], v1, s[24:25]
	s_add_u32 s24, s18, 0x6e00
	s_addc_u32 s25, s19, 0
	global_load_dwordx2 v[86:87], v1, s[24:25]
	s_add_i32 s17, s16, 8
	s_lshl_b32 s17, s17, 2
	s_mul_i32 s17, s17, 0x8400
	s_add_u32 s18, s42, s17
	s_addc_u32 s19, s43, 0
	s_add_i32 s17, s16, 8
	s_and_b32 s17, s17, 31
	s_cmp_eq_u32 s17, 0
	s_cselect_b32 s26, 0, 0x8400
	s_cselect_b32 s27, 0, 0x6e00
	s_sub_u32 s24, s18, s26
	s_subb_u32 s25, s19, 0
	global_load_dwordx2 v[88:89], v1, s[24:25]
	s_sub_u32 s24, s18, s27
	s_subb_u32 s25, s19, 0
	global_load_dwordx2 v[90:91], v1, s[24:25]
	s_add_u32 s24, s18, 0x2c00
	s_addc_u32 s25, s19, 0
	global_load_dwordx2 v[92:93], v1, s[24:25]
	s_add_u32 s24, s18, 0x4200
	s_addc_u32 s25, s19, 0
	global_load_dwordx2 v[94:95], v1, s[24:25]
	s_add_u32 s24, s18, 0x5800
	s_addc_u32 s25, s19, 0
	global_load_dwordx2 v[96:97], v1, s[24:25]
	s_add_u32 s24, s18, 0x6e00
	s_addc_u32 s25, s19, 0
	global_load_dwordx2 v[98:99], v1, s[24:25]
	s_add_i32 s17, s16, 8
	s_lshl_b32 s17, s17, 2
	s_add_i32 s17, s17, 1
	s_mul_i32 s17, s17, 0x8400
	s_add_u32 s18, s42, s17
	s_addc_u32 s19, s43, 0
; __device__ __forceinline__ unsigned cvt_pk_bf16(float lo, float hi) { unsigned r; asm volatile("v_cvt_pk_bf16_f32 %0, %1, %2" : "=v"(r) : "v"(lo), "v"(hi)); return r; }
; __device__ __forceinline__ float bf_lo(unsigned w) { return __uint_as_float(w << 16); }
; __device__ __forceinline__ float bf_hi(unsigned w) { return __uint_as_float(w & 0xffff0000u); }
; __device__ __forceinline__ float silu_f(float x) { return x * __builtin_amdgcn_rcpf(1.0f + __builtin_amdgcn_exp2f(x * -1.44269504f)); }
; template <int MODE, class Sched> __device__ __forceinline__ void fixup_local(const bf16_t* halo, const float* cw, const float* cb, bf16_t* out, int C, const Sched& S) {
;     ...
;             for (int k = 0; k < 4; ++k) { const int s = 4 * u.pm + k; const bf16_t* hb = halo + (size_t)s * 6 * C + c; const bool first = (s & 127) == 0;
;                 const f32x4 z = (f32x4){0.f, 0.f, 0.f, 0.f};
;                 auto ld4 = [](const bf16_t* ptr) { const u32x2 w = *(const u32x2*)ptr; return (f32x4){bf_lo(w.x), bf_hi(w.x), bf_lo(w.y), bf_hi(w.y)}; };
;                 t0[k] = ld4(first ? hb : hb - (size_t)6 * C); t1[k] = ld4(first ? hb : hb - (size_t)5 * C);
;                 if (first) { t0[k] = z; t1[k] = z; }
;                 h0[k] = ld4(hb + (size_t)2 * C); h1[k] = ld4(hb + (size_t)3 * C);
;                 y0[k] = ld4(hb + (size_t)4 * C); y1[k] = ld4(hb + (size_t)5 * C); }
; #pragma unroll
;             for (int k = 0; k < 4; ++k) { const int s = 4 * u.pm + k; float o0[4], o1[4];
; #pragma unroll
;                 for (int j = 0; j < 4; ++j) {
;                     const float cv0 = w2[j] * h0[k][j] + w1[j] * t1[k][j] + w0[j] * t0[k][j] + bb[j];
;                     const float cv1 = w2[j] * h1[k][j] + w1[j] * h0[k][j] + w0[j] * t1[k][j] + bb[j];
;                     o0[j] = MODE == 0 ? silu_f(cv0) * y0[k][j] : cv0 * y0[k][j]; o1[j] = MODE == 0 ? silu_f(cv1) * y1[k][j] : cv1 * y1[k][j]; }
;                 u32x2 a; a.x = cvt_pk_bf16(o0[0], o0[1]); a.y = cvt_pk_bf16(o0[2], o0[3]); u32x2 b; b.x = cvt_pk_bf16(o1[0], o1[1]); b.y = cvt_pk_bf16(o1[2], o1[3]);
;                 *(u32x2*)(out + ((size_t)s * 64) * C + c) = a; *(u32x2*)(out + ((size_t)s * 64 + 1) * C + c) = b; }
	s_mov_b32 s26, 0x8400
	s_mov_b32 s27, 0x6e00
	s_sub_u32 s24, s18, s26
	s_subb_u32 s25, s19, 0
	global_load_dwordx2 v[100:101], v1, s[24:25]
	s_sub_u32 s24, s18, s27
	s_subb_u32 s25, s19, 0
	global_load_dwordx2 v[102:103], v1, s[24:25]
	s_add_u32 s24, s18, 0x2c00
	s_addc_u32 s25, s19, 0
	global_load_dwordx2 v[104:105], v1, s[24:25]
	s_add_u32 s24, s18, 0x4200
	s_addc_u32 s25, s19, 0
	global_load_dwordx2 v[106:107], v1, s[24:25]
	s_add_u32 s24, s18, 0x5800
	s_addc_u32 s25, s19, 0
	global_load_dwordx2 v[108:109], v1, s[24:25]
	s_add_u32 s24, s18, 0x6e00
	s_addc_u32 s25, s19, 0
	global_load_dwordx2 v[110:111], v1, s[24:25]
	s_add_i32 s17, s16, 8
	s_lshl_b32 s17, s17, 2
	s_add_i32 s17, s17, 2
	s_mul_i32 s17, s17, 0x8400
	s_add_u32 s18, s42, s17
	s_addc_u32 s19, s43, 0
	s_mov_b32 s26, 0x8400
	s_mov_b32 s27, 0x6e00
	s_sub_u32 s24, s18, s26
	s_subb_u32 s25, s19, 0
	global_load_dwordx2 v[112:113], v1, s[24:25]
	s_sub_u32 s24, s18, s27
	s_subb_u32 s25, s19, 0
	global_load_dwordx2 v[114:115], v1, s[24:25]
	s_add_u32 s24, s18, 0x2c00
	s_addc_u32 s25, s19, 0
	global_load_dwordx2 v[116:117], v1, s[24:25]
	s_add_u32 s24, s18, 0x4200
	s_addc_u32 s25, s19, 0
	global_load_dwordx2 v[118:119], v1, s[24:25]
	s_add_u32 s24, s18, 0x5800
	s_addc_u32 s25, s19, 0
	global_load_dwordx2 v[120:121], v1, s[24:25]
	s_add_u32 s24, s18, 0x6e00
	s_addc_u32 s25, s19, 0
	global_load_dwordx2 v[122:123], v1, s[24:25]
	s_add_i32 s17, s16, 8
	s_lshl_b32 s17, s17, 2
	s_add_i32 s17, s17, 3
	s_mul_i32 s17, s17, 0x8400
	s_add_u32 s18, s42, s17
	s_addc_u32 s19, s43, 0
	s_mov_b32 s26, 0x8400
	s_mov_b32 s27, 0x6e00
	s_sub_u32 s24, s18, s26
	s_subb_u32 s25, s19, 0
	global_load_dwordx2 v[124:125], v1, s[24:25]
	s_sub_u32 s24, s18, s27
	s_subb_u32 s25, s19, 0
	global_load_dwordx2 v[126:127], v1, s[24:25]
	s_add_u32 s24, s18, 0x2c00
	s_addc_u32 s25, s19, 0
	global_load_dwordx2 v[128:129], v1, s[24:25]
	s_add_u32 s24, s18, 0x4200
	s_addc_u32 s25, s19, 0
	global_load_dwordx2 v[130:131], v1, s[24:25]
	s_add_u32 s24, s18, 0x5800
	s_addc_u32 s25, s19, 0
	global_load_dwordx2 v[132:133], v1, s[24:25]
	s_add_u32 s24, s18, 0x6e00
	s_addc_u32 s25, s19, 0
	global_load_dwordx2 v[134:135], v1, s[24:25]
	s_waitcnt vmcnt(24)
	s_add_i32 s17, s16, 0
	s_and_b32 s17, s17, 31
	s_cmp_lg_u32 s17, 0
	s_cbranch_scc1 .Lfix0_nz2
	v_mov_b32_e32 v40, 0
	v_mov_b32_e32 v41, 0
	v_mov_b32_e32 v42, 0
	v_mov_b32_e32 v43, 0
.Lfix0_nz2:
	v_lshlrev_b32_e32 v136, 16, v41
	v_and_b32_e32 v137, 0xffff0000, v41
	v_and_b32_e32 v41, 0xffff0000, v40
	v_lshlrev_b32_e32 v40, 16, v40
	v_lshlrev_b32_e32 v138, 16, v43
	v_and_b32_e32 v139, 0xffff0000, v43
	v_and_b32_e32 v43, 0xffff0000, v42
	v_lshlrev_b32_e32 v42, 16, v42
	v_lshlrev_b32_e32 v140, 16, v45
	v_and_b32_e32 v141, 0xffff0000, v45
	v_and_b32_e32 v45, 0xffff0000, v44
	v_lshlrev_b32_e32 v44, 16, v44
	v_lshlrev_b32_e32 v142, 16, v47
	v_and_b32_e32 v143, 0xffff0000, v47
	v_and_b32_e32 v47, 0xffff0000, v46
	v_lshlrev_b32_e32 v46, 16, v46
	v_lshlrev_b32_e32 v144, 16, v49
	v_and_b32_e32 v145, 0xffff0000, v49
	v_and_b32_e32 v49, 0xffff0000, v48
	v_lshlrev_b32_e32 v48, 16, v48
	v_lshlrev_b32_e32 v146, 16, v51
	v_and_b32_e32 v147, 0xffff0000, v51
	v_and_b32_e32 v51, 0xffff0000, v50
	v_lshlrev_b32_e32 v50, 16, v50
	v_pk_mul_f32 v[148:149], v[16:17], v[44:45]
	v_pk_mul_f32 v[150:151], v[18:19], v[140:141]
	v_pk_mul_f32 v[152:153], v[16:17], v[46:47]
	v_pk_mul_f32 v[154:155], v[18:19], v[142:143]
	v_pk_fma_f32 v[148:149], v[12:13], v[42:43], v[148:149]
	v_pk_fma_f32 v[150:151], v[14:15], v[138:139], v[150:151]
	v_pk_fma_f32 v[152:153], v[12:13], v[44:45], v[152:153]
	v_pk_fma_f32 v[154:155], v[14:15], v[140:141], v[154:155]
	v_pk_fma_f32 v[148:149], v[8:9], v[40:41], v[148:149]
	v_pk_fma_f32 v[150:151], v[10:11], v[136:137], v[150:151]
	v_pk_fma_f32 v[152:153], v[8:9], v[42:43], v[152:153]
	v_pk_fma_f32 v[154:155], v[10:11], v[138:139], v[154:155]
	v_pk_add_f32 v[148:149], v[148:149], v[20:21]
	v_pk_add_f32 v[150:151], v[150:151], v[22:23]
	v_pk_add_f32 v[152:153], v[152:153], v[20:21]
	v_pk_add_f32 v[154:155], v[154:155], v[22:23]
	v_pk_mul_f32 v[156:157], v[148:149], s[12:13] op_sel_hi:[1,0]
	v_pk_mul_f32 v[158:159], v[150:151], s[12:13] op_sel_hi:[1,0]
	v_pk_mul_f32 v[160:161], v[152:153], s[12:13] op_sel_hi:[1,0]
	v_pk_mul_f32 v[162:163], v[154:155], s[12:13] op_sel_hi:[1,0]
	v_exp_f32_e32 v156, v156
	v_exp_f32_e32 v157, v157
	v_exp_f32_e32 v158, v158
	v_exp_f32_e32 v159, v159
	v_exp_f32_e32 v160, v160
	v_exp_f32_e32 v161, v161
	v_exp_f32_e32 v162, v162
	v_exp_f32_e32 v163, v163
	v_pk_add_f32 v[156:157], v[156:157], s[12:13] op_sel:[0,1]
	v_pk_add_f32 v[158:159], v[158:159], s[12:13] op_sel:[0,1]
	v_pk_add_f32 v[160:161], v[160:161], s[12:13] op_sel:[0,1]
	v_pk_add_f32 v[162:163], v[162:163], s[12:13] op_sel:[0,1]
	v_rcp_f32_e32 v156, v156
	v_rcp_f32_e32 v157, v157
	v_rcp_f32_e32 v158, v158
	v_rcp_f32_e32 v159, v159
	v_rcp_f32_e32 v160, v160
	v_rcp_f32_e32 v161, v161
	v_rcp_f32_e32 v162, v162
	v_rcp_f32_e32 v163, v163
	v_pk_mul_f32 v[148:149], v[148:149], v[156:157]
	v_pk_mul_f32 v[150:151], v[150:151], v[158:159]
	v_pk_mul_f32 v[152:153], v[152:153], v[160:161]
	v_pk_mul_f32 v[154:155], v[154:155], v[162:163]
	v_pk_mul_f32 v[148:149], v[148:149], v[48:49]
	v_pk_mul_f32 v[150:151], v[150:151], v[144:145]
	v_pk_mul_f32 v[152:153], v[152:153], v[50:51]
	v_pk_mul_f32 v[154:155], v[154:155], v[146:147]
	v_cvt_pk_bf16_f32 v164, v148, v149
	v_cvt_pk_bf16_f32 v165, v150, v151
	v_cvt_pk_bf16_f32 v166, v152, v153
	v_cvt_pk_bf16_f32 v167, v154, v155
	s_add_i32 s17, s16, 0
	s_lshl_b32 s17, s17, 2
	s_mul_i32 s17, s17, 0x58000
	s_add_u32 s36, s96, s17
	s_addc_u32 s37, s97, 0
	s_add_u32 s38, s36, 0x1600
; __device__ __forceinline__ unsigned cvt_pk_bf16(float lo, float hi) { unsigned r; asm volatile("v_cvt_pk_bf16_f32 %0, %1, %2" : "=v"(r) : "v"(lo), "v"(hi)); return r; }
; __device__ __forceinline__ float silu_f(float x) { return x * __builtin_amdgcn_rcpf(1.0f + __builtin_amdgcn_exp2f(x * -1.44269504f)); }
; template <int MODE, class Sched> __device__ __forceinline__ void fixup_local(const bf16_t* halo, const float* cw, const float* cb, bf16_t* out, int C, const Sched& S) {
;     ...
;             for (int k = 0; k < 4; ++k) { const int s = 4 * u.pm + k; float o0[4], o1[4];
; #pragma unroll
;                 for (int j = 0; j < 4; ++j) {
;                     const float cv0 = w2[j] * h0[k][j] + w1[j] * t1[k][j] + w0[j] * t0[k][j] + bb[j];
;                     const float cv1 = w2[j] * h1[k][j] + w1[j] * h0[k][j] + w0[j] * t1[k][j] + bb[j];
;                     o0[j] = MODE == 0 ? silu_f(cv0) * y0[k][j] : cv0 * y0[k][j]; o1[j] = MODE == 0 ? silu_f(cv1) * y1[k][j] : cv1 * y1[k][j]; }
;                 u32x2 a; a.x = cvt_pk_bf16(o0[0], o0[1]); a.y = cvt_pk_bf16(o0[2], o0[3]); u32x2 b; b.x = cvt_pk_bf16(o1[0], o1[1]); b.y = cvt_pk_bf16(o1[2], o1[3]);
;                 *(u32x2*)(out + ((size_t)s * 64) * C + c) = a; *(u32x2*)(out + ((size_t)s * 64 + 1) * C + c) = b; }
	s_addc_u32 s39, s37, 0
	global_store_dwordx2 v1, v[164:165], s[36:37]
	global_store_dwordx2 v1, v[166:167], s[38:39]
	v_lshlrev_b32_e32 v136, 16, v53
	v_and_b32_e32 v137, 0xffff0000, v53
	v_and_b32_e32 v53, 0xffff0000, v52
	v_lshlrev_b32_e32 v52, 16, v52
	v_lshlrev_b32_e32 v138, 16, v55
	v_and_b32_e32 v139, 0xffff0000, v55
	v_and_b32_e32 v55, 0xffff0000, v54
	v_lshlrev_b32_e32 v54, 16, v54
	v_lshlrev_b32_e32 v140, 16, v57
	v_and_b32_e32 v141, 0xffff0000, v57
	v_and_b32_e32 v57, 0xffff0000, v56
	v_lshlrev_b32_e32 v56, 16, v56
	v_lshlrev_b32_e32 v142, 16, v59
	v_and_b32_e32 v143, 0xffff0000, v59
	v_and_b32_e32 v59, 0xffff0000, v58
	v_lshlrev_b32_e32 v58, 16, v58
	v_lshlrev_b32_e32 v144, 16, v61
	v_and_b32_e32 v145, 0xffff0000, v61
	v_and_b32_e32 v61, 0xffff0000, v60
	v_lshlrev_b32_e32 v60, 16, v60
	v_lshlrev_b32_e32 v146, 16, v63
	v_and_b32_e32 v147, 0xffff0000, v63
	v_and_b32_e32 v63, 0xffff0000, v62
	v_lshlrev_b32_e32 v62, 16, v62
	v_pk_mul_f32 v[148:149], v[16:17], v[56:57]
	v_pk_mul_f32 v[150:151], v[18:19], v[140:141]
	v_pk_mul_f32 v[152:153], v[16:17], v[58:59]
	v_pk_mul_f32 v[154:155], v[18:19], v[142:143]
	v_pk_fma_f32 v[148:149], v[12:13], v[54:55], v[148:149]
	v_pk_fma_f32 v[150:151], v[14:15], v[138:139], v[150:151]
	v_pk_fma_f32 v[152:153], v[12:13], v[56:57], v[152:153]
	v_pk_fma_f32 v[154:155], v[14:15], v[140:141], v[154:155]
	v_pk_fma_f32 v[148:149], v[8:9], v[52:53], v[148:149]
	v_pk_fma_f32 v[150:151], v[10:11], v[136:137], v[150:151]
	v_pk_fma_f32 v[152:153], v[8:9], v[54:55], v[152:153]
	v_pk_fma_f32 v[154:155], v[10:11], v[138:139], v[154:155]
	v_pk_add_f32 v[148:149], v[148:149], v[20:21]
	v_pk_add_f32 v[150:151], v[150:151], v[22:23]
	v_pk_add_f32 v[152:153], v[152:153], v[20:21]
	v_pk_add_f32 v[154:155], v[154:155], v[22:23]
	v_pk_mul_f32 v[156:157], v[148:149], s[12:13] op_sel_hi:[1,0]
	v_pk_mul_f32 v[158:159], v[150:151], s[12:13] op_sel_hi:[1,0]
	v_pk_mul_f32 v[160:161], v[152:153], s[12:13] op_sel_hi:[1,0]
	v_pk_mul_f32 v[162:163], v[154:155], s[12:13] op_sel_hi:[1,0]
	v_exp_f32_e32 v156, v156
	v_exp_f32_e32 v157, v157
	v_exp_f32_e32 v158, v158
	v_exp_f32_e32 v159, v159
	v_exp_f32_e32 v160, v160
	v_exp_f32_e32 v161, v161
	v_exp_f32_e32 v162, v162
	v_exp_f32_e32 v163, v163
	v_pk_add_f32 v[156:157], v[156:157], s[12:13] op_sel:[0,1]
	v_pk_add_f32 v[158:159], v[158:159], s[12:13] op_sel:[0,1]
	v_pk_add_f32 v[160:161], v[160:161], s[12:13] op_sel:[0,1]
	v_pk_add_f32 v[162:163], v[162:163], s[12:13] op_sel:[0,1]
	v_rcp_f32_e32 v156, v156
	v_rcp_f32_e32 v157, v157
	v_rcp_f32_e32 v158, v158
	v_rcp_f32_e32 v159, v159
	v_rcp_f32_e32 v160, v160
	v_rcp_f32_e32 v161, v161
	v_rcp_f32_e32 v162, v162
	v_rcp_f32_e32 v163, v163
	v_pk_mul_f32 v[148:149], v[148:149], v[156:157]
	v_pk_mul_f32 v[150:151], v[150:151], v[158:159]
	v_pk_mul_f32 v[152:153], v[152:153], v[160:161]
	v_pk_mul_f32 v[154:155], v[154:155], v[162:163]
	v_pk_mul_f32 v[148:149], v[148:149], v[60:61]
	v_pk_mul_f32 v[150:151], v[150:151], v[144:145]
	v_pk_mul_f32 v[152:153], v[152:153], v[62:63]
	v_pk_mul_f32 v[154:155], v[154:155], v[146:147]
	v_cvt_pk_bf16_f32 v164, v148, v149
	v_cvt_pk_bf16_f32 v165, v150, v151
	v_cvt_pk_bf16_f32 v166, v152, v153
	v_cvt_pk_bf16_f32 v167, v154, v155
	s_add_i32 s17, s16, 0
	s_lshl_b32 s17, s17, 2
	s_add_i32 s17, s17, 1
	s_mul_i32 s17, s17, 0x58000
	s_add_u32 s36, s96, s17
	s_addc_u32 s37, s97, 0
	s_add_u32 s38, s36, 0x1600
	s_addc_u32 s39, s37, 0
	global_store_dwordx2 v1, v[164:165], s[36:37]
	global_store_dwordx2 v1, v[166:167], s[38:39]
	v_lshlrev_b32_e32 v136, 16, v65
	v_and_b32_e32 v137, 0xffff0000, v65
	v_and_b32_e32 v65, 0xffff0000, v64
	v_lshlrev_b32_e32 v64, 16, v64
	v_lshlrev_b32_e32 v138, 16, v67
	v_and_b32_e32 v139, 0xffff0000, v67
	v_and_b32_e32 v67, 0xffff0000, v66
	v_lshlrev_b32_e32 v66, 16, v66
	v_lshlrev_b32_e32 v140, 16, v69
	v_and_b32_e32 v141, 0xffff0000, v69
	v_and_b32_e32 v69, 0xffff0000, v68
	v_lshlrev_b32_e32 v68, 16, v68
	v_lshlrev_b32_e32 v142, 16, v71
	v_and_b32_e32 v143, 0xffff0000, v71
	v_and_b32_e32 v71, 0xffff0000, v70
	v_lshlrev_b32_e32 v70, 16, v70
	v_lshlrev_b32_e32 v144, 16, v73
	v_and_b32_e32 v145, 0xffff0000, v73
	v_and_b32_e32 v73, 0xffff0000, v72
	v_lshlrev_b32_e32 v72, 16, v72
	v_lshlrev_b32_e32 v146, 16, v75
	v_and_b32_e32 v147, 0xffff0000, v75
	v_and_b32_e32 v75, 0xffff0000, v74
	v_lshlrev_b32_e32 v74, 16, v74
	v_pk_mul_f32 v[148:149], v[16:17], v[68:69]
	v_pk_mul_f32 v[150:151], v[18:19], v[140:141]
	v_pk_mul_f32 v[152:153], v[16:17], v[70:71]
	v_pk_mul_f32 v[154:155], v[18:19], v[142:143]
	v_pk_fma_f32 v[148:149], v[12:13], v[66:67], v[148:149]
	v_pk_fma_f32 v[150:151], v[14:15], v[138:139], v[150:151]
	v_pk_fma_f32 v[152:153], v[12:13], v[68:69], v[152:153]
	v_pk_fma_f32 v[154:155], v[14:15], v[140:141], v[154:155]
	v_pk_fma_f32 v[148:149], v[8:9], v[64:65], v[148:149]
	v_pk_fma_f32 v[150:151], v[10:11], v[136:137], v[150:151]
	v_pk_fma_f32 v[152:153], v[8:9], v[66:67], v[152:153]
	v_pk_fma_f32 v[154:155], v[10:11], v[138:139], v[154:155]
	v_pk_add_f32 v[148:149], v[148:149], v[20:21]
	v_pk_add_f32 v[150:151], v[150:151], v[22:23]
	v_pk_add_f32 v[152:153], v[152:153], v[20:21]
	v_pk_add_f32 v[154:155], v[154:155], v[22:23]
	v_pk_mul_f32 v[156:157], v[148:149], s[12:13] op_sel_hi:[1,0]
	v_pk_mul_f32 v[158:159], v[150:151], s[12:13] op_sel_hi:[1,0]
	v_pk_mul_f32 v[160:161], v[152:153], s[12:13] op_sel_hi:[1,0]
	v_pk_mul_f32 v[162:163], v[154:155], s[12:13] op_sel_hi:[1,0]
	v_exp_f32_e32 v156, v156
	v_exp_f32_e32 v157, v157
	v_exp_f32_e32 v158, v158
	v_exp_f32_e32 v159, v159
	v_exp_f32_e32 v160, v160
	v_exp_f32_e32 v161, v161
	v_exp_f32_e32 v162, v162
	v_exp_f32_e32 v163, v163
; __device__ __forceinline__ unsigned cvt_pk_bf16(float lo, float hi) { unsigned r; asm volatile("v_cvt_pk_bf16_f32 %0, %1, %2" : "=v"(r) : "v"(lo), "v"(hi)); return r; }
; __device__ __forceinline__ float bf_lo(unsigned w) { return __uint_as_float(w << 16); }
; template <int MODE, class Sched> __device__ __forceinline__ void fixup_local(const bf16_t* halo, const float* cw, const float* cb, bf16_t* out, int C, const Sched& S) {
;     ...
;         for (int c4 = tid; c4 < C4; c4 += 512) {
;             const int c = c4 * 4;
;             const f32x4 w0 = *(const f32x4*)(cw + c), w1 = *(const f32x4*)(cw + C + c), w2 = *(const f32x4*)(cw + 2 * C + c);
;             f32x4 bb = (f32x4){0.f, 0.f, 0.f, 0.f}; if (MODE == 0) bb = *(const f32x4*)(cb + c);
;             f32x4 t0[4], t1[4], h0[4], h1[4], y0[4], y1[4];
; #pragma unroll
;             for (int k = 0; k < 4; ++k) { const int s = 4 * u.pm + k; const bf16_t* hb = halo + (size_t)s * 6 * C + c; const bool first = (s & 127) == 0;
;                 const f32x4 z = (f32x4){0.f, 0.f, 0.f, 0.f};
;                 auto ld4 = [](const bf16_t* ptr) { const u32x2 w = *(const u32x2*)ptr; return (f32x4){bf_lo(w.x), bf_hi(w.x), bf_lo(w.y), bf_hi(w.y)}; };
;                 t0[k] = ld4(first ? hb : hb - (size_t)6 * C); t1[k] = ld4(first ? hb : hb - (size_t)5 * C);
;                 if (first) { t0[k] = z; t1[k] = z; }
;                 h0[k] = ld4(hb + (size_t)2 * C); h1[k] = ld4(hb + (size_t)3 * C);
;                 y0[k] = ld4(hb + (size_t)4 * C); y1[k] = ld4(hb + (size_t)5 * C); }
; #pragma unroll
;             for (int k = 0; k < 4; ++k) { const int s = 4 * u.pm + k; float o0[4], o1[4];
; #pragma unroll
;                 for (int j = 0; j < 4; ++j) {
;                     const float cv0 = w2[j] * h0[k][j] + w1[j] * t1[k][j] + w0[j] * t0[k][j] + bb[j];
;                     const float cv1 = w2[j] * h1[k][j] + w1[j] * h0[k][j] + w0[j] * t1[k][j] + bb[j];
;                     o0[j] = MODE == 0 ? silu_f(cv0) * y0[k][j] : cv0 * y0[k][j]; o1[j] = MODE == 0 ? silu_f(cv1) * y1[k][j] : cv1 * y1[k][j]; }
;                 u32x2 a; a.x = cvt_pk_bf16(o0[0], o0[1]); a.y = cvt_pk_bf16(o0[2], o0[3]); u32x2 b; b.x = cvt_pk_bf16(o1[0], o1[1]); b.y = cvt_pk_bf16(o1[2], o1[3]);
;                 *(u32x2*)(out + ((size_t)s * 64) * C + c) = a; *(u32x2*)(out + ((size_t)s * 64 + 1) * C + c) = b; }
	v_pk_add_f32 v[156:157], v[156:157], s[12:13] op_sel:[0,1]
	v_pk_add_f32 v[158:159], v[158:159], s[12:13] op_sel:[0,1]
	v_pk_add_f32 v[160:161], v[160:161], s[12:13] op_sel:[0,1]
	v_pk_add_f32 v[162:163], v[162:163], s[12:13] op_sel:[0,1]
	v_rcp_f32_e32 v156, v156
	v_rcp_f32_e32 v157, v157
	v_rcp_f32_e32 v158, v158
	v_rcp_f32_e32 v159, v159
	v_rcp_f32_e32 v160, v160
	v_rcp_f32_e32 v161, v161
	v_rcp_f32_e32 v162, v162
	v_rcp_f32_e32 v163, v163
	v_pk_mul_f32 v[148:149], v[148:149], v[156:157]
	v_pk_mul_f32 v[150:151], v[150:151], v[158:159]
	v_pk_mul_f32 v[152:153], v[152:153], v[160:161]
	v_pk_mul_f32 v[154:155], v[154:155], v[162:163]
	v_pk_mul_f32 v[148:149], v[148:149], v[72:73]
	v_pk_mul_f32 v[150:151], v[150:151], v[144:145]
	v_pk_mul_f32 v[152:153], v[152:153], v[74:75]
	v_pk_mul_f32 v[154:155], v[154:155], v[146:147]
	v_cvt_pk_bf16_f32 v164, v148, v149
	v_cvt_pk_bf16_f32 v165, v150, v151
	v_cvt_pk_bf16_f32 v166, v152, v153
	v_cvt_pk_bf16_f32 v167, v154, v155
	s_add_i32 s17, s16, 0
	s_lshl_b32 s17, s17, 2
	s_add_i32 s17, s17, 2
	s_mul_i32 s17, s17, 0x58000
	s_add_u32 s36, s96, s17
	s_addc_u32 s37, s97, 0
	s_add_u32 s38, s36, 0x1600
	s_addc_u32 s39, s37, 0
	global_store_dwordx2 v1, v[164:165], s[36:37]
	global_store_dwordx2 v1, v[166:167], s[38:39]
	v_lshlrev_b32_e32 v136, 16, v77
	v_and_b32_e32 v137, 0xffff0000, v77
	v_and_b32_e32 v77, 0xffff0000, v76
	v_lshlrev_b32_e32 v76, 16, v76
	v_lshlrev_b32_e32 v138, 16, v79
	v_and_b32_e32 v139, 0xffff0000, v79
	v_and_b32_e32 v79, 0xffff0000, v78
	v_lshlrev_b32_e32 v78, 16, v78
	v_lshlrev_b32_e32 v140, 16, v81
	v_and_b32_e32 v141, 0xffff0000, v81
	v_and_b32_e32 v81, 0xffff0000, v80
	v_lshlrev_b32_e32 v80, 16, v80
	v_lshlrev_b32_e32 v142, 16, v83
	v_and_b32_e32 v143, 0xffff0000, v83
	v_and_b32_e32 v83, 0xffff0000, v82
	v_lshlrev_b32_e32 v82, 16, v82
	v_lshlrev_b32_e32 v144, 16, v85
	v_and_b32_e32 v145, 0xffff0000, v85
	v_and_b32_e32 v85, 0xffff0000, v84
	v_lshlrev_b32_e32 v84, 16, v84
	v_lshlrev_b32_e32 v146, 16, v87
	v_and_b32_e32 v147, 0xffff0000, v87
	v_and_b32_e32 v87, 0xffff0000, v86
	v_lshlrev_b32_e32 v86, 16, v86
	v_pk_mul_f32 v[148:149], v[16:17], v[80:81]
	v_pk_mul_f32 v[150:151], v[18:19], v[140:141]
	v_pk_mul_f32 v[152:153], v[16:17], v[82:83]
	v_pk_mul_f32 v[154:155], v[18:19], v[142:143]
	v_pk_fma_f32 v[148:149], v[12:13], v[78:79], v[148:149]
	v_pk_fma_f32 v[150:151], v[14:15], v[138:139], v[150:151]
	v_pk_fma_f32 v[152:153], v[12:13], v[80:81], v[152:153]
	v_pk_fma_f32 v[154:155], v[14:15], v[140:141], v[154:155]
	v_pk_fma_f32 v[148:149], v[8:9], v[76:77], v[148:149]
	v_pk_fma_f32 v[150:151], v[10:11], v[136:137], v[150:151]
	v_pk_fma_f32 v[152:153], v[8:9], v[78:79], v[152:153]
	v_pk_fma_f32 v[154:155], v[10:11], v[138:139], v[154:155]
	v_pk_add_f32 v[148:149], v[148:149], v[20:21]
	v_pk_add_f32 v[150:151], v[150:151], v[22:23]
	v_pk_add_f32 v[152:153], v[152:153], v[20:21]
	v_pk_add_f32 v[154:155], v[154:155], v[22:23]
	v_pk_mul_f32 v[156:157], v[148:149], s[12:13] op_sel_hi:[1,0]
	v_pk_mul_f32 v[158:159], v[150:151], s[12:13] op_sel_hi:[1,0]
	v_pk_mul_f32 v[160:161], v[152:153], s[12:13] op_sel_hi:[1,0]
	v_pk_mul_f32 v[162:163], v[154:155], s[12:13] op_sel_hi:[1,0]
	v_exp_f32_e32 v156, v156
	v_exp_f32_e32 v157, v157
	v_exp_f32_e32 v158, v158
	v_exp_f32_e32 v159, v159
	v_exp_f32_e32 v160, v160
	v_exp_f32_e32 v161, v161
	v_exp_f32_e32 v162, v162
	v_exp_f32_e32 v163, v163
	v_pk_add_f32 v[156:157], v[156:157], s[12:13] op_sel:[0,1]
	v_pk_add_f32 v[158:159], v[158:159], s[12:13] op_sel:[0,1]
	v_pk_add_f32 v[160:161], v[160:161], s[12:13] op_sel:[0,1]
	v_pk_add_f32 v[162:163], v[162:163], s[12:13] op_sel:[0,1]
	v_rcp_f32_e32 v156, v156
	v_rcp_f32_e32 v157, v157
	v_rcp_f32_e32 v158, v158
	v_rcp_f32_e32 v159, v159
	v_rcp_f32_e32 v160, v160
	v_rcp_f32_e32 v161, v161
	v_rcp_f32_e32 v162, v162
	v_rcp_f32_e32 v163, v163
	v_pk_mul_f32 v[148:149], v[148:149], v[156:157]
	v_pk_mul_f32 v[150:151], v[150:151], v[158:159]
	v_pk_mul_f32 v[152:153], v[152:153], v[160:161]
	v_pk_mul_f32 v[154:155], v[154:155], v[162:163]
	v_pk_mul_f32 v[148:149], v[148:149], v[84:85]
	v_pk_mul_f32 v[150:151], v[150:151], v[144:145]
	v_pk_mul_f32 v[152:153], v[152:153], v[86:87]
	v_pk_mul_f32 v[154:155], v[154:155], v[146:147]
	v_cvt_pk_bf16_f32 v164, v148, v149
	v_cvt_pk_bf16_f32 v165, v150, v151
	v_cvt_pk_bf16_f32 v166, v152, v153
	v_cvt_pk_bf16_f32 v167, v154, v155
	s_add_i32 s17, s16, 0
	s_lshl_b32 s17, s17, 2
	s_add_i32 s17, s17, 3
	s_mul_i32 s17, s17, 0x58000
	s_add_u32 s36, s96, s17
	s_addc_u32 s37, s97, 0
	s_add_u32 s38, s36, 0x1600
	s_addc_u32 s39, s37, 0
	global_store_dwordx2 v1, v[164:165], s[36:37]
	global_store_dwordx2 v1, v[166:167], s[38:39]
	s_and_b64 exec, exec, s[30:31]
	global_load_dwordx4 v[24:27], v4, s[54:55]
	global_load_dwordx4 v[28:31], v4, s[0:1]
	global_load_dwordx4 v[32:35], v4, s[6:7]
	global_load_dwordx4 v[36:39], v4, s[56:57]
	s_add_i32 s17, s16, 0
	s_lshl_b32 s17, s17, 2
	s_mul_i32 s17, s17, 0x8400
	s_add_u32 s18, s42, s17
	s_addc_u32 s19, s43, 0
	s_add_i32 s17, s16, 0
	s_and_b32 s17, s17, 31
	s_cmp_eq_u32 s17, 0
	s_cselect_b32 s26, 0, 0x8400
	s_cselect_b32 s27, 0, 0x6e00
	s_sub_u32 s24, s18, s26
	s_subb_u32 s25, s19, 0
	global_load_dwordx2 v[40:41], v2, s[24:25]
	s_sub_u32 s24, s18, s27
	s_subb_u32 s25, s19, 0
	global_load_dwordx2 v[42:43], v2, s[24:25]
	s_add_u32 s24, s18, 0x2c00
	s_addc_u32 s25, s19, 0
	global_load_dwordx2 v[44:45], v2, s[24:25]
	s_add_u32 s24, s18, 0x4200
	s_addc_u32 s25, s19, 0
	global_load_dwordx2 v[46:47], v2, s[24:25]
	s_add_u32 s24, s18, 0x5800
	s_addc_u32 s25, s19, 0
	global_load_dwordx2 v[48:49], v2, s[24:25]
	s_add_u32 s24, s18, 0x6e00
	s_addc_u32 s25, s19, 0
; __device__ __forceinline__ unsigned cvt_pk_bf16(float lo, float hi) { unsigned r; asm volatile("v_cvt_pk_bf16_f32 %0, %1, %2" : "=v"(r) : "v"(lo), "v"(hi)); return r; }
; __device__ __forceinline__ float bf_lo(unsigned w) { return __uint_as_float(w << 16); }
; __device__ __forceinline__ float bf_hi(unsigned w) { return __uint_as_float(w & 0xffff0000u); }
; __device__ __forceinline__ float silu_f(float x) { return x * __builtin_amdgcn_rcpf(1.0f + __builtin_amdgcn_exp2f(x * -1.44269504f)); }
; template <int MODE, class Sched> __device__ __forceinline__ void fixup_local(const bf16_t* halo, const float* cw, const float* cb, bf16_t* out, int C, const Sched& S) {
;     ...
;             for (int k = 0; k < 4; ++k) { const int s = 4 * u.pm + k; const bf16_t* hb = halo + (size_t)s * 6 * C + c; const bool first = (s & 127) == 0;
;                 const f32x4 z = (f32x4){0.f, 0.f, 0.f, 0.f};
;                 auto ld4 = [](const bf16_t* ptr) { const u32x2 w = *(const u32x2*)ptr; return (f32x4){bf_lo(w.x), bf_hi(w.x), bf_lo(w.y), bf_hi(w.y)}; };
;                 t0[k] = ld4(first ? hb : hb - (size_t)6 * C); t1[k] = ld4(first ? hb : hb - (size_t)5 * C);
;                 if (first) { t0[k] = z; t1[k] = z; }
;                 h0[k] = ld4(hb + (size_t)2 * C); h1[k] = ld4(hb + (size_t)3 * C);
;                 y0[k] = ld4(hb + (size_t)4 * C); y1[k] = ld4(hb + (size_t)5 * C); }
; #pragma unroll
;             for (int k = 0; k < 4; ++k) { const int s = 4 * u.pm + k; float o0[4], o1[4];
; #pragma unroll
;                 for (int j = 0; j < 4; ++j) {
;                     const float cv0 = w2[j] * h0[k][j] + w1[j] * t1[k][j] + w0[j] * t0[k][j] + bb[j];
;                     const float cv1 = w2[j] * h1[k][j] + w1[j] * h0[k][j] + w0[j] * t1[k][j] + bb[j];
;                     o0[j] = MODE == 0 ? silu_f(cv0) * y0[k][j] : cv0 * y0[k][j]; o1[j] = MODE == 0 ? silu_f(cv1) * y1[k][j] : cv1 * y1[k][j]; }
;                 u32x2 a; a.x = cvt_pk_bf16(o0[0], o0[1]); a.y = cvt_pk_bf16(o0[2], o0[3]); u32x2 b; b.x = cvt_pk_bf16(o1[0], o1[1]); b.y = cvt_pk_bf16(o1[2], o1[3]);
;                 *(u32x2*)(out + ((size_t)s * 64) * C + c) = a; *(u32x2*)(out + ((size_t)s * 64 + 1) * C + c) = b; }
	global_load_dwordx2 v[50:51], v2, s[24:25]
	s_add_i32 s17, s16, 0
	s_lshl_b32 s17, s17, 2
	s_add_i32 s17, s17, 1
	s_mul_i32 s17, s17, 0x8400
	s_add_u32 s18, s42, s17
	s_addc_u32 s19, s43, 0
	s_mov_b32 s26, 0x8400
	s_mov_b32 s27, 0x6e00
	s_sub_u32 s24, s18, s26
	s_subb_u32 s25, s19, 0
	global_load_dwordx2 v[52:53], v2, s[24:25]
	s_sub_u32 s24, s18, s27
	s_subb_u32 s25, s19, 0
	global_load_dwordx2 v[54:55], v2, s[24:25]
	s_add_u32 s24, s18, 0x2c00
	s_addc_u32 s25, s19, 0
	global_load_dwordx2 v[56:57], v2, s[24:25]
	s_add_u32 s24, s18, 0x4200
	s_addc_u32 s25, s19, 0
	global_load_dwordx2 v[58:59], v2, s[24:25]
	s_add_u32 s24, s18, 0x5800
	s_addc_u32 s25, s19, 0
	global_load_dwordx2 v[60:61], v2, s[24:25]
	s_add_u32 s24, s18, 0x6e00
	s_addc_u32 s25, s19, 0
	global_load_dwordx2 v[62:63], v2, s[24:25]
	s_add_i32 s17, s16, 0
	s_lshl_b32 s17, s17, 2
	s_add_i32 s17, s17, 2
	s_mul_i32 s17, s17, 0x8400
	s_add_u32 s18, s42, s17
	s_addc_u32 s19, s43, 0
	s_mov_b32 s26, 0x8400
	s_mov_b32 s27, 0x6e00
	s_sub_u32 s24, s18, s26
	s_subb_u32 s25, s19, 0
	global_load_dwordx2 v[64:65], v2, s[24:25]
	s_sub_u32 s24, s18, s27
	s_subb_u32 s25, s19, 0
	global_load_dwordx2 v[66:67], v2, s[24:25]
	s_add_u32 s24, s18, 0x2c00
	s_addc_u32 s25, s19, 0
	global_load_dwordx2 v[68:69], v2, s[24:25]
	s_add_u32 s24, s18, 0x4200
	s_addc_u32 s25, s19, 0
	global_load_dwordx2 v[70:71], v2, s[24:25]
	s_add_u32 s24, s18, 0x5800
	s_addc_u32 s25, s19, 0
	global_load_dwordx2 v[72:73], v2, s[24:25]
	s_add_u32 s24, s18, 0x6e00
	s_addc_u32 s25, s19, 0
	global_load_dwordx2 v[74:75], v2, s[24:25]
	s_add_i32 s17, s16, 0
	s_lshl_b32 s17, s17, 2
	s_add_i32 s17, s17, 3
	s_mul_i32 s17, s17, 0x8400
	s_add_u32 s18, s42, s17
	s_addc_u32 s19, s43, 0
	s_mov_b32 s26, 0x8400
	s_mov_b32 s27, 0x6e00
	s_sub_u32 s24, s18, s26
	s_subb_u32 s25, s19, 0
	global_load_dwordx2 v[76:77], v2, s[24:25]
	s_sub_u32 s24, s18, s27
	s_subb_u32 s25, s19, 0
	global_load_dwordx2 v[78:79], v2, s[24:25]
	s_add_u32 s24, s18, 0x2c00
	s_addc_u32 s25, s19, 0
	global_load_dwordx2 v[80:81], v2, s[24:25]
	s_add_u32 s24, s18, 0x4200
	s_addc_u32 s25, s19, 0
	global_load_dwordx2 v[82:83], v2, s[24:25]
	s_add_u32 s24, s18, 0x5800
	s_addc_u32 s25, s19, 0
	global_load_dwordx2 v[84:85], v2, s[24:25]
	s_add_u32 s24, s18, 0x6e00
	s_addc_u32 s25, s19, 0
	global_load_dwordx2 v[86:87], v2, s[24:25]
	s_mov_b64 exec, s[10:11]
	s_waitcnt vmcnt(36)
	s_add_i32 s17, s16, 8
	s_and_b32 s17, s17, 31
	s_cmp_lg_u32 s17, 0
	s_cbranch_scc1 .Lfix0_nz3
	v_mov_b32_e32 v88, 0
	v_mov_b32_e32 v89, 0
	v_mov_b32_e32 v90, 0
	v_mov_b32_e32 v91, 0
.Lfix0_nz3:
	v_lshlrev_b32_e32 v136, 16, v89
	v_and_b32_e32 v137, 0xffff0000, v89
	v_and_b32_e32 v89, 0xffff0000, v88
	v_lshlrev_b32_e32 v88, 16, v88
	v_lshlrev_b32_e32 v138, 16, v91
	v_and_b32_e32 v139, 0xffff0000, v91
	v_and_b32_e32 v91, 0xffff0000, v90
	v_lshlrev_b32_e32 v90, 16, v90
	v_lshlrev_b32_e32 v140, 16, v93
	v_and_b32_e32 v141, 0xffff0000, v93
	v_and_b32_e32 v93, 0xffff0000, v92
	v_lshlrev_b32_e32 v92, 16, v92
	v_lshlrev_b32_e32 v142, 16, v95
	v_and_b32_e32 v143, 0xffff0000, v95
	v_and_b32_e32 v95, 0xffff0000, v94
	v_lshlrev_b32_e32 v94, 16, v94
	v_lshlrev_b32_e32 v144, 16, v97
	v_and_b32_e32 v145, 0xffff0000, v97
	v_and_b32_e32 v97, 0xffff0000, v96
	v_lshlrev_b32_e32 v96, 16, v96
	v_lshlrev_b32_e32 v146, 16, v99
	v_and_b32_e32 v147, 0xffff0000, v99
	v_and_b32_e32 v99, 0xffff0000, v98
	v_lshlrev_b32_e32 v98, 16, v98
	v_pk_mul_f32 v[148:149], v[16:17], v[92:93]
	v_pk_mul_f32 v[150:151], v[18:19], v[140:141]
	v_pk_mul_f32 v[152:153], v[16:17], v[94:95]
	v_pk_mul_f32 v[154:155], v[18:19], v[142:143]
	v_pk_fma_f32 v[148:149], v[12:13], v[90:91], v[148:149]
	v_pk_fma_f32 v[150:151], v[14:15], v[138:139], v[150:151]
	v_pk_fma_f32 v[152:153], v[12:13], v[92:93], v[152:153]
	v_pk_fma_f32 v[154:155], v[14:15], v[140:141], v[154:155]
	v_pk_fma_f32 v[148:149], v[8:9], v[88:89], v[148:149]
	v_pk_fma_f32 v[150:151], v[10:11], v[136:137], v[150:151]
	v_pk_fma_f32 v[152:153], v[8:9], v[90:91], v[152:153]
	v_pk_fma_f32 v[154:155], v[10:11], v[138:139], v[154:155]
	v_pk_add_f32 v[148:149], v[148:149], v[20:21]
	v_pk_add_f32 v[150:151], v[150:151], v[22:23]
	v_pk_add_f32 v[152:153], v[152:153], v[20:21]
	v_pk_add_f32 v[154:155], v[154:155], v[22:23]
	v_pk_mul_f32 v[156:157], v[148:149], s[12:13] op_sel_hi:[1,0]
	v_pk_mul_f32 v[158:159], v[150:151], s[12:13] op_sel_hi:[1,0]
	v_pk_mul_f32 v[160:161], v[152:153], s[12:13] op_sel_hi:[1,0]
	v_pk_mul_f32 v[162:163], v[154:155], s[12:13] op_sel_hi:[1,0]
	v_exp_f32_e32 v156, v156
	v_exp_f32_e32 v157, v157
	v_exp_f32_e32 v158, v158
	v_exp_f32_e32 v159, v159
	v_exp_f32_e32 v160, v160
	v_exp_f32_e32 v161, v161
	v_exp_f32_e32 v162, v162
	v_exp_f32_e32 v163, v163
	v_pk_add_f32 v[156:157], v[156:157], s[12:13] op_sel:[0,1]
	v_pk_add_f32 v[158:159], v[158:159], s[12:13] op_sel:[0,1]
	v_pk_add_f32 v[160:161], v[160:161], s[12:13] op_sel:[0,1]
	v_pk_add_f32 v[162:163], v[162:163], s[12:13] op_sel:[0,1]
	v_rcp_f32_e32 v156, v156
	v_rcp_f32_e32 v157, v157
	v_rcp_f32_e32 v158, v158
	v_rcp_f32_e32 v159, v159
	v_rcp_f32_e32 v160, v160
	v_rcp_f32_e32 v161, v161
	v_rcp_f32_e32 v162, v162
	v_rcp_f32_e32 v163, v163
	v_pk_mul_f32 v[148:149], v[148:149], v[156:157]
	v_pk_mul_f32 v[150:151], v[150:151], v[158:159]
	v_pk_mul_f32 v[152:153], v[152:153], v[160:161]
	v_pk_mul_f32 v[154:155], v[154:155], v[162:163]
	v_pk_mul_f32 v[148:149], v[148:149], v[96:97]
	v_pk_mul_f32 v[150:151], v[150:151], v[144:145]
	v_pk_mul_f32 v[152:153], v[152:153], v[98:99]
	v_pk_mul_f32 v[154:155], v[154:155], v[146:147]
	v_cvt_pk_bf16_f32 v164, v148, v149
	v_cvt_pk_bf16_f32 v165, v150, v151
	v_cvt_pk_bf16_f32 v166, v152, v153
; __device__ __forceinline__ unsigned cvt_pk_bf16(float lo, float hi) { unsigned r; asm volatile("v_cvt_pk_bf16_f32 %0, %1, %2" : "=v"(r) : "v"(lo), "v"(hi)); return r; }
; __device__ __forceinline__ float bf_lo(unsigned w) { return __uint_as_float(w << 16); }
; __device__ __forceinline__ float bf_hi(unsigned w) { return __uint_as_float(w & 0xffff0000u); }
; __device__ __forceinline__ float silu_f(float x) { return x * __builtin_amdgcn_rcpf(1.0f + __builtin_amdgcn_exp2f(x * -1.44269504f)); }
; template <int MODE, class Sched> __device__ __forceinline__ void fixup_local(const bf16_t* halo, const float* cw, const float* cb, bf16_t* out, int C, const Sched& S) {
;     ...
;             for (int k = 0; k < 4; ++k) { const int s = 4 * u.pm + k; const bf16_t* hb = halo + (size_t)s * 6 * C + c; const bool first = (s & 127) == 0;
;                 const f32x4 z = (f32x4){0.f, 0.f, 0.f, 0.f};
;                 auto ld4 = [](const bf16_t* ptr) { const u32x2 w = *(const u32x2*)ptr; return (f32x4){bf_lo(w.x), bf_hi(w.x), bf_lo(w.y), bf_hi(w.y)}; };
;                 t0[k] = ld4(first ? hb : hb - (size_t)6 * C); t1[k] = ld4(first ? hb : hb - (size_t)5 * C);
;                 if (first) { t0[k] = z; t1[k] = z; }
;                 h0[k] = ld4(hb + (size_t)2 * C); h1[k] = ld4(hb + (size_t)3 * C);
;                 y0[k] = ld4(hb + (size_t)4 * C); y1[k] = ld4(hb + (size_t)5 * C); }
; #pragma unroll
;             for (int k = 0; k < 4; ++k) { const int s = 4 * u.pm + k; float o0[4], o1[4];
; #pragma unroll
;                 for (int j = 0; j < 4; ++j) {
;                     const float cv0 = w2[j] * h0[k][j] + w1[j] * t1[k][j] + w0[j] * t0[k][j] + bb[j];
;                     const float cv1 = w2[j] * h1[k][j] + w1[j] * h0[k][j] + w0[j] * t1[k][j] + bb[j];
;                     o0[j] = MODE == 0 ? silu_f(cv0) * y0[k][j] : cv0 * y0[k][j]; o1[j] = MODE == 0 ? silu_f(cv1) * y1[k][j] : cv1 * y1[k][j]; }
;                 u32x2 a; a.x = cvt_pk_bf16(o0[0], o0[1]); a.y = cvt_pk_bf16(o0[2], o0[3]); u32x2 b; b.x = cvt_pk_bf16(o1[0], o1[1]); b.y = cvt_pk_bf16(o1[2], o1[3]);
;                 *(u32x2*)(out + ((size_t)s * 64) * C + c) = a; *(u32x2*)(out + ((size_t)s * 64 + 1) * C + c) = b; }
	v_cvt_pk_bf16_f32 v167, v154, v155
	s_add_i32 s17, s16, 8
	s_lshl_b32 s17, s17, 2
	s_mul_i32 s17, s17, 0x58000
	s_add_u32 s36, s96, s17
	s_addc_u32 s37, s97, 0
	s_add_u32 s38, s36, 0x1600
	s_addc_u32 s39, s37, 0
	global_store_dwordx2 v1, v[164:165], s[36:37]
	global_store_dwordx2 v1, v[166:167], s[38:39]
	v_lshlrev_b32_e32 v136, 16, v101
	v_and_b32_e32 v137, 0xffff0000, v101
	v_and_b32_e32 v101, 0xffff0000, v100
	v_lshlrev_b32_e32 v100, 16, v100
	v_lshlrev_b32_e32 v138, 16, v103
	v_and_b32_e32 v139, 0xffff0000, v103
	v_and_b32_e32 v103, 0xffff0000, v102
	v_lshlrev_b32_e32 v102, 16, v102
	v_lshlrev_b32_e32 v140, 16, v105
	v_and_b32_e32 v141, 0xffff0000, v105
	v_and_b32_e32 v105, 0xffff0000, v104
	v_lshlrev_b32_e32 v104, 16, v104
	v_lshlrev_b32_e32 v142, 16, v107
	v_and_b32_e32 v143, 0xffff0000, v107
	v_and_b32_e32 v107, 0xffff0000, v106
	v_lshlrev_b32_e32 v106, 16, v106
	v_lshlrev_b32_e32 v144, 16, v109
	v_and_b32_e32 v145, 0xffff0000, v109
	v_and_b32_e32 v109, 0xffff0000, v108
	v_lshlrev_b32_e32 v108, 16, v108
	v_lshlrev_b32_e32 v146, 16, v111
	v_and_b32_e32 v147, 0xffff0000, v111
	v_and_b32_e32 v111, 0xffff0000, v110
	v_lshlrev_b32_e32 v110, 16, v110
	v_pk_mul_f32 v[148:149], v[16:17], v[104:105]
	v_pk_mul_f32 v[150:151], v[18:19], v[140:141]
	v_pk_mul_f32 v[152:153], v[16:17], v[106:107]
	v_pk_mul_f32 v[154:155], v[18:19], v[142:143]
	v_pk_fma_f32 v[148:149], v[12:13], v[102:103], v[148:149]
	v_pk_fma_f32 v[150:151], v[14:15], v[138:139], v[150:151]
	v_pk_fma_f32 v[152:153], v[12:13], v[104:105], v[152:153]
	v_pk_fma_f32 v[154:155], v[14:15], v[140:141], v[154:155]
	v_pk_fma_f32 v[148:149], v[8:9], v[100:101], v[148:149]
	v_pk_fma_f32 v[150:151], v[10:11], v[136:137], v[150:151]
	v_pk_fma_f32 v[152:153], v[8:9], v[102:103], v[152:153]
	v_pk_fma_f32 v[154:155], v[10:11], v[138:139], v[154:155]
	v_pk_add_f32 v[148:149], v[148:149], v[20:21]
	v_pk_add_f32 v[150:151], v[150:151], v[22:23]
	v_pk_add_f32 v[152:153], v[152:153], v[20:21]
	v_pk_add_f32 v[154:155], v[154:155], v[22:23]
	v_pk_mul_f32 v[156:157], v[148:149], s[12:13] op_sel_hi:[1,0]
	v_pk_mul_f32 v[158:159], v[150:151], s[12:13] op_sel_hi:[1,0]
	v_pk_mul_f32 v[160:161], v[152:153], s[12:13] op_sel_hi:[1,0]
	v_pk_mul_f32 v[162:163], v[154:155], s[12:13] op_sel_hi:[1,0]
	v_exp_f32_e32 v156, v156
	v_exp_f32_e32 v157, v157
	v_exp_f32_e32 v158, v158
	v_exp_f32_e32 v159, v159
	v_exp_f32_e32 v160, v160
	v_exp_f32_e32 v161, v161
	v_exp_f32_e32 v162, v162
	v_exp_f32_e32 v163, v163
	v_pk_add_f32 v[156:157], v[156:157], s[12:13] op_sel:[0,1]
	v_pk_add_f32 v[158:159], v[158:159], s[12:13] op_sel:[0,1]
	v_pk_add_f32 v[160:161], v[160:161], s[12:13] op_sel:[0,1]
	v_pk_add_f32 v[162:163], v[162:163], s[12:13] op_sel:[0,1]
	v_rcp_f32_e32 v156, v156
	v_rcp_f32_e32 v157, v157
	v_rcp_f32_e32 v158, v158
	v_rcp_f32_e32 v159, v159
	v_rcp_f32_e32 v160, v160
	v_rcp_f32_e32 v161, v161
	v_rcp_f32_e32 v162, v162
	v_rcp_f32_e32 v163, v163
	v_pk_mul_f32 v[148:149], v[148:149], v[156:157]
	v_pk_mul_f32 v[150:151], v[150:151], v[158:159]
	v_pk_mul_f32 v[152:153], v[152:153], v[160:161]
	v_pk_mul_f32 v[154:155], v[154:155], v[162:163]
	v_pk_mul_f32 v[148:149], v[148:149], v[108:109]
	v_pk_mul_f32 v[150:151], v[150:151], v[144:145]
	v_pk_mul_f32 v[152:153], v[152:153], v[110:111]
	v_pk_mul_f32 v[154:155], v[154:155], v[146:147]
	v_cvt_pk_bf16_f32 v164, v148, v149
	v_cvt_pk_bf16_f32 v165, v150, v151
	v_cvt_pk_bf16_f32 v166, v152, v153
	v_cvt_pk_bf16_f32 v167, v154, v155
	s_add_i32 s17, s16, 8
	s_lshl_b32 s17, s17, 2
	s_add_i32 s17, s17, 1
	s_mul_i32 s17, s17, 0x58000
	s_add_u32 s36, s96, s17
	s_addc_u32 s37, s97, 0
	s_add_u32 s38, s36, 0x1600
	s_addc_u32 s39, s37, 0
	global_store_dwordx2 v1, v[164:165], s[36:37]
	global_store_dwordx2 v1, v[166:167], s[38:39]
	v_lshlrev_b32_e32 v136, 16, v113
	v_and_b32_e32 v137, 0xffff0000, v113
	v_and_b32_e32 v113, 0xffff0000, v112
	v_lshlrev_b32_e32 v112, 16, v112
	v_lshlrev_b32_e32 v138, 16, v115
	v_and_b32_e32 v139, 0xffff0000, v115
	v_and_b32_e32 v115, 0xffff0000, v114
	v_lshlrev_b32_e32 v114, 16, v114
	v_lshlrev_b32_e32 v140, 16, v117
	v_and_b32_e32 v141, 0xffff0000, v117
	v_and_b32_e32 v117, 0xffff0000, v116
	v_lshlrev_b32_e32 v116, 16, v116
	v_lshlrev_b32_e32 v142, 16, v119
	v_and_b32_e32 v143, 0xffff0000, v119
	v_and_b32_e32 v119, 0xffff0000, v118
	v_lshlrev_b32_e32 v118, 16, v118
	v_lshlrev_b32_e32 v144, 16, v121
	v_and_b32_e32 v145, 0xffff0000, v121
	v_and_b32_e32 v121, 0xffff0000, v120
	v_lshlrev_b32_e32 v120, 16, v120
	v_lshlrev_b32_e32 v146, 16, v123
	v_and_b32_e32 v147, 0xffff0000, v123
	v_and_b32_e32 v123, 0xffff0000, v122
	v_lshlrev_b32_e32 v122, 16, v122
	v_pk_mul_f32 v[148:149], v[16:17], v[116:117]
	v_pk_mul_f32 v[150:151], v[18:19], v[140:141]
	v_pk_mul_f32 v[152:153], v[16:17], v[118:119]
	v_pk_mul_f32 v[154:155], v[18:19], v[142:143]
	v_pk_fma_f32 v[148:149], v[12:13], v[114:115], v[148:149]
	v_pk_fma_f32 v[150:151], v[14:15], v[138:139], v[150:151]
	v_pk_fma_f32 v[152:153], v[12:13], v[116:117], v[152:153]
	v_pk_fma_f32 v[154:155], v[14:15], v[140:141], v[154:155]
	v_pk_fma_f32 v[148:149], v[8:9], v[112:113], v[148:149]
	v_pk_fma_f32 v[150:151], v[10:11], v[136:137], v[150:151]
	v_pk_fma_f32 v[152:153], v[8:9], v[114:115], v[152:153]
	v_pk_fma_f32 v[154:155], v[10:11], v[138:139], v[154:155]
	v_pk_add_f32 v[148:149], v[148:149], v[20:21]
	v_pk_add_f32 v[150:151], v[150:151], v[22:23]
	v_pk_add_f32 v[152:153], v[152:153], v[20:21]
	v_pk_add_f32 v[154:155], v[154:155], v[22:23]
	v_pk_mul_f32 v[156:157], v[148:149], s[12:13] op_sel_hi:[1,0]
	v_pk_mul_f32 v[158:159], v[150:151], s[12:13] op_sel_hi:[1,0]
	v_pk_mul_f32 v[160:161], v[152:153], s[12:13] op_sel_hi:[1,0]
; __device__ __forceinline__ unsigned cvt_pk_bf16(float lo, float hi) { unsigned r; asm volatile("v_cvt_pk_bf16_f32 %0, %1, %2" : "=v"(r) : "v"(lo), "v"(hi)); return r; }
; __device__ __forceinline__ float bf_lo(unsigned w) { return __uint_as_float(w << 16); }
; __device__ __forceinline__ float bf_hi(unsigned w) { return __uint_as_float(w & 0xffff0000u); }
; __device__ __forceinline__ float silu_f(float x) { return x * __builtin_amdgcn_rcpf(1.0f + __builtin_amdgcn_exp2f(x * -1.44269504f)); }
; template <int MODE, class Sched> __device__ __forceinline__ void fixup_local(const bf16_t* halo, const float* cw, const float* cb, bf16_t* out, int C, const Sched& S) {
;     ...
;             for (int k = 0; k < 4; ++k) { const int s = 4 * u.pm + k; const bf16_t* hb = halo + (size_t)s * 6 * C + c; const bool first = (s & 127) == 0;
;                 const f32x4 z = (f32x4){0.f, 0.f, 0.f, 0.f};
;                 auto ld4 = [](const bf16_t* ptr) { const u32x2 w = *(const u32x2*)ptr; return (f32x4){bf_lo(w.x), bf_hi(w.x), bf_lo(w.y), bf_hi(w.y)}; };
;                 t0[k] = ld4(first ? hb : hb - (size_t)6 * C); t1[k] = ld4(first ? hb : hb - (size_t)5 * C);
;                 if (first) { t0[k] = z; t1[k] = z; }
;                 h0[k] = ld4(hb + (size_t)2 * C); h1[k] = ld4(hb + (size_t)3 * C);
;                 y0[k] = ld4(hb + (size_t)4 * C); y1[k] = ld4(hb + (size_t)5 * C); }
; #pragma unroll
;             for (int k = 0; k < 4; ++k) { const int s = 4 * u.pm + k; float o0[4], o1[4];
; #pragma unroll
;                 for (int j = 0; j < 4; ++j) {
;                     const float cv0 = w2[j] * h0[k][j] + w1[j] * t1[k][j] + w0[j] * t0[k][j] + bb[j];
;                     const float cv1 = w2[j] * h1[k][j] + w1[j] * h0[k][j] + w0[j] * t1[k][j] + bb[j];
;                     o0[j] = MODE == 0 ? silu_f(cv0) * y0[k][j] : cv0 * y0[k][j]; o1[j] = MODE == 0 ? silu_f(cv1) * y1[k][j] : cv1 * y1[k][j]; }
;                 u32x2 a; a.x = cvt_pk_bf16(o0[0], o0[1]); a.y = cvt_pk_bf16(o0[2], o0[3]); u32x2 b; b.x = cvt_pk_bf16(o1[0], o1[1]); b.y = cvt_pk_bf16(o1[2], o1[3]);
;                 *(u32x2*)(out + ((size_t)s * 64) * C + c) = a; *(u32x2*)(out + ((size_t)s * 64 + 1) * C + c) = b; }
	v_pk_mul_f32 v[162:163], v[154:155], s[12:13] op_sel_hi:[1,0]
	v_exp_f32_e32 v156, v156
	v_exp_f32_e32 v157, v157
	v_exp_f32_e32 v158, v158
	v_exp_f32_e32 v159, v159
	v_exp_f32_e32 v160, v160
	v_exp_f32_e32 v161, v161
	v_exp_f32_e32 v162, v162
	v_exp_f32_e32 v163, v163
	v_pk_add_f32 v[156:157], v[156:157], s[12:13] op_sel:[0,1]
	v_pk_add_f32 v[158:159], v[158:159], s[12:13] op_sel:[0,1]
	v_pk_add_f32 v[160:161], v[160:161], s[12:13] op_sel:[0,1]
	v_pk_add_f32 v[162:163], v[162:163], s[12:13] op_sel:[0,1]
	v_rcp_f32_e32 v156, v156
	v_rcp_f32_e32 v157, v157
	v_rcp_f32_e32 v158, v158
	v_rcp_f32_e32 v159, v159
	v_rcp_f32_e32 v160, v160
	v_rcp_f32_e32 v161, v161
	v_rcp_f32_e32 v162, v162
	v_rcp_f32_e32 v163, v163
	v_pk_mul_f32 v[148:149], v[148:149], v[156:157]
	v_pk_mul_f32 v[150:151], v[150:151], v[158:159]
	v_pk_mul_f32 v[152:153], v[152:153], v[160:161]
	v_pk_mul_f32 v[154:155], v[154:155], v[162:163]
	v_pk_mul_f32 v[148:149], v[148:149], v[120:121]
	v_pk_mul_f32 v[150:151], v[150:151], v[144:145]
	v_pk_mul_f32 v[152:153], v[152:153], v[122:123]
	v_pk_mul_f32 v[154:155], v[154:155], v[146:147]
	v_cvt_pk_bf16_f32 v164, v148, v149
	v_cvt_pk_bf16_f32 v165, v150, v151
	v_cvt_pk_bf16_f32 v166, v152, v153
	v_cvt_pk_bf16_f32 v167, v154, v155
	s_add_i32 s17, s16, 8
	s_lshl_b32 s17, s17, 2
	s_add_i32 s17, s17, 2
	s_mul_i32 s17, s17, 0x58000
	s_add_u32 s36, s96, s17
	s_addc_u32 s37, s97, 0
	s_add_u32 s38, s36, 0x1600
	s_addc_u32 s39, s37, 0
	global_store_dwordx2 v1, v[164:165], s[36:37]
	global_store_dwordx2 v1, v[166:167], s[38:39]
	v_lshlrev_b32_e32 v136, 16, v125
	v_and_b32_e32 v137, 0xffff0000, v125
	v_and_b32_e32 v125, 0xffff0000, v124
	v_lshlrev_b32_e32 v124, 16, v124
	v_lshlrev_b32_e32 v138, 16, v127
	v_and_b32_e32 v139, 0xffff0000, v127
	v_and_b32_e32 v127, 0xffff0000, v126
	v_lshlrev_b32_e32 v126, 16, v126
	v_lshlrev_b32_e32 v140, 16, v129
	v_and_b32_e32 v141, 0xffff0000, v129
	v_and_b32_e32 v129, 0xffff0000, v128
	v_lshlrev_b32_e32 v128, 16, v128
	v_lshlrev_b32_e32 v142, 16, v131
	v_and_b32_e32 v143, 0xffff0000, v131
	v_and_b32_e32 v131, 0xffff0000, v130
	v_lshlrev_b32_e32 v130, 16, v130
	v_lshlrev_b32_e32 v144, 16, v133
	v_and_b32_e32 v145, 0xffff0000, v133
	v_and_b32_e32 v133, 0xffff0000, v132
	v_lshlrev_b32_e32 v132, 16, v132
	v_lshlrev_b32_e32 v146, 16, v135
	v_and_b32_e32 v147, 0xffff0000, v135
	v_and_b32_e32 v135, 0xffff0000, v134
	v_lshlrev_b32_e32 v134, 16, v134
	v_pk_mul_f32 v[148:149], v[16:17], v[128:129]
	v_pk_mul_f32 v[150:151], v[18:19], v[140:141]
	v_pk_mul_f32 v[152:153], v[16:17], v[130:131]
	v_pk_mul_f32 v[154:155], v[18:19], v[142:143]
	v_pk_fma_f32 v[148:149], v[12:13], v[126:127], v[148:149]
	v_pk_fma_f32 v[150:151], v[14:15], v[138:139], v[150:151]
	v_pk_fma_f32 v[152:153], v[12:13], v[128:129], v[152:153]
	v_pk_fma_f32 v[154:155], v[14:15], v[140:141], v[154:155]
	v_pk_fma_f32 v[148:149], v[8:9], v[124:125], v[148:149]
	v_pk_fma_f32 v[150:151], v[10:11], v[136:137], v[150:151]
	v_pk_fma_f32 v[152:153], v[8:9], v[126:127], v[152:153]
	v_pk_fma_f32 v[154:155], v[10:11], v[138:139], v[154:155]
	v_pk_add_f32 v[148:149], v[148:149], v[20:21]
	v_pk_add_f32 v[150:151], v[150:151], v[22:23]
	v_pk_add_f32 v[152:153], v[152:153], v[20:21]
	v_pk_add_f32 v[154:155], v[154:155], v[22:23]
	v_pk_mul_f32 v[156:157], v[148:149], s[12:13] op_sel_hi:[1,0]
	v_pk_mul_f32 v[158:159], v[150:151], s[12:13] op_sel_hi:[1,0]
	v_pk_mul_f32 v[160:161], v[152:153], s[12:13] op_sel_hi:[1,0]
	v_pk_mul_f32 v[162:163], v[154:155], s[12:13] op_sel_hi:[1,0]
	v_exp_f32_e32 v156, v156
	v_exp_f32_e32 v157, v157
	v_exp_f32_e32 v158, v158
	v_exp_f32_e32 v159, v159
	v_exp_f32_e32 v160, v160
	v_exp_f32_e32 v161, v161
	v_exp_f32_e32 v162, v162
	v_exp_f32_e32 v163, v163
	v_pk_add_f32 v[156:157], v[156:157], s[12:13] op_sel:[0,1]
	v_pk_add_f32 v[158:159], v[158:159], s[12:13] op_sel:[0,1]
	v_pk_add_f32 v[160:161], v[160:161], s[12:13] op_sel:[0,1]
	v_pk_add_f32 v[162:163], v[162:163], s[12:13] op_sel:[0,1]
	v_rcp_f32_e32 v156, v156
	v_rcp_f32_e32 v157, v157
	v_rcp_f32_e32 v158, v158
	v_rcp_f32_e32 v159, v159
	v_rcp_f32_e32 v160, v160
	v_rcp_f32_e32 v161, v161
	v_rcp_f32_e32 v162, v162
	v_rcp_f32_e32 v163, v163
	v_pk_mul_f32 v[148:149], v[148:149], v[156:157]
	v_pk_mul_f32 v[150:151], v[150:151], v[158:159]
	v_pk_mul_f32 v[152:153], v[152:153], v[160:161]
	v_pk_mul_f32 v[154:155], v[154:155], v[162:163]
	v_pk_mul_f32 v[148:149], v[148:149], v[132:133]
	v_pk_mul_f32 v[150:151], v[150:151], v[144:145]
	v_pk_mul_f32 v[152:153], v[152:153], v[134:135]
	v_pk_mul_f32 v[154:155], v[154:155], v[146:147]
	v_cvt_pk_bf16_f32 v164, v148, v149
	v_cvt_pk_bf16_f32 v165, v150, v151
	v_cvt_pk_bf16_f32 v166, v152, v153
	v_cvt_pk_bf16_f32 v167, v154, v155
	s_add_i32 s17, s16, 8
	s_lshl_b32 s17, s17, 2
	s_add_i32 s17, s17, 3
	s_mul_i32 s17, s17, 0x58000
	s_add_u32 s36, s96, s17
	s_addc_u32 s37, s97, 0
	s_add_u32 s38, s36, 0x1600
	s_addc_u32 s39, s37, 0
	global_store_dwordx2 v1, v[164:165], s[36:37]
	global_store_dwordx2 v1, v[166:167], s[38:39]
	s_and_b64 exec, exec, s[30:31]
	s_cbranch_execz .Lfix0_end1
; __device__ __forceinline__ unsigned cvt_pk_bf16(float lo, float hi) { unsigned r; asm volatile("v_cvt_pk_bf16_f32 %0, %1, %2" : "=v"(r) : "v"(lo), "v"(hi)); return r; }
; __device__ __forceinline__ float bf_lo(unsigned w) { return __uint_as_float(w << 16); }
; template <int MODE, class Sched> __device__ __forceinline__ void fixup_local(const bf16_t* halo, const float* cw, const float* cb, bf16_t* out, int C, const Sched& S) {
;     ...
;         for (int c4 = tid; c4 < C4; c4 += 512) {
;             const int c = c4 * 4;
;             const f32x4 w0 = *(const f32x4*)(cw + c), w1 = *(const f32x4*)(cw + C + c), w2 = *(const f32x4*)(cw + 2 * C + c);
;             f32x4 bb = (f32x4){0.f, 0.f, 0.f, 0.f}; if (MODE == 0) bb = *(const f32x4*)(cb + c);
;             f32x4 t0[4], t1[4], h0[4], h1[4], y0[4], y1[4];
; #pragma unroll
;             for (int k = 0; k < 4; ++k) { const int s = 4 * u.pm + k; const bf16_t* hb = halo + (size_t)s * 6 * C + c; const bool first = (s & 127) == 0;
;                 const f32x4 z = (f32x4){0.f, 0.f, 0.f, 0.f};
;                 auto ld4 = [](const bf16_t* ptr) { const u32x2 w = *(const u32x2*)ptr; return (f32x4){bf_lo(w.x), bf_hi(w.x), bf_lo(w.y), bf_hi(w.y)}; };
;                 t0[k] = ld4(first ? hb : hb - (size_t)6 * C); t1[k] = ld4(first ? hb : hb - (size_t)5 * C);
;                 if (first) { t0[k] = z; t1[k] = z; }
;                 h0[k] = ld4(hb + (size_t)2 * C); h1[k] = ld4(hb + (size_t)3 * C);
;                 y0[k] = ld4(hb + (size_t)4 * C); y1[k] = ld4(hb + (size_t)5 * C); }
; #pragma unroll
;             for (int k = 0; k < 4; ++k) { const int s = 4 * u.pm + k; float o0[4], o1[4];
; #pragma unroll
;                 for (int j = 0; j < 4; ++j) {
;                     const float cv0 = w2[j] * h0[k][j] + w1[j] * t1[k][j] + w0[j] * t0[k][j] + bb[j];
;                     const float cv1 = w2[j] * h1[k][j] + w1[j] * h0[k][j] + w0[j] * t1[k][j] + bb[j];
;                     o0[j] = MODE == 0 ? silu_f(cv0) * y0[k][j] : cv0 * y0[k][j]; o1[j] = MODE == 0 ? silu_f(cv1) * y1[k][j] : cv1 * y1[k][j]; }
;                 u32x2 a; a.x = cvt_pk_bf16(o0[0], o0[1]); a.y = cvt_pk_bf16(o0[2], o0[3]); u32x2 b; b.x = cvt_pk_bf16(o1[0], o1[1]); b.y = cvt_pk_bf16(o1[2], o1[3]);
;                 *(u32x2*)(out + ((size_t)s * 64) * C + c) = a; *(u32x2*)(out + ((size_t)s * 64 + 1) * C + c) = b; }
	s_add_i32 s17, s16, 8
	s_lshl_b32 s17, s17, 2
	s_mul_i32 s17, s17, 0x8400
	s_add_u32 s18, s42, s17
	s_addc_u32 s19, s43, 0
	s_add_i32 s17, s16, 8
	s_and_b32 s17, s17, 31
	s_cmp_eq_u32 s17, 0
	s_cselect_b32 s26, 0, 0x8400
	s_cselect_b32 s27, 0, 0x6e00
	s_sub_u32 s24, s18, s26
	s_subb_u32 s25, s19, 0
	global_load_dwordx2 v[88:89], v2, s[24:25]
	s_sub_u32 s24, s18, s27
	s_subb_u32 s25, s19, 0
	global_load_dwordx2 v[90:91], v2, s[24:25]
	s_add_u32 s24, s18, 0x2c00
	s_addc_u32 s25, s19, 0
	global_load_dwordx2 v[92:93], v2, s[24:25]
	s_add_u32 s24, s18, 0x4200
	s_addc_u32 s25, s19, 0
	global_load_dwordx2 v[94:95], v2, s[24:25]
	s_add_u32 s24, s18, 0x5800
	s_addc_u32 s25, s19, 0
	global_load_dwordx2 v[96:97], v2, s[24:25]
	s_add_u32 s24, s18, 0x6e00
	s_addc_u32 s25, s19, 0
	global_load_dwordx2 v[98:99], v2, s[24:25]
	s_add_i32 s17, s16, 8
	s_lshl_b32 s17, s17, 2
	s_add_i32 s17, s17, 1
	s_mul_i32 s17, s17, 0x8400
	s_add_u32 s18, s42, s17
	s_addc_u32 s19, s43, 0
	s_mov_b32 s26, 0x8400
	s_mov_b32 s27, 0x6e00
	s_sub_u32 s24, s18, s26
	s_subb_u32 s25, s19, 0
	global_load_dwordx2 v[100:101], v2, s[24:25]
	s_sub_u32 s24, s18, s27
	s_subb_u32 s25, s19, 0
	global_load_dwordx2 v[102:103], v2, s[24:25]
	s_add_u32 s24, s18, 0x2c00
	s_addc_u32 s25, s19, 0
	global_load_dwordx2 v[104:105], v2, s[24:25]
	s_add_u32 s24, s18, 0x4200
	s_addc_u32 s25, s19, 0
	global_load_dwordx2 v[106:107], v2, s[24:25]
	s_add_u32 s24, s18, 0x5800
	s_addc_u32 s25, s19, 0
	global_load_dwordx2 v[108:109], v2, s[24:25]
	s_add_u32 s24, s18, 0x6e00
	s_addc_u32 s25, s19, 0
	global_load_dwordx2 v[110:111], v2, s[24:25]
	s_add_i32 s17, s16, 8
	s_lshl_b32 s17, s17, 2
	s_add_i32 s17, s17, 2
	s_mul_i32 s17, s17, 0x8400
	s_add_u32 s18, s42, s17
	s_addc_u32 s19, s43, 0
	s_mov_b32 s26, 0x8400
	s_mov_b32 s27, 0x6e00
	s_sub_u32 s24, s18, s26
	s_subb_u32 s25, s19, 0
	global_load_dwordx2 v[112:113], v2, s[24:25]
	s_sub_u32 s24, s18, s27
	s_subb_u32 s25, s19, 0
	global_load_dwordx2 v[114:115], v2, s[24:25]
	s_add_u32 s24, s18, 0x2c00
	s_addc_u32 s25, s19, 0
	global_load_dwordx2 v[116:117], v2, s[24:25]
	s_add_u32 s24, s18, 0x4200
	s_addc_u32 s25, s19, 0
	global_load_dwordx2 v[118:119], v2, s[24:25]
	s_add_u32 s24, s18, 0x5800
	s_addc_u32 s25, s19, 0
	global_load_dwordx2 v[120:121], v2, s[24:25]
	s_add_u32 s24, s18, 0x6e00
	s_addc_u32 s25, s19, 0
	global_load_dwordx2 v[122:123], v2, s[24:25]
	s_add_i32 s17, s16, 8
	s_lshl_b32 s17, s17, 2
	s_add_i32 s17, s17, 3
	s_mul_i32 s17, s17, 0x8400
	s_add_u32 s18, s42, s17
	s_addc_u32 s19, s43, 0
	s_mov_b32 s26, 0x8400
	s_mov_b32 s27, 0x6e00
	s_sub_u32 s24, s18, s26
	s_subb_u32 s25, s19, 0
	global_load_dwordx2 v[124:125], v2, s[24:25]
	s_sub_u32 s24, s18, s27
	s_subb_u32 s25, s19, 0
	global_load_dwordx2 v[126:127], v2, s[24:25]
	s_add_u32 s24, s18, 0x2c00
	s_addc_u32 s25, s19, 0
	global_load_dwordx2 v[128:129], v2, s[24:25]
	s_add_u32 s24, s18, 0x4200
	s_addc_u32 s25, s19, 0
	global_load_dwordx2 v[130:131], v2, s[24:25]
	s_add_u32 s24, s18, 0x5800
	s_addc_u32 s25, s19, 0
	global_load_dwordx2 v[132:133], v2, s[24:25]
	s_add_u32 s24, s18, 0x6e00
	s_addc_u32 s25, s19, 0
	global_load_dwordx2 v[134:135], v2, s[24:25]
	s_waitcnt vmcnt(32)
	s_add_i32 s17, s16, 0
	s_and_b32 s17, s17, 31
	s_cmp_lg_u32 s17, 0
	s_cbranch_scc1 .Lfix0_nz4
	v_mov_b32_e32 v40, 0
	v_mov_b32_e32 v41, 0
	v_mov_b32_e32 v42, 0
	v_mov_b32_e32 v43, 0
.Lfix0_nz4:
	v_lshlrev_b32_e32 v136, 16, v41
	v_and_b32_e32 v137, 0xffff0000, v41
	v_and_b32_e32 v41, 0xffff0000, v40
	v_lshlrev_b32_e32 v40, 16, v40
	v_lshlrev_b32_e32 v138, 16, v43
	v_and_b32_e32 v139, 0xffff0000, v43
	v_and_b32_e32 v43, 0xffff0000, v42
	v_lshlrev_b32_e32 v42, 16, v42
	v_lshlrev_b32_e32 v140, 16, v45
	v_and_b32_e32 v141, 0xffff0000, v45
	v_and_b32_e32 v45, 0xffff0000, v44
	v_lshlrev_b32_e32 v44, 16, v44
	v_lshlrev_b32_e32 v142, 16, v47
	v_and_b32_e32 v143, 0xffff0000, v47
	v_and_b32_e32 v47, 0xffff0000, v46
	v_lshlrev_b32_e32 v46, 16, v46
	v_lshlrev_b32_e32 v144, 16, v49
	v_and_b32_e32 v145, 0xffff0000, v49
	v_and_b32_e32 v49, 0xffff0000, v48
	v_lshlrev_b32_e32 v48, 16, v48
	v_lshlrev_b32_e32 v146, 16, v51
	v_and_b32_e32 v147, 0xffff0000, v51
	v_and_b32_e32 v51, 0xffff0000, v50
	v_lshlrev_b32_e32 v50, 16, v50
	v_pk_mul_f32 v[148:149], v[32:33], v[44:45]
	v_pk_mul_f32 v[150:151], v[34:35], v[140:141]
	v_pk_mul_f32 v[152:153], v[32:33], v[46:47]
	v_pk_mul_f32 v[154:155], v[34:35], v[142:143]
	v_pk_fma_f32 v[148:149], v[28:29], v[42:43], v[148:149]
	v_pk_fma_f32 v[150:151], v[30:31], v[138:139], v[150:151]
	v_pk_fma_f32 v[152:153], v[28:29], v[44:45], v[152:153]
	v_pk_fma_f32 v[154:155], v[30:31], v[140:141], v[154:155]
	v_pk_fma_f32 v[148:149], v[24:25], v[40:41], v[148:149]
	v_pk_fma_f32 v[150:151], v[26:27], v[136:137], v[150:151]
	v_pk_fma_f32 v[152:153], v[24:25], v[42:43], v[152:153]
	v_pk_fma_f32 v[154:155], v[26:27], v[138:139], v[154:155]
	v_pk_add_f32 v[148:149], v[148:149], v[36:37]
	v_pk_add_f32 v[150:151], v[150:151], v[38:39]
	v_pk_add_f32 v[152:153], v[152:153], v[36:37]
	v_pk_add_f32 v[154:155], v[154:155], v[38:39]
	v_pk_mul_f32 v[156:157], v[148:149], s[12:13] op_sel_hi:[1,0]
	v_pk_mul_f32 v[158:159], v[150:151], s[12:13] op_sel_hi:[1,0]
	v_pk_mul_f32 v[160:161], v[152:153], s[12:13] op_sel_hi:[1,0]
	v_pk_mul_f32 v[162:163], v[154:155], s[12:13] op_sel_hi:[1,0]
	v_exp_f32_e32 v156, v156
	v_exp_f32_e32 v157, v157
	v_exp_f32_e32 v158, v158
	v_exp_f32_e32 v159, v159
	v_exp_f32_e32 v160, v160
	v_exp_f32_e32 v161, v161
	v_exp_f32_e32 v162, v162
	v_exp_f32_e32 v163, v163
	v_pk_add_f32 v[156:157], v[156:157], s[12:13] op_sel:[0,1]
	v_pk_add_f32 v[158:159], v[158:159], s[12:13] op_sel:[0,1]
	v_pk_add_f32 v[160:161], v[160:161], s[12:13] op_sel:[0,1]
; __device__ __forceinline__ unsigned cvt_pk_bf16(float lo, float hi) { unsigned r; asm volatile("v_cvt_pk_bf16_f32 %0, %1, %2" : "=v"(r) : "v"(lo), "v"(hi)); return r; }
; __device__ __forceinline__ float bf_lo(unsigned w) { return __uint_as_float(w << 16); }
; __device__ __forceinline__ float bf_hi(unsigned w) { return __uint_as_float(w & 0xffff0000u); }
; __device__ __forceinline__ float silu_f(float x) { return x * __builtin_amdgcn_rcpf(1.0f + __builtin_amdgcn_exp2f(x * -1.44269504f)); }
; template <int MODE, class Sched> __device__ __forceinline__ void fixup_local(const bf16_t* halo, const float* cw, const float* cb, bf16_t* out, int C, const Sched& S) {
;     ...
;             for (int k = 0; k < 4; ++k) { const int s = 4 * u.pm + k; const bf16_t* hb = halo + (size_t)s * 6 * C + c; const bool first = (s & 127) == 0;
;                 const f32x4 z = (f32x4){0.f, 0.f, 0.f, 0.f};
;                 auto ld4 = [](const bf16_t* ptr) { const u32x2 w = *(const u32x2*)ptr; return (f32x4){bf_lo(w.x), bf_hi(w.x), bf_lo(w.y), bf_hi(w.y)}; };
;                 t0[k] = ld4(first ? hb : hb - (size_t)6 * C); t1[k] = ld4(first ? hb : hb - (size_t)5 * C);
;                 if (first) { t0[k] = z; t1[k] = z; }
;                 h0[k] = ld4(hb + (size_t)2 * C); h1[k] = ld4(hb + (size_t)3 * C);
;                 y0[k] = ld4(hb + (size_t)4 * C); y1[k] = ld4(hb + (size_t)5 * C); }
; #pragma unroll
;             for (int k = 0; k < 4; ++k) { const int s = 4 * u.pm + k; float o0[4], o1[4];
; #pragma unroll
;                 for (int j = 0; j < 4; ++j) {
;                     const float cv0 = w2[j] * h0[k][j] + w1[j] * t1[k][j] + w0[j] * t0[k][j] + bb[j];
;                     const float cv1 = w2[j] * h1[k][j] + w1[j] * h0[k][j] + w0[j] * t1[k][j] + bb[j];
;                     o0[j] = MODE == 0 ? silu_f(cv0) * y0[k][j] : cv0 * y0[k][j]; o1[j] = MODE == 0 ? silu_f(cv1) * y1[k][j] : cv1 * y1[k][j]; }
;                 u32x2 a; a.x = cvt_pk_bf16(o0[0], o0[1]); a.y = cvt_pk_bf16(o0[2], o0[3]); u32x2 b; b.x = cvt_pk_bf16(o1[0], o1[1]); b.y = cvt_pk_bf16(o1[2], o1[3]);
;                 *(u32x2*)(out + ((size_t)s * 64) * C + c) = a; *(u32x2*)(out + ((size_t)s * 64 + 1) * C + c) = b; }
	v_pk_add_f32 v[162:163], v[162:163], s[12:13] op_sel:[0,1]
	v_rcp_f32_e32 v156, v156
	v_rcp_f32_e32 v157, v157
	v_rcp_f32_e32 v158, v158
	v_rcp_f32_e32 v159, v159
	v_rcp_f32_e32 v160, v160
	v_rcp_f32_e32 v161, v161
	v_rcp_f32_e32 v162, v162
	v_rcp_f32_e32 v163, v163
	v_pk_mul_f32 v[148:149], v[148:149], v[156:157]
	v_pk_mul_f32 v[150:151], v[150:151], v[158:159]
	v_pk_mul_f32 v[152:153], v[152:153], v[160:161]
	v_pk_mul_f32 v[154:155], v[154:155], v[162:163]
	v_pk_mul_f32 v[148:149], v[148:149], v[48:49]
	v_pk_mul_f32 v[150:151], v[150:151], v[144:145]
	v_pk_mul_f32 v[152:153], v[152:153], v[50:51]
	v_pk_mul_f32 v[154:155], v[154:155], v[146:147]
	v_cvt_pk_bf16_f32 v164, v148, v149
	v_cvt_pk_bf16_f32 v165, v150, v151
	v_cvt_pk_bf16_f32 v166, v152, v153
	v_cvt_pk_bf16_f32 v167, v154, v155
	s_add_i32 s17, s16, 0
	s_lshl_b32 s17, s17, 2
	s_mul_i32 s17, s17, 0x58000
	s_add_u32 s36, s96, s17
	s_addc_u32 s37, s97, 0
	s_add_u32 s38, s36, 0x1600
	s_addc_u32 s39, s37, 0
	global_store_dwordx2 v2, v[164:165], s[36:37]
	global_store_dwordx2 v2, v[166:167], s[38:39]
	v_lshlrev_b32_e32 v136, 16, v53
	v_and_b32_e32 v137, 0xffff0000, v53
	v_and_b32_e32 v53, 0xffff0000, v52
	v_lshlrev_b32_e32 v52, 16, v52
	v_lshlrev_b32_e32 v138, 16, v55
	v_and_b32_e32 v139, 0xffff0000, v55
	v_and_b32_e32 v55, 0xffff0000, v54
	v_lshlrev_b32_e32 v54, 16, v54
	v_lshlrev_b32_e32 v140, 16, v57
	v_and_b32_e32 v141, 0xffff0000, v57
	v_and_b32_e32 v57, 0xffff0000, v56
	v_lshlrev_b32_e32 v56, 16, v56
	v_lshlrev_b32_e32 v142, 16, v59
	v_and_b32_e32 v143, 0xffff0000, v59
	v_and_b32_e32 v59, 0xffff0000, v58
	v_lshlrev_b32_e32 v58, 16, v58
	v_lshlrev_b32_e32 v144, 16, v61
	v_and_b32_e32 v145, 0xffff0000, v61
	v_and_b32_e32 v61, 0xffff0000, v60
	v_lshlrev_b32_e32 v60, 16, v60
	v_lshlrev_b32_e32 v146, 16, v63
	v_and_b32_e32 v147, 0xffff0000, v63
	v_and_b32_e32 v63, 0xffff0000, v62
	v_lshlrev_b32_e32 v62, 16, v62
	v_pk_mul_f32 v[148:149], v[32:33], v[56:57]
	v_pk_mul_f32 v[150:151], v[34:35], v[140:141]
	v_pk_mul_f32 v[152:153], v[32:33], v[58:59]
	v_pk_mul_f32 v[154:155], v[34:35], v[142:143]
	v_pk_fma_f32 v[148:149], v[28:29], v[54:55], v[148:149]
	v_pk_fma_f32 v[150:151], v[30:31], v[138:139], v[150:151]
	v_pk_fma_f32 v[152:153], v[28:29], v[56:57], v[152:153]
	v_pk_fma_f32 v[154:155], v[30:31], v[140:141], v[154:155]
	v_pk_fma_f32 v[148:149], v[24:25], v[52:53], v[148:149]
	v_pk_fma_f32 v[150:151], v[26:27], v[136:137], v[150:151]
	v_pk_fma_f32 v[152:153], v[24:25], v[54:55], v[152:153]
	v_pk_fma_f32 v[154:155], v[26:27], v[138:139], v[154:155]
	v_pk_add_f32 v[148:149], v[148:149], v[36:37]
	v_pk_add_f32 v[150:151], v[150:151], v[38:39]
	v_pk_add_f32 v[152:153], v[152:153], v[36:37]
	v_pk_add_f32 v[154:155], v[154:155], v[38:39]
	v_pk_mul_f32 v[156:157], v[148:149], s[12:13] op_sel_hi:[1,0]
	v_pk_mul_f32 v[158:159], v[150:151], s[12:13] op_sel_hi:[1,0]
	v_pk_mul_f32 v[160:161], v[152:153], s[12:13] op_sel_hi:[1,0]
	v_pk_mul_f32 v[162:163], v[154:155], s[12:13] op_sel_hi:[1,0]
	v_exp_f32_e32 v156, v156
	v_exp_f32_e32 v157, v157
	v_exp_f32_e32 v158, v158
	v_exp_f32_e32 v159, v159
	v_exp_f32_e32 v160, v160
	v_exp_f32_e32 v161, v161
	v_exp_f32_e32 v162, v162
	v_exp_f32_e32 v163, v163
	v_pk_add_f32 v[156:157], v[156:157], s[12:13] op_sel:[0,1]
	v_pk_add_f32 v[158:159], v[158:159], s[12:13] op_sel:[0,1]
	v_pk_add_f32 v[160:161], v[160:161], s[12:13] op_sel:[0,1]
	v_pk_add_f32 v[162:163], v[162:163], s[12:13] op_sel:[0,1]
	v_rcp_f32_e32 v156, v156
	v_rcp_f32_e32 v157, v157
	v_rcp_f32_e32 v158, v158
	v_rcp_f32_e32 v159, v159
	v_rcp_f32_e32 v160, v160
	v_rcp_f32_e32 v161, v161
	v_rcp_f32_e32 v162, v162
	v_rcp_f32_e32 v163, v163
	v_pk_mul_f32 v[148:149], v[148:149], v[156:157]
	v_pk_mul_f32 v[150:151], v[150:151], v[158:159]
	v_pk_mul_f32 v[152:153], v[152:153], v[160:161]
	v_pk_mul_f32 v[154:155], v[154:155], v[162:163]
	v_pk_mul_f32 v[148:149], v[148:149], v[60:61]
	v_pk_mul_f32 v[150:151], v[150:151], v[144:145]
	v_pk_mul_f32 v[152:153], v[152:153], v[62:63]
	v_pk_mul_f32 v[154:155], v[154:155], v[146:147]
	v_cvt_pk_bf16_f32 v164, v148, v149
	v_cvt_pk_bf16_f32 v165, v150, v151
	v_cvt_pk_bf16_f32 v166, v152, v153
	v_cvt_pk_bf16_f32 v167, v154, v155
	s_add_i32 s17, s16, 0
	s_lshl_b32 s17, s17, 2
	s_add_i32 s17, s17, 1
	s_mul_i32 s17, s17, 0x58000
	s_add_u32 s36, s96, s17
	s_addc_u32 s37, s97, 0
	s_add_u32 s38, s36, 0x1600
	s_addc_u32 s39, s37, 0
	global_store_dwordx2 v2, v[164:165], s[36:37]
	global_store_dwordx2 v2, v[166:167], s[38:39]
	v_lshlrev_b32_e32 v136, 16, v65
	v_and_b32_e32 v137, 0xffff0000, v65
	v_and_b32_e32 v65, 0xffff0000, v64
	v_lshlrev_b32_e32 v64, 16, v64
	v_lshlrev_b32_e32 v138, 16, v67
	v_and_b32_e32 v139, 0xffff0000, v67
	v_and_b32_e32 v67, 0xffff0000, v66
	v_lshlrev_b32_e32 v66, 16, v66
	v_lshlrev_b32_e32 v140, 16, v69
	v_and_b32_e32 v141, 0xffff0000, v69
	v_and_b32_e32 v69, 0xffff0000, v68
	v_lshlrev_b32_e32 v68, 16, v68
	v_lshlrev_b32_e32 v142, 16, v71
	v_and_b32_e32 v143, 0xffff0000, v71
	v_and_b32_e32 v71, 0xffff0000, v70
	v_lshlrev_b32_e32 v70, 16, v70
	v_lshlrev_b32_e32 v144, 16, v73
	v_and_b32_e32 v145, 0xffff0000, v73
	v_and_b32_e32 v73, 0xffff0000, v72
	v_lshlrev_b32_e32 v72, 16, v72
	v_lshlrev_b32_e32 v146, 16, v75
	v_and_b32_e32 v147, 0xffff0000, v75
	v_and_b32_e32 v75, 0xffff0000, v74
	v_lshlrev_b32_e32 v74, 16, v74
	v_pk_mul_f32 v[148:149], v[32:33], v[68:69]
	v_pk_mul_f32 v[150:151], v[34:35], v[140:141]
	v_pk_mul_f32 v[152:153], v[32:33], v[70:71]
	v_pk_mul_f32 v[154:155], v[34:35], v[142:143]
	v_pk_fma_f32 v[148:149], v[28:29], v[66:67], v[148:149]
	v_pk_fma_f32 v[150:151], v[30:31], v[138:139], v[150:151]
	v_pk_fma_f32 v[152:153], v[28:29], v[68:69], v[152:153]
; __device__ __forceinline__ unsigned cvt_pk_bf16(float lo, float hi) { unsigned r; asm volatile("v_cvt_pk_bf16_f32 %0, %1, %2" : "=v"(r) : "v"(lo), "v"(hi)); return r; }
; __device__ __forceinline__ float bf_lo(unsigned w) { return __uint_as_float(w << 16); }
; __device__ __forceinline__ float bf_hi(unsigned w) { return __uint_as_float(w & 0xffff0000u); }
; __device__ __forceinline__ float silu_f(float x) { return x * __builtin_amdgcn_rcpf(1.0f + __builtin_amdgcn_exp2f(x * -1.44269504f)); }
; template <int MODE, class Sched> __device__ __forceinline__ void fixup_local(const bf16_t* halo, const float* cw, const float* cb, bf16_t* out, int C, const Sched& S) {
;     ...
;             for (int k = 0; k < 4; ++k) { const int s = 4 * u.pm + k; const bf16_t* hb = halo + (size_t)s * 6 * C + c; const bool first = (s & 127) == 0;
;                 const f32x4 z = (f32x4){0.f, 0.f, 0.f, 0.f};
;                 auto ld4 = [](const bf16_t* ptr) { const u32x2 w = *(const u32x2*)ptr; return (f32x4){bf_lo(w.x), bf_hi(w.x), bf_lo(w.y), bf_hi(w.y)}; };
;                 t0[k] = ld4(first ? hb : hb - (size_t)6 * C); t1[k] = ld4(first ? hb : hb - (size_t)5 * C);
;                 if (first) { t0[k] = z; t1[k] = z; }
;                 h0[k] = ld4(hb + (size_t)2 * C); h1[k] = ld4(hb + (size_t)3 * C);
;                 y0[k] = ld4(hb + (size_t)4 * C); y1[k] = ld4(hb + (size_t)5 * C); }
; #pragma unroll
;             for (int k = 0; k < 4; ++k) { const int s = 4 * u.pm + k; float o0[4], o1[4];
; #pragma unroll
;                 for (int j = 0; j < 4; ++j) {
;                     const float cv0 = w2[j] * h0[k][j] + w1[j] * t1[k][j] + w0[j] * t0[k][j] + bb[j];
;                     const float cv1 = w2[j] * h1[k][j] + w1[j] * h0[k][j] + w0[j] * t1[k][j] + bb[j];
;                     o0[j] = MODE == 0 ? silu_f(cv0) * y0[k][j] : cv0 * y0[k][j]; o1[j] = MODE == 0 ? silu_f(cv1) * y1[k][j] : cv1 * y1[k][j]; }
;                 u32x2 a; a.x = cvt_pk_bf16(o0[0], o0[1]); a.y = cvt_pk_bf16(o0[2], o0[3]); u32x2 b; b.x = cvt_pk_bf16(o1[0], o1[1]); b.y = cvt_pk_bf16(o1[2], o1[3]);
;                 *(u32x2*)(out + ((size_t)s * 64) * C + c) = a; *(u32x2*)(out + ((size_t)s * 64 + 1) * C + c) = b; }
	v_pk_fma_f32 v[154:155], v[30:31], v[140:141], v[154:155]
	v_pk_fma_f32 v[148:149], v[24:25], v[64:65], v[148:149]
	v_pk_fma_f32 v[150:151], v[26:27], v[136:137], v[150:151]
	v_pk_fma_f32 v[152:153], v[24:25], v[66:67], v[152:153]
	v_pk_fma_f32 v[154:155], v[26:27], v[138:139], v[154:155]
	v_pk_add_f32 v[148:149], v[148:149], v[36:37]
	v_pk_add_f32 v[150:151], v[150:151], v[38:39]
	v_pk_add_f32 v[152:153], v[152:153], v[36:37]
	v_pk_add_f32 v[154:155], v[154:155], v[38:39]
	v_pk_mul_f32 v[156:157], v[148:149], s[12:13] op_sel_hi:[1,0]
	v_pk_mul_f32 v[158:159], v[150:151], s[12:13] op_sel_hi:[1,0]
	v_pk_mul_f32 v[160:161], v[152:153], s[12:13] op_sel_hi:[1,0]
	v_pk_mul_f32 v[162:163], v[154:155], s[12:13] op_sel_hi:[1,0]
	v_exp_f32_e32 v156, v156
	v_exp_f32_e32 v157, v157
	v_exp_f32_e32 v158, v158
	v_exp_f32_e32 v159, v159
	v_exp_f32_e32 v160, v160
	v_exp_f32_e32 v161, v161
	v_exp_f32_e32 v162, v162
	v_exp_f32_e32 v163, v163
	v_pk_add_f32 v[156:157], v[156:157], s[12:13] op_sel:[0,1]
	v_pk_add_f32 v[158:159], v[158:159], s[12:13] op_sel:[0,1]
	v_pk_add_f32 v[160:161], v[160:161], s[12:13] op_sel:[0,1]
	v_pk_add_f32 v[162:163], v[162:163], s[12:13] op_sel:[0,1]
	v_rcp_f32_e32 v156, v156
	v_rcp_f32_e32 v157, v157
	v_rcp_f32_e32 v158, v158
	v_rcp_f32_e32 v159, v159
	v_rcp_f32_e32 v160, v160
	v_rcp_f32_e32 v161, v161
	v_rcp_f32_e32 v162, v162
	v_rcp_f32_e32 v163, v163
	v_pk_mul_f32 v[148:149], v[148:149], v[156:157]
	v_pk_mul_f32 v[150:151], v[150:151], v[158:159]
	v_pk_mul_f32 v[152:153], v[152:153], v[160:161]
	v_pk_mul_f32 v[154:155], v[154:155], v[162:163]
	v_pk_mul_f32 v[148:149], v[148:149], v[72:73]
	v_pk_mul_f32 v[150:151], v[150:151], v[144:145]
	v_pk_mul_f32 v[152:153], v[152:153], v[74:75]
	v_pk_mul_f32 v[154:155], v[154:155], v[146:147]
	v_cvt_pk_bf16_f32 v164, v148, v149
	v_cvt_pk_bf16_f32 v165, v150, v151
	v_cvt_pk_bf16_f32 v166, v152, v153
	v_cvt_pk_bf16_f32 v167, v154, v155
	s_add_i32 s17, s16, 0
	s_lshl_b32 s17, s17, 2
	s_add_i32 s17, s17, 2
	s_mul_i32 s17, s17, 0x58000
	s_add_u32 s36, s96, s17
	s_addc_u32 s37, s97, 0
	s_add_u32 s38, s36, 0x1600
	s_addc_u32 s39, s37, 0
	global_store_dwordx2 v2, v[164:165], s[36:37]
	global_store_dwordx2 v2, v[166:167], s[38:39]
	v_lshlrev_b32_e32 v136, 16, v77
	v_and_b32_e32 v137, 0xffff0000, v77
	v_and_b32_e32 v77, 0xffff0000, v76
	v_lshlrev_b32_e32 v76, 16, v76
	v_lshlrev_b32_e32 v138, 16, v79
	v_and_b32_e32 v139, 0xffff0000, v79
	v_and_b32_e32 v79, 0xffff0000, v78
	v_lshlrev_b32_e32 v78, 16, v78
	v_lshlrev_b32_e32 v140, 16, v81
	v_and_b32_e32 v141, 0xffff0000, v81
	v_and_b32_e32 v81, 0xffff0000, v80
	v_lshlrev_b32_e32 v80, 16, v80
	v_lshlrev_b32_e32 v142, 16, v83
	v_and_b32_e32 v143, 0xffff0000, v83
	v_and_b32_e32 v83, 0xffff0000, v82
	v_lshlrev_b32_e32 v82, 16, v82
	v_lshlrev_b32_e32 v144, 16, v85
	v_and_b32_e32 v145, 0xffff0000, v85
	v_and_b32_e32 v85, 0xffff0000, v84
	v_lshlrev_b32_e32 v84, 16, v84
	v_lshlrev_b32_e32 v146, 16, v87
	v_and_b32_e32 v147, 0xffff0000, v87
	v_and_b32_e32 v87, 0xffff0000, v86
	v_lshlrev_b32_e32 v86, 16, v86
	v_pk_mul_f32 v[148:149], v[32:33], v[80:81]
	v_pk_mul_f32 v[150:151], v[34:35], v[140:141]
	v_pk_mul_f32 v[152:153], v[32:33], v[82:83]
	v_pk_mul_f32 v[154:155], v[34:35], v[142:143]
	v_pk_fma_f32 v[148:149], v[28:29], v[78:79], v[148:149]
	v_pk_fma_f32 v[150:151], v[30:31], v[138:139], v[150:151]
	v_pk_fma_f32 v[152:153], v[28:29], v[80:81], v[152:153]
	v_pk_fma_f32 v[154:155], v[30:31], v[140:141], v[154:155]
	v_pk_fma_f32 v[148:149], v[24:25], v[76:77], v[148:149]
	v_pk_fma_f32 v[150:151], v[26:27], v[136:137], v[150:151]
	v_pk_fma_f32 v[152:153], v[24:25], v[78:79], v[152:153]
	v_pk_fma_f32 v[154:155], v[26:27], v[138:139], v[154:155]
	v_pk_add_f32 v[148:149], v[148:149], v[36:37]
	v_pk_add_f32 v[150:151], v[150:151], v[38:39]
	v_pk_add_f32 v[152:153], v[152:153], v[36:37]
	v_pk_add_f32 v[154:155], v[154:155], v[38:39]
	v_pk_mul_f32 v[156:157], v[148:149], s[12:13] op_sel_hi:[1,0]
	v_pk_mul_f32 v[158:159], v[150:151], s[12:13] op_sel_hi:[1,0]
	v_pk_mul_f32 v[160:161], v[152:153], s[12:13] op_sel_hi:[1,0]
	v_pk_mul_f32 v[162:163], v[154:155], s[12:13] op_sel_hi:[1,0]
	v_exp_f32_e32 v156, v156
	v_exp_f32_e32 v157, v157
	v_exp_f32_e32 v158, v158
	v_exp_f32_e32 v159, v159
	v_exp_f32_e32 v160, v160
	v_exp_f32_e32 v161, v161
	v_exp_f32_e32 v162, v162
	v_exp_f32_e32 v163, v163
	v_pk_add_f32 v[156:157], v[156:157], s[12:13] op_sel:[0,1]
	v_pk_add_f32 v[158:159], v[158:159], s[12:13] op_sel:[0,1]
	v_pk_add_f32 v[160:161], v[160:161], s[12:13] op_sel:[0,1]
	v_pk_add_f32 v[162:163], v[162:163], s[12:13] op_sel:[0,1]
	v_rcp_f32_e32 v156, v156
	v_rcp_f32_e32 v157, v157
	v_rcp_f32_e32 v158, v158
	v_rcp_f32_e32 v159, v159
	v_rcp_f32_e32 v160, v160
	v_rcp_f32_e32 v161, v161
	v_rcp_f32_e32 v162, v162
	v_rcp_f32_e32 v163, v163
	v_pk_mul_f32 v[148:149], v[148:149], v[156:157]
	v_pk_mul_f32 v[150:151], v[150:151], v[158:159]
	v_pk_mul_f32 v[152:153], v[152:153], v[160:161]
	v_pk_mul_f32 v[154:155], v[154:155], v[162:163]
	v_pk_mul_f32 v[148:149], v[148:149], v[84:85]
	v_pk_mul_f32 v[150:151], v[150:151], v[144:145]
	v_pk_mul_f32 v[152:153], v[152:153], v[86:87]
	v_pk_mul_f32 v[154:155], v[154:155], v[146:147]
	v_cvt_pk_bf16_f32 v164, v148, v149
	v_cvt_pk_bf16_f32 v165, v150, v151
	v_cvt_pk_bf16_f32 v166, v152, v153
	v_cvt_pk_bf16_f32 v167, v154, v155
	s_add_i32 s17, s16, 0
	s_lshl_b32 s17, s17, 2
	s_add_i32 s17, s17, 3
	s_mul_i32 s17, s17, 0x58000
	s_add_u32 s36, s96, s17
	s_addc_u32 s37, s97, 0
	s_add_u32 s38, s36, 0x1600
	s_addc_u32 s39, s37, 0
	global_store_dwordx2 v2, v[164:165], s[36:37]
	global_store_dwordx2 v2, v[166:167], s[38:39]
	s_waitcnt vmcnt(8)
	s_add_i32 s17, s16, 8
	s_and_b32 s17, s17, 31
	s_cmp_lg_u32 s17, 0
	s_cbranch_scc1 .Lfix0_nz5
	v_mov_b32_e32 v88, 0
	v_mov_b32_e32 v89, 0
	v_mov_b32_e32 v90, 0
	v_mov_b32_e32 v91, 0
; __device__ __forceinline__ unsigned cvt_pk_bf16(float lo, float hi) { unsigned r; asm volatile("v_cvt_pk_bf16_f32 %0, %1, %2" : "=v"(r) : "v"(lo), "v"(hi)); return r; }
; __device__ __forceinline__ float bf_lo(unsigned w) { return __uint_as_float(w << 16); }
; __device__ __forceinline__ float bf_hi(unsigned w) { return __uint_as_float(w & 0xffff0000u); }
; __device__ __forceinline__ float silu_f(float x) { return x * __builtin_amdgcn_rcpf(1.0f + __builtin_amdgcn_exp2f(x * -1.44269504f)); }
; template <int MODE, class Sched> __device__ __forceinline__ void fixup_local(const bf16_t* halo, const float* cw, const float* cb, bf16_t* out, int C, const Sched& S) {
;     ...
;             for (int k = 0; k < 4; ++k) { const int s = 4 * u.pm + k; const bf16_t* hb = halo + (size_t)s * 6 * C + c; const bool first = (s & 127) == 0;
;                 const f32x4 z = (f32x4){0.f, 0.f, 0.f, 0.f};
;                 auto ld4 = [](const bf16_t* ptr) { const u32x2 w = *(const u32x2*)ptr; return (f32x4){bf_lo(w.x), bf_hi(w.x), bf_lo(w.y), bf_hi(w.y)}; };
;                 t0[k] = ld4(first ? hb : hb - (size_t)6 * C); t1[k] = ld4(first ? hb : hb - (size_t)5 * C);
;                 if (first) { t0[k] = z; t1[k] = z; }
;                 h0[k] = ld4(hb + (size_t)2 * C); h1[k] = ld4(hb + (size_t)3 * C);
;                 y0[k] = ld4(hb + (size_t)4 * C); y1[k] = ld4(hb + (size_t)5 * C); }
; #pragma unroll
;             for (int k = 0; k < 4; ++k) { const int s = 4 * u.pm + k; float o0[4], o1[4];
; #pragma unroll
;                 for (int j = 0; j < 4; ++j) {
;                     const float cv0 = w2[j] * h0[k][j] + w1[j] * t1[k][j] + w0[j] * t0[k][j] + bb[j];
;                     const float cv1 = w2[j] * h1[k][j] + w1[j] * h0[k][j] + w0[j] * t1[k][j] + bb[j];
;                     o0[j] = MODE == 0 ? silu_f(cv0) * y0[k][j] : cv0 * y0[k][j]; o1[j] = MODE == 0 ? silu_f(cv1) * y1[k][j] : cv1 * y1[k][j]; }
;                 u32x2 a; a.x = cvt_pk_bf16(o0[0], o0[1]); a.y = cvt_pk_bf16(o0[2], o0[3]); u32x2 b; b.x = cvt_pk_bf16(o1[0], o1[1]); b.y = cvt_pk_bf16(o1[2], o1[3]);
;                 *(u32x2*)(out + ((size_t)s * 64) * C + c) = a; *(u32x2*)(out + ((size_t)s * 64 + 1) * C + c) = b; }
.Lfix0_nz5:
	v_lshlrev_b32_e32 v136, 16, v89
	v_and_b32_e32 v137, 0xffff0000, v89
	v_and_b32_e32 v89, 0xffff0000, v88
	v_lshlrev_b32_e32 v88, 16, v88
	v_lshlrev_b32_e32 v138, 16, v91
	v_and_b32_e32 v139, 0xffff0000, v91
	v_and_b32_e32 v91, 0xffff0000, v90
	v_lshlrev_b32_e32 v90, 16, v90
	v_lshlrev_b32_e32 v140, 16, v93
	v_and_b32_e32 v141, 0xffff0000, v93
	v_and_b32_e32 v93, 0xffff0000, v92
	v_lshlrev_b32_e32 v92, 16, v92
	v_lshlrev_b32_e32 v142, 16, v95
	v_and_b32_e32 v143, 0xffff0000, v95
	v_and_b32_e32 v95, 0xffff0000, v94
	v_lshlrev_b32_e32 v94, 16, v94
	v_lshlrev_b32_e32 v144, 16, v97
	v_and_b32_e32 v145, 0xffff0000, v97
	v_and_b32_e32 v97, 0xffff0000, v96
	v_lshlrev_b32_e32 v96, 16, v96
	v_lshlrev_b32_e32 v146, 16, v99
	v_and_b32_e32 v147, 0xffff0000, v99
	v_and_b32_e32 v99, 0xffff0000, v98
	v_lshlrev_b32_e32 v98, 16, v98
	v_pk_mul_f32 v[148:149], v[32:33], v[92:93]
	v_pk_mul_f32 v[150:151], v[34:35], v[140:141]
	v_pk_mul_f32 v[152:153], v[32:33], v[94:95]
	v_pk_mul_f32 v[154:155], v[34:35], v[142:143]
	v_pk_fma_f32 v[148:149], v[28:29], v[90:91], v[148:149]
	v_pk_fma_f32 v[150:151], v[30:31], v[138:139], v[150:151]
	v_pk_fma_f32 v[152:153], v[28:29], v[92:93], v[152:153]
	v_pk_fma_f32 v[154:155], v[30:31], v[140:141], v[154:155]
	v_pk_fma_f32 v[148:149], v[24:25], v[88:89], v[148:149]
	v_pk_fma_f32 v[150:151], v[26:27], v[136:137], v[150:151]
	v_pk_fma_f32 v[152:153], v[24:25], v[90:91], v[152:153]
	v_pk_fma_f32 v[154:155], v[26:27], v[138:139], v[154:155]
	v_pk_add_f32 v[148:149], v[148:149], v[36:37]
	v_pk_add_f32 v[150:151], v[150:151], v[38:39]
	v_pk_add_f32 v[152:153], v[152:153], v[36:37]
	v_pk_add_f32 v[154:155], v[154:155], v[38:39]
	v_pk_mul_f32 v[156:157], v[148:149], s[12:13] op_sel_hi:[1,0]
	v_pk_mul_f32 v[158:159], v[150:151], s[12:13] op_sel_hi:[1,0]
	v_pk_mul_f32 v[160:161], v[152:153], s[12:13] op_sel_hi:[1,0]
	v_pk_mul_f32 v[162:163], v[154:155], s[12:13] op_sel_hi:[1,0]
	v_exp_f32_e32 v156, v156
	v_exp_f32_e32 v157, v157
	v_exp_f32_e32 v158, v158
	v_exp_f32_e32 v159, v159
	v_exp_f32_e32 v160, v160
	v_exp_f32_e32 v161, v161
	v_exp_f32_e32 v162, v162
	v_exp_f32_e32 v163, v163
	v_pk_add_f32 v[156:157], v[156:157], s[12:13] op_sel:[0,1]
	v_pk_add_f32 v[158:159], v[158:159], s[12:13] op_sel:[0,1]
	v_pk_add_f32 v[160:161], v[160:161], s[12:13] op_sel:[0,1]
	v_pk_add_f32 v[162:163], v[162:163], s[12:13] op_sel:[0,1]
	v_rcp_f32_e32 v156, v156
	v_rcp_f32_e32 v157, v157
	v_rcp_f32_e32 v158, v158
	v_rcp_f32_e32 v159, v159
	v_rcp_f32_e32 v160, v160
	v_rcp_f32_e32 v161, v161
	v_rcp_f32_e32 v162, v162
	v_rcp_f32_e32 v163, v163
	v_pk_mul_f32 v[148:149], v[148:149], v[156:157]
	v_pk_mul_f32 v[150:151], v[150:151], v[158:159]
	v_pk_mul_f32 v[152:153], v[152:153], v[160:161]
	v_pk_mul_f32 v[154:155], v[154:155], v[162:163]
	v_pk_mul_f32 v[148:149], v[148:149], v[96:97]
	v_pk_mul_f32 v[150:151], v[150:151], v[144:145]
	v_pk_mul_f32 v[152:153], v[152:153], v[98:99]
	v_pk_mul_f32 v[154:155], v[154:155], v[146:147]
	v_cvt_pk_bf16_f32 v164, v148, v149
	v_cvt_pk_bf16_f32 v165, v150, v151
	v_cvt_pk_bf16_f32 v166, v152, v153
	v_cvt_pk_bf16_f32 v167, v154, v155
	s_add_i32 s17, s16, 8
	s_lshl_b32 s17, s17, 2
	s_mul_i32 s17, s17, 0x58000
	s_add_u32 s36, s96, s17
	s_addc_u32 s37, s97, 0
	s_add_u32 s38, s36, 0x1600
	s_addc_u32 s39, s37, 0
	global_store_dwordx2 v2, v[164:165], s[36:37]
	global_store_dwordx2 v2, v[166:167], s[38:39]
	v_lshlrev_b32_e32 v136, 16, v101
	v_and_b32_e32 v137, 0xffff0000, v101
	v_and_b32_e32 v101, 0xffff0000, v100
	v_lshlrev_b32_e32 v100, 16, v100
	v_lshlrev_b32_e32 v138, 16, v103
	v_and_b32_e32 v139, 0xffff0000, v103
	v_and_b32_e32 v103, 0xffff0000, v102
	v_lshlrev_b32_e32 v102, 16, v102
	v_lshlrev_b32_e32 v140, 16, v105
	v_and_b32_e32 v141, 0xffff0000, v105
	v_and_b32_e32 v105, 0xffff0000, v104
	v_lshlrev_b32_e32 v104, 16, v104
	v_lshlrev_b32_e32 v142, 16, v107
	v_and_b32_e32 v143, 0xffff0000, v107
	v_and_b32_e32 v107, 0xffff0000, v106
	v_lshlrev_b32_e32 v106, 16, v106
	v_lshlrev_b32_e32 v144, 16, v109
	v_and_b32_e32 v145, 0xffff0000, v109
	v_and_b32_e32 v109, 0xffff0000, v108
	v_lshlrev_b32_e32 v108, 16, v108
	v_lshlrev_b32_e32 v146, 16, v111
	v_and_b32_e32 v147, 0xffff0000, v111
	v_and_b32_e32 v111, 0xffff0000, v110
	v_lshlrev_b32_e32 v110, 16, v110
	v_pk_mul_f32 v[148:149], v[32:33], v[104:105]
	v_pk_mul_f32 v[150:151], v[34:35], v[140:141]
	v_pk_mul_f32 v[152:153], v[32:33], v[106:107]
	v_pk_mul_f32 v[154:155], v[34:35], v[142:143]
	v_pk_fma_f32 v[148:149], v[28:29], v[102:103], v[148:149]
	v_pk_fma_f32 v[150:151], v[30:31], v[138:139], v[150:151]
	v_pk_fma_f32 v[152:153], v[28:29], v[104:105], v[152:153]
	v_pk_fma_f32 v[154:155], v[30:31], v[140:141], v[154:155]
	v_pk_fma_f32 v[148:149], v[24:25], v[100:101], v[148:149]
	v_pk_fma_f32 v[150:151], v[26:27], v[136:137], v[150:151]
	v_pk_fma_f32 v[152:153], v[24:25], v[102:103], v[152:153]
	v_pk_fma_f32 v[154:155], v[26:27], v[138:139], v[154:155]
	v_pk_add_f32 v[148:149], v[148:149], v[36:37]
	v_pk_add_f32 v[150:151], v[150:151], v[38:39]
	v_pk_add_f32 v[152:153], v[152:153], v[36:37]
	v_pk_add_f32 v[154:155], v[154:155], v[38:39]
	v_pk_mul_f32 v[156:157], v[148:149], s[12:13] op_sel_hi:[1,0]
	v_pk_mul_f32 v[158:159], v[150:151], s[12:13] op_sel_hi:[1,0]
	v_pk_mul_f32 v[160:161], v[152:153], s[12:13] op_sel_hi:[1,0]
	v_pk_mul_f32 v[162:163], v[154:155], s[12:13] op_sel_hi:[1,0]
	v_exp_f32_e32 v156, v156
	v_exp_f32_e32 v157, v157
	v_exp_f32_e32 v158, v158
	v_exp_f32_e32 v159, v159
	v_exp_f32_e32 v160, v160
	v_exp_f32_e32 v161, v161
	v_exp_f32_e32 v162, v162
	v_exp_f32_e32 v163, v163
	v_pk_add_f32 v[156:157], v[156:157], s[12:13] op_sel:[0,1]
; __device__ __forceinline__ unsigned cvt_pk_bf16(float lo, float hi) { unsigned r; asm volatile("v_cvt_pk_bf16_f32 %0, %1, %2" : "=v"(r) : "v"(lo), "v"(hi)); return r; }
; __device__ __forceinline__ float bf_lo(unsigned w) { return __uint_as_float(w << 16); }
; __device__ __forceinline__ float bf_hi(unsigned w) { return __uint_as_float(w & 0xffff0000u); }
; __device__ __forceinline__ float silu_f(float x) { return x * __builtin_amdgcn_rcpf(1.0f + __builtin_amdgcn_exp2f(x * -1.44269504f)); }
; template <int MODE, class Sched> __device__ __forceinline__ void fixup_local(const bf16_t* halo, const float* cw, const float* cb, bf16_t* out, int C, const Sched& S) {
;     ...
;             for (int k = 0; k < 4; ++k) { const int s = 4 * u.pm + k; const bf16_t* hb = halo + (size_t)s * 6 * C + c; const bool first = (s & 127) == 0;
;                 const f32x4 z = (f32x4){0.f, 0.f, 0.f, 0.f};
;                 auto ld4 = [](const bf16_t* ptr) { const u32x2 w = *(const u32x2*)ptr; return (f32x4){bf_lo(w.x), bf_hi(w.x), bf_lo(w.y), bf_hi(w.y)}; };
;                 t0[k] = ld4(first ? hb : hb - (size_t)6 * C); t1[k] = ld4(first ? hb : hb - (size_t)5 * C);
;                 if (first) { t0[k] = z; t1[k] = z; }
;                 h0[k] = ld4(hb + (size_t)2 * C); h1[k] = ld4(hb + (size_t)3 * C);
;                 y0[k] = ld4(hb + (size_t)4 * C); y1[k] = ld4(hb + (size_t)5 * C); }
; #pragma unroll
;             for (int k = 0; k < 4; ++k) { const int s = 4 * u.pm + k; float o0[4], o1[4];
; #pragma unroll
;                 for (int j = 0; j < 4; ++j) {
;                     const float cv0 = w2[j] * h0[k][j] + w1[j] * t1[k][j] + w0[j] * t0[k][j] + bb[j];
;                     const float cv1 = w2[j] * h1[k][j] + w1[j] * h0[k][j] + w0[j] * t1[k][j] + bb[j];
;                     o0[j] = MODE == 0 ? silu_f(cv0) * y0[k][j] : cv0 * y0[k][j]; o1[j] = MODE == 0 ? silu_f(cv1) * y1[k][j] : cv1 * y1[k][j]; }
;                 u32x2 a; a.x = cvt_pk_bf16(o0[0], o0[1]); a.y = cvt_pk_bf16(o0[2], o0[3]); u32x2 b; b.x = cvt_pk_bf16(o1[0], o1[1]); b.y = cvt_pk_bf16(o1[2], o1[3]);
;                 *(u32x2*)(out + ((size_t)s * 64) * C + c) = a; *(u32x2*)(out + ((size_t)s * 64 + 1) * C + c) = b; }
	v_pk_add_f32 v[158:159], v[158:159], s[12:13] op_sel:[0,1]
	v_pk_add_f32 v[160:161], v[160:161], s[12:13] op_sel:[0,1]
	v_pk_add_f32 v[162:163], v[162:163], s[12:13] op_sel:[0,1]
	v_rcp_f32_e32 v156, v156
	v_rcp_f32_e32 v157, v157
	v_rcp_f32_e32 v158, v158
	v_rcp_f32_e32 v159, v159
	v_rcp_f32_e32 v160, v160
	v_rcp_f32_e32 v161, v161
	v_rcp_f32_e32 v162, v162
	v_rcp_f32_e32 v163, v163
	v_pk_mul_f32 v[148:149], v[148:149], v[156:157]
	v_pk_mul_f32 v[150:151], v[150:151], v[158:159]
	v_pk_mul_f32 v[152:153], v[152:153], v[160:161]
	v_pk_mul_f32 v[154:155], v[154:155], v[162:163]
	v_pk_mul_f32 v[148:149], v[148:149], v[108:109]
	v_pk_mul_f32 v[150:151], v[150:151], v[144:145]
	v_pk_mul_f32 v[152:153], v[152:153], v[110:111]
	v_pk_mul_f32 v[154:155], v[154:155], v[146:147]
	v_cvt_pk_bf16_f32 v164, v148, v149
	v_cvt_pk_bf16_f32 v165, v150, v151
	v_cvt_pk_bf16_f32 v166, v152, v153
	v_cvt_pk_bf16_f32 v167, v154, v155
	s_add_i32 s17, s16, 8
	s_lshl_b32 s17, s17, 2
	s_add_i32 s17, s17, 1
	s_mul_i32 s17, s17, 0x58000
	s_add_u32 s36, s96, s17
	s_addc_u32 s37, s97, 0
	s_add_u32 s38, s36, 0x1600
	s_addc_u32 s39, s37, 0
	global_store_dwordx2 v2, v[164:165], s[36:37]
	global_store_dwordx2 v2, v[166:167], s[38:39]
	v_lshlrev_b32_e32 v136, 16, v113
	v_and_b32_e32 v137, 0xffff0000, v113
	v_and_b32_e32 v113, 0xffff0000, v112
	v_lshlrev_b32_e32 v112, 16, v112
	v_lshlrev_b32_e32 v138, 16, v115
	v_and_b32_e32 v139, 0xffff0000, v115
	v_and_b32_e32 v115, 0xffff0000, v114
	v_lshlrev_b32_e32 v114, 16, v114
	v_lshlrev_b32_e32 v140, 16, v117
	v_and_b32_e32 v141, 0xffff0000, v117
	v_and_b32_e32 v117, 0xffff0000, v116
	v_lshlrev_b32_e32 v116, 16, v116
	v_lshlrev_b32_e32 v142, 16, v119
	v_and_b32_e32 v143, 0xffff0000, v119
	v_and_b32_e32 v119, 0xffff0000, v118
	v_lshlrev_b32_e32 v118, 16, v118
	v_lshlrev_b32_e32 v144, 16, v121
	v_and_b32_e32 v145, 0xffff0000, v121
	v_and_b32_e32 v121, 0xffff0000, v120
	v_lshlrev_b32_e32 v120, 16, v120
	v_lshlrev_b32_e32 v146, 16, v123
	v_and_b32_e32 v147, 0xffff0000, v123
	v_and_b32_e32 v123, 0xffff0000, v122
	v_lshlrev_b32_e32 v122, 16, v122
	v_pk_mul_f32 v[148:149], v[32:33], v[116:117]
	v_pk_mul_f32 v[150:151], v[34:35], v[140:141]
	v_pk_mul_f32 v[152:153], v[32:33], v[118:119]
	v_pk_mul_f32 v[154:155], v[34:35], v[142:143]
	v_pk_fma_f32 v[148:149], v[28:29], v[114:115], v[148:149]
	v_pk_fma_f32 v[150:151], v[30:31], v[138:139], v[150:151]
	v_pk_fma_f32 v[152:153], v[28:29], v[116:117], v[152:153]
	v_pk_fma_f32 v[154:155], v[30:31], v[140:141], v[154:155]
	v_pk_fma_f32 v[148:149], v[24:25], v[112:113], v[148:149]
	v_pk_fma_f32 v[150:151], v[26:27], v[136:137], v[150:151]
	v_pk_fma_f32 v[152:153], v[24:25], v[114:115], v[152:153]
	v_pk_fma_f32 v[154:155], v[26:27], v[138:139], v[154:155]
	v_pk_add_f32 v[148:149], v[148:149], v[36:37]
	v_pk_add_f32 v[150:151], v[150:151], v[38:39]
	v_pk_add_f32 v[152:153], v[152:153], v[36:37]
	v_pk_add_f32 v[154:155], v[154:155], v[38:39]
	v_pk_mul_f32 v[156:157], v[148:149], s[12:13] op_sel_hi:[1,0]
	v_pk_mul_f32 v[158:159], v[150:151], s[12:13] op_sel_hi:[1,0]
	v_pk_mul_f32 v[160:161], v[152:153], s[12:13] op_sel_hi:[1,0]
	v_pk_mul_f32 v[162:163], v[154:155], s[12:13] op_sel_hi:[1,0]
	v_exp_f32_e32 v156, v156
	v_exp_f32_e32 v157, v157
	v_exp_f32_e32 v158, v158
	v_exp_f32_e32 v159, v159
	v_exp_f32_e32 v160, v160
	v_exp_f32_e32 v161, v161
	v_exp_f32_e32 v162, v162
	v_exp_f32_e32 v163, v163
	v_pk_add_f32 v[156:157], v[156:157], s[12:13] op_sel:[0,1]
	v_pk_add_f32 v[158:159], v[158:159], s[12:13] op_sel:[0,1]
	v_pk_add_f32 v[160:161], v[160:161], s[12:13] op_sel:[0,1]
	v_pk_add_f32 v[162:163], v[162:163], s[12:13] op_sel:[0,1]
	v_rcp_f32_e32 v156, v156
	v_rcp_f32_e32 v157, v157
	v_rcp_f32_e32 v158, v158
	v_rcp_f32_e32 v159, v159
	v_rcp_f32_e32 v160, v160
	v_rcp_f32_e32 v161, v161
	v_rcp_f32_e32 v162, v162
	v_rcp_f32_e32 v163, v163
	v_pk_mul_f32 v[148:149], v[148:149], v[156:157]
	v_pk_mul_f32 v[150:151], v[150:151], v[158:159]
	v_pk_mul_f32 v[152:153], v[152:153], v[160:161]
	v_pk_mul_f32 v[154:155], v[154:155], v[162:163]
	v_pk_mul_f32 v[148:149], v[148:149], v[120:121]
; __device__ __forceinline__ unsigned cvt_pk_bf16(float lo, float hi) { unsigned r; asm volatile("v_cvt_pk_bf16_f32 %0, %1, %2" : "=v"(r) : "v"(lo), "v"(hi)); return r; }
; __device__ __forceinline__ float bf_lo(unsigned w) { return __uint_as_float(w << 16); }
; __device__ __forceinline__ float bf_hi(unsigned w) { return __uint_as_float(w & 0xffff0000u); }
; __device__ __forceinline__ float silu_f(float x) { return x * __builtin_amdgcn_rcpf(1.0f + __builtin_amdgcn_exp2f(x * -1.44269504f)); }
; template <int MODE, class Sched> __device__ __forceinline__ void fixup_local(const bf16_t* halo, const float* cw, const float* cb, bf16_t* out, int C, const Sched& S) {
;     ...
;             for (int k = 0; k < 4; ++k) { const int s = 4 * u.pm + k; const bf16_t* hb = halo + (size_t)s * 6 * C + c; const bool first = (s & 127) == 0;
;                 const f32x4 z = (f32x4){0.f, 0.f, 0.f, 0.f};
;                 auto ld4 = [](const bf16_t* ptr) { const u32x2 w = *(const u32x2*)ptr; return (f32x4){bf_lo(w.x), bf_hi(w.x), bf_lo(w.y), bf_hi(w.y)}; };
;                 t0[k] = ld4(first ? hb : hb - (size_t)6 * C); t1[k] = ld4(first ? hb : hb - (size_t)5 * C);
;                 if (first) { t0[k] = z; t1[k] = z; }
;                 h0[k] = ld4(hb + (size_t)2 * C); h1[k] = ld4(hb + (size_t)3 * C);
;                 y0[k] = ld4(hb + (size_t)4 * C); y1[k] = ld4(hb + (size_t)5 * C); }
; #pragma unroll
;             for (int k = 0; k < 4; ++k) { const int s = 4 * u.pm + k; float o0[4], o1[4];
; #pragma unroll
;                 for (int j = 0; j < 4; ++j) {
;                     const float cv0 = w2[j] * h0[k][j] + w1[j] * t1[k][j] + w0[j] * t0[k][j] + bb[j];
;                     const float cv1 = w2[j] * h1[k][j] + w1[j] * h0[k][j] + w0[j] * t1[k][j] + bb[j];
;                     o0[j] = MODE == 0 ? silu_f(cv0) * y0[k][j] : cv0 * y0[k][j]; o1[j] = MODE == 0 ? silu_f(cv1) * y1[k][j] : cv1 * y1[k][j]; }
;                 u32x2 a; a.x = cvt_pk_bf16(o0[0], o0[1]); a.y = cvt_pk_bf16(o0[2], o0[3]); u32x2 b; b.x = cvt_pk_bf16(o1[0], o1[1]); b.y = cvt_pk_bf16(o1[2], o1[3]);
;                 *(u32x2*)(out + ((size_t)s * 64) * C + c) = a; *(u32x2*)(out + ((size_t)s * 64 + 1) * C + c) = b; }
;         }
;     asm volatile("s_waitcnt vmcnt(0)" ::: "memory");
;     __syncthreads();
; }
	v_pk_mul_f32 v[150:151], v[150:151], v[144:145]
	v_pk_mul_f32 v[152:153], v[152:153], v[122:123]
	v_pk_mul_f32 v[154:155], v[154:155], v[146:147]
	v_cvt_pk_bf16_f32 v164, v148, v149
	v_cvt_pk_bf16_f32 v165, v150, v151
	v_cvt_pk_bf16_f32 v166, v152, v153
	v_cvt_pk_bf16_f32 v167, v154, v155
	s_add_i32 s17, s16, 8
	s_lshl_b32 s17, s17, 2
	s_add_i32 s17, s17, 2
	s_mul_i32 s17, s17, 0x58000
	s_add_u32 s36, s96, s17
	s_addc_u32 s37, s97, 0
	s_add_u32 s38, s36, 0x1600
	s_addc_u32 s39, s37, 0
	global_store_dwordx2 v2, v[164:165], s[36:37]
	global_store_dwordx2 v2, v[166:167], s[38:39]
	v_lshlrev_b32_e32 v136, 16, v125
	v_and_b32_e32 v137, 0xffff0000, v125
	v_and_b32_e32 v125, 0xffff0000, v124
	v_lshlrev_b32_e32 v124, 16, v124
	v_lshlrev_b32_e32 v138, 16, v127
	v_and_b32_e32 v139, 0xffff0000, v127
	v_and_b32_e32 v127, 0xffff0000, v126
	v_lshlrev_b32_e32 v126, 16, v126
	v_lshlrev_b32_e32 v140, 16, v129
	v_and_b32_e32 v141, 0xffff0000, v129
	v_and_b32_e32 v129, 0xffff0000, v128
	v_lshlrev_b32_e32 v128, 16, v128
	v_lshlrev_b32_e32 v142, 16, v131
	v_and_b32_e32 v143, 0xffff0000, v131
	v_and_b32_e32 v131, 0xffff0000, v130
	v_lshlrev_b32_e32 v130, 16, v130
	v_lshlrev_b32_e32 v144, 16, v133
	v_and_b32_e32 v145, 0xffff0000, v133
	v_and_b32_e32 v133, 0xffff0000, v132
	v_lshlrev_b32_e32 v132, 16, v132
	v_lshlrev_b32_e32 v146, 16, v135
	v_and_b32_e32 v147, 0xffff0000, v135
	v_and_b32_e32 v135, 0xffff0000, v134
	v_lshlrev_b32_e32 v134, 16, v134
	v_pk_mul_f32 v[148:149], v[32:33], v[128:129]
	v_pk_mul_f32 v[150:151], v[34:35], v[140:141]
	v_pk_mul_f32 v[152:153], v[32:33], v[130:131]
	v_pk_mul_f32 v[154:155], v[34:35], v[142:143]
	v_pk_fma_f32 v[148:149], v[28:29], v[126:127], v[148:149]
	v_pk_fma_f32 v[150:151], v[30:31], v[138:139], v[150:151]
	v_pk_fma_f32 v[152:153], v[28:29], v[128:129], v[152:153]
	v_pk_fma_f32 v[154:155], v[30:31], v[140:141], v[154:155]
	v_pk_fma_f32 v[148:149], v[24:25], v[124:125], v[148:149]
	v_pk_fma_f32 v[150:151], v[26:27], v[136:137], v[150:151]
	v_pk_fma_f32 v[152:153], v[24:25], v[126:127], v[152:153]
	v_pk_fma_f32 v[154:155], v[26:27], v[138:139], v[154:155]
	v_pk_add_f32 v[148:149], v[148:149], v[36:37]
	v_pk_add_f32 v[150:151], v[150:151], v[38:39]
	v_pk_add_f32 v[152:153], v[152:153], v[36:37]
	v_pk_add_f32 v[154:155], v[154:155], v[38:39]
	v_pk_mul_f32 v[156:157], v[148:149], s[12:13] op_sel_hi:[1,0]
	v_pk_mul_f32 v[158:159], v[150:151], s[12:13] op_sel_hi:[1,0]
	v_pk_mul_f32 v[160:161], v[152:153], s[12:13] op_sel_hi:[1,0]
	v_pk_mul_f32 v[162:163], v[154:155], s[12:13] op_sel_hi:[1,0]
	v_exp_f32_e32 v156, v156
	v_exp_f32_e32 v157, v157
	v_exp_f32_e32 v158, v158
	v_exp_f32_e32 v159, v159
	v_exp_f32_e32 v160, v160
	v_exp_f32_e32 v161, v161
	v_exp_f32_e32 v162, v162
	v_exp_f32_e32 v163, v163
	v_pk_add_f32 v[156:157], v[156:157], s[12:13] op_sel:[0,1]
	v_pk_add_f32 v[158:159], v[158:159], s[12:13] op_sel:[0,1]
	v_pk_add_f32 v[160:161], v[160:161], s[12:13] op_sel:[0,1]
	v_pk_add_f32 v[162:163], v[162:163], s[12:13] op_sel:[0,1]
	v_rcp_f32_e32 v156, v156
	v_rcp_f32_e32 v157, v157
	v_rcp_f32_e32 v158, v158
	v_rcp_f32_e32 v159, v159
	v_rcp_f32_e32 v160, v160
	v_rcp_f32_e32 v161, v161
	v_rcp_f32_e32 v162, v162
	v_rcp_f32_e32 v163, v163
	v_pk_mul_f32 v[148:149], v[148:149], v[156:157]
	v_pk_mul_f32 v[150:151], v[150:151], v[158:159]
	v_pk_mul_f32 v[152:153], v[152:153], v[160:161]
	v_pk_mul_f32 v[154:155], v[154:155], v[162:163]
	v_pk_mul_f32 v[148:149], v[148:149], v[132:133]
	v_pk_mul_f32 v[150:151], v[150:151], v[144:145]
	v_pk_mul_f32 v[152:153], v[152:153], v[134:135]
	v_pk_mul_f32 v[154:155], v[154:155], v[146:147]
	v_cvt_pk_bf16_f32 v164, v148, v149
	v_cvt_pk_bf16_f32 v165, v150, v151
	v_cvt_pk_bf16_f32 v166, v152, v153
	v_cvt_pk_bf16_f32 v167, v154, v155
	s_add_i32 s17, s16, 8
	s_lshl_b32 s17, s17, 2
	s_add_i32 s17, s17, 3
	s_mul_i32 s17, s17, 0x58000
	s_add_u32 s36, s96, s17
	s_addc_u32 s37, s97, 0
	s_add_u32 s38, s36, 0x1600
	s_addc_u32 s39, s37, 0
	global_store_dwordx2 v2, v[164:165], s[36:37]
	global_store_dwordx2 v2, v[166:167], s[38:39]
.Lfix0_end1:
	s_mov_b64 exec, s[10:11]
	s_branch .LBB0_749
.Lfix0_generic:
	s_branch .LBB0_741

;     __device__ __forceinline__ void operator()(const Acc& acc, const Unit& u, int wr, int wc, int fr, int fq, LAS unsigned char* lds, f32x4 epar) const {
;     ...
;         LAS float* pw = (LAS float*)(lds + STAGE_BYTES + 64 + (wr * 4 + wc) * 1024);
;         *(LAS f32x4*)(pw + (fq * 16 + fr) * 4) = epar;
;         asm volatile("s_waitcnt lgkmcnt(0)" ::: "memory");
;         float w0[NV], w1[NV], w2[NV], bb[NV];
; #pragma unroll
;         for (int i = 0; i < NV; i += 4) { const f32x4 a = *(const LAS f32x4*)(pw + NV * fq + i), b = *(const LAS f32x4*)(pw + 32 + NV * fq + i), c = *(const LAS f32x4*)(pw + 64 + NV * fq + i);
;             f32x4 d = (f32x4){0.f, 0.f, 0.f, 0.f}; if (MODE == 0) d = *(const LAS f32x4*)(pw + 96 + NV * fq + i);
; #pragma unroll
;             for (int j = 0; j < 4; ++j) { w0[i + j] = a[j]; w1[i + j] = b[j]; w2[i + j] = c[j]; bb[i + j] = d[j]; } }
;         float sq[2][4];
; #pragma unroll
;         for (int ai = 0; ai < 2; ++ai)
; #pragma unroll
;             for (int m = 0; m < 4; ++m) sq[ai][m] = pw[128 + ai * 64 + m * 16 + fr];
; #pragma unroll
;         for (int ai = 0; ai < 2; ++ai) {
;             const int strip = u.pm * 4 + ai * 2 + wr;
;             float p1prev[NV], p2prev[NV];
; #pragma unroll
;             for (int i = 0; i < NV; ++i) { p1prev[i] = 0.f; p2prev[i] = 0.f; }
; #pragma unroll
;             for (int m = 0; m < 4; ++m) {
;                 const int r = u.pm * BM + ai * HALF + wr * 64 + m * 16 + fr;
;                 const float rs = __builtin_amdgcn_rsqf(sq[ai][m] * (1.0f / DM) + RMS_EPS);
;                 float X[NV], Y[NV], o[NV];
;                 if (MODE == 0) {
; #pragma unroll
;                     for (int n = 0; n < 2; ++n)
; #pragma unroll
;                         for (int j = 0; j < 4; ++j) { X[n * 4 + j] = acc[ai][0][m][n][j] * rs; Y[n * 4 + j] = acc[ai][1][m][n][j] * rs; }
;                 } else {
; #pragma unroll
;                     for (int j = 0; j < 4; ++j) { X[j] = (acc[ai][0][m][1][j] * rs) * (acc[ai][1][m][0][j] * rs); Y[j] = acc[ai][0][m][0][j] * rs; }
;                 }
; #pragma unroll
;                 for (int i = 0; i < NV; ++i) {
;                     const float a1 = dpp_rot<0x121>(X[i]), a2 = dpp_rot<0x122>(X[i]);
;                     const float q1 = fr >= 1 ? a1 : p1prev[i], q2 = fr >= 2 ? a2 : p2prev[i];
;                     p1prev[i] = a1; p2prev[i] = a2;
.LBB0_846:
	ds_write_b128 v146, v[24:27]
	s_mov_b64 s[24:25], exec
	s_waitcnt lgkmcnt(0)
	ds_read_b128 v[186:189], v147
	ds_read_b128 v[190:193], v147 offset:128
	ds_read_b128 v[194:197], v147 offset:256
	ds_read2_b32 v[198:199], v139 offset0:128 offset1:144
	ds_read2_b32 v[200:201], v139 offset0:160 offset1:176
	ds_read2_b32 v[202:203], v139 offset0:192 offset1:208
	ds_read2_b32 v[204:205], v139 offset0:224 offset1:240
	v_lshl_add_u32 v206, s70, 8, v138
	v_lshl_or_b32 v207, s72, 6, v140
	v_lshlrev_b32_e32 v206, 11, v206
	s_lshl_b32 s22, s70, 2
	s_add_i32 s22, s22, s15
	s_mul_i32 s16, s22, 6
	v_and_b32_e32 v208, 15, v138
	v_lshl_add_u32 v206, v207, 1, v206
	v_add_u32_e32 v208, s16, v208
	v_lshlrev_b32_e32 v208, 11, v208
	s_nop 0
	v_lshl_add_u32 v208, v207, 1, v208
	s_waitcnt lgkmcnt(0)
	v_fmamk_f32 v198, v198, 0x3a800000, v148
	v_fmamk_f32 v199, v199, 0x3a800000, v148
	v_fmamk_f32 v200, v200, 0x3a800000, v148
	v_fmamk_f32 v201, v201, 0x3a800000, v148
	v_fmamk_f32 v202, v202, 0x3a800000, v148
	v_fmamk_f32 v203, v203, 0x3a800000, v148
	v_fmamk_f32 v204, v204, 0x3a800000, v148
	v_fmamk_f32 v205, v205, 0x3a800000, v148
	v_rsq_f32_e32 v198, v198
	v_rsq_f32_e32 v199, v199
	v_rsq_f32_e32 v200, v200
	v_rsq_f32_e32 v201, v201
	v_rsq_f32_e32 v202, v202
	v_rsq_f32_e32 v203, v203
	v_rsq_f32_e32 v204, v204
	v_rsq_f32_e32 v205, v205
	s_nop 0
	v_pk_mul_f32 v[96:97], v[96:97], v[198:199] op_sel_hi:[1,0]
	v_pk_mul_f32 v[98:99], v[98:99], v[198:199] op_sel_hi:[1,0]
	v_pk_mul_f32 v[92:93], v[92:93], v[198:199] op_sel_hi:[1,0]
	v_pk_mul_f32 v[94:95], v[94:95], v[198:199] op_sel_hi:[1,0]
	v_pk_mul_f32 v[88:89], v[88:89], v[198:199] op_sel_hi:[1,0]
	v_pk_mul_f32 v[90:91], v[90:91], v[198:199] op_sel_hi:[1,0]
	v_pk_mul_f32 v[96:97], v[96:97], v[92:93]
	v_pk_mul_f32 v[98:99], v[98:99], v[94:95]
	v_mul_f32_e32 v209, v96, v194
	v_mul_f32_e32 v210, v97, v195
	v_mul_f32_e32 v211, v98, v196
	v_mul_f32_e32 v212, v99, v197
	v_cvt_pk_bf16_f32 v218, v96, v97
	v_cvt_pk_bf16_f32 v219, v98, v99
	v_cvt_pk_bf16_f32 v220, v88, v89
	v_cvt_pk_bf16_f32 v221, v90, v91
	v_add_u32_e32 v216, 0x1000, v208
	v_add_u32_e32 v217, 0x2000, v208
	s_andn2_b64 exec, exec, s[8:9]
	global_store_dwordx2 v216, v[218:219], s[42:43]
	global_store_dwordx2 v217, v[220:221], s[42:43]
	s_mov_b64 exec, s[24:25]
	v_fmac_f32_dpp v209, v96, v190 row_shr:1 row_mask:0xf bank_mask:0xf
	v_fmac_f32_dpp v210, v97, v191 row_shr:1 row_mask:0xf bank_mask:0xf
	v_fmac_f32_dpp v211, v98, v192 row_shr:1 row_mask:0xf bank_mask:0xf
	v_fmac_f32_dpp v212, v99, v193 row_shr:1 row_mask:0xf bank_mask:0xf
	v_fmac_f32_dpp v209, v96, v186 row_shr:2 row_mask:0xf bank_mask:0xf
	v_fmac_f32_dpp v210, v97, v187 row_shr:2 row_mask:0xf bank_mask:0xf
	v_fmac_f32_dpp v211, v98, v188 row_shr:2 row_mask:0xf bank_mask:0xf
	v_fmac_f32_dpp v212, v99, v189 row_shr:2 row_mask:0xf bank_mask:0xf
	v_mul_f32_e32 v88, v209, v88
	v_mul_f32_e32 v89, v210, v89
	v_mul_f32_e32 v90, v211, v90
	v_mul_f32_e32 v91, v212, v91
	v_cvt_pk_bf16_f32 v214, v88, v89
	v_cvt_pk_bf16_f32 v215, v90, v91
	v_add_u32_e32 v216, 0x0, v206
	s_and_b64 exec, exec, s[8:9]
	global_store_dwordx2 v216, v[214:215], s[40:41] nt
	s_mov_b64 exec, s[24:25]
	v_pk_mul_f32 v[84:85], v[84:85], v[198:199] op_sel:[0,1]
	v_pk_mul_f32 v[86:87], v[86:87], v[198:199] op_sel:[0,1]
	v_pk_mul_f32 v[80:81], v[80:81], v[198:199] op_sel:[0,1]
	v_pk_mul_f32 v[82:83], v[82:83], v[198:199] op_sel:[0,1]
	v_pk_mul_f32 v[76:77], v[76:77], v[198:199] op_sel:[0,1]
	v_pk_mul_f32 v[78:79], v[78:79], v[198:199] op_sel:[0,1]
	v_pk_mul_f32 v[84:85], v[84:85], v[80:81]
	v_pk_mul_f32 v[86:87], v[86:87], v[82:83]
	v_mul_f32_e32 v209, v84, v194
	v_mul_f32_e32 v210, v85, v195
	v_mul_f32_e32 v211, v86, v196
	v_mul_f32_e32 v212, v87, v197
	v_fmac_f32_dpp v209, v84, v190 row_shr:1 row_mask:0xf bank_mask:0xf
	v_fmac_f32_dpp v210, v85, v191 row_shr:1 row_mask:0xf bank_mask:0xf
	v_fmac_f32_dpp v211, v86, v192 row_shr:1 row_mask:0xf bank_mask:0xf
	v_fmac_f32_dpp v212, v87, v193 row_shr:1 row_mask:0xf bank_mask:0xf
	v_fmac_f32_dpp v209, v84, v186 row_shr:2 row_mask:0xf bank_mask:0xf
	v_fmac_f32_dpp v210, v85, v187 row_shr:2 row_mask:0xf bank_mask:0xf
	v_fmac_f32_dpp v211, v86, v188 row_shr:2 row_mask:0xf bank_mask:0xf
	v_fmac_f32_dpp v212, v87, v189 row_shr:2 row_mask:0xf bank_mask:0xf
	v_fmac_f32_dpp v209, v96, v190 row_shl:15 row_mask:0xf bank_mask:0xf
	v_fmac_f32_dpp v210, v97, v191 row_shl:15 row_mask:0xf bank_mask:0xf
	v_fmac_f32_dpp v211, v98, v192 row_shl:15 row_mask:0xf bank_mask:0xf
	v_fmac_f32_dpp v212, v99, v193 row_shl:15 row_mask:0xf bank_mask:0xf
	v_fmac_f32_dpp v209, v96, v186 row_shl:14 row_mask:0xf bank_mask:0xf
	v_fmac_f32_dpp v210, v97, v187 row_shl:14 row_mask:0xf bank_mask:0xf
	v_fmac_f32_dpp v211, v98, v188 row_shl:14 row_mask:0xf bank_mask:0xf
	v_fmac_f32_dpp v212, v99, v189 row_shl:14 row_mask:0xf bank_mask:0xf
	v_mul_f32_e32 v76, v209, v76
	v_mul_f32_e32 v77, v210, v77
	v_mul_f32_e32 v78, v211, v78
	v_mul_f32_e32 v79, v212, v79
	v_cvt_pk_bf16_f32 v214, v76, v77
	v_cvt_pk_bf16_f32 v215, v78, v79
	v_add_u32_e32 v216, 0x8000, v206
	global_store_dwordx2 v216, v[214:215], s[40:41] nt
	v_pk_mul_f32 v[72:73], v[72:73], v[200:201] op_sel_hi:[1,0]
	v_pk_mul_f32 v[74:75], v[74:75], v[200:201] op_sel_hi:[1,0]
	v_pk_mul_f32 v[68:69], v[68:69], v[200:201] op_sel_hi:[1,0]
	v_pk_mul_f32 v[70:71], v[70:71], v[200:201] op_sel_hi:[1,0]
	v_pk_mul_f32 v[64:65], v[64:65], v[200:201] op_sel_hi:[1,0]
	v_pk_mul_f32 v[66:67], v[66:67], v[200:201] op_sel_hi:[1,0]
	v_pk_mul_f32 v[72:73], v[72:73], v[68:69]
	v_pk_mul_f32 v[74:75], v[74:75], v[70:71]
	v_mul_f32_e32 v209, v72, v194
	v_mul_f32_e32 v210, v73, v195
	v_mul_f32_e32 v211, v74, v196
;     __device__ __forceinline__ void operator()(const Acc& acc, const Unit& u, int wr, int wc, int fr, int fq, LAS unsigned char* lds, f32x4 epar) const {
;     ...
;             for (int m = 0; m < 4; ++m) {
;                 const int r = u.pm * BM + ai * HALF + wr * 64 + m * 16 + fr;
;                 const float rs = __builtin_amdgcn_rsqf(sq[ai][m] * (1.0f / DM) + RMS_EPS);
;                 float X[NV], Y[NV], o[NV];
;                 if (MODE == 0) {
; #pragma unroll
;                     for (int n = 0; n < 2; ++n)
; #pragma unroll
;                         for (int j = 0; j < 4; ++j) { X[n * 4 + j] = acc[ai][0][m][n][j] * rs; Y[n * 4 + j] = acc[ai][1][m][n][j] * rs; }
;                 } else {
; #pragma unroll
;                     for (int j = 0; j < 4; ++j) { X[j] = (acc[ai][0][m][1][j] * rs) * (acc[ai][1][m][0][j] * rs); Y[j] = acc[ai][0][m][0][j] * rs; }
;                 }
; #pragma unroll
;                 for (int i = 0; i < NV; ++i) {
;                     const float a1 = dpp_rot<0x121>(X[i]), a2 = dpp_rot<0x122>(X[i]);
;                     const float q1 = fr >= 1 ? a1 : p1prev[i], q2 = fr >= 2 ? a2 : p2prev[i];
;                     p1prev[i] = a1; p2prev[i] = a2;
;                     const float cv = w2[i] * X[i] + w1[i] * q1 + w0[i] * q2 + bb[i];
;                     o[i] = MODE == 0 ? silu_f(cv) * Y[i] : cv * Y[i];
;                 }
;                 if (m == 0 && fr < 2) {
;                     bf16_t* hx = halo + ((size_t)strip * 6 + 2 + fr) * C + c0; bf16_t* hy = halo + ((size_t)strip * 6 + 4 + fr) * C + c0;
;                     u32x4 px, py; px.x = cvt_pk_bf16(X[0], X[1]); px.y = cvt_pk_bf16(X[2], X[3]); px.z = cvt_pk_bf16(X[4 % NV], X[5 % NV]); px.w = cvt_pk_bf16(X[6 % NV], X[7 % NV]);
;                     py.x = cvt_pk_bf16(Y[0], Y[1]); py.y = cvt_pk_bf16(Y[2], Y[3]); py.z = cvt_pk_bf16(Y[4 % NV], Y[5 % NV]); py.w = cvt_pk_bf16(Y[6 % NV], Y[7 % NV]);
;                     if (MODE == 0) { *(u32x4*)hx = px; *(u32x4*)hy = py; } else { u32x2 a; a.x = px.x; a.y = px.y; *(u32x2*)hx = a; u32x2 b; b.x = py.x; b.y = py.y; *(u32x2*)hy = b; }
;                 } else {
;                     if (MODE == 0) { u32x4 w; w.x = cvt_pk_bf16(o[0], o[1]); w.y = cvt_pk_bf16(o[2], o[3]); w.z = cvt_pk_bf16(o[4 % NV], o[5 % NV]); w.w = cvt_pk_bf16(o[6 % NV], o[7 % NV]);
	v_mul_f32_e32 v212, v75, v197
	v_fmac_f32_dpp v209, v72, v190 row_shr:1 row_mask:0xf bank_mask:0xf
	v_fmac_f32_dpp v210, v73, v191 row_shr:1 row_mask:0xf bank_mask:0xf
	v_fmac_f32_dpp v211, v74, v192 row_shr:1 row_mask:0xf bank_mask:0xf
	v_fmac_f32_dpp v212, v75, v193 row_shr:1 row_mask:0xf bank_mask:0xf
	v_fmac_f32_dpp v209, v72, v186 row_shr:2 row_mask:0xf bank_mask:0xf
	v_fmac_f32_dpp v210, v73, v187 row_shr:2 row_mask:0xf bank_mask:0xf
	v_fmac_f32_dpp v211, v74, v188 row_shr:2 row_mask:0xf bank_mask:0xf
	v_fmac_f32_dpp v212, v75, v189 row_shr:2 row_mask:0xf bank_mask:0xf
	v_fmac_f32_dpp v209, v84, v190 row_shl:15 row_mask:0xf bank_mask:0xf
	v_fmac_f32_dpp v210, v85, v191 row_shl:15 row_mask:0xf bank_mask:0xf
	v_fmac_f32_dpp v211, v86, v192 row_shl:15 row_mask:0xf bank_mask:0xf
	v_fmac_f32_dpp v212, v87, v193 row_shl:15 row_mask:0xf bank_mask:0xf
	v_fmac_f32_dpp v209, v84, v186 row_shl:14 row_mask:0xf bank_mask:0xf
	v_fmac_f32_dpp v210, v85, v187 row_shl:14 row_mask:0xf bank_mask:0xf
	v_fmac_f32_dpp v211, v86, v188 row_shl:14 row_mask:0xf bank_mask:0xf
	v_fmac_f32_dpp v212, v87, v189 row_shl:14 row_mask:0xf bank_mask:0xf
	v_mul_f32_e32 v64, v209, v64
	v_mul_f32_e32 v65, v210, v65
	v_mul_f32_e32 v66, v211, v66
	v_mul_f32_e32 v67, v212, v67
	v_cvt_pk_bf16_f32 v214, v64, v65
	v_cvt_pk_bf16_f32 v215, v66, v67
	v_add_u32_e32 v216, 0x10000, v206
	global_store_dwordx2 v216, v[214:215], s[40:41] nt
	v_pk_mul_f32 v[60:61], v[60:61], v[200:201] op_sel:[0,1]
	v_pk_mul_f32 v[62:63], v[62:63], v[200:201] op_sel:[0,1]
	v_pk_mul_f32 v[56:57], v[56:57], v[200:201] op_sel:[0,1]
	v_pk_mul_f32 v[58:59], v[58:59], v[200:201] op_sel:[0,1]
	v_pk_mul_f32 v[52:53], v[52:53], v[200:201] op_sel:[0,1]
	v_pk_mul_f32 v[54:55], v[54:55], v[200:201] op_sel:[0,1]
	v_pk_mul_f32 v[60:61], v[60:61], v[56:57]
	v_pk_mul_f32 v[62:63], v[62:63], v[58:59]
	v_mul_f32_e32 v209, v60, v194
	v_mul_f32_e32 v210, v61, v195
	v_mul_f32_e32 v211, v62, v196
	v_mul_f32_e32 v212, v63, v197
	v_cvt_pk_bf16_f32 v218, v60, v61
	v_cvt_pk_bf16_f32 v219, v62, v63
	v_add_u32_e32 v217, 0xffff9000, v208
	s_and_b64 exec, exec, s[10:11]
	global_store_dwordx2 v217, v[218:219], s[42:43]
	s_mov_b64 exec, s[24:25]
	v_fmac_f32_dpp v209, v60, v190 row_shr:1 row_mask:0xf bank_mask:0xf
	v_fmac_f32_dpp v210, v61, v191 row_shr:1 row_mask:0xf bank_mask:0xf
	v_fmac_f32_dpp v211, v62, v192 row_shr:1 row_mask:0xf bank_mask:0xf
	v_fmac_f32_dpp v212, v63, v193 row_shr:1 row_mask:0xf bank_mask:0xf
	v_fmac_f32_dpp v209, v60, v186 row_shr:2 row_mask:0xf bank_mask:0xf
	v_fmac_f32_dpp v210, v61, v187 row_shr:2 row_mask:0xf bank_mask:0xf
	v_fmac_f32_dpp v211, v62, v188 row_shr:2 row_mask:0xf bank_mask:0xf
	v_fmac_f32_dpp v212, v63, v189 row_shr:2 row_mask:0xf bank_mask:0xf
	v_fmac_f32_dpp v209, v72, v190 row_shl:15 row_mask:0xf bank_mask:0xf
	v_fmac_f32_dpp v210, v73, v191 row_shl:15 row_mask:0xf bank_mask:0xf
	v_fmac_f32_dpp v211, v74, v192 row_shl:15 row_mask:0xf bank_mask:0xf
	v_fmac_f32_dpp v212, v75, v193 row_shl:15 row_mask:0xf bank_mask:0xf
	v_fmac_f32_dpp v209, v72, v186 row_shl:14 row_mask:0xf bank_mask:0xf
	v_fmac_f32_dpp v210, v73, v187 row_shl:14 row_mask:0xf bank_mask:0xf
	v_fmac_f32_dpp v211, v74, v188 row_shl:14 row_mask:0xf bank_mask:0xf
	v_fmac_f32_dpp v212, v75, v189 row_shl:14 row_mask:0xf bank_mask:0xf
	v_mul_f32_e32 v52, v209, v52
	v_mul_f32_e32 v53, v210, v53
	v_mul_f32_e32 v54, v211, v54
	v_mul_f32_e32 v55, v212, v55
	v_cvt_pk_bf16_f32 v214, v52, v53
	v_cvt_pk_bf16_f32 v215, v54, v55
	v_add_u32_e32 v216, 0x18000, v206
	global_store_dwordx2 v216, v[214:215], s[40:41] nt
	v_pk_mul_f32 v[48:49], v[48:49], v[202:203] op_sel_hi:[1,0]
	v_pk_mul_f32 v[50:51], v[50:51], v[202:203] op_sel_hi:[1,0]
	v_pk_mul_f32 v[40:41], v[40:41], v[202:203] op_sel_hi:[1,0]
	v_pk_mul_f32 v[42:43], v[42:43], v[202:203] op_sel_hi:[1,0]
	v_pk_mul_f32 v[44:45], v[44:45], v[202:203] op_sel_hi:[1,0]
	v_pk_mul_f32 v[46:47], v[46:47], v[202:203] op_sel_hi:[1,0]
	v_pk_mul_f32 v[48:49], v[48:49], v[40:41]
	v_pk_mul_f32 v[50:51], v[50:51], v[42:43]
	v_mul_f32_e32 v209, v48, v194
	v_mul_f32_e32 v210, v49, v195
	v_mul_f32_e32 v211, v50, v196
	v_mul_f32_e32 v212, v51, v197
	v_cvt_pk_bf16_f32 v218, v48, v49
	v_cvt_pk_bf16_f32 v219, v50, v51
	v_cvt_pk_bf16_f32 v220, v44, v45
	v_cvt_pk_bf16_f32 v221, v46, v47
	v_add_u32_e32 v216, 0x7000, v208
	v_add_u32_e32 v217, 0x8000, v208
	s_andn2_b64 exec, exec, s[8:9]
	global_store_dwordx2 v216, v[218:219], s[42:43]
	global_store_dwordx2 v217, v[220:221], s[42:43]
	s_mov_b64 exec, s[24:25]
	v_fmac_f32_dpp v209, v48, v190 row_shr:1 row_mask:0xf bank_mask:0xf
	v_fmac_f32_dpp v210, v49, v191 row_shr:1 row_mask:0xf bank_mask:0xf
	v_fmac_f32_dpp v211, v50, v192 row_shr:1 row_mask:0xf bank_mask:0xf
	v_fmac_f32_dpp v212, v51, v193 row_shr:1 row_mask:0xf bank_mask:0xf
	v_fmac_f32_dpp v209, v48, v186 row_shr:2 row_mask:0xf bank_mask:0xf
	v_fmac_f32_dpp v210, v49, v187 row_shr:2 row_mask:0xf bank_mask:0xf
	v_fmac_f32_dpp v211, v50, v188 row_shr:2 row_mask:0xf bank_mask:0xf
	v_fmac_f32_dpp v212, v51, v189 row_shr:2 row_mask:0xf bank_mask:0xf
	v_mul_f32_e32 v44, v209, v44
	v_mul_f32_e32 v45, v210, v45
	v_mul_f32_e32 v46, v211, v46
	v_mul_f32_e32 v47, v212, v47
	v_cvt_pk_bf16_f32 v214, v44, v45
	v_cvt_pk_bf16_f32 v215, v46, v47
	v_add_u32_e32 v216, 0x40000, v206
	s_and_b64 exec, exec, s[8:9]
	global_store_dwordx2 v216, v[214:215], s[40:41] nt
	s_mov_b64 exec, s[24:25]
	v_pk_mul_f32 v[36:37], v[36:37], v[202:203] op_sel:[0,1]
	v_pk_mul_f32 v[38:39], v[38:39], v[202:203] op_sel:[0,1]
	v_pk_mul_f32 v[32:33], v[32:33], v[202:203] op_sel:[0,1]
	v_pk_mul_f32 v[34:35], v[34:35], v[202:203] op_sel:[0,1]
;     __device__ __forceinline__ void operator()(const Acc& acc, const Unit& u, int wr, int wc, int fr, int fq, LAS unsigned char* lds, f32x4 epar) const {
;     ...
;             for (int m = 0; m < 4; ++m) {
;                 const int r = u.pm * BM + ai * HALF + wr * 64 + m * 16 + fr;
;                 const float rs = __builtin_amdgcn_rsqf(sq[ai][m] * (1.0f / DM) + RMS_EPS);
;                 float X[NV], Y[NV], o[NV];
;                 if (MODE == 0) {
; #pragma unroll
;                     for (int n = 0; n < 2; ++n)
; #pragma unroll
;                         for (int j = 0; j < 4; ++j) { X[n * 4 + j] = acc[ai][0][m][n][j] * rs; Y[n * 4 + j] = acc[ai][1][m][n][j] * rs; }
;                 } else {
; #pragma unroll
;                     for (int j = 0; j < 4; ++j) { X[j] = (acc[ai][0][m][1][j] * rs) * (acc[ai][1][m][0][j] * rs); Y[j] = acc[ai][0][m][0][j] * rs; }
;                 }
; #pragma unroll
;                 for (int i = 0; i < NV; ++i) {
;                     const float a1 = dpp_rot<0x121>(X[i]), a2 = dpp_rot<0x122>(X[i]);
;                     const float q1 = fr >= 1 ? a1 : p1prev[i], q2 = fr >= 2 ? a2 : p2prev[i];
;                     p1prev[i] = a1; p2prev[i] = a2;
;                     const float cv = w2[i] * X[i] + w1[i] * q1 + w0[i] * q2 + bb[i];
;                     o[i] = MODE == 0 ? silu_f(cv) * Y[i] : cv * Y[i];
;                 }
;                 if (m == 0 && fr < 2) {
;                     bf16_t* hx = halo + ((size_t)strip * 6 + 2 + fr) * C + c0; bf16_t* hy = halo + ((size_t)strip * 6 + 4 + fr) * C + c0;
;                     u32x4 px, py; px.x = cvt_pk_bf16(X[0], X[1]); px.y = cvt_pk_bf16(X[2], X[3]); px.z = cvt_pk_bf16(X[4 % NV], X[5 % NV]); px.w = cvt_pk_bf16(X[6 % NV], X[7 % NV]);
;                     py.x = cvt_pk_bf16(Y[0], Y[1]); py.y = cvt_pk_bf16(Y[2], Y[3]); py.z = cvt_pk_bf16(Y[4 % NV], Y[5 % NV]); py.w = cvt_pk_bf16(Y[6 % NV], Y[7 % NV]);
;                     if (MODE == 0) { *(u32x4*)hx = px; *(u32x4*)hy = py; } else { u32x2 a; a.x = px.x; a.y = px.y; *(u32x2*)hx = a; u32x2 b; b.x = py.x; b.y = py.y; *(u32x2*)hy = b; }
;                 } else {
;                     if (MODE == 0) { u32x4 w; w.x = cvt_pk_bf16(o[0], o[1]); w.y = cvt_pk_bf16(o[2], o[3]); w.z = cvt_pk_bf16(o[4 % NV], o[5 % NV]); w.w = cvt_pk_bf16(o[6 % NV], o[7 % NV]);
	v_pk_mul_f32 v[28:29], v[28:29], v[202:203] op_sel:[0,1]
	v_pk_mul_f32 v[30:31], v[30:31], v[202:203] op_sel:[0,1]
	v_pk_mul_f32 v[36:37], v[36:37], v[32:33]
	v_pk_mul_f32 v[38:39], v[38:39], v[34:35]
	v_mul_f32_e32 v209, v36, v194
	v_mul_f32_e32 v210, v37, v195
	v_mul_f32_e32 v211, v38, v196
	v_mul_f32_e32 v212, v39, v197
	v_fmac_f32_dpp v209, v36, v190 row_shr:1 row_mask:0xf bank_mask:0xf
	v_fmac_f32_dpp v210, v37, v191 row_shr:1 row_mask:0xf bank_mask:0xf
	v_fmac_f32_dpp v211, v38, v192 row_shr:1 row_mask:0xf bank_mask:0xf
	v_fmac_f32_dpp v212, v39, v193 row_shr:1 row_mask:0xf bank_mask:0xf
	v_fmac_f32_dpp v209, v36, v186 row_shr:2 row_mask:0xf bank_mask:0xf
	v_fmac_f32_dpp v210, v37, v187 row_shr:2 row_mask:0xf bank_mask:0xf
	v_fmac_f32_dpp v211, v38, v188 row_shr:2 row_mask:0xf bank_mask:0xf
	v_fmac_f32_dpp v212, v39, v189 row_shr:2 row_mask:0xf bank_mask:0xf
	v_fmac_f32_dpp v209, v48, v190 row_shl:15 row_mask:0xf bank_mask:0xf
	v_fmac_f32_dpp v210, v49, v191 row_shl:15 row_mask:0xf bank_mask:0xf
	v_fmac_f32_dpp v211, v50, v192 row_shl:15 row_mask:0xf bank_mask:0xf
	v_fmac_f32_dpp v212, v51, v193 row_shl:15 row_mask:0xf bank_mask:0xf
	v_fmac_f32_dpp v209, v48, v186 row_shl:14 row_mask:0xf bank_mask:0xf
	v_fmac_f32_dpp v210, v49, v187 row_shl:14 row_mask:0xf bank_mask:0xf
	v_fmac_f32_dpp v211, v50, v188 row_shl:14 row_mask:0xf bank_mask:0xf
	v_fmac_f32_dpp v212, v51, v189 row_shl:14 row_mask:0xf bank_mask:0xf
	v_mul_f32_e32 v28, v209, v28
	v_mul_f32_e32 v29, v210, v29
	v_mul_f32_e32 v30, v211, v30
	v_mul_f32_e32 v31, v212, v31
	v_cvt_pk_bf16_f32 v214, v28, v29
	v_cvt_pk_bf16_f32 v215, v30, v31
	v_add_u32_e32 v216, 0x48000, v206
	global_store_dwordx2 v216, v[214:215], s[40:41] nt
	v_pk_mul_f32 v[20:21], v[20:21], v[204:205] op_sel_hi:[1,0]
	v_pk_mul_f32 v[22:23], v[22:23], v[204:205] op_sel_hi:[1,0]
	v_pk_mul_f32 v[16:17], v[16:17], v[204:205] op_sel_hi:[1,0]
	v_pk_mul_f32 v[18:19], v[18:19], v[204:205] op_sel_hi:[1,0]
	v_pk_mul_f32 v[12:13], v[12:13], v[204:205] op_sel_hi:[1,0]
	v_pk_mul_f32 v[14:15], v[14:15], v[204:205] op_sel_hi:[1,0]
	v_pk_mul_f32 v[20:21], v[20:21], v[16:17]
	v_pk_mul_f32 v[22:23], v[22:23], v[18:19]
	v_mul_f32_e32 v209, v20, v194
	v_mul_f32_e32 v210, v21, v195
	v_mul_f32_e32 v211, v22, v196
	v_mul_f32_e32 v212, v23, v197
	v_fmac_f32_dpp v209, v20, v190 row_shr:1 row_mask:0xf bank_mask:0xf
	v_fmac_f32_dpp v210, v21, v191 row_shr:1 row_mask:0xf bank_mask:0xf
	v_fmac_f32_dpp v211, v22, v192 row_shr:1 row_mask:0xf bank_mask:0xf
	v_fmac_f32_dpp v212, v23, v193 row_shr:1 row_mask:0xf bank_mask:0xf
	v_fmac_f32_dpp v209, v20, v186 row_shr:2 row_mask:0xf bank_mask:0xf
	v_fmac_f32_dpp v210, v21, v187 row_shr:2 row_mask:0xf bank_mask:0xf
	v_fmac_f32_dpp v211, v22, v188 row_shr:2 row_mask:0xf bank_mask:0xf
	v_fmac_f32_dpp v212, v23, v189 row_shr:2 row_mask:0xf bank_mask:0xf
	v_fmac_f32_dpp v209, v36, v190 row_shl:15 row_mask:0xf bank_mask:0xf
	v_fmac_f32_dpp v210, v37, v191 row_shl:15 row_mask:0xf bank_mask:0xf
	v_fmac_f32_dpp v211, v38, v192 row_shl:15 row_mask:0xf bank_mask:0xf
	v_fmac_f32_dpp v212, v39, v193 row_shl:15 row_mask:0xf bank_mask:0xf
	v_fmac_f32_dpp v209, v36, v186 row_shl:14 row_mask:0xf bank_mask:0xf
	v_fmac_f32_dpp v210, v37, v187 row_shl:14 row_mask:0xf bank_mask:0xf
	v_fmac_f32_dpp v211, v38, v188 row_shl:14 row_mask:0xf bank_mask:0xf
	v_fmac_f32_dpp v212, v39, v189 row_shl:14 row_mask:0xf bank_mask:0xf
	v_mul_f32_e32 v12, v209, v12
	v_mul_f32_e32 v13, v210, v13
	v_mul_f32_e32 v14, v211, v14
	v_mul_f32_e32 v15, v212, v15
	v_cvt_pk_bf16_f32 v214, v12, v13
	v_cvt_pk_bf16_f32 v215, v14, v15
	v_add_u32_e32 v216, 0x50000, v206
	global_store_dwordx2 v216, v[214:215], s[40:41] nt
	v_pk_mul_f32 v[8:9], v[8:9], v[204:205] op_sel:[0,1]
	v_pk_mul_f32 v[10:11], v[10:11], v[204:205] op_sel:[0,1]
	v_pk_mul_f32 v[4:5], v[4:5], v[204:205] op_sel:[0,1]
	v_pk_mul_f32 v[6:7], v[6:7], v[204:205] op_sel:[0,1]
	v_pk_mul_f32 v[0:1], v[0:1], v[204:205] op_sel:[0,1]
	v_pk_mul_f32 v[2:3], v[2:3], v[204:205] op_sel:[0,1]
	v_pk_mul_f32 v[8:9], v[8:9], v[4:5]
	v_pk_mul_f32 v[10:11], v[10:11], v[6:7]
	v_mul_f32_e32 v209, v8, v194
	v_mul_f32_e32 v210, v9, v195
	v_mul_f32_e32 v211, v10, v196
	v_mul_f32_e32 v212, v11, v197
	v_cvt_pk_bf16_f32 v218, v8, v9
	v_cvt_pk_bf16_f32 v219, v10, v11
	v_add_u32_e32 v217, 0xfffff000, v208
	s_and_b64 exec, exec, s[10:11]
	global_store_dwordx2 v217, v[218:219], s[42:43]
	s_mov_b64 exec, s[24:25]
	v_fmac_f32_dpp v209, v8, v190 row_shr:1 row_mask:0xf bank_mask:0xf
	v_fmac_f32_dpp v210, v9, v191 row_shr:1 row_mask:0xf bank_mask:0xf
	v_fmac_f32_dpp v211, v10, v192 row_shr:1 row_mask:0xf bank_mask:0xf
	v_fmac_f32_dpp v212, v11, v193 row_shr:1 row_mask:0xf bank_mask:0xf
	v_fmac_f32_dpp v209, v8, v186 row_shr:2 row_mask:0xf bank_mask:0xf
	v_fmac_f32_dpp v210, v9, v187 row_shr:2 row_mask:0xf bank_mask:0xf
	v_fmac_f32_dpp v211, v10, v188 row_shr:2 row_mask:0xf bank_mask:0xf
	v_fmac_f32_dpp v212, v11, v189 row_shr:2 row_mask:0xf bank_mask:0xf
	v_fmac_f32_dpp v209, v20, v190 row_shl:15 row_mask:0xf bank_mask:0xf
	v_fmac_f32_dpp v210, v21, v191 row_shl:15 row_mask:0xf bank_mask:0xf
	v_fmac_f32_dpp v211, v22, v192 row_shl:15 row_mask:0xf bank_mask:0xf
	v_fmac_f32_dpp v212, v23, v193 row_shl:15 row_mask:0xf bank_mask:0xf
	v_fmac_f32_dpp v209, v20, v186 row_shl:14 row_mask:0xf bank_mask:0xf
	v_fmac_f32_dpp v210, v21, v187 row_shl:14 row_mask:0xf bank_mask:0xf
	v_fmac_f32_dpp v211, v22, v188 row_shl:14 row_mask:0xf bank_mask:0xf
	v_fmac_f32_dpp v212, v23, v189 row_shl:14 row_mask:0xf bank_mask:0xf
	v_mul_f32_e32 v0, v209, v0
	v_mul_f32_e32 v1, v210, v1
	v_mul_f32_e32 v2, v211, v2
	v_mul_f32_e32 v3, v212, v3
	v_cvt_pk_bf16_f32 v214, v0, v1
	v_cvt_pk_bf16_f32 v215, v2, v3
	v_add_u32_e32 v216, 0x58000, v206
	global_store_dwordx2 v216, v[214:215], s[40:41] nt

;     __device__ __forceinline__ void operator()(const Acc& acc, const Unit& u, int wr, int wc, int fr, int fq, LAS unsigned char* lds, f32x4 epar) const {
;     ...
;         LAS float* pw = (LAS float*)(lds + STAGE_BYTES + 64 + (wr * 4 + wc) * 1024);
;         *(LAS f32x4*)(pw + (fq * 16 + fr) * 4) = epar;
;         asm volatile("s_waitcnt lgkmcnt(0)" ::: "memory");
;         float w0[NV], w1[NV], w2[NV], bb[NV];
; #pragma unroll
;         for (int i = 0; i < NV; i += 4) { const f32x4 a = *(const LAS f32x4*)(pw + NV * fq + i), b = *(const LAS f32x4*)(pw + 32 + NV * fq + i), c = *(const LAS f32x4*)(pw + 64 + NV * fq + i);
;             f32x4 d = (f32x4){0.f, 0.f, 0.f, 0.f}; if (MODE == 0) d = *(const LAS f32x4*)(pw + 96 + NV * fq + i);
; #pragma unroll
;             for (int j = 0; j < 4; ++j) { w0[i + j] = a[j]; w1[i + j] = b[j]; w2[i + j] = c[j]; bb[i + j] = d[j]; } }
;         float sq[2][4];
; #pragma unroll
;         for (int ai = 0; ai < 2; ++ai)
; #pragma unroll
;             for (int m = 0; m < 4; ++m) sq[ai][m] = pw[128 + ai * 64 + m * 16 + fr];
; #pragma unroll
;         for (int ai = 0; ai < 2; ++ai) {
;             const int strip = u.pm * 4 + ai * 2 + wr;
;             float p1prev[NV], p2prev[NV];
; #pragma unroll
;             for (int i = 0; i < NV; ++i) { p1prev[i] = 0.f; p2prev[i] = 0.f; }
; #pragma unroll
;             for (int m = 0; m < 4; ++m) {
;                 const int r = u.pm * BM + ai * HALF + wr * 64 + m * 16 + fr;
;                 const float rs = __builtin_amdgcn_rsqf(sq[ai][m] * (1.0f / DM) + RMS_EPS);
;                 float X[NV], Y[NV], o[NV];
;                 if (MODE == 0) {
; #pragma unroll
;                     for (int n = 0; n < 2; ++n)
; #pragma unroll
;                         for (int j = 0; j < 4; ++j) { X[n * 4 + j] = acc[ai][0][m][n][j] * rs; Y[n * 4 + j] = acc[ai][1][m][n][j] * rs; }
;                 } else {
; #pragma unroll
;                     for (int j = 0; j < 4; ++j) { X[j] = (acc[ai][0][m][1][j] * rs) * (acc[ai][1][m][0][j] * rs); Y[j] = acc[ai][0][m][0][j] * rs; }
;                 }
; #pragma unroll
;                 for (int i = 0; i < NV; ++i) {
;                     const float a1 = dpp_rot<0x121>(X[i]), a2 = dpp_rot<0x122>(X[i]);
;                     const float q1 = fr >= 1 ? a1 : p1prev[i], q2 = fr >= 2 ? a2 : p2prev[i];
;                     p1prev[i] = a1; p2prev[i] = a2;
.LBB0_986:
	s_mov_b32 s100, 0xbfb8aa3b
	ds_write_b128 v198, v[72:75]
	s_mov_b64 s[24:25], exec
	s_waitcnt lgkmcnt(0)
	ds_read_b128 v[88:91], v199
	ds_read_b128 v[92:95], v199 offset:16
	ds_read_b128 v[128:131], v199 offset:128
	ds_read_b128 v[132:135], v199 offset:144
	ds_read_b128 v[136:139], v199 offset:256
	ds_read_b128 v[140:143], v199 offset:272
	ds_read_b128 v[174:177], v199 offset:384
	ds_read_b128 v[178:181], v199 offset:400
	ds_read2_b32 v[182:183], v191 offset0:128 offset1:144
	ds_read2_b32 v[184:185], v191 offset0:160 offset1:176
	ds_read2_b32 v[76:77], v191 offset0:192 offset1:208
	ds_read2_b32 v[78:79], v191 offset0:224 offset1:240
	v_lshl_add_u32 v230, s66, 8, v190
	v_lshl_or_b32 v231, s70, 7, v192
	v_mul_u32_u24_e32 v230, 0x1600, v230
	s_lshl_b32 s26, s66, 2
	s_add_i32 s26, s26, s15
	s_mul_i32 s16, s26, 6
	v_and_b32_e32 v233, 15, v190
	v_lshl_add_u32 v230, v231, 1, v230
	v_add_u32_e32 v233, s16, v233
	v_mul_u32_u24_e32 v233, 0x1600, v233
	s_nop 0
	v_lshl_add_u32 v233, v231, 1, v233
	s_waitcnt lgkmcnt(0)
	v_pk_mul_f32 v[88:89], s[100:101], v[88:89] op_sel_hi:[0,1]
	v_pk_mul_f32 v[90:91], s[100:101], v[90:91] op_sel_hi:[0,1]
	v_pk_mul_f32 v[92:93], s[100:101], v[92:93] op_sel_hi:[0,1]
	v_pk_mul_f32 v[94:95], s[100:101], v[94:95] op_sel_hi:[0,1]
	v_pk_mul_f32 v[128:129], s[100:101], v[128:129] op_sel_hi:[0,1]
	v_pk_mul_f32 v[130:131], s[100:101], v[130:131] op_sel_hi:[0,1]
	v_pk_mul_f32 v[132:133], s[100:101], v[132:133] op_sel_hi:[0,1]
	v_pk_mul_f32 v[134:135], s[100:101], v[134:135] op_sel_hi:[0,1]
	v_pk_mul_f32 v[136:137], s[100:101], v[136:137] op_sel_hi:[0,1]
	v_pk_mul_f32 v[138:139], s[100:101], v[138:139] op_sel_hi:[0,1]
	v_pk_mul_f32 v[140:141], s[100:101], v[140:141] op_sel_hi:[0,1]
	v_pk_mul_f32 v[142:143], s[100:101], v[142:143] op_sel_hi:[0,1]
	v_pk_mul_f32 v[174:175], s[100:101], v[174:175] op_sel_hi:[0,1]
	v_pk_mul_f32 v[176:177], s[100:101], v[176:177] op_sel_hi:[0,1]
	v_pk_mul_f32 v[178:179], s[100:101], v[178:179] op_sel_hi:[0,1]
	v_pk_mul_f32 v[180:181], s[100:101], v[180:181] op_sel_hi:[0,1]
	v_fmamk_f32 v182, v182, 0x3a800000, v200
	v_fmamk_f32 v183, v183, 0x3a800000, v200
	v_fmamk_f32 v184, v184, 0x3a800000, v200
	v_fmamk_f32 v185, v185, 0x3a800000, v200
	v_fmamk_f32 v76, v76, 0x3a800000, v200
	v_fmamk_f32 v77, v77, 0x3a800000, v200
	v_fmamk_f32 v78, v78, 0x3a800000, v200
	v_fmamk_f32 v79, v79, 0x3a800000, v200
	v_pk_mul_f32 v[202:203], s[100:101], v[182:183] op_sel_hi:[0,1]
	v_pk_mul_f32 v[204:205], s[100:101], v[184:185] op_sel_hi:[0,1]
	v_pk_mul_f32 v[206:207], s[100:101], v[76:77] op_sel_hi:[0,1]
	v_pk_mul_f32 v[208:209], s[100:101], v[78:79] op_sel_hi:[0,1]
	v_rsq_f32_e32 v182, v182
	v_rsq_f32_e32 v183, v183
	v_rsq_f32_e32 v184, v184
	v_rsq_f32_e32 v185, v185
	v_rsq_f32_e32 v76, v76
	v_rsq_f32_e32 v77, v77
	v_rsq_f32_e32 v78, v78
	v_rsq_f32_e32 v79, v79
	s_nop 0
	v_pk_mul_f32 v[202:203], v[202:203], v[182:183]
	v_pk_mul_f32 v[204:205], v[204:205], v[184:185]
	v_pk_mul_f32 v[206:207], v[206:207], v[76:77]
	v_pk_mul_f32 v[208:209], v[208:209], v[78:79]
	v_pk_mul_f32 v[152:153], v[152:153], v[182:183] op_sel_hi:[1,0]
	v_pk_mul_f32 v[154:155], v[154:155], v[182:183] op_sel_hi:[1,0]
	v_pk_mul_f32 v[144:145], v[144:145], v[182:183] op_sel_hi:[1,0]
	v_pk_mul_f32 v[146:147], v[146:147], v[182:183] op_sel_hi:[1,0]
	v_pk_fma_f32 v[210:211], v[152:153], v[136:137], v[174:175]
	v_pk_fma_f32 v[212:213], v[154:155], v[138:139], v[176:177]
	v_pk_fma_f32 v[214:215], v[144:145], v[140:141], v[178:179]
	v_pk_fma_f32 v[216:217], v[146:147], v[142:143], v[180:181]
	v_pk_mul_f32 v[218:219], v[156:157], v[182:183] op_sel_hi:[1,0]
	v_pk_mul_f32 v[220:221], v[158:159], v[182:183] op_sel_hi:[1,0]
	v_pk_mul_f32 v[222:223], v[148:149], v[182:183] op_sel_hi:[1,0]
	v_pk_mul_f32 v[224:225], v[150:151], v[182:183] op_sel_hi:[1,0]
	v_cvt_pk_bf16_f32 v236, v152, v153
	v_cvt_pk_bf16_f32 v237, v154, v155
	v_cvt_pk_bf16_f32 v238, v144, v145
	v_cvt_pk_bf16_f32 v239, v146, v147
	v_cvt_pk_bf16_f32 v240, v218, v219
	v_cvt_pk_bf16_f32 v241, v220, v221
	v_cvt_pk_bf16_f32 v242, v222, v223
	v_cvt_pk_bf16_f32 v243, v224, v225
	v_add_u32_e32 v234, 0x2c00, v233
	v_add_u32_e32 v235, 0x5800, v233
	s_andn2_b64 exec, exec, s[8:9]
	global_store_dwordx4 v234, v[236:239], s[42:43]
	global_store_dwordx4 v235, v[240:243], s[42:43]
	s_mov_b64 exec, s[24:25]
	v_fmac_f32_dpp v210, v152, v128 row_shr:1 row_mask:0xf bank_mask:0xf
	v_fmac_f32_dpp v211, v153, v129 row_shr:1 row_mask:0xf bank_mask:0xf
	v_fmac_f32_dpp v212, v154, v130 row_shr:1 row_mask:0xf bank_mask:0xf
	v_fmac_f32_dpp v213, v155, v131 row_shr:1 row_mask:0xf bank_mask:0xf
	v_fmac_f32_dpp v214, v144, v132 row_shr:1 row_mask:0xf bank_mask:0xf
	v_fmac_f32_dpp v215, v145, v133 row_shr:1 row_mask:0xf bank_mask:0xf
	v_fmac_f32_dpp v216, v146, v134 row_shr:1 row_mask:0xf bank_mask:0xf
	v_fmac_f32_dpp v217, v147, v135 row_shr:1 row_mask:0xf bank_mask:0xf
	v_fmac_f32_dpp v210, v152, v88 row_shr:2 row_mask:0xf bank_mask:0xf
	v_fmac_f32_dpp v211, v153, v89 row_shr:2 row_mask:0xf bank_mask:0xf
	v_fmac_f32_dpp v212, v154, v90 row_shr:2 row_mask:0xf bank_mask:0xf
	v_fmac_f32_dpp v213, v155, v91 row_shr:2 row_mask:0xf bank_mask:0xf
	v_fmac_f32_dpp v214, v144, v92 row_shr:2 row_mask:0xf bank_mask:0xf
	v_fmac_f32_dpp v215, v145, v93 row_shr:2 row_mask:0xf bank_mask:0xf
	v_fmac_f32_dpp v216, v146, v94 row_shr:2 row_mask:0xf bank_mask:0xf
	v_fmac_f32_dpp v217, v147, v95 row_shr:2 row_mask:0xf bank_mask:0xf
	v_exp_f32_e32 v218, v210
	v_exp_f32_e32 v219, v211
	v_exp_f32_e32 v220, v212
	v_exp_f32_e32 v221, v213
	v_exp_f32_e32 v222, v214
	v_exp_f32_e32 v223, v215
	v_exp_f32_e32 v224, v216
	v_exp_f32_e32 v225, v217
;     __device__ __forceinline__ void operator()(const Acc& acc, const Unit& u, int wr, int wc, int fr, int fq, LAS unsigned char* lds, f32x4 epar) const {
;     ...
;             for (int m = 0; m < 4; ++m) {
;                 const int r = u.pm * BM + ai * HALF + wr * 64 + m * 16 + fr;
;                 const float rs = __builtin_amdgcn_rsqf(sq[ai][m] * (1.0f / DM) + RMS_EPS);
;                 float X[NV], Y[NV], o[NV];
;                 if (MODE == 0) {
; #pragma unroll
;                     for (int n = 0; n < 2; ++n)
; #pragma unroll
;                         for (int j = 0; j < 4; ++j) { X[n * 4 + j] = acc[ai][0][m][n][j] * rs; Y[n * 4 + j] = acc[ai][1][m][n][j] * rs; }
;                 } else {
; #pragma unroll
;                     for (int j = 0; j < 4; ++j) { X[j] = (acc[ai][0][m][1][j] * rs) * (acc[ai][1][m][0][j] * rs); Y[j] = acc[ai][0][m][0][j] * rs; }
;                 }
; #pragma unroll
;                 for (int i = 0; i < NV; ++i) {
;                     const float a1 = dpp_rot<0x121>(X[i]), a2 = dpp_rot<0x122>(X[i]);
;                     const float q1 = fr >= 1 ? a1 : p1prev[i], q2 = fr >= 2 ? a2 : p2prev[i];
;                     p1prev[i] = a1; p2prev[i] = a2;
;                     const float cv = w2[i] * X[i] + w1[i] * q1 + w0[i] * q2 + bb[i];
;                     o[i] = MODE == 0 ? silu_f(cv) * Y[i] : cv * Y[i];
;                 }
;                 if (m == 0 && fr < 2) {
;                     bf16_t* hx = halo + ((size_t)strip * 6 + 2 + fr) * C + c0; bf16_t* hy = halo + ((size_t)strip * 6 + 4 + fr) * C + c0;
;                     u32x4 px, py; px.x = cvt_pk_bf16(X[0], X[1]); px.y = cvt_pk_bf16(X[2], X[3]); px.z = cvt_pk_bf16(X[4 % NV], X[5 % NV]); px.w = cvt_pk_bf16(X[6 % NV], X[7 % NV]);
;                     py.x = cvt_pk_bf16(Y[0], Y[1]); py.y = cvt_pk_bf16(Y[2], Y[3]); py.z = cvt_pk_bf16(Y[4 % NV], Y[5 % NV]); py.w = cvt_pk_bf16(Y[6 % NV], Y[7 % NV]);
;                     if (MODE == 0) { *(u32x4*)hx = px; *(u32x4*)hy = py; } else { u32x2 a; a.x = px.x; a.y = px.y; *(u32x2*)hx = a; u32x2 b; b.x = py.x; b.y = py.y; *(u32x2*)hy = b; }
;                 } else {
;                     if (MODE == 0) { u32x4 w; w.x = cvt_pk_bf16(o[0], o[1]); w.y = cvt_pk_bf16(o[2], o[3]); w.z = cvt_pk_bf16(o[4 % NV], o[5 % NV]); w.w = cvt_pk_bf16(o[6 % NV], o[7 % NV]);
	v_pk_fma_f32 v[218:219], v[218:219], v[202:203], v[202:203] op_sel_hi:[1,0,0]
	v_pk_fma_f32 v[220:221], v[220:221], v[202:203], v[202:203] op_sel_hi:[1,0,0]
	v_pk_fma_f32 v[222:223], v[222:223], v[202:203], v[202:203] op_sel_hi:[1,0,0]
	v_pk_fma_f32 v[224:225], v[224:225], v[202:203], v[202:203] op_sel_hi:[1,0,0]
	v_rcp_f32_e32 v218, v218
	v_rcp_f32_e32 v219, v219
	v_rcp_f32_e32 v220, v220
	v_rcp_f32_e32 v221, v221
	v_rcp_f32_e32 v222, v222
	v_rcp_f32_e32 v223, v223
	v_rcp_f32_e32 v224, v224
	v_rcp_f32_e32 v225, v225
	v_pk_mul_f32 v[210:211], v[210:211], v[218:219]
	v_pk_mul_f32 v[212:213], v[212:213], v[220:221]
	v_pk_mul_f32 v[214:215], v[214:215], v[222:223]
	v_pk_mul_f32 v[216:217], v[216:217], v[224:225]
	v_pk_mul_f32 v[156:157], v[210:211], v[156:157]
	v_pk_mul_f32 v[158:159], v[212:213], v[158:159]
	v_pk_mul_f32 v[148:149], v[214:215], v[148:149]
	v_pk_mul_f32 v[150:151], v[216:217], v[150:151]
	v_cvt_pk_bf16_f32 v226, v156, v157
	v_cvt_pk_bf16_f32 v227, v158, v159
	v_cvt_pk_bf16_f32 v228, v148, v149
	v_cvt_pk_bf16_f32 v229, v150, v151
	v_add_u32_e32 v234, 0x0, v230
	s_and_b64 exec, exec, s[8:9]
	global_store_dwordx4 v234, v[226:229], s[96:97] nt
	s_mov_b64 exec, s[24:25]
	v_pk_mul_f32 v[124:125], v[124:125], v[182:183] op_sel:[0,1]
	v_pk_mul_f32 v[126:127], v[126:127], v[182:183] op_sel:[0,1]
	v_pk_mul_f32 v[120:121], v[120:121], v[182:183] op_sel:[0,1]
	v_pk_mul_f32 v[122:123], v[122:123], v[182:183] op_sel:[0,1]
	v_pk_fma_f32 v[210:211], v[124:125], v[136:137], v[174:175]
	v_pk_fma_f32 v[212:213], v[126:127], v[138:139], v[176:177]
	v_pk_fma_f32 v[214:215], v[120:121], v[140:141], v[178:179]
	v_pk_fma_f32 v[216:217], v[122:123], v[142:143], v[180:181]
	v_fmac_f32_dpp v210, v124, v128 row_shr:1 row_mask:0xf bank_mask:0xf
	v_fmac_f32_dpp v211, v125, v129 row_shr:1 row_mask:0xf bank_mask:0xf
	v_fmac_f32_dpp v212, v126, v130 row_shr:1 row_mask:0xf bank_mask:0xf
	v_fmac_f32_dpp v213, v127, v131 row_shr:1 row_mask:0xf bank_mask:0xf
	v_fmac_f32_dpp v214, v120, v132 row_shr:1 row_mask:0xf bank_mask:0xf
	v_fmac_f32_dpp v215, v121, v133 row_shr:1 row_mask:0xf bank_mask:0xf
	v_fmac_f32_dpp v216, v122, v134 row_shr:1 row_mask:0xf bank_mask:0xf
	v_fmac_f32_dpp v217, v123, v135 row_shr:1 row_mask:0xf bank_mask:0xf
	v_fmac_f32_dpp v210, v124, v88 row_shr:2 row_mask:0xf bank_mask:0xf
	v_fmac_f32_dpp v211, v125, v89 row_shr:2 row_mask:0xf bank_mask:0xf
	v_fmac_f32_dpp v212, v126, v90 row_shr:2 row_mask:0xf bank_mask:0xf
	v_fmac_f32_dpp v213, v127, v91 row_shr:2 row_mask:0xf bank_mask:0xf
	v_fmac_f32_dpp v214, v120, v92 row_shr:2 row_mask:0xf bank_mask:0xf
	v_fmac_f32_dpp v215, v121, v93 row_shr:2 row_mask:0xf bank_mask:0xf
	v_fmac_f32_dpp v216, v122, v94 row_shr:2 row_mask:0xf bank_mask:0xf
	v_fmac_f32_dpp v217, v123, v95 row_shr:2 row_mask:0xf bank_mask:0xf
	v_fmac_f32_dpp v210, v152, v128 row_shl:15 row_mask:0xf bank_mask:0xf
	v_fmac_f32_dpp v211, v153, v129 row_shl:15 row_mask:0xf bank_mask:0xf
	v_fmac_f32_dpp v212, v154, v130 row_shl:15 row_mask:0xf bank_mask:0xf
	v_fmac_f32_dpp v213, v155, v131 row_shl:15 row_mask:0xf bank_mask:0xf
	v_fmac_f32_dpp v214, v144, v132 row_shl:15 row_mask:0xf bank_mask:0xf
	v_fmac_f32_dpp v215, v145, v133 row_shl:15 row_mask:0xf bank_mask:0xf
	v_fmac_f32_dpp v216, v146, v134 row_shl:15 row_mask:0xf bank_mask:0xf
	v_fmac_f32_dpp v217, v147, v135 row_shl:15 row_mask:0xf bank_mask:0xf
	v_fmac_f32_dpp v210, v152, v88 row_shl:14 row_mask:0xf bank_mask:0xf
	v_fmac_f32_dpp v211, v153, v89 row_shl:14 row_mask:0xf bank_mask:0xf
	v_fmac_f32_dpp v212, v154, v90 row_shl:14 row_mask:0xf bank_mask:0xf
	v_fmac_f32_dpp v213, v155, v91 row_shl:14 row_mask:0xf bank_mask:0xf
	v_fmac_f32_dpp v214, v144, v92 row_shl:14 row_mask:0xf bank_mask:0xf
	v_fmac_f32_dpp v215, v145, v93 row_shl:14 row_mask:0xf bank_mask:0xf
	v_fmac_f32_dpp v216, v146, v94 row_shl:14 row_mask:0xf bank_mask:0xf
	v_fmac_f32_dpp v217, v147, v95 row_shl:14 row_mask:0xf bank_mask:0xf
	v_exp_f32_e32 v218, v210
	v_exp_f32_e32 v219, v211
	v_exp_f32_e32 v220, v212
	v_exp_f32_e32 v221, v213
	v_exp_f32_e32 v222, v214
	v_exp_f32_e32 v223, v215
	v_exp_f32_e32 v224, v216
	v_exp_f32_e32 v225, v217
	v_pk_fma_f32 v[218:219], v[218:219], v[202:203], v[202:203] op_sel:[0,1,1]
	v_pk_fma_f32 v[220:221], v[220:221], v[202:203], v[202:203] op_sel:[0,1,1]
	v_pk_fma_f32 v[222:223], v[222:223], v[202:203], v[202:203] op_sel:[0,1,1]
	v_pk_fma_f32 v[224:225], v[224:225], v[202:203], v[202:203] op_sel:[0,1,1]
	v_rcp_f32_e32 v218, v218
	v_rcp_f32_e32 v219, v219
	v_rcp_f32_e32 v220, v220
	v_rcp_f32_e32 v221, v221
	v_rcp_f32_e32 v222, v222
	v_rcp_f32_e32 v223, v223
	v_rcp_f32_e32 v224, v224
	v_rcp_f32_e32 v225, v225
	v_pk_mul_f32 v[210:211], v[210:211], v[218:219]
	v_pk_mul_f32 v[212:213], v[212:213], v[220:221]
	v_pk_mul_f32 v[214:215], v[214:215], v[222:223]
	v_pk_mul_f32 v[216:217], v[216:217], v[224:225]
	v_pk_mul_f32 v[116:117], v[210:211], v[116:117]
	v_pk_mul_f32 v[118:119], v[212:213], v[118:119]
	v_pk_mul_f32 v[112:113], v[214:215], v[112:113]
	v_pk_mul_f32 v[114:115], v[216:217], v[114:115]
	v_cvt_pk_bf16_f32 v226, v116, v117
	v_cvt_pk_bf16_f32 v227, v118, v119
	v_cvt_pk_bf16_f32 v228, v112, v113
	v_cvt_pk_bf16_f32 v229, v114, v115
	v_add_u32_e32 v234, 0x16000, v230
	global_store_dwordx4 v234, v[226:229], s[96:97] nt
	v_pk_mul_f32 v[108:109], v[108:109], v[184:185] op_sel_hi:[1,0]
	v_pk_mul_f32 v[110:111], v[110:111], v[184:185] op_sel_hi:[1,0]
	v_pk_mul_f32 v[104:105], v[104:105], v[184:185] op_sel_hi:[1,0]
	v_pk_mul_f32 v[106:107], v[106:107], v[184:185] op_sel_hi:[1,0]
	v_pk_fma_f32 v[210:211], v[108:109], v[136:137], v[174:175]
	v_pk_fma_f32 v[212:213], v[110:111], v[138:139], v[176:177]
;     __device__ __forceinline__ void operator()(const Acc& acc, const Unit& u, int wr, int wc, int fr, int fq, LAS unsigned char* lds, f32x4 epar) const {
;     ...
;             for (int m = 0; m < 4; ++m) {
;                 const int r = u.pm * BM + ai * HALF + wr * 64 + m * 16 + fr;
;                 const float rs = __builtin_amdgcn_rsqf(sq[ai][m] * (1.0f / DM) + RMS_EPS);
;                 float X[NV], Y[NV], o[NV];
;                 if (MODE == 0) {
; #pragma unroll
;                     for (int n = 0; n < 2; ++n)
; #pragma unroll
;                         for (int j = 0; j < 4; ++j) { X[n * 4 + j] = acc[ai][0][m][n][j] * rs; Y[n * 4 + j] = acc[ai][1][m][n][j] * rs; }
;                 } else {
; #pragma unroll
;                     for (int j = 0; j < 4; ++j) { X[j] = (acc[ai][0][m][1][j] * rs) * (acc[ai][1][m][0][j] * rs); Y[j] = acc[ai][0][m][0][j] * rs; }
;                 }
; #pragma unroll
;                 for (int i = 0; i < NV; ++i) {
;                     const float a1 = dpp_rot<0x121>(X[i]), a2 = dpp_rot<0x122>(X[i]);
;                     const float q1 = fr >= 1 ? a1 : p1prev[i], q2 = fr >= 2 ? a2 : p2prev[i];
;                     p1prev[i] = a1; p2prev[i] = a2;
;                     const float cv = w2[i] * X[i] + w1[i] * q1 + w0[i] * q2 + bb[i];
;                     o[i] = MODE == 0 ? silu_f(cv) * Y[i] : cv * Y[i];
;                 }
;                 if (m == 0 && fr < 2) {
;                     bf16_t* hx = halo + ((size_t)strip * 6 + 2 + fr) * C + c0; bf16_t* hy = halo + ((size_t)strip * 6 + 4 + fr) * C + c0;
;                     u32x4 px, py; px.x = cvt_pk_bf16(X[0], X[1]); px.y = cvt_pk_bf16(X[2], X[3]); px.z = cvt_pk_bf16(X[4 % NV], X[5 % NV]); px.w = cvt_pk_bf16(X[6 % NV], X[7 % NV]);
;                     py.x = cvt_pk_bf16(Y[0], Y[1]); py.y = cvt_pk_bf16(Y[2], Y[3]); py.z = cvt_pk_bf16(Y[4 % NV], Y[5 % NV]); py.w = cvt_pk_bf16(Y[6 % NV], Y[7 % NV]);
;                     if (MODE == 0) { *(u32x4*)hx = px; *(u32x4*)hy = py; } else { u32x2 a; a.x = px.x; a.y = px.y; *(u32x2*)hx = a; u32x2 b; b.x = py.x; b.y = py.y; *(u32x2*)hy = b; }
;                 } else {
;                     if (MODE == 0) { u32x4 w; w.x = cvt_pk_bf16(o[0], o[1]); w.y = cvt_pk_bf16(o[2], o[3]); w.z = cvt_pk_bf16(o[4 % NV], o[5 % NV]); w.w = cvt_pk_bf16(o[6 % NV], o[7 % NV]);
	v_pk_fma_f32 v[214:215], v[104:105], v[140:141], v[178:179]
	v_pk_fma_f32 v[216:217], v[106:107], v[142:143], v[180:181]
	v_fmac_f32_dpp v210, v108, v128 row_shr:1 row_mask:0xf bank_mask:0xf
	v_fmac_f32_dpp v211, v109, v129 row_shr:1 row_mask:0xf bank_mask:0xf
	v_fmac_f32_dpp v212, v110, v130 row_shr:1 row_mask:0xf bank_mask:0xf
	v_fmac_f32_dpp v213, v111, v131 row_shr:1 row_mask:0xf bank_mask:0xf
	v_fmac_f32_dpp v214, v104, v132 row_shr:1 row_mask:0xf bank_mask:0xf
	v_fmac_f32_dpp v215, v105, v133 row_shr:1 row_mask:0xf bank_mask:0xf
	v_fmac_f32_dpp v216, v106, v134 row_shr:1 row_mask:0xf bank_mask:0xf
	v_fmac_f32_dpp v217, v107, v135 row_shr:1 row_mask:0xf bank_mask:0xf
	v_fmac_f32_dpp v210, v108, v88 row_shr:2 row_mask:0xf bank_mask:0xf
	v_fmac_f32_dpp v211, v109, v89 row_shr:2 row_mask:0xf bank_mask:0xf
	v_fmac_f32_dpp v212, v110, v90 row_shr:2 row_mask:0xf bank_mask:0xf
	v_fmac_f32_dpp v213, v111, v91 row_shr:2 row_mask:0xf bank_mask:0xf
	v_fmac_f32_dpp v214, v104, v92 row_shr:2 row_mask:0xf bank_mask:0xf
	v_fmac_f32_dpp v215, v105, v93 row_shr:2 row_mask:0xf bank_mask:0xf
	v_fmac_f32_dpp v216, v106, v94 row_shr:2 row_mask:0xf bank_mask:0xf
	v_fmac_f32_dpp v217, v107, v95 row_shr:2 row_mask:0xf bank_mask:0xf
	v_fmac_f32_dpp v210, v124, v128 row_shl:15 row_mask:0xf bank_mask:0xf
	v_fmac_f32_dpp v211, v125, v129 row_shl:15 row_mask:0xf bank_mask:0xf
	v_fmac_f32_dpp v212, v126, v130 row_shl:15 row_mask:0xf bank_mask:0xf
	v_fmac_f32_dpp v213, v127, v131 row_shl:15 row_mask:0xf bank_mask:0xf
	v_fmac_f32_dpp v214, v120, v132 row_shl:15 row_mask:0xf bank_mask:0xf
	v_fmac_f32_dpp v215, v121, v133 row_shl:15 row_mask:0xf bank_mask:0xf
	v_fmac_f32_dpp v216, v122, v134 row_shl:15 row_mask:0xf bank_mask:0xf
	v_fmac_f32_dpp v217, v123, v135 row_shl:15 row_mask:0xf bank_mask:0xf
	v_fmac_f32_dpp v210, v124, v88 row_shl:14 row_mask:0xf bank_mask:0xf
	v_fmac_f32_dpp v211, v125, v89 row_shl:14 row_mask:0xf bank_mask:0xf
	v_fmac_f32_dpp v212, v126, v90 row_shl:14 row_mask:0xf bank_mask:0xf
	v_fmac_f32_dpp v213, v127, v91 row_shl:14 row_mask:0xf bank_mask:0xf
	v_fmac_f32_dpp v214, v120, v92 row_shl:14 row_mask:0xf bank_mask:0xf
	v_fmac_f32_dpp v215, v121, v93 row_shl:14 row_mask:0xf bank_mask:0xf
	v_fmac_f32_dpp v216, v122, v94 row_shl:14 row_mask:0xf bank_mask:0xf
	v_fmac_f32_dpp v217, v123, v95 row_shl:14 row_mask:0xf bank_mask:0xf
	v_exp_f32_e32 v218, v210
	v_exp_f32_e32 v219, v211
	v_exp_f32_e32 v220, v212
	v_exp_f32_e32 v221, v213
	v_exp_f32_e32 v222, v214
	v_exp_f32_e32 v223, v215
	v_exp_f32_e32 v224, v216
	v_exp_f32_e32 v225, v217
	v_pk_fma_f32 v[218:219], v[218:219], v[204:205], v[204:205] op_sel_hi:[1,0,0]
	v_pk_fma_f32 v[220:221], v[220:221], v[204:205], v[204:205] op_sel_hi:[1,0,0]
	v_pk_fma_f32 v[222:223], v[222:223], v[204:205], v[204:205] op_sel_hi:[1,0,0]
	v_pk_fma_f32 v[224:225], v[224:225], v[204:205], v[204:205] op_sel_hi:[1,0,0]
	v_rcp_f32_e32 v218, v218
	v_rcp_f32_e32 v219, v219
	v_rcp_f32_e32 v220, v220
	v_rcp_f32_e32 v221, v221
	v_rcp_f32_e32 v222, v222
	v_rcp_f32_e32 v223, v223
	v_rcp_f32_e32 v224, v224
	v_rcp_f32_e32 v225, v225
	v_pk_mul_f32 v[210:211], v[210:211], v[218:219]
	v_pk_mul_f32 v[212:213], v[212:213], v[220:221]
	v_pk_mul_f32 v[214:215], v[214:215], v[222:223]
	v_pk_mul_f32 v[216:217], v[216:217], v[224:225]
	v_pk_mul_f32 v[100:101], v[210:211], v[100:101]
	v_pk_mul_f32 v[102:103], v[212:213], v[102:103]
	v_pk_mul_f32 v[96:97], v[214:215], v[96:97]
	v_pk_mul_f32 v[98:99], v[216:217], v[98:99]
	v_cvt_pk_bf16_f32 v226, v100, v101
	v_cvt_pk_bf16_f32 v227, v102, v103
	v_cvt_pk_bf16_f32 v228, v96, v97
	v_cvt_pk_bf16_f32 v229, v98, v99
	v_add_u32_e32 v234, 0x2c000, v230
	global_store_dwordx4 v234, v[226:229], s[96:97] nt
	v_pk_mul_f32 v[84:85], v[84:85], v[184:185] op_sel:[0,1]
	v_pk_mul_f32 v[86:87], v[86:87], v[184:185] op_sel:[0,1]
	v_pk_mul_f32 v[80:81], v[80:81], v[184:185] op_sel:[0,1]
	v_pk_mul_f32 v[82:83], v[82:83], v[184:185] op_sel:[0,1]
	v_pk_fma_f32 v[210:211], v[84:85], v[136:137], v[174:175]
	v_pk_fma_f32 v[212:213], v[86:87], v[138:139], v[176:177]
	v_pk_fma_f32 v[214:215], v[80:81], v[140:141], v[178:179]
	v_pk_fma_f32 v[216:217], v[82:83], v[142:143], v[180:181]
	v_cvt_pk_bf16_f32 v236, v84, v85
	v_cvt_pk_bf16_f32 v237, v86, v87
	v_cvt_pk_bf16_f32 v238, v80, v81
	v_cvt_pk_bf16_f32 v239, v82, v83
	v_add_u32_e32 v235, 0xfffecc00, v233
	s_and_b64 exec, exec, s[10:11]
	global_store_dwordx4 v235, v[236:239], s[42:43]
	s_mov_b64 exec, s[24:25]
	v_fmac_f32_dpp v210, v84, v128 row_shr:1 row_mask:0xf bank_mask:0xf
	v_fmac_f32_dpp v211, v85, v129 row_shr:1 row_mask:0xf bank_mask:0xf
	v_fmac_f32_dpp v212, v86, v130 row_shr:1 row_mask:0xf bank_mask:0xf
	v_fmac_f32_dpp v213, v87, v131 row_shr:1 row_mask:0xf bank_mask:0xf
	v_fmac_f32_dpp v214, v80, v132 row_shr:1 row_mask:0xf bank_mask:0xf
	v_fmac_f32_dpp v215, v81, v133 row_shr:1 row_mask:0xf bank_mask:0xf
	v_fmac_f32_dpp v216, v82, v134 row_shr:1 row_mask:0xf bank_mask:0xf
	v_fmac_f32_dpp v217, v83, v135 row_shr:1 row_mask:0xf bank_mask:0xf
	v_fmac_f32_dpp v210, v84, v88 row_shr:2 row_mask:0xf bank_mask:0xf
	v_fmac_f32_dpp v211, v85, v89 row_shr:2 row_mask:0xf bank_mask:0xf
	v_fmac_f32_dpp v212, v86, v90 row_shr:2 row_mask:0xf bank_mask:0xf
	v_fmac_f32_dpp v213, v87, v91 row_shr:2 row_mask:0xf bank_mask:0xf
	v_fmac_f32_dpp v214, v80, v92 row_shr:2 row_mask:0xf bank_mask:0xf
	v_fmac_f32_dpp v215, v81, v93 row_shr:2 row_mask:0xf bank_mask:0xf
	v_fmac_f32_dpp v216, v82, v94 row_shr:2 row_mask:0xf bank_mask:0xf
	v_fmac_f32_dpp v217, v83, v95 row_shr:2 row_mask:0xf bank_mask:0xf
	v_fmac_f32_dpp v210, v108, v128 row_shl:15 row_mask:0xf bank_mask:0xf
;     __device__ __forceinline__ void operator()(const Acc& acc, const Unit& u, int wr, int wc, int fr, int fq, LAS unsigned char* lds, f32x4 epar) const {
;     ...
;             for (int m = 0; m < 4; ++m) {
;                 const int r = u.pm * BM + ai * HALF + wr * 64 + m * 16 + fr;
;                 const float rs = __builtin_amdgcn_rsqf(sq[ai][m] * (1.0f / DM) + RMS_EPS);
;                 float X[NV], Y[NV], o[NV];
;                 if (MODE == 0) {
; #pragma unroll
;                     for (int n = 0; n < 2; ++n)
; #pragma unroll
;                         for (int j = 0; j < 4; ++j) { X[n * 4 + j] = acc[ai][0][m][n][j] * rs; Y[n * 4 + j] = acc[ai][1][m][n][j] * rs; }
;                 } else {
; #pragma unroll
;                     for (int j = 0; j < 4; ++j) { X[j] = (acc[ai][0][m][1][j] * rs) * (acc[ai][1][m][0][j] * rs); Y[j] = acc[ai][0][m][0][j] * rs; }
;                 }
; #pragma unroll
;                 for (int i = 0; i < NV; ++i) {
;                     const float a1 = dpp_rot<0x121>(X[i]), a2 = dpp_rot<0x122>(X[i]);
;                     const float q1 = fr >= 1 ? a1 : p1prev[i], q2 = fr >= 2 ? a2 : p2prev[i];
;                     p1prev[i] = a1; p2prev[i] = a2;
;                     const float cv = w2[i] * X[i] + w1[i] * q1 + w0[i] * q2 + bb[i];
;                     o[i] = MODE == 0 ? silu_f(cv) * Y[i] : cv * Y[i];
;                 }
;                 if (m == 0 && fr < 2) {
;                     bf16_t* hx = halo + ((size_t)strip * 6 + 2 + fr) * C + c0; bf16_t* hy = halo + ((size_t)strip * 6 + 4 + fr) * C + c0;
;                     u32x4 px, py; px.x = cvt_pk_bf16(X[0], X[1]); px.y = cvt_pk_bf16(X[2], X[3]); px.z = cvt_pk_bf16(X[4 % NV], X[5 % NV]); px.w = cvt_pk_bf16(X[6 % NV], X[7 % NV]);
;                     py.x = cvt_pk_bf16(Y[0], Y[1]); py.y = cvt_pk_bf16(Y[2], Y[3]); py.z = cvt_pk_bf16(Y[4 % NV], Y[5 % NV]); py.w = cvt_pk_bf16(Y[6 % NV], Y[7 % NV]);
;                     if (MODE == 0) { *(u32x4*)hx = px; *(u32x4*)hy = py; } else { u32x2 a; a.x = px.x; a.y = px.y; *(u32x2*)hx = a; u32x2 b; b.x = py.x; b.y = py.y; *(u32x2*)hy = b; }
;                 } else {
;                     if (MODE == 0) { u32x4 w; w.x = cvt_pk_bf16(o[0], o[1]); w.y = cvt_pk_bf16(o[2], o[3]); w.z = cvt_pk_bf16(o[4 % NV], o[5 % NV]); w.w = cvt_pk_bf16(o[6 % NV], o[7 % NV]);
	v_fmac_f32_dpp v211, v109, v129 row_shl:15 row_mask:0xf bank_mask:0xf
	v_fmac_f32_dpp v212, v110, v130 row_shl:15 row_mask:0xf bank_mask:0xf
	v_fmac_f32_dpp v213, v111, v131 row_shl:15 row_mask:0xf bank_mask:0xf
	v_fmac_f32_dpp v214, v104, v132 row_shl:15 row_mask:0xf bank_mask:0xf
	v_fmac_f32_dpp v215, v105, v133 row_shl:15 row_mask:0xf bank_mask:0xf
	v_fmac_f32_dpp v216, v106, v134 row_shl:15 row_mask:0xf bank_mask:0xf
	v_fmac_f32_dpp v217, v107, v135 row_shl:15 row_mask:0xf bank_mask:0xf
	v_fmac_f32_dpp v210, v108, v88 row_shl:14 row_mask:0xf bank_mask:0xf
	v_fmac_f32_dpp v211, v109, v89 row_shl:14 row_mask:0xf bank_mask:0xf
	v_fmac_f32_dpp v212, v110, v90 row_shl:14 row_mask:0xf bank_mask:0xf
	v_fmac_f32_dpp v213, v111, v91 row_shl:14 row_mask:0xf bank_mask:0xf
	v_fmac_f32_dpp v214, v104, v92 row_shl:14 row_mask:0xf bank_mask:0xf
	v_fmac_f32_dpp v215, v105, v93 row_shl:14 row_mask:0xf bank_mask:0xf
	v_fmac_f32_dpp v216, v106, v94 row_shl:14 row_mask:0xf bank_mask:0xf
	v_fmac_f32_dpp v217, v107, v95 row_shl:14 row_mask:0xf bank_mask:0xf
	v_exp_f32_e32 v218, v210
	v_exp_f32_e32 v219, v211
	v_exp_f32_e32 v220, v212
	v_exp_f32_e32 v221, v213
	v_exp_f32_e32 v222, v214
	v_exp_f32_e32 v223, v215
	v_exp_f32_e32 v224, v216
	v_exp_f32_e32 v225, v217
	v_pk_fma_f32 v[218:219], v[218:219], v[204:205], v[204:205] op_sel:[0,1,1]
	v_pk_fma_f32 v[220:221], v[220:221], v[204:205], v[204:205] op_sel:[0,1,1]
	v_pk_fma_f32 v[222:223], v[222:223], v[204:205], v[204:205] op_sel:[0,1,1]
	v_pk_fma_f32 v[224:225], v[224:225], v[204:205], v[204:205] op_sel:[0,1,1]
	v_rcp_f32_e32 v218, v218
	v_rcp_f32_e32 v219, v219
	v_rcp_f32_e32 v220, v220
	v_rcp_f32_e32 v221, v221
	v_rcp_f32_e32 v222, v222
	v_rcp_f32_e32 v223, v223
	v_rcp_f32_e32 v224, v224
	v_rcp_f32_e32 v225, v225
	v_pk_mul_f32 v[210:211], v[210:211], v[218:219]
	v_pk_mul_f32 v[212:213], v[212:213], v[220:221]
	v_pk_mul_f32 v[214:215], v[214:215], v[222:223]
	v_pk_mul_f32 v[216:217], v[216:217], v[224:225]
	v_pk_mul_f32 v[68:69], v[210:211], v[68:69]
	v_pk_mul_f32 v[70:71], v[212:213], v[70:71]
	v_pk_mul_f32 v[64:65], v[214:215], v[64:65]
	v_pk_mul_f32 v[66:67], v[216:217], v[66:67]
	v_cvt_pk_bf16_f32 v226, v68, v69
	v_cvt_pk_bf16_f32 v227, v70, v71
	v_cvt_pk_bf16_f32 v228, v64, v65
	v_cvt_pk_bf16_f32 v229, v66, v67
	v_add_u32_e32 v234, 0x42000, v230
	global_store_dwordx4 v234, v[226:229], s[96:97] nt
	v_pk_mul_f32 v[60:61], v[60:61], v[76:77] op_sel_hi:[1,0]
	v_pk_mul_f32 v[62:63], v[62:63], v[76:77] op_sel_hi:[1,0]
	v_pk_mul_f32 v[52:53], v[52:53], v[76:77] op_sel_hi:[1,0]
	v_pk_mul_f32 v[54:55], v[54:55], v[76:77] op_sel_hi:[1,0]
	v_pk_fma_f32 v[210:211], v[60:61], v[136:137], v[174:175]
	v_pk_fma_f32 v[212:213], v[62:63], v[138:139], v[176:177]
	v_pk_fma_f32 v[214:215], v[52:53], v[140:141], v[178:179]
	v_pk_fma_f32 v[216:217], v[54:55], v[142:143], v[180:181]
	v_pk_mul_f32 v[218:219], v[56:57], v[76:77] op_sel_hi:[1,0]
	v_pk_mul_f32 v[220:221], v[58:59], v[76:77] op_sel_hi:[1,0]
	v_pk_mul_f32 v[222:223], v[48:49], v[76:77] op_sel_hi:[1,0]
	v_pk_mul_f32 v[224:225], v[50:51], v[76:77] op_sel_hi:[1,0]
	v_cvt_pk_bf16_f32 v236, v60, v61
	v_cvt_pk_bf16_f32 v237, v62, v63
	v_cvt_pk_bf16_f32 v238, v52, v53
	v_cvt_pk_bf16_f32 v239, v54, v55
	v_cvt_pk_bf16_f32 v240, v218, v219
	v_cvt_pk_bf16_f32 v241, v220, v221
	v_cvt_pk_bf16_f32 v242, v222, v223
	v_cvt_pk_bf16_f32 v243, v224, v225
	v_add_u32_e32 v234, 0x13400, v233
	v_add_u32_e32 v235, 0x16000, v233
	s_andn2_b64 exec, exec, s[8:9]
	global_store_dwordx4 v234, v[236:239], s[42:43]
	global_store_dwordx4 v235, v[240:243], s[42:43]
	s_mov_b64 exec, s[24:25]
	v_fmac_f32_dpp v210, v60, v128 row_shr:1 row_mask:0xf bank_mask:0xf
	v_fmac_f32_dpp v211, v61, v129 row_shr:1 row_mask:0xf bank_mask:0xf
	v_fmac_f32_dpp v212, v62, v130 row_shr:1 row_mask:0xf bank_mask:0xf
	v_fmac_f32_dpp v213, v63, v131 row_shr:1 row_mask:0xf bank_mask:0xf
	v_fmac_f32_dpp v214, v52, v132 row_shr:1 row_mask:0xf bank_mask:0xf
	v_fmac_f32_dpp v215, v53, v133 row_shr:1 row_mask:0xf bank_mask:0xf
	v_fmac_f32_dpp v216, v54, v134 row_shr:1 row_mask:0xf bank_mask:0xf
	v_fmac_f32_dpp v217, v55, v135 row_shr:1 row_mask:0xf bank_mask:0xf
	v_fmac_f32_dpp v210, v60, v88 row_shr:2 row_mask:0xf bank_mask:0xf
	v_fmac_f32_dpp v211, v61, v89 row_shr:2 row_mask:0xf bank_mask:0xf
	v_fmac_f32_dpp v212, v62, v90 row_shr:2 row_mask:0xf bank_mask:0xf
	v_fmac_f32_dpp v213, v63, v91 row_shr:2 row_mask:0xf bank_mask:0xf
	v_fmac_f32_dpp v214, v52, v92 row_shr:2 row_mask:0xf bank_mask:0xf
	v_fmac_f32_dpp v215, v53, v93 row_shr:2 row_mask:0xf bank_mask:0xf
	v_fmac_f32_dpp v216, v54, v94 row_shr:2 row_mask:0xf bank_mask:0xf
	v_fmac_f32_dpp v217, v55, v95 row_shr:2 row_mask:0xf bank_mask:0xf
	v_exp_f32_e32 v218, v210
	v_exp_f32_e32 v219, v211
	v_exp_f32_e32 v220, v212
	v_exp_f32_e32 v221, v213
	v_exp_f32_e32 v222, v214
	v_exp_f32_e32 v223, v215
	v_exp_f32_e32 v224, v216
	v_exp_f32_e32 v225, v217
	v_pk_fma_f32 v[218:219], v[218:219], v[206:207], v[206:207] op_sel_hi:[1,0,0]
	v_pk_fma_f32 v[220:221], v[220:221], v[206:207], v[206:207] op_sel_hi:[1,0,0]
	v_pk_fma_f32 v[222:223], v[222:223], v[206:207], v[206:207] op_sel_hi:[1,0,0]
	v_pk_fma_f32 v[224:225], v[224:225], v[206:207], v[206:207] op_sel_hi:[1,0,0]
	v_rcp_f32_e32 v218, v218
	v_rcp_f32_e32 v219, v219
	v_rcp_f32_e32 v220, v220
	v_rcp_f32_e32 v221, v221
	v_rcp_f32_e32 v222, v222
	v_rcp_f32_e32 v223, v223
	v_rcp_f32_e32 v224, v224
	v_rcp_f32_e32 v225, v225
	v_pk_mul_f32 v[210:211], v[210:211], v[218:219]
	v_pk_mul_f32 v[212:213], v[212:213], v[220:221]
	v_pk_mul_f32 v[214:215], v[214:215], v[222:223]
	v_pk_mul_f32 v[216:217], v[216:217], v[224:225]
;     __device__ __forceinline__ void operator()(const Acc& acc, const Unit& u, int wr, int wc, int fr, int fq, LAS unsigned char* lds, f32x4 epar) const {
;     ...
;             for (int m = 0; m < 4; ++m) {
;                 const int r = u.pm * BM + ai * HALF + wr * 64 + m * 16 + fr;
;                 const float rs = __builtin_amdgcn_rsqf(sq[ai][m] * (1.0f / DM) + RMS_EPS);
;                 float X[NV], Y[NV], o[NV];
;                 if (MODE == 0) {
; #pragma unroll
;                     for (int n = 0; n < 2; ++n)
; #pragma unroll
;                         for (int j = 0; j < 4; ++j) { X[n * 4 + j] = acc[ai][0][m][n][j] * rs; Y[n * 4 + j] = acc[ai][1][m][n][j] * rs; }
;                 } else {
; #pragma unroll
;                     for (int j = 0; j < 4; ++j) { X[j] = (acc[ai][0][m][1][j] * rs) * (acc[ai][1][m][0][j] * rs); Y[j] = acc[ai][0][m][0][j] * rs; }
;                 }
; #pragma unroll
;                 for (int i = 0; i < NV; ++i) {
;                     const float a1 = dpp_rot<0x121>(X[i]), a2 = dpp_rot<0x122>(X[i]);
;                     const float q1 = fr >= 1 ? a1 : p1prev[i], q2 = fr >= 2 ? a2 : p2prev[i];
;                     p1prev[i] = a1; p2prev[i] = a2;
;                     const float cv = w2[i] * X[i] + w1[i] * q1 + w0[i] * q2 + bb[i];
;                     o[i] = MODE == 0 ? silu_f(cv) * Y[i] : cv * Y[i];
;                 }
;                 if (m == 0 && fr < 2) {
;                     bf16_t* hx = halo + ((size_t)strip * 6 + 2 + fr) * C + c0; bf16_t* hy = halo + ((size_t)strip * 6 + 4 + fr) * C + c0;
;                     u32x4 px, py; px.x = cvt_pk_bf16(X[0], X[1]); px.y = cvt_pk_bf16(X[2], X[3]); px.z = cvt_pk_bf16(X[4 % NV], X[5 % NV]); px.w = cvt_pk_bf16(X[6 % NV], X[7 % NV]);
;                     py.x = cvt_pk_bf16(Y[0], Y[1]); py.y = cvt_pk_bf16(Y[2], Y[3]); py.z = cvt_pk_bf16(Y[4 % NV], Y[5 % NV]); py.w = cvt_pk_bf16(Y[6 % NV], Y[7 % NV]);
;                     if (MODE == 0) { *(u32x4*)hx = px; *(u32x4*)hy = py; } else { u32x2 a; a.x = px.x; a.y = px.y; *(u32x2*)hx = a; u32x2 b; b.x = py.x; b.y = py.y; *(u32x2*)hy = b; }
;                 } else {
;                     if (MODE == 0) { u32x4 w; w.x = cvt_pk_bf16(o[0], o[1]); w.y = cvt_pk_bf16(o[2], o[3]); w.z = cvt_pk_bf16(o[4 % NV], o[5 % NV]); w.w = cvt_pk_bf16(o[6 % NV], o[7 % NV]);
	v_pk_mul_f32 v[56:57], v[210:211], v[56:57]
	v_pk_mul_f32 v[58:59], v[212:213], v[58:59]
	v_pk_mul_f32 v[48:49], v[214:215], v[48:49]
	v_pk_mul_f32 v[50:51], v[216:217], v[50:51]
	v_cvt_pk_bf16_f32 v226, v56, v57
	v_cvt_pk_bf16_f32 v227, v58, v59
	v_cvt_pk_bf16_f32 v228, v48, v49
	v_cvt_pk_bf16_f32 v229, v50, v51
	v_add_u32_e32 v234, 0xb0000, v230
	s_and_b64 exec, exec, s[8:9]
	global_store_dwordx4 v234, v[226:229], s[96:97] nt
	s_mov_b64 exec, s[24:25]
	v_pk_mul_f32 v[44:45], v[44:45], v[76:77] op_sel:[0,1]
	v_pk_mul_f32 v[46:47], v[46:47], v[76:77] op_sel:[0,1]
	v_pk_mul_f32 v[40:41], v[40:41], v[76:77] op_sel:[0,1]
	v_pk_mul_f32 v[42:43], v[42:43], v[76:77] op_sel:[0,1]
	v_pk_fma_f32 v[210:211], v[44:45], v[136:137], v[174:175]
	v_pk_fma_f32 v[212:213], v[46:47], v[138:139], v[176:177]
	v_pk_fma_f32 v[214:215], v[40:41], v[140:141], v[178:179]
	v_pk_fma_f32 v[216:217], v[42:43], v[142:143], v[180:181]
	v_fmac_f32_dpp v210, v44, v128 row_shr:1 row_mask:0xf bank_mask:0xf
	v_fmac_f32_dpp v211, v45, v129 row_shr:1 row_mask:0xf bank_mask:0xf
	v_fmac_f32_dpp v212, v46, v130 row_shr:1 row_mask:0xf bank_mask:0xf
	v_fmac_f32_dpp v213, v47, v131 row_shr:1 row_mask:0xf bank_mask:0xf
	v_fmac_f32_dpp v214, v40, v132 row_shr:1 row_mask:0xf bank_mask:0xf
	v_fmac_f32_dpp v215, v41, v133 row_shr:1 row_mask:0xf bank_mask:0xf
	v_fmac_f32_dpp v216, v42, v134 row_shr:1 row_mask:0xf bank_mask:0xf
	v_fmac_f32_dpp v217, v43, v135 row_shr:1 row_mask:0xf bank_mask:0xf
	v_fmac_f32_dpp v210, v44, v88 row_shr:2 row_mask:0xf bank_mask:0xf
	v_fmac_f32_dpp v211, v45, v89 row_shr:2 row_mask:0xf bank_mask:0xf
	v_fmac_f32_dpp v212, v46, v90 row_shr:2 row_mask:0xf bank_mask:0xf
	v_fmac_f32_dpp v213, v47, v91 row_shr:2 row_mask:0xf bank_mask:0xf
	v_fmac_f32_dpp v214, v40, v92 row_shr:2 row_mask:0xf bank_mask:0xf
	v_fmac_f32_dpp v215, v41, v93 row_shr:2 row_mask:0xf bank_mask:0xf
	v_fmac_f32_dpp v216, v42, v94 row_shr:2 row_mask:0xf bank_mask:0xf
	v_fmac_f32_dpp v217, v43, v95 row_shr:2 row_mask:0xf bank_mask:0xf
	v_fmac_f32_dpp v210, v60, v128 row_shl:15 row_mask:0xf bank_mask:0xf
	v_fmac_f32_dpp v211, v61, v129 row_shl:15 row_mask:0xf bank_mask:0xf
	v_fmac_f32_dpp v212, v62, v130 row_shl:15 row_mask:0xf bank_mask:0xf
	v_fmac_f32_dpp v213, v63, v131 row_shl:15 row_mask:0xf bank_mask:0xf
	v_fmac_f32_dpp v214, v52, v132 row_shl:15 row_mask:0xf bank_mask:0xf
	v_fmac_f32_dpp v215, v53, v133 row_shl:15 row_mask:0xf bank_mask:0xf
	v_fmac_f32_dpp v216, v54, v134 row_shl:15 row_mask:0xf bank_mask:0xf
	v_fmac_f32_dpp v217, v55, v135 row_shl:15 row_mask:0xf bank_mask:0xf
	v_fmac_f32_dpp v210, v60, v88 row_shl:14 row_mask:0xf bank_mask:0xf
	v_fmac_f32_dpp v211, v61, v89 row_shl:14 row_mask:0xf bank_mask:0xf
	v_fmac_f32_dpp v212, v62, v90 row_shl:14 row_mask:0xf bank_mask:0xf
	v_fmac_f32_dpp v213, v63, v91 row_shl:14 row_mask:0xf bank_mask:0xf
	v_fmac_f32_dpp v214, v52, v92 row_shl:14 row_mask:0xf bank_mask:0xf
	v_fmac_f32_dpp v215, v53, v93 row_shl:14 row_mask:0xf bank_mask:0xf
	v_fmac_f32_dpp v216, v54, v94 row_shl:14 row_mask:0xf bank_mask:0xf
	v_fmac_f32_dpp v217, v55, v95 row_shl:14 row_mask:0xf bank_mask:0xf
	v_exp_f32_e32 v218, v210
	v_exp_f32_e32 v219, v211
	v_exp_f32_e32 v220, v212
	v_exp_f32_e32 v221, v213
	v_exp_f32_e32 v222, v214
	v_exp_f32_e32 v223, v215
	v_exp_f32_e32 v224, v216
	v_exp_f32_e32 v225, v217
	v_pk_fma_f32 v[218:219], v[218:219], v[206:207], v[206:207] op_sel:[0,1,1]
	v_pk_fma_f32 v[220:221], v[220:221], v[206:207], v[206:207] op_sel:[0,1,1]
	v_pk_fma_f32 v[222:223], v[222:223], v[206:207], v[206:207] op_sel:[0,1,1]
	v_pk_fma_f32 v[224:225], v[224:225], v[206:207], v[206:207] op_sel:[0,1,1]
	v_rcp_f32_e32 v218, v218
	v_rcp_f32_e32 v219, v219
	v_rcp_f32_e32 v220, v220
	v_rcp_f32_e32 v221, v221
	v_rcp_f32_e32 v222, v222
	v_rcp_f32_e32 v223, v223
	v_rcp_f32_e32 v224, v224
	v_rcp_f32_e32 v225, v225
	v_pk_mul_f32 v[210:211], v[210:211], v[218:219]
	v_pk_mul_f32 v[212:213], v[212:213], v[220:221]
	v_pk_mul_f32 v[214:215], v[214:215], v[222:223]
	v_pk_mul_f32 v[216:217], v[216:217], v[224:225]
	v_pk_mul_f32 v[36:37], v[210:211], v[36:37]
	v_pk_mul_f32 v[38:39], v[212:213], v[38:39]
	v_pk_mul_f32 v[32:33], v[214:215], v[32:33]
	v_pk_mul_f32 v[34:35], v[216:217], v[34:35]
	v_cvt_pk_bf16_f32 v226, v36, v37
	v_cvt_pk_bf16_f32 v227, v38, v39
	v_cvt_pk_bf16_f32 v228, v32, v33
	v_cvt_pk_bf16_f32 v229, v34, v35
	v_add_u32_e32 v234, 0xc6000, v230
	global_store_dwordx4 v234, v[226:229], s[96:97] nt
	v_pk_mul_f32 v[28:29], v[28:29], v[78:79] op_sel_hi:[1,0]
	v_pk_mul_f32 v[30:31], v[30:31], v[78:79] op_sel_hi:[1,0]
	v_pk_mul_f32 v[24:25], v[24:25], v[78:79] op_sel_hi:[1,0]
	v_pk_mul_f32 v[26:27], v[26:27], v[78:79] op_sel_hi:[1,0]
	v_pk_fma_f32 v[210:211], v[28:29], v[136:137], v[174:175]
	v_pk_fma_f32 v[212:213], v[30:31], v[138:139], v[176:177]
	v_pk_fma_f32 v[214:215], v[24:25], v[140:141], v[178:179]
	v_pk_fma_f32 v[216:217], v[26:27], v[142:143], v[180:181]
	v_fmac_f32_dpp v210, v28, v128 row_shr:1 row_mask:0xf bank_mask:0xf
	v_fmac_f32_dpp v211, v29, v129 row_shr:1 row_mask:0xf bank_mask:0xf
	v_fmac_f32_dpp v212, v30, v130 row_shr:1 row_mask:0xf bank_mask:0xf
	v_fmac_f32_dpp v213, v31, v131 row_shr:1 row_mask:0xf bank_mask:0xf
	v_fmac_f32_dpp v214, v24, v132 row_shr:1 row_mask:0xf bank_mask:0xf
	v_fmac_f32_dpp v215, v25, v133 row_shr:1 row_mask:0xf bank_mask:0xf
	v_fmac_f32_dpp v216, v26, v134 row_shr:1 row_mask:0xf bank_mask:0xf
	v_fmac_f32_dpp v217, v27, v135 row_shr:1 row_mask:0xf bank_mask:0xf
	v_fmac_f32_dpp v210, v28, v88 row_shr:2 row_mask:0xf bank_mask:0xf
	v_fmac_f32_dpp v211, v29, v89 row_shr:2 row_mask:0xf bank_mask:0xf
;     __device__ __forceinline__ void operator()(const Acc& acc, const Unit& u, int wr, int wc, int fr, int fq, LAS unsigned char* lds, f32x4 epar) const {
;     ...
;             for (int m = 0; m < 4; ++m) {
;                 const int r = u.pm * BM + ai * HALF + wr * 64 + m * 16 + fr;
;                 const float rs = __builtin_amdgcn_rsqf(sq[ai][m] * (1.0f / DM) + RMS_EPS);
;                 float X[NV], Y[NV], o[NV];
;                 if (MODE == 0) {
; #pragma unroll
;                     for (int n = 0; n < 2; ++n)
; #pragma unroll
;                         for (int j = 0; j < 4; ++j) { X[n * 4 + j] = acc[ai][0][m][n][j] * rs; Y[n * 4 + j] = acc[ai][1][m][n][j] * rs; }
;                 } else {
; #pragma unroll
;                     for (int j = 0; j < 4; ++j) { X[j] = (acc[ai][0][m][1][j] * rs) * (acc[ai][1][m][0][j] * rs); Y[j] = acc[ai][0][m][0][j] * rs; }
;                 }
; #pragma unroll
;                 for (int i = 0; i < NV; ++i) {
;                     const float a1 = dpp_rot<0x121>(X[i]), a2 = dpp_rot<0x122>(X[i]);
;                     const float q1 = fr >= 1 ? a1 : p1prev[i], q2 = fr >= 2 ? a2 : p2prev[i];
;                     p1prev[i] = a1; p2prev[i] = a2;
;                     const float cv = w2[i] * X[i] + w1[i] * q1 + w0[i] * q2 + bb[i];
;                     o[i] = MODE == 0 ? silu_f(cv) * Y[i] : cv * Y[i];
;                 }
;                 if (m == 0 && fr < 2) {
;                     bf16_t* hx = halo + ((size_t)strip * 6 + 2 + fr) * C + c0; bf16_t* hy = halo + ((size_t)strip * 6 + 4 + fr) * C + c0;
;                     u32x4 px, py; px.x = cvt_pk_bf16(X[0], X[1]); px.y = cvt_pk_bf16(X[2], X[3]); px.z = cvt_pk_bf16(X[4 % NV], X[5 % NV]); px.w = cvt_pk_bf16(X[6 % NV], X[7 % NV]);
;                     py.x = cvt_pk_bf16(Y[0], Y[1]); py.y = cvt_pk_bf16(Y[2], Y[3]); py.z = cvt_pk_bf16(Y[4 % NV], Y[5 % NV]); py.w = cvt_pk_bf16(Y[6 % NV], Y[7 % NV]);
;                     if (MODE == 0) { *(u32x4*)hx = px; *(u32x4*)hy = py; } else { u32x2 a; a.x = px.x; a.y = px.y; *(u32x2*)hx = a; u32x2 b; b.x = py.x; b.y = py.y; *(u32x2*)hy = b; }
;                 } else {
;                     if (MODE == 0) { u32x4 w; w.x = cvt_pk_bf16(o[0], o[1]); w.y = cvt_pk_bf16(o[2], o[3]); w.z = cvt_pk_bf16(o[4 % NV], o[5 % NV]); w.w = cvt_pk_bf16(o[6 % NV], o[7 % NV]);
	v_fmac_f32_dpp v212, v30, v90 row_shr:2 row_mask:0xf bank_mask:0xf
	v_fmac_f32_dpp v213, v31, v91 row_shr:2 row_mask:0xf bank_mask:0xf
	v_fmac_f32_dpp v214, v24, v92 row_shr:2 row_mask:0xf bank_mask:0xf
	v_fmac_f32_dpp v215, v25, v93 row_shr:2 row_mask:0xf bank_mask:0xf
	v_fmac_f32_dpp v216, v26, v94 row_shr:2 row_mask:0xf bank_mask:0xf
	v_fmac_f32_dpp v217, v27, v95 row_shr:2 row_mask:0xf bank_mask:0xf
	v_fmac_f32_dpp v210, v44, v128 row_shl:15 row_mask:0xf bank_mask:0xf
	v_fmac_f32_dpp v211, v45, v129 row_shl:15 row_mask:0xf bank_mask:0xf
	v_fmac_f32_dpp v212, v46, v130 row_shl:15 row_mask:0xf bank_mask:0xf
	v_fmac_f32_dpp v213, v47, v131 row_shl:15 row_mask:0xf bank_mask:0xf
	v_fmac_f32_dpp v214, v40, v132 row_shl:15 row_mask:0xf bank_mask:0xf
	v_fmac_f32_dpp v215, v41, v133 row_shl:15 row_mask:0xf bank_mask:0xf
	v_fmac_f32_dpp v216, v42, v134 row_shl:15 row_mask:0xf bank_mask:0xf
	v_fmac_f32_dpp v217, v43, v135 row_shl:15 row_mask:0xf bank_mask:0xf
	v_fmac_f32_dpp v210, v44, v88 row_shl:14 row_mask:0xf bank_mask:0xf
	v_fmac_f32_dpp v211, v45, v89 row_shl:14 row_mask:0xf bank_mask:0xf
	v_fmac_f32_dpp v212, v46, v90 row_shl:14 row_mask:0xf bank_mask:0xf
	v_fmac_f32_dpp v213, v47, v91 row_shl:14 row_mask:0xf bank_mask:0xf
	v_fmac_f32_dpp v214, v40, v92 row_shl:14 row_mask:0xf bank_mask:0xf
	v_fmac_f32_dpp v215, v41, v93 row_shl:14 row_mask:0xf bank_mask:0xf
	v_fmac_f32_dpp v216, v42, v94 row_shl:14 row_mask:0xf bank_mask:0xf
	v_fmac_f32_dpp v217, v43, v95 row_shl:14 row_mask:0xf bank_mask:0xf
	v_exp_f32_e32 v218, v210
	v_exp_f32_e32 v219, v211
	v_exp_f32_e32 v220, v212
	v_exp_f32_e32 v221, v213
	v_exp_f32_e32 v222, v214
	v_exp_f32_e32 v223, v215
	v_exp_f32_e32 v224, v216
	v_exp_f32_e32 v225, v217
	v_pk_fma_f32 v[218:219], v[218:219], v[208:209], v[208:209] op_sel_hi:[1,0,0]
	v_pk_fma_f32 v[220:221], v[220:221], v[208:209], v[208:209] op_sel_hi:[1,0,0]
	v_pk_fma_f32 v[222:223], v[222:223], v[208:209], v[208:209] op_sel_hi:[1,0,0]
	v_pk_fma_f32 v[224:225], v[224:225], v[208:209], v[208:209] op_sel_hi:[1,0,0]
	v_rcp_f32_e32 v218, v218
	v_rcp_f32_e32 v219, v219
	v_rcp_f32_e32 v220, v220
	v_rcp_f32_e32 v221, v221
	v_rcp_f32_e32 v222, v222
	v_rcp_f32_e32 v223, v223
	v_rcp_f32_e32 v224, v224
	v_rcp_f32_e32 v225, v225
	v_pk_mul_f32 v[210:211], v[210:211], v[218:219]
	v_pk_mul_f32 v[212:213], v[212:213], v[220:221]
	v_pk_mul_f32 v[214:215], v[214:215], v[222:223]
	v_pk_mul_f32 v[216:217], v[216:217], v[224:225]
	v_pk_mul_f32 v[20:21], v[210:211], v[20:21]
	v_pk_mul_f32 v[22:23], v[212:213], v[22:23]
	v_pk_mul_f32 v[16:17], v[214:215], v[16:17]
	v_pk_mul_f32 v[18:19], v[216:217], v[18:19]
	v_cvt_pk_bf16_f32 v226, v20, v21
	v_cvt_pk_bf16_f32 v227, v22, v23
	v_cvt_pk_bf16_f32 v228, v16, v17
	v_cvt_pk_bf16_f32 v229, v18, v19
	v_add_u32_e32 v234, 0xdc000, v230
	global_store_dwordx4 v234, v[226:229], s[96:97] nt
	v_pk_mul_f32 v[12:13], v[12:13], v[78:79] op_sel:[0,1]
	v_pk_mul_f32 v[14:15], v[14:15], v[78:79] op_sel:[0,1]
	v_pk_mul_f32 v[8:9], v[8:9], v[78:79] op_sel:[0,1]
	v_pk_mul_f32 v[10:11], v[10:11], v[78:79] op_sel:[0,1]
	v_pk_fma_f32 v[210:211], v[12:13], v[136:137], v[174:175]
	v_pk_fma_f32 v[212:213], v[14:15], v[138:139], v[176:177]
	v_pk_fma_f32 v[214:215], v[8:9], v[140:141], v[178:179]
	v_pk_fma_f32 v[216:217], v[10:11], v[142:143], v[180:181]
	v_cvt_pk_bf16_f32 v236, v12, v13
	v_cvt_pk_bf16_f32 v237, v14, v15
	v_cvt_pk_bf16_f32 v238, v8, v9
	v_cvt_pk_bf16_f32 v239, v10, v11
	v_add_u32_e32 v235, 0xffffd400, v233
	s_and_b64 exec, exec, s[10:11]
	global_store_dwordx4 v235, v[236:239], s[42:43]
;     __device__ __forceinline__ void operator()(const Acc& acc, const Unit& u, int wr, int wc, int fr, int fq, LAS unsigned char* lds, f32x4 epar) const {
;     ...
;             for (int m = 0; m < 4; ++m) {
;                 const int r = u.pm * BM + ai * HALF + wr * 64 + m * 16 + fr;
;                 const float rs = __builtin_amdgcn_rsqf(sq[ai][m] * (1.0f / DM) + RMS_EPS);
;                 float X[NV], Y[NV], o[NV];
;                 if (MODE == 0) {
; #pragma unroll
;                     for (int n = 0; n < 2; ++n)
; #pragma unroll
;                         for (int j = 0; j < 4; ++j) { X[n * 4 + j] = acc[ai][0][m][n][j] * rs; Y[n * 4 + j] = acc[ai][1][m][n][j] * rs; }
;                 } else {
; #pragma unroll
;                     for (int j = 0; j < 4; ++j) { X[j] = (acc[ai][0][m][1][j] * rs) * (acc[ai][1][m][0][j] * rs); Y[j] = acc[ai][0][m][0][j] * rs; }
;                 }
; #pragma unroll
;                 for (int i = 0; i < NV; ++i) {
;                     const float a1 = dpp_rot<0x121>(X[i]), a2 = dpp_rot<0x122>(X[i]);
;                     const float q1 = fr >= 1 ? a1 : p1prev[i], q2 = fr >= 2 ? a2 : p2prev[i];
;                     p1prev[i] = a1; p2prev[i] = a2;
;                     const float cv = w2[i] * X[i] + w1[i] * q1 + w0[i] * q2 + bb[i];
;                     o[i] = MODE == 0 ? silu_f(cv) * Y[i] : cv * Y[i];
;                 }
;                 if (m == 0 && fr < 2) {
;                     bf16_t* hx = halo + ((size_t)strip * 6 + 2 + fr) * C + c0; bf16_t* hy = halo + ((size_t)strip * 6 + 4 + fr) * C + c0;
;                     u32x4 px, py; px.x = cvt_pk_bf16(X[0], X[1]); px.y = cvt_pk_bf16(X[2], X[3]); px.z = cvt_pk_bf16(X[4 % NV], X[5 % NV]); px.w = cvt_pk_bf16(X[6 % NV], X[7 % NV]);
;                     py.x = cvt_pk_bf16(Y[0], Y[1]); py.y = cvt_pk_bf16(Y[2], Y[3]); py.z = cvt_pk_bf16(Y[4 % NV], Y[5 % NV]); py.w = cvt_pk_bf16(Y[6 % NV], Y[7 % NV]);
;                     if (MODE == 0) { *(u32x4*)hx = px; *(u32x4*)hy = py; } else { u32x2 a; a.x = px.x; a.y = px.y; *(u32x2*)hx = a; u32x2 b; b.x = py.x; b.y = py.y; *(u32x2*)hy = b; }
;                 } else {
;                     if (MODE == 0) { u32x4 w; w.x = cvt_pk_bf16(o[0], o[1]); w.y = cvt_pk_bf16(o[2], o[3]); w.z = cvt_pk_bf16(o[4 % NV], o[5 % NV]); w.w = cvt_pk_bf16(o[6 % NV], o[7 % NV]);
	s_mov_b64 exec, s[24:25]
	v_fmac_f32_dpp v210, v12, v128 row_shr:1 row_mask:0xf bank_mask:0xf
	v_fmac_f32_dpp v211, v13, v129 row_shr:1 row_mask:0xf bank_mask:0xf
	v_fmac_f32_dpp v212, v14, v130 row_shr:1 row_mask:0xf bank_mask:0xf
	v_fmac_f32_dpp v213, v15, v131 row_shr:1 row_mask:0xf bank_mask:0xf
	v_fmac_f32_dpp v214, v8, v132 row_shr:1 row_mask:0xf bank_mask:0xf
	v_fmac_f32_dpp v215, v9, v133 row_shr:1 row_mask:0xf bank_mask:0xf
	v_fmac_f32_dpp v216, v10, v134 row_shr:1 row_mask:0xf bank_mask:0xf
	v_fmac_f32_dpp v217, v11, v135 row_shr:1 row_mask:0xf bank_mask:0xf
	v_fmac_f32_dpp v210, v12, v88 row_shr:2 row_mask:0xf bank_mask:0xf
	v_fmac_f32_dpp v211, v13, v89 row_shr:2 row_mask:0xf bank_mask:0xf
	v_fmac_f32_dpp v212, v14, v90 row_shr:2 row_mask:0xf bank_mask:0xf
	v_fmac_f32_dpp v213, v15, v91 row_shr:2 row_mask:0xf bank_mask:0xf
	v_fmac_f32_dpp v214, v8, v92 row_shr:2 row_mask:0xf bank_mask:0xf
	v_fmac_f32_dpp v215, v9, v93 row_shr:2 row_mask:0xf bank_mask:0xf
	v_fmac_f32_dpp v216, v10, v94 row_shr:2 row_mask:0xf bank_mask:0xf
	v_fmac_f32_dpp v217, v11, v95 row_shr:2 row_mask:0xf bank_mask:0xf
	v_fmac_f32_dpp v210, v28, v128 row_shl:15 row_mask:0xf bank_mask:0xf
	v_fmac_f32_dpp v211, v29, v129 row_shl:15 row_mask:0xf bank_mask:0xf
	v_fmac_f32_dpp v212, v30, v130 row_shl:15 row_mask:0xf bank_mask:0xf
	v_fmac_f32_dpp v213, v31, v131 row_shl:15 row_mask:0xf bank_mask:0xf
	v_fmac_f32_dpp v214, v24, v132 row_shl:15 row_mask:0xf bank_mask:0xf
	v_fmac_f32_dpp v215, v25, v133 row_shl:15 row_mask:0xf bank_mask:0xf
	v_fmac_f32_dpp v216, v26, v134 row_shl:15 row_mask:0xf bank_mask:0xf
	v_fmac_f32_dpp v217, v27, v135 row_shl:15 row_mask:0xf bank_mask:0xf
	v_fmac_f32_dpp v210, v28, v88 row_shl:14 row_mask:0xf bank_mask:0xf
	v_fmac_f32_dpp v211, v29, v89 row_shl:14 row_mask:0xf bank_mask:0xf
	v_fmac_f32_dpp v212, v30, v90 row_shl:14 row_mask:0xf bank_mask:0xf
	v_fmac_f32_dpp v213, v31, v91 row_shl:14 row_mask:0xf bank_mask:0xf
	v_fmac_f32_dpp v214, v24, v92 row_shl:14 row_mask:0xf bank_mask:0xf
	v_fmac_f32_dpp v215, v25, v93 row_shl:14 row_mask:0xf bank_mask:0xf
	v_fmac_f32_dpp v216, v26, v94 row_shl:14 row_mask:0xf bank_mask:0xf
	v_fmac_f32_dpp v217, v27, v95 row_shl:14 row_mask:0xf bank_mask:0xf
	v_exp_f32_e32 v218, v210
	v_exp_f32_e32 v219, v211
	v_exp_f32_e32 v220, v212
	v_exp_f32_e32 v221, v213
	v_exp_f32_e32 v222, v214
	v_exp_f32_e32 v223, v215
	v_exp_f32_e32 v224, v216
	v_exp_f32_e32 v225, v217
	v_pk_fma_f32 v[218:219], v[218:219], v[208:209], v[208:209] op_sel:[0,1,1]
	v_pk_fma_f32 v[220:221], v[220:221], v[208:209], v[208:209] op_sel:[0,1,1]
	v_pk_fma_f32 v[222:223], v[222:223], v[208:209], v[208:209] op_sel:[0,1,1]
	v_pk_fma_f32 v[224:225], v[224:225], v[208:209], v[208:209] op_sel:[0,1,1]
	v_rcp_f32_e32 v218, v218
	v_rcp_f32_e32 v219, v219
	v_rcp_f32_e32 v220, v220
	v_rcp_f32_e32 v221, v221
	v_rcp_f32_e32 v222, v222
	v_rcp_f32_e32 v223, v223
	v_rcp_f32_e32 v224, v224
	v_rcp_f32_e32 v225, v225
	v_pk_mul_f32 v[210:211], v[210:211], v[218:219]
	v_pk_mul_f32 v[212:213], v[212:213], v[220:221]
	v_pk_mul_f32 v[214:215], v[214:215], v[222:223]
	v_pk_mul_f32 v[216:217], v[216:217], v[224:225]
	v_pk_mul_f32 v[4:5], v[210:211], v[4:5]
	v_pk_mul_f32 v[6:7], v[212:213], v[6:7]
	v_pk_mul_f32 v[0:1], v[214:215], v[0:1]
	v_pk_mul_f32 v[2:3], v[216:217], v[2:3]
	v_cvt_pk_bf16_f32 v226, v4, v5
	v_cvt_pk_bf16_f32 v227, v6, v7
	v_cvt_pk_bf16_f32 v228, v0, v1
	v_cvt_pk_bf16_f32 v229, v2, v3
	v_add_u32_e32 v234, 0xf2000, v230
	global_store_dwordx4 v234, v[226:229], s[96:97] nt

; __device__ __forceinline__ float bf_lo(unsigned w) { return __uint_as_float(w << 16); }
; __device__ __forceinline__ float bf_hi(unsigned w) { return __uint_as_float(w & 0xffff0000u); }
; __device__ __forceinline__ int otid() { int t = threadIdx.x; asm volatile("" : "+v"(t)); return t; }
;     __device__ __forceinline__ bool next(int i, Unit& u) const { const long L = (long)i * G + c; if (L >= NG * 8) return false; u.g = (int)(L >> 3); u.pm = (int)(L & 7); u.pn = 0; return true; }
;     __device__ __forceinline__ bool next(int i, Unit& u) const { if (i >= 2) return false; u.g = g; u.pm = 2 * b + i; u.pn = 0; return true; }
; template <int MODE, class Sched> __device__ __forceinline__ void fixup_local(const bf16_t* halo, const float* cw, const float* cb, bf16_t* out, int C, const Sched& S) {
;     const int C4 = C >> 2, tid = otid(); Unit u;
;     for (int i = 0; S.next(i, u); ++i)
;         for (int c4 = tid; c4 < C4; c4 += 512) {
;             const int c = c4 * 4;
;             const f32x4 w0 = *(const f32x4*)(cw + c), w1 = *(const f32x4*)(cw + C + c), w2 = *(const f32x4*)(cw + 2 * C + c);
;             f32x4 bb = (f32x4){0.f, 0.f, 0.f, 0.f}; if (MODE == 0) bb = *(const f32x4*)(cb + c);
;             f32x4 t0[4], t1[4], h0[4], h1[4], y0[4], y1[4];
; #pragma unroll
;             for (int k = 0; k < 4; ++k) { const int s = 4 * u.pm + k; const bf16_t* hb = halo + (size_t)s * 6 * C + c; const bool first = (s & 127) == 0;
;                 const f32x4 z = (f32x4){0.f, 0.f, 0.f, 0.f};
;                 auto ld4 = [](const bf16_t* ptr) { const u32x2 w = *(const u32x2*)ptr; return (f32x4){bf_lo(w.x), bf_hi(w.x), bf_lo(w.y), bf_hi(w.y)}; };
;                 t0[k] = ld4(first ? hb : hb - (size_t)6 * C); t1[k] = ld4(first ? hb : hb - (size_t)5 * C);
;                 if (first) { t0[k] = z; t1[k] = z; }
;                 h0[k] = ld4(hb + (size_t)2 * C); h1[k] = ld4(hb + (size_t)3 * C);
;                 y0[k] = ld4(hb + (size_t)4 * C); y1[k] = ld4(hb + (size_t)5 * C); }
.LBB0_1032:
	s_or_b64 exec, exec, s[4:5]
	s_add_u32 s6, s54, 0xb000
	v_readlane_b32 s4, v252, 48
	s_addc_u32 s7, s55, 0
	s_mov_b32 s10, 4
	s_mov_b32 s2, s4
	s_add_u32 s8, s54, 0xdc00
	s_waitcnt lgkmcnt(0)
	s_barrier
	s_addc_u32 s9, s55, 0
	s_lshl_b32 s14, s10, 3
	s_abs_i32 s15, s14
	v_cvt_f32_u32_e32 v0, s15
	s_bfe_i32 s35, s10, 0x1001c
	s_sub_i32 s10, 0, s15
	v_readlane_b32 s5, v252, 49
	v_rcp_iflag_f32_e32 v0, v0
	v_mov_b32_e32 v1, v232
	s_movk_i32 s4, 0x2c0
	v_mul_f32_e32 v0, 0x4f7ffffe, v0
	v_cvt_u32_f32_e32 v0, v0
	v_cmp_gt_i32_e64 s[4:5], s4, v1
	s_ashr_i32 s33, s2, 31
	s_mov_b32 s59, 0
	v_readfirstlane_b32 s11, v0
	s_mul_i32 s10, s10, s11
	s_mul_hi_u32 s10, s11, s10
	s_add_i32 s58, s11, s10
	v_add_u32_e32 v60, 0xfffffe00, v1
	v_lshlrev_b32_e32 v61, 2, v1
	v_mov_b64_e32 v[16:17], 0x1ff
	s_movk_i32 s64, 0x2000
	s_movk_i32 s65, 0x4000
	s_movk_i32 s66, 0x5000
	s_movk_i32 s67, 0x6000
	s_movk_i32 s70, 0x8000
	s_movk_i32 s71, 0xa000
	s_movk_i32 s72, 0xbf
	s_cmp_lg_u32 s34, 0x100
	s_cbranch_scc1 .Lfix1_generic
	s_mov_b64 s[10:11], exec
	s_mov_b32 s12, 0xbfb8aa3b
	s_mov_b32 s13, 1.0
	v_lshlrev_b32_e32 v1, 3, v232
	v_add_u32_e32 v2, 0x1000, v1
	v_lshlrev_b32_e32 v3, 4, v232
	v_add_u32_e32 v4, 0x2000, v3
	v_mov_b32_e32 v5, 0xc0
	v_cmp_gt_u32_e64 s[30:31], v5, v232
	s_and_b32 s16, s2, 7
	s_lshl_b32 s16, s16, 4
	s_bfe_u32 s17, s2, 0x30003
	s_add_i32 s16, s16, s17
	global_load_dwordx4 v[8:11], v3, s[0:1]
	global_load_dwordx4 v[12:15], v3, s[6:7]
	global_load_dwordx4 v[16:19], v3, s[8:9]
	global_load_dwordx4 v[20:23], v3, s[40:41]
	s_add_i32 s17, s16, 0
	s_lshl_b32 s17, s17, 2
	s_mul_i32 s17, s17, 0x8400
	s_add_u32 s18, s42, s17
	s_addc_u32 s19, s43, 0
	s_add_i32 s17, s16, 0
	s_and_b32 s17, s17, 31
	s_cmp_eq_u32 s17, 0
	s_cselect_b32 s26, 0, 0x8400
	s_cselect_b32 s27, 0, 0x6e00
	s_sub_u32 s24, s18, s26
	s_subb_u32 s25, s19, 0
	global_load_dwordx2 v[40:41], v1, s[24:25]
	s_sub_u32 s24, s18, s27
	s_subb_u32 s25, s19, 0
	global_load_dwordx2 v[42:43], v1, s[24:25]
	s_add_u32 s24, s18, 0x2c00
	s_addc_u32 s25, s19, 0
	global_load_dwordx2 v[44:45], v1, s[24:25]
	s_add_u32 s24, s18, 0x4200
	s_addc_u32 s25, s19, 0
	global_load_dwordx2 v[46:47], v1, s[24:25]
	s_add_u32 s24, s18, 0x5800
	s_addc_u32 s25, s19, 0
	global_load_dwordx2 v[48:49], v1, s[24:25]
	s_add_u32 s24, s18, 0x6e00
	s_addc_u32 s25, s19, 0
	global_load_dwordx2 v[50:51], v1, s[24:25]
	s_add_i32 s17, s16, 0
	s_lshl_b32 s17, s17, 2
	s_add_i32 s17, s17, 1
	s_mul_i32 s17, s17, 0x8400
	s_add_u32 s18, s42, s17
	s_addc_u32 s19, s43, 0
	s_mov_b32 s26, 0x8400
	s_mov_b32 s27, 0x6e00
	s_sub_u32 s24, s18, s26
	s_subb_u32 s25, s19, 0
	global_load_dwordx2 v[52:53], v1, s[24:25]
	s_sub_u32 s24, s18, s27
	s_subb_u32 s25, s19, 0
	global_load_dwordx2 v[54:55], v1, s[24:25]
	s_add_u32 s24, s18, 0x2c00
	s_addc_u32 s25, s19, 0
	global_load_dwordx2 v[56:57], v1, s[24:25]
	s_add_u32 s24, s18, 0x4200
	s_addc_u32 s25, s19, 0
	global_load_dwordx2 v[58:59], v1, s[24:25]
	s_add_u32 s24, s18, 0x5800
	s_addc_u32 s25, s19, 0
	global_load_dwordx2 v[60:61], v1, s[24:25]
	s_add_u32 s24, s18, 0x6e00
	s_addc_u32 s25, s19, 0
	global_load_dwordx2 v[62:63], v1, s[24:25]
	s_add_i32 s17, s16, 0
	s_lshl_b32 s17, s17, 2
	s_add_i32 s17, s17, 2
	s_mul_i32 s17, s17, 0x8400
	s_add_u32 s18, s42, s17
	s_addc_u32 s19, s43, 0
	s_mov_b32 s26, 0x8400
	s_mov_b32 s27, 0x6e00
	s_sub_u32 s24, s18, s26
	s_subb_u32 s25, s19, 0
	global_load_dwordx2 v[64:65], v1, s[24:25]
	s_sub_u32 s24, s18, s27
	s_subb_u32 s25, s19, 0
	global_load_dwordx2 v[66:67], v1, s[24:25]
	s_add_u32 s24, s18, 0x2c00
	s_addc_u32 s25, s19, 0
	global_load_dwordx2 v[68:69], v1, s[24:25]
	s_add_u32 s24, s18, 0x4200
	s_addc_u32 s25, s19, 0
	global_load_dwordx2 v[70:71], v1, s[24:25]
	s_add_u32 s24, s18, 0x5800
	s_addc_u32 s25, s19, 0
	global_load_dwordx2 v[72:73], v1, s[24:25]
	s_add_u32 s24, s18, 0x6e00
	s_addc_u32 s25, s19, 0
	global_load_dwordx2 v[74:75], v1, s[24:25]
	s_add_i32 s17, s16, 0
	s_lshl_b32 s17, s17, 2
	s_add_i32 s17, s17, 3
	s_mul_i32 s17, s17, 0x8400
	s_add_u32 s18, s42, s17
	s_addc_u32 s19, s43, 0
	s_mov_b32 s26, 0x8400
	s_mov_b32 s27, 0x6e00
	s_sub_u32 s24, s18, s26
	s_subb_u32 s25, s19, 0
	global_load_dwordx2 v[76:77], v1, s[24:25]
	s_sub_u32 s24, s18, s27
	s_subb_u32 s25, s19, 0
	global_load_dwordx2 v[78:79], v1, s[24:25]
	s_add_u32 s24, s18, 0x2c00
	s_addc_u32 s25, s19, 0
	global_load_dwordx2 v[80:81], v1, s[24:25]
	s_add_u32 s24, s18, 0x4200
	s_addc_u32 s25, s19, 0
	global_load_dwordx2 v[82:83], v1, s[24:25]
	s_add_u32 s24, s18, 0x5800
	s_addc_u32 s25, s19, 0
	global_load_dwordx2 v[84:85], v1, s[24:25]
	s_add_u32 s24, s18, 0x6e00
	s_addc_u32 s25, s19, 0
	global_load_dwordx2 v[86:87], v1, s[24:25]
	s_add_i32 s17, s16, 8
	s_lshl_b32 s17, s17, 2
	s_mul_i32 s17, s17, 0x8400
	s_add_u32 s18, s42, s17
	s_addc_u32 s19, s43, 0
	s_add_i32 s17, s16, 8
	s_and_b32 s17, s17, 31
	s_cmp_eq_u32 s17, 0
	s_cselect_b32 s26, 0, 0x8400
	s_cselect_b32 s27, 0, 0x6e00
	s_sub_u32 s24, s18, s26
	s_subb_u32 s25, s19, 0
	global_load_dwordx2 v[88:89], v1, s[24:25]
	s_sub_u32 s24, s18, s27
	s_subb_u32 s25, s19, 0
	global_load_dwordx2 v[90:91], v1, s[24:25]
	s_add_u32 s24, s18, 0x2c00
	s_addc_u32 s25, s19, 0
	global_load_dwordx2 v[92:93], v1, s[24:25]
	s_add_u32 s24, s18, 0x4200
	s_addc_u32 s25, s19, 0
	global_load_dwordx2 v[94:95], v1, s[24:25]
	s_add_u32 s24, s18, 0x5800
	s_addc_u32 s25, s19, 0
	global_load_dwordx2 v[96:97], v1, s[24:25]
	s_add_u32 s24, s18, 0x6e00
	s_addc_u32 s25, s19, 0
	global_load_dwordx2 v[98:99], v1, s[24:25]
	s_add_i32 s17, s16, 8
	s_lshl_b32 s17, s17, 2
	s_add_i32 s17, s17, 1
	s_mul_i32 s17, s17, 0x8400
	s_add_u32 s18, s42, s17
	s_addc_u32 s19, s43, 0
; __device__ __forceinline__ unsigned cvt_pk_bf16(float lo, float hi) { unsigned r; asm volatile("v_cvt_pk_bf16_f32 %0, %1, %2" : "=v"(r) : "v"(lo), "v"(hi)); return r; }
; __device__ __forceinline__ float bf_lo(unsigned w) { return __uint_as_float(w << 16); }
; __device__ __forceinline__ float bf_hi(unsigned w) { return __uint_as_float(w & 0xffff0000u); }
; __device__ __forceinline__ float silu_f(float x) { return x * __builtin_amdgcn_rcpf(1.0f + __builtin_amdgcn_exp2f(x * -1.44269504f)); }
; template <int MODE, class Sched> __device__ __forceinline__ void fixup_local(const bf16_t* halo, const float* cw, const float* cb, bf16_t* out, int C, const Sched& S) {
;     ...
;             for (int k = 0; k < 4; ++k) { const int s = 4 * u.pm + k; const bf16_t* hb = halo + (size_t)s * 6 * C + c; const bool first = (s & 127) == 0;
;                 const f32x4 z = (f32x4){0.f, 0.f, 0.f, 0.f};
;                 auto ld4 = [](const bf16_t* ptr) { const u32x2 w = *(const u32x2*)ptr; return (f32x4){bf_lo(w.x), bf_hi(w.x), bf_lo(w.y), bf_hi(w.y)}; };
;                 t0[k] = ld4(first ? hb : hb - (size_t)6 * C); t1[k] = ld4(first ? hb : hb - (size_t)5 * C);
;                 if (first) { t0[k] = z; t1[k] = z; }
;                 h0[k] = ld4(hb + (size_t)2 * C); h1[k] = ld4(hb + (size_t)3 * C);
;                 y0[k] = ld4(hb + (size_t)4 * C); y1[k] = ld4(hb + (size_t)5 * C); }
; #pragma unroll
;             for (int k = 0; k < 4; ++k) { const int s = 4 * u.pm + k; float o0[4], o1[4];
; #pragma unroll
;                 for (int j = 0; j < 4; ++j) {
;                     const float cv0 = w2[j] * h0[k][j] + w1[j] * t1[k][j] + w0[j] * t0[k][j] + bb[j];
;                     const float cv1 = w2[j] * h1[k][j] + w1[j] * h0[k][j] + w0[j] * t1[k][j] + bb[j];
;                     o0[j] = MODE == 0 ? silu_f(cv0) * y0[k][j] : cv0 * y0[k][j]; o1[j] = MODE == 0 ? silu_f(cv1) * y1[k][j] : cv1 * y1[k][j]; }
;                 u32x2 a; a.x = cvt_pk_bf16(o0[0], o0[1]); a.y = cvt_pk_bf16(o0[2], o0[3]); u32x2 b; b.x = cvt_pk_bf16(o1[0], o1[1]); b.y = cvt_pk_bf16(o1[2], o1[3]);
;                 *(u32x2*)(out + ((size_t)s * 64) * C + c) = a; *(u32x2*)(out + ((size_t)s * 64 + 1) * C + c) = b; }
	s_mov_b32 s26, 0x8400
	s_mov_b32 s27, 0x6e00
	s_sub_u32 s24, s18, s26
	s_subb_u32 s25, s19, 0
	global_load_dwordx2 v[100:101], v1, s[24:25]
	s_sub_u32 s24, s18, s27
	s_subb_u32 s25, s19, 0
	global_load_dwordx2 v[102:103], v1, s[24:25]
	s_add_u32 s24, s18, 0x2c00
	s_addc_u32 s25, s19, 0
	global_load_dwordx2 v[104:105], v1, s[24:25]
	s_add_u32 s24, s18, 0x4200
	s_addc_u32 s25, s19, 0
	global_load_dwordx2 v[106:107], v1, s[24:25]
	s_add_u32 s24, s18, 0x5800
	s_addc_u32 s25, s19, 0
	global_load_dwordx2 v[108:109], v1, s[24:25]
	s_add_u32 s24, s18, 0x6e00
	s_addc_u32 s25, s19, 0
	global_load_dwordx2 v[110:111], v1, s[24:25]
	s_add_i32 s17, s16, 8
	s_lshl_b32 s17, s17, 2
	s_add_i32 s17, s17, 2
	s_mul_i32 s17, s17, 0x8400
	s_add_u32 s18, s42, s17
	s_addc_u32 s19, s43, 0
	s_mov_b32 s26, 0x8400
	s_mov_b32 s27, 0x6e00
	s_sub_u32 s24, s18, s26
	s_subb_u32 s25, s19, 0
	global_load_dwordx2 v[112:113], v1, s[24:25]
	s_sub_u32 s24, s18, s27
	s_subb_u32 s25, s19, 0
	global_load_dwordx2 v[114:115], v1, s[24:25]
	s_add_u32 s24, s18, 0x2c00
	s_addc_u32 s25, s19, 0
	global_load_dwordx2 v[116:117], v1, s[24:25]
	s_add_u32 s24, s18, 0x4200
	s_addc_u32 s25, s19, 0
	global_load_dwordx2 v[118:119], v1, s[24:25]
	s_add_u32 s24, s18, 0x5800
	s_addc_u32 s25, s19, 0
	global_load_dwordx2 v[120:121], v1, s[24:25]
	s_add_u32 s24, s18, 0x6e00
	s_addc_u32 s25, s19, 0
	global_load_dwordx2 v[122:123], v1, s[24:25]
	s_add_i32 s17, s16, 8
	s_lshl_b32 s17, s17, 2
	s_add_i32 s17, s17, 3
	s_mul_i32 s17, s17, 0x8400
	s_add_u32 s18, s42, s17
	s_addc_u32 s19, s43, 0
	s_mov_b32 s26, 0x8400
	s_mov_b32 s27, 0x6e00
	s_sub_u32 s24, s18, s26
	s_subb_u32 s25, s19, 0
	global_load_dwordx2 v[124:125], v1, s[24:25]
	s_sub_u32 s24, s18, s27
	s_subb_u32 s25, s19, 0
	global_load_dwordx2 v[126:127], v1, s[24:25]
	s_add_u32 s24, s18, 0x2c00
	s_addc_u32 s25, s19, 0
	global_load_dwordx2 v[128:129], v1, s[24:25]
	s_add_u32 s24, s18, 0x4200
	s_addc_u32 s25, s19, 0
	global_load_dwordx2 v[130:131], v1, s[24:25]
	s_add_u32 s24, s18, 0x5800
	s_addc_u32 s25, s19, 0
	global_load_dwordx2 v[132:133], v1, s[24:25]
	s_add_u32 s24, s18, 0x6e00
	s_addc_u32 s25, s19, 0
	global_load_dwordx2 v[134:135], v1, s[24:25]
	s_waitcnt vmcnt(24)
	s_add_i32 s17, s16, 0
	s_and_b32 s17, s17, 31
	s_cmp_lg_u32 s17, 0
	s_cbranch_scc1 .Lfix1_nz2
	v_mov_b32_e32 v40, 0
	v_mov_b32_e32 v41, 0
	v_mov_b32_e32 v42, 0
	v_mov_b32_e32 v43, 0
.Lfix1_nz2:
	v_lshlrev_b32_e32 v136, 16, v41
	v_and_b32_e32 v137, 0xffff0000, v41
	v_and_b32_e32 v41, 0xffff0000, v40
	v_lshlrev_b32_e32 v40, 16, v40
	v_lshlrev_b32_e32 v138, 16, v43
	v_and_b32_e32 v139, 0xffff0000, v43
	v_and_b32_e32 v43, 0xffff0000, v42
	v_lshlrev_b32_e32 v42, 16, v42
	v_lshlrev_b32_e32 v140, 16, v45
	v_and_b32_e32 v141, 0xffff0000, v45
	v_and_b32_e32 v45, 0xffff0000, v44
	v_lshlrev_b32_e32 v44, 16, v44
	v_lshlrev_b32_e32 v142, 16, v47
	v_and_b32_e32 v143, 0xffff0000, v47
	v_and_b32_e32 v47, 0xffff0000, v46
	v_lshlrev_b32_e32 v46, 16, v46
	v_lshlrev_b32_e32 v144, 16, v49
	v_and_b32_e32 v145, 0xffff0000, v49
	v_and_b32_e32 v49, 0xffff0000, v48
	v_lshlrev_b32_e32 v48, 16, v48
	v_lshlrev_b32_e32 v146, 16, v51
	v_and_b32_e32 v147, 0xffff0000, v51
	v_and_b32_e32 v51, 0xffff0000, v50
	v_lshlrev_b32_e32 v50, 16, v50
	v_pk_mul_f32 v[148:149], v[16:17], v[44:45]
	v_pk_mul_f32 v[150:151], v[18:19], v[140:141]
	v_pk_mul_f32 v[152:153], v[16:17], v[46:47]
	v_pk_mul_f32 v[154:155], v[18:19], v[142:143]
	v_pk_fma_f32 v[148:149], v[12:13], v[42:43], v[148:149]
	v_pk_fma_f32 v[150:151], v[14:15], v[138:139], v[150:151]
	v_pk_fma_f32 v[152:153], v[12:13], v[44:45], v[152:153]
	v_pk_fma_f32 v[154:155], v[14:15], v[140:141], v[154:155]
	v_pk_fma_f32 v[148:149], v[8:9], v[40:41], v[148:149]
	v_pk_fma_f32 v[150:151], v[10:11], v[136:137], v[150:151]
	v_pk_fma_f32 v[152:153], v[8:9], v[42:43], v[152:153]
	v_pk_fma_f32 v[154:155], v[10:11], v[138:139], v[154:155]
	v_pk_add_f32 v[148:149], v[148:149], v[20:21]
	v_pk_add_f32 v[150:151], v[150:151], v[22:23]
	v_pk_add_f32 v[152:153], v[152:153], v[20:21]
	v_pk_add_f32 v[154:155], v[154:155], v[22:23]
	v_pk_mul_f32 v[156:157], v[148:149], s[12:13] op_sel_hi:[1,0]
	v_pk_mul_f32 v[158:159], v[150:151], s[12:13] op_sel_hi:[1,0]
	v_pk_mul_f32 v[160:161], v[152:153], s[12:13] op_sel_hi:[1,0]
	v_pk_mul_f32 v[162:163], v[154:155], s[12:13] op_sel_hi:[1,0]
	v_exp_f32_e32 v156, v156
	v_exp_f32_e32 v157, v157
	v_exp_f32_e32 v158, v158
	v_exp_f32_e32 v159, v159
	v_exp_f32_e32 v160, v160
	v_exp_f32_e32 v161, v161
	v_exp_f32_e32 v162, v162
	v_exp_f32_e32 v163, v163
	v_pk_add_f32 v[156:157], v[156:157], s[12:13] op_sel:[0,1]
	v_pk_add_f32 v[158:159], v[158:159], s[12:13] op_sel:[0,1]
	v_pk_add_f32 v[160:161], v[160:161], s[12:13] op_sel:[0,1]
	v_pk_add_f32 v[162:163], v[162:163], s[12:13] op_sel:[0,1]
	v_rcp_f32_e32 v156, v156
	v_rcp_f32_e32 v157, v157
	v_rcp_f32_e32 v158, v158
	v_rcp_f32_e32 v159, v159
	v_rcp_f32_e32 v160, v160
	v_rcp_f32_e32 v161, v161
	v_rcp_f32_e32 v162, v162
	v_rcp_f32_e32 v163, v163
	v_pk_mul_f32 v[148:149], v[148:149], v[156:157]
	v_pk_mul_f32 v[150:151], v[150:151], v[158:159]
	v_pk_mul_f32 v[152:153], v[152:153], v[160:161]
	v_pk_mul_f32 v[154:155], v[154:155], v[162:163]
	v_pk_mul_f32 v[148:149], v[148:149], v[48:49]
	v_pk_mul_f32 v[150:151], v[150:151], v[144:145]
	v_pk_mul_f32 v[152:153], v[152:153], v[50:51]
	v_pk_mul_f32 v[154:155], v[154:155], v[146:147]
	v_cvt_pk_bf16_f32 v164, v148, v149
	v_cvt_pk_bf16_f32 v165, v150, v151
	v_cvt_pk_bf16_f32 v166, v152, v153
	v_cvt_pk_bf16_f32 v167, v154, v155
	s_add_i32 s17, s16, 0
	s_lshl_b32 s17, s17, 2
	s_mul_i32 s17, s17, 0x58000
	s_add_u32 s36, s96, s17
	s_addc_u32 s37, s97, 0
	s_add_u32 s38, s36, 0x1600
; __device__ __forceinline__ unsigned cvt_pk_bf16(float lo, float hi) { unsigned r; asm volatile("v_cvt_pk_bf16_f32 %0, %1, %2" : "=v"(r) : "v"(lo), "v"(hi)); return r; }
; __device__ __forceinline__ float silu_f(float x) { return x * __builtin_amdgcn_rcpf(1.0f + __builtin_amdgcn_exp2f(x * -1.44269504f)); }
; template <int MODE, class Sched> __device__ __forceinline__ void fixup_local(const bf16_t* halo, const float* cw, const float* cb, bf16_t* out, int C, const Sched& S) {
;     ...
;                 y0[k] = ld4(hb + (size_t)4 * C); y1[k] = ld4(hb + (size_t)5 * C); }
; #pragma unroll
;             for (int k = 0; k < 4; ++k) { const int s = 4 * u.pm + k; float o0[4], o1[4];
; #pragma unroll
;                 for (int j = 0; j < 4; ++j) {
;                     const float cv0 = w2[j] * h0[k][j] + w1[j] * t1[k][j] + w0[j] * t0[k][j] + bb[j];
;                     const float cv1 = w2[j] * h1[k][j] + w1[j] * h0[k][j] + w0[j] * t1[k][j] + bb[j];
;                     o0[j] = MODE == 0 ? silu_f(cv0) * y0[k][j] : cv0 * y0[k][j]; o1[j] = MODE == 0 ? silu_f(cv1) * y1[k][j] : cv1 * y1[k][j]; }
;                 u32x2 a; a.x = cvt_pk_bf16(o0[0], o0[1]); a.y = cvt_pk_bf16(o0[2], o0[3]); u32x2 b; b.x = cvt_pk_bf16(o1[0], o1[1]); b.y = cvt_pk_bf16(o1[2], o1[3]);
;                 *(u32x2*)(out + ((size_t)s * 64) * C + c) = a; *(u32x2*)(out + ((size_t)s * 64 + 1) * C + c) = b; }
	s_addc_u32 s39, s37, 0
	global_store_dwordx2 v1, v[164:165], s[36:37]
	global_store_dwordx2 v1, v[166:167], s[38:39]
	v_lshlrev_b32_e32 v136, 16, v53
	v_and_b32_e32 v137, 0xffff0000, v53
	v_and_b32_e32 v53, 0xffff0000, v52
	v_lshlrev_b32_e32 v52, 16, v52
	v_lshlrev_b32_e32 v138, 16, v55
	v_and_b32_e32 v139, 0xffff0000, v55
	v_and_b32_e32 v55, 0xffff0000, v54
	v_lshlrev_b32_e32 v54, 16, v54
	v_lshlrev_b32_e32 v140, 16, v57
	v_and_b32_e32 v141, 0xffff0000, v57
	v_and_b32_e32 v57, 0xffff0000, v56
	v_lshlrev_b32_e32 v56, 16, v56
	v_lshlrev_b32_e32 v142, 16, v59
	v_and_b32_e32 v143, 0xffff0000, v59
	v_and_b32_e32 v59, 0xffff0000, v58
	v_lshlrev_b32_e32 v58, 16, v58
	v_lshlrev_b32_e32 v144, 16, v61
	v_and_b32_e32 v145, 0xffff0000, v61
	v_and_b32_e32 v61, 0xffff0000, v60
	v_lshlrev_b32_e32 v60, 16, v60
	v_lshlrev_b32_e32 v146, 16, v63
	v_and_b32_e32 v147, 0xffff0000, v63
	v_and_b32_e32 v63, 0xffff0000, v62
	v_lshlrev_b32_e32 v62, 16, v62
	v_pk_mul_f32 v[148:149], v[16:17], v[56:57]
	v_pk_mul_f32 v[150:151], v[18:19], v[140:141]
	v_pk_mul_f32 v[152:153], v[16:17], v[58:59]
	v_pk_mul_f32 v[154:155], v[18:19], v[142:143]
	v_pk_fma_f32 v[148:149], v[12:13], v[54:55], v[148:149]
	v_pk_fma_f32 v[150:151], v[14:15], v[138:139], v[150:151]
	v_pk_fma_f32 v[152:153], v[12:13], v[56:57], v[152:153]
	v_pk_fma_f32 v[154:155], v[14:15], v[140:141], v[154:155]
	v_pk_fma_f32 v[148:149], v[8:9], v[52:53], v[148:149]
	v_pk_fma_f32 v[150:151], v[10:11], v[136:137], v[150:151]
	v_pk_fma_f32 v[152:153], v[8:9], v[54:55], v[152:153]
	v_pk_fma_f32 v[154:155], v[10:11], v[138:139], v[154:155]
	v_pk_add_f32 v[148:149], v[148:149], v[20:21]
	v_pk_add_f32 v[150:151], v[150:151], v[22:23]
	v_pk_add_f32 v[152:153], v[152:153], v[20:21]
	v_pk_add_f32 v[154:155], v[154:155], v[22:23]
	v_pk_mul_f32 v[156:157], v[148:149], s[12:13] op_sel_hi:[1,0]
	v_pk_mul_f32 v[158:159], v[150:151], s[12:13] op_sel_hi:[1,0]
	v_pk_mul_f32 v[160:161], v[152:153], s[12:13] op_sel_hi:[1,0]
	v_pk_mul_f32 v[162:163], v[154:155], s[12:13] op_sel_hi:[1,0]
	v_exp_f32_e32 v156, v156
	v_exp_f32_e32 v157, v157
	v_exp_f32_e32 v158, v158
	v_exp_f32_e32 v159, v159
	v_exp_f32_e32 v160, v160
	v_exp_f32_e32 v161, v161
	v_exp_f32_e32 v162, v162
	v_exp_f32_e32 v163, v163
	v_pk_add_f32 v[156:157], v[156:157], s[12:13] op_sel:[0,1]
	v_pk_add_f32 v[158:159], v[158:159], s[12:13] op_sel:[0,1]
	v_pk_add_f32 v[160:161], v[160:161], s[12:13] op_sel:[0,1]
	v_pk_add_f32 v[162:163], v[162:163], s[12:13] op_sel:[0,1]
	v_rcp_f32_e32 v156, v156
	v_rcp_f32_e32 v157, v157
	v_rcp_f32_e32 v158, v158
	v_rcp_f32_e32 v159, v159
	v_rcp_f32_e32 v160, v160
	v_rcp_f32_e32 v161, v161
	v_rcp_f32_e32 v162, v162
	v_rcp_f32_e32 v163, v163
	v_pk_mul_f32 v[148:149], v[148:149], v[156:157]
	v_pk_mul_f32 v[150:151], v[150:151], v[158:159]
	v_pk_mul_f32 v[152:153], v[152:153], v[160:161]
	v_pk_mul_f32 v[154:155], v[154:155], v[162:163]
	v_pk_mul_f32 v[148:149], v[148:149], v[60:61]
	v_pk_mul_f32 v[150:151], v[150:151], v[144:145]
	v_pk_mul_f32 v[152:153], v[152:153], v[62:63]
	v_pk_mul_f32 v[154:155], v[154:155], v[146:147]
	v_cvt_pk_bf16_f32 v164, v148, v149
	v_cvt_pk_bf16_f32 v165, v150, v151
	v_cvt_pk_bf16_f32 v166, v152, v153
	v_cvt_pk_bf16_f32 v167, v154, v155
	s_add_i32 s17, s16, 0
	s_lshl_b32 s17, s17, 2
	s_add_i32 s17, s17, 1
	s_mul_i32 s17, s17, 0x58000
	s_add_u32 s36, s96, s17
	s_addc_u32 s37, s97, 0
	s_add_u32 s38, s36, 0x1600
	s_addc_u32 s39, s37, 0
	global_store_dwordx2 v1, v[164:165], s[36:37]
	global_store_dwordx2 v1, v[166:167], s[38:39]
	v_lshlrev_b32_e32 v136, 16, v65
	v_and_b32_e32 v137, 0xffff0000, v65
	v_and_b32_e32 v65, 0xffff0000, v64
	v_lshlrev_b32_e32 v64, 16, v64
	v_lshlrev_b32_e32 v138, 16, v67
	v_and_b32_e32 v139, 0xffff0000, v67
	v_and_b32_e32 v67, 0xffff0000, v66
	v_lshlrev_b32_e32 v66, 16, v66
	v_lshlrev_b32_e32 v140, 16, v69
	v_and_b32_e32 v141, 0xffff0000, v69
	v_and_b32_e32 v69, 0xffff0000, v68
	v_lshlrev_b32_e32 v68, 16, v68
	v_lshlrev_b32_e32 v142, 16, v71
	v_and_b32_e32 v143, 0xffff0000, v71
	v_and_b32_e32 v71, 0xffff0000, v70
	v_lshlrev_b32_e32 v70, 16, v70
	v_lshlrev_b32_e32 v144, 16, v73
	v_and_b32_e32 v145, 0xffff0000, v73
	v_and_b32_e32 v73, 0xffff0000, v72
	v_lshlrev_b32_e32 v72, 16, v72
	v_lshlrev_b32_e32 v146, 16, v75
	v_and_b32_e32 v147, 0xffff0000, v75
	v_and_b32_e32 v75, 0xffff0000, v74
	v_lshlrev_b32_e32 v74, 16, v74
	v_pk_mul_f32 v[148:149], v[16:17], v[68:69]
	v_pk_mul_f32 v[150:151], v[18:19], v[140:141]
	v_pk_mul_f32 v[152:153], v[16:17], v[70:71]
	v_pk_mul_f32 v[154:155], v[18:19], v[142:143]
	v_pk_fma_f32 v[148:149], v[12:13], v[66:67], v[148:149]
	v_pk_fma_f32 v[150:151], v[14:15], v[138:139], v[150:151]
	v_pk_fma_f32 v[152:153], v[12:13], v[68:69], v[152:153]
	v_pk_fma_f32 v[154:155], v[14:15], v[140:141], v[154:155]
	v_pk_fma_f32 v[148:149], v[8:9], v[64:65], v[148:149]
	v_pk_fma_f32 v[150:151], v[10:11], v[136:137], v[150:151]
	v_pk_fma_f32 v[152:153], v[8:9], v[66:67], v[152:153]
	v_pk_fma_f32 v[154:155], v[10:11], v[138:139], v[154:155]
	v_pk_add_f32 v[148:149], v[148:149], v[20:21]
	v_pk_add_f32 v[150:151], v[150:151], v[22:23]
	v_pk_add_f32 v[152:153], v[152:153], v[20:21]
	v_pk_add_f32 v[154:155], v[154:155], v[22:23]
	v_pk_mul_f32 v[156:157], v[148:149], s[12:13] op_sel_hi:[1,0]
	v_pk_mul_f32 v[158:159], v[150:151], s[12:13] op_sel_hi:[1,0]
	v_pk_mul_f32 v[160:161], v[152:153], s[12:13] op_sel_hi:[1,0]
	v_pk_mul_f32 v[162:163], v[154:155], s[12:13] op_sel_hi:[1,0]
	v_exp_f32_e32 v156, v156
	v_exp_f32_e32 v157, v157
	v_exp_f32_e32 v158, v158
	v_exp_f32_e32 v159, v159
	v_exp_f32_e32 v160, v160
	v_exp_f32_e32 v161, v161
	v_exp_f32_e32 v162, v162
	v_exp_f32_e32 v163, v163
; __device__ __forceinline__ unsigned cvt_pk_bf16(float lo, float hi) { unsigned r; asm volatile("v_cvt_pk_bf16_f32 %0, %1, %2" : "=v"(r) : "v"(lo), "v"(hi)); return r; }
; __device__ __forceinline__ float silu_f(float x) { return x * __builtin_amdgcn_rcpf(1.0f + __builtin_amdgcn_exp2f(x * -1.44269504f)); }
; template <int MODE, class Sched> __device__ __forceinline__ void fixup_local(const bf16_t* halo, const float* cw, const float* cb, bf16_t* out, int C, const Sched& S) {
;     ...
;                 y0[k] = ld4(hb + (size_t)4 * C); y1[k] = ld4(hb + (size_t)5 * C); }
; #pragma unroll
;             for (int k = 0; k < 4; ++k) { const int s = 4 * u.pm + k; float o0[4], o1[4];
; #pragma unroll
;                 for (int j = 0; j < 4; ++j) {
;                     const float cv0 = w2[j] * h0[k][j] + w1[j] * t1[k][j] + w0[j] * t0[k][j] + bb[j];
;                     const float cv1 = w2[j] * h1[k][j] + w1[j] * h0[k][j] + w0[j] * t1[k][j] + bb[j];
;                     o0[j] = MODE == 0 ? silu_f(cv0) * y0[k][j] : cv0 * y0[k][j]; o1[j] = MODE == 0 ? silu_f(cv1) * y1[k][j] : cv1 * y1[k][j]; }
;                 u32x2 a; a.x = cvt_pk_bf16(o0[0], o0[1]); a.y = cvt_pk_bf16(o0[2], o0[3]); u32x2 b; b.x = cvt_pk_bf16(o1[0], o1[1]); b.y = cvt_pk_bf16(o1[2], o1[3]);
;                 *(u32x2*)(out + ((size_t)s * 64) * C + c) = a; *(u32x2*)(out + ((size_t)s * 64 + 1) * C + c) = b; }
	v_pk_add_f32 v[156:157], v[156:157], s[12:13] op_sel:[0,1]
	v_pk_add_f32 v[158:159], v[158:159], s[12:13] op_sel:[0,1]
	v_pk_add_f32 v[160:161], v[160:161], s[12:13] op_sel:[0,1]
	v_pk_add_f32 v[162:163], v[162:163], s[12:13] op_sel:[0,1]
	v_rcp_f32_e32 v156, v156
	v_rcp_f32_e32 v157, v157
	v_rcp_f32_e32 v158, v158
	v_rcp_f32_e32 v159, v159
	v_rcp_f32_e32 v160, v160
	v_rcp_f32_e32 v161, v161
	v_rcp_f32_e32 v162, v162
	v_rcp_f32_e32 v163, v163
	v_pk_mul_f32 v[148:149], v[148:149], v[156:157]
	v_pk_mul_f32 v[150:151], v[150:151], v[158:159]
	v_pk_mul_f32 v[152:153], v[152:153], v[160:161]
	v_pk_mul_f32 v[154:155], v[154:155], v[162:163]
	v_pk_mul_f32 v[148:149], v[148:149], v[72:73]
	v_pk_mul_f32 v[150:151], v[150:151], v[144:145]
	v_pk_mul_f32 v[152:153], v[152:153], v[74:75]
	v_pk_mul_f32 v[154:155], v[154:155], v[146:147]
	v_cvt_pk_bf16_f32 v164, v148, v149
	v_cvt_pk_bf16_f32 v165, v150, v151
	v_cvt_pk_bf16_f32 v166, v152, v153
	v_cvt_pk_bf16_f32 v167, v154, v155
	s_add_i32 s17, s16, 0
	s_lshl_b32 s17, s17, 2
	s_add_i32 s17, s17, 2
	s_mul_i32 s17, s17, 0x58000
	s_add_u32 s36, s96, s17
	s_addc_u32 s37, s97, 0
	s_add_u32 s38, s36, 0x1600
	s_addc_u32 s39, s37, 0
	global_store_dwordx2 v1, v[164:165], s[36:37]
	global_store_dwordx2 v1, v[166:167], s[38:39]
	v_lshlrev_b32_e32 v136, 16, v77
	v_and_b32_e32 v137, 0xffff0000, v77
	v_and_b32_e32 v77, 0xffff0000, v76
	v_lshlrev_b32_e32 v76, 16, v76
	v_lshlrev_b32_e32 v138, 16, v79
	v_and_b32_e32 v139, 0xffff0000, v79
	v_and_b32_e32 v79, 0xffff0000, v78
	v_lshlrev_b32_e32 v78, 16, v78
	v_lshlrev_b32_e32 v140, 16, v81
	v_and_b32_e32 v141, 0xffff0000, v81
	v_and_b32_e32 v81, 0xffff0000, v80
	v_lshlrev_b32_e32 v80, 16, v80
	v_lshlrev_b32_e32 v142, 16, v83
	v_and_b32_e32 v143, 0xffff0000, v83
	v_and_b32_e32 v83, 0xffff0000, v82
	v_lshlrev_b32_e32 v82, 16, v82
	v_lshlrev_b32_e32 v144, 16, v85
	v_and_b32_e32 v145, 0xffff0000, v85
	v_and_b32_e32 v85, 0xffff0000, v84
	v_lshlrev_b32_e32 v84, 16, v84
	v_lshlrev_b32_e32 v146, 16, v87
	v_and_b32_e32 v147, 0xffff0000, v87
	v_and_b32_e32 v87, 0xffff0000, v86
	v_lshlrev_b32_e32 v86, 16, v86
	v_pk_mul_f32 v[148:149], v[16:17], v[80:81]
	v_pk_mul_f32 v[150:151], v[18:19], v[140:141]
	v_pk_mul_f32 v[152:153], v[16:17], v[82:83]
	v_pk_mul_f32 v[154:155], v[18:19], v[142:143]
	v_pk_fma_f32 v[148:149], v[12:13], v[78:79], v[148:149]
	v_pk_fma_f32 v[150:151], v[14:15], v[138:139], v[150:151]
	v_pk_fma_f32 v[152:153], v[12:13], v[80:81], v[152:153]
	v_pk_fma_f32 v[154:155], v[14:15], v[140:141], v[154:155]
	v_pk_fma_f32 v[148:149], v[8:9], v[76:77], v[148:149]
	v_pk_fma_f32 v[150:151], v[10:11], v[136:137], v[150:151]
	v_pk_fma_f32 v[152:153], v[8:9], v[78:79], v[152:153]
	v_pk_fma_f32 v[154:155], v[10:11], v[138:139], v[154:155]
	v_pk_add_f32 v[148:149], v[148:149], v[20:21]
	v_pk_add_f32 v[150:151], v[150:151], v[22:23]
	v_pk_add_f32 v[152:153], v[152:153], v[20:21]
	v_pk_add_f32 v[154:155], v[154:155], v[22:23]
	v_pk_mul_f32 v[156:157], v[148:149], s[12:13] op_sel_hi:[1,0]
	v_pk_mul_f32 v[158:159], v[150:151], s[12:13] op_sel_hi:[1,0]
	v_pk_mul_f32 v[160:161], v[152:153], s[12:13] op_sel_hi:[1,0]
	v_pk_mul_f32 v[162:163], v[154:155], s[12:13] op_sel_hi:[1,0]
	v_exp_f32_e32 v156, v156
	v_exp_f32_e32 v157, v157
	v_exp_f32_e32 v158, v158
	v_exp_f32_e32 v159, v159
	v_exp_f32_e32 v160, v160
	v_exp_f32_e32 v161, v161
	v_exp_f32_e32 v162, v162
	v_exp_f32_e32 v163, v163
	v_pk_add_f32 v[156:157], v[156:157], s[12:13] op_sel:[0,1]
	v_pk_add_f32 v[158:159], v[158:159], s[12:13] op_sel:[0,1]
	v_pk_add_f32 v[160:161], v[160:161], s[12:13] op_sel:[0,1]
	v_pk_add_f32 v[162:163], v[162:163], s[12:13] op_sel:[0,1]
	v_rcp_f32_e32 v156, v156
	v_rcp_f32_e32 v157, v157
	v_rcp_f32_e32 v158, v158
	v_rcp_f32_e32 v159, v159
	v_rcp_f32_e32 v160, v160
	v_rcp_f32_e32 v161, v161
	v_rcp_f32_e32 v162, v162
	v_rcp_f32_e32 v163, v163
	v_pk_mul_f32 v[148:149], v[148:149], v[156:157]
	v_pk_mul_f32 v[150:151], v[150:151], v[158:159]
	v_pk_mul_f32 v[152:153], v[152:153], v[160:161]
	v_pk_mul_f32 v[154:155], v[154:155], v[162:163]
	v_pk_mul_f32 v[148:149], v[148:149], v[84:85]
; __device__ __forceinline__ float bf_lo(unsigned w) { return __uint_as_float(w << 16); }
; __device__ __forceinline__ float bf_hi(unsigned w) { return __uint_as_float(w & 0xffff0000u); }
; template <int MODE, class Sched> __device__ __forceinline__ void fixup_local(const bf16_t* halo, const float* cw, const float* cb, bf16_t* out, int C, const Sched& S) {
;     ...
;         for (int c4 = tid; c4 < C4; c4 += 512) {
;             const int c = c4 * 4;
;             const f32x4 w0 = *(const f32x4*)(cw + c), w1 = *(const f32x4*)(cw + C + c), w2 = *(const f32x4*)(cw + 2 * C + c);
;             f32x4 bb = (f32x4){0.f, 0.f, 0.f, 0.f}; if (MODE == 0) bb = *(const f32x4*)(cb + c);
;             f32x4 t0[4], t1[4], h0[4], h1[4], y0[4], y1[4];
; #pragma unroll
;             for (int k = 0; k < 4; ++k) { const int s = 4 * u.pm + k; const bf16_t* hb = halo + (size_t)s * 6 * C + c; const bool first = (s & 127) == 0;
;                 const f32x4 z = (f32x4){0.f, 0.f, 0.f, 0.f};
;                 auto ld4 = [](const bf16_t* ptr) { const u32x2 w = *(const u32x2*)ptr; return (f32x4){bf_lo(w.x), bf_hi(w.x), bf_lo(w.y), bf_hi(w.y)}; };
;                 t0[k] = ld4(first ? hb : hb - (size_t)6 * C); t1[k] = ld4(first ? hb : hb - (size_t)5 * C);
;                 if (first) { t0[k] = z; t1[k] = z; }
;                 h0[k] = ld4(hb + (size_t)2 * C); h1[k] = ld4(hb + (size_t)3 * C);
;                 y0[k] = ld4(hb + (size_t)4 * C); y1[k] = ld4(hb + (size_t)5 * C); }
	v_pk_mul_f32 v[150:151], v[150:151], v[144:145]
	v_pk_mul_f32 v[152:153], v[152:153], v[86:87]
	v_pk_mul_f32 v[154:155], v[154:155], v[146:147]
	v_cvt_pk_bf16_f32 v164, v148, v149
	v_cvt_pk_bf16_f32 v165, v150, v151
	v_cvt_pk_bf16_f32 v166, v152, v153
	v_cvt_pk_bf16_f32 v167, v154, v155
	s_add_i32 s17, s16, 0
	s_lshl_b32 s17, s17, 2
	s_add_i32 s17, s17, 3
	s_mul_i32 s17, s17, 0x58000
	s_add_u32 s36, s96, s17
	s_addc_u32 s37, s97, 0
	s_add_u32 s38, s36, 0x1600
	s_addc_u32 s39, s37, 0
	global_store_dwordx2 v1, v[164:165], s[36:37]
	global_store_dwordx2 v1, v[166:167], s[38:39]
	s_and_b64 exec, exec, s[30:31]
	global_load_dwordx4 v[24:27], v4, s[0:1]
	global_load_dwordx4 v[28:31], v4, s[6:7]
	global_load_dwordx4 v[32:35], v4, s[8:9]
	global_load_dwordx4 v[36:39], v4, s[40:41]
	s_add_i32 s17, s16, 0
	s_lshl_b32 s17, s17, 2
	s_mul_i32 s17, s17, 0x8400
	s_add_u32 s18, s42, s17
	s_addc_u32 s19, s43, 0
	s_add_i32 s17, s16, 0
	s_and_b32 s17, s17, 31
	s_cmp_eq_u32 s17, 0
	s_cselect_b32 s26, 0, 0x8400
	s_cselect_b32 s27, 0, 0x6e00
	s_sub_u32 s24, s18, s26
	s_subb_u32 s25, s19, 0
	global_load_dwordx2 v[40:41], v2, s[24:25]
	s_sub_u32 s24, s18, s27
	s_subb_u32 s25, s19, 0
	global_load_dwordx2 v[42:43], v2, s[24:25]
	s_add_u32 s24, s18, 0x2c00
	s_addc_u32 s25, s19, 0
	global_load_dwordx2 v[44:45], v2, s[24:25]
	s_add_u32 s24, s18, 0x4200
	s_addc_u32 s25, s19, 0
	global_load_dwordx2 v[46:47], v2, s[24:25]
	s_add_u32 s24, s18, 0x5800
	s_addc_u32 s25, s19, 0
	global_load_dwordx2 v[48:49], v2, s[24:25]
	s_add_u32 s24, s18, 0x6e00
	s_addc_u32 s25, s19, 0
	global_load_dwordx2 v[50:51], v2, s[24:25]
	s_add_i32 s17, s16, 0
	s_lshl_b32 s17, s17, 2
	s_add_i32 s17, s17, 1
	s_mul_i32 s17, s17, 0x8400
	s_add_u32 s18, s42, s17
	s_addc_u32 s19, s43, 0
	s_mov_b32 s26, 0x8400
	s_mov_b32 s27, 0x6e00
	s_sub_u32 s24, s18, s26
	s_subb_u32 s25, s19, 0
	global_load_dwordx2 v[52:53], v2, s[24:25]
	s_sub_u32 s24, s18, s27
	s_subb_u32 s25, s19, 0
	global_load_dwordx2 v[54:55], v2, s[24:25]
	s_add_u32 s24, s18, 0x2c00
	s_addc_u32 s25, s19, 0
	global_load_dwordx2 v[56:57], v2, s[24:25]
	s_add_u32 s24, s18, 0x4200
	s_addc_u32 s25, s19, 0
	global_load_dwordx2 v[58:59], v2, s[24:25]
	s_add_u32 s24, s18, 0x5800
	s_addc_u32 s25, s19, 0
	global_load_dwordx2 v[60:61], v2, s[24:25]
	s_add_u32 s24, s18, 0x6e00
	s_addc_u32 s25, s19, 0
	global_load_dwordx2 v[62:63], v2, s[24:25]
	s_add_i32 s17, s16, 0
	s_lshl_b32 s17, s17, 2
	s_add_i32 s17, s17, 2
	s_mul_i32 s17, s17, 0x8400
	s_add_u32 s18, s42, s17
	s_addc_u32 s19, s43, 0
	s_mov_b32 s26, 0x8400
	s_mov_b32 s27, 0x6e00
	s_sub_u32 s24, s18, s26
	s_subb_u32 s25, s19, 0
	global_load_dwordx2 v[64:65], v2, s[24:25]
	s_sub_u32 s24, s18, s27
	s_subb_u32 s25, s19, 0
	global_load_dwordx2 v[66:67], v2, s[24:25]
	s_add_u32 s24, s18, 0x2c00
	s_addc_u32 s25, s19, 0
	global_load_dwordx2 v[68:69], v2, s[24:25]
	s_add_u32 s24, s18, 0x4200
	s_addc_u32 s25, s19, 0
	global_load_dwordx2 v[70:71], v2, s[24:25]
	s_add_u32 s24, s18, 0x5800
	s_addc_u32 s25, s19, 0
	global_load_dwordx2 v[72:73], v2, s[24:25]
	s_add_u32 s24, s18, 0x6e00
	s_addc_u32 s25, s19, 0
	global_load_dwordx2 v[74:75], v2, s[24:25]
	s_add_i32 s17, s16, 0
	s_lshl_b32 s17, s17, 2
	s_add_i32 s17, s17, 3
	s_mul_i32 s17, s17, 0x8400
	s_add_u32 s18, s42, s17
	s_addc_u32 s19, s43, 0
	s_mov_b32 s26, 0x8400
	s_mov_b32 s27, 0x6e00
	s_sub_u32 s24, s18, s26
	s_subb_u32 s25, s19, 0
	global_load_dwordx2 v[76:77], v2, s[24:25]
	s_sub_u32 s24, s18, s27
	s_subb_u32 s25, s19, 0
	global_load_dwordx2 v[78:79], v2, s[24:25]
	s_add_u32 s24, s18, 0x2c00
	s_addc_u32 s25, s19, 0
	global_load_dwordx2 v[80:81], v2, s[24:25]
	s_add_u32 s24, s18, 0x4200
	s_addc_u32 s25, s19, 0
	global_load_dwordx2 v[82:83], v2, s[24:25]
	s_add_u32 s24, s18, 0x5800
	s_addc_u32 s25, s19, 0
	global_load_dwordx2 v[84:85], v2, s[24:25]
	s_add_u32 s24, s18, 0x6e00
	s_addc_u32 s25, s19, 0
	global_load_dwordx2 v[86:87], v2, s[24:25]
	s_mov_b64 exec, s[10:11]
	s_waitcnt vmcnt(36)
	s_add_i32 s17, s16, 8
	s_and_b32 s17, s17, 31
	s_cmp_lg_u32 s17, 0
	s_cbranch_scc1 .Lfix1_nz3
	v_mov_b32_e32 v88, 0
	v_mov_b32_e32 v89, 0
	v_mov_b32_e32 v90, 0
	v_mov_b32_e32 v91, 0

; __device__ __forceinline__ unsigned cvt_pk_bf16(float lo, float hi) { unsigned r; asm volatile("v_cvt_pk_bf16_f32 %0, %1, %2" : "=v"(r) : "v"(lo), "v"(hi)); return r; }
; __device__ __forceinline__ float bf_lo(unsigned w) { return __uint_as_float(w << 16); }
; __device__ __forceinline__ float bf_hi(unsigned w) { return __uint_as_float(w & 0xffff0000u); }
;     __device__ __forceinline__ void operator()(const Acc& acc, const Unit& u, int wr, int wc, int fr, int fq, LAS unsigned char* lds, f32x4 epar) const {
;     ...
;         for (int ai = 0; ai < 2; ++ai)
; #pragma unroll
;             for (int m = 0; m < 4; ++m) { const int r = u.pm * BM + ai * HALF + wr * 64 + m * 16 + fr; float s = 0.f;
; #pragma unroll
;                 for (int bj = 0; bj < 2; ++bj) { const size_t off = (size_t)r * DM + u.pn * 256 + bj * 128 + wc * 32 + 8 * fq;
;                     const u32x4 q = hv[ai][m][bj];
;                     f32x4 v0 = (f32x4){bf_lo(q.x), bf_hi(q.x), bf_lo(q.y), bf_hi(q.y)}, v1 = (f32x4){bf_lo(q.z), bf_hi(q.z), bf_lo(q.w), bf_hi(q.w)};
;                     v0 += acc[ai][bj][m][0]; v1 += acc[ai][bj][m][1];
;                     u32x4 w; w.x = cvt_pk_bf16(v0[0], v0[1]); w.y = cvt_pk_bf16(v0[2], v0[3]); w.z = cvt_pk_bf16(v1[0], v1[1]); w.w = cvt_pk_bf16(v1[2], v1[3]);
;                     *(u32x4*)(HB + off) = w;
;                     s += (v0[0] * v0[0] + v0[1] * v0[1]) + (v0[2] * v0[2] + v0[3] * v0[3]) + (v1[0] * v1[0] + v1[1] * v1[1]) + (v1[2] * v1[2] + v1[3] * v1[3]); }
;                 s += __shfl_xor(s, 16); s += __shfl_xor(s, 32);
;                 if (fq == 0) unsafeAtomicAdd(ssq + r, s); }
.LBB0_1067:
	s_cmp_lg_u32 s34, 0x100
	s_cbranch_scc1 .Ldn1_epi_generic
	v_readlane_b32 s98, v252, 50
	v_readlane_b32 s99, v252, 51
	v_readlane_b32 s100, v252, 12
	v_readlane_b32 s101, v252, 13
	v_lshl_add_u32 v216, s78, 8, v226
	s_lshl_b32 s8, s77, 9
	v_lshlrev_b32_e32 v217, 11, v216
	v_mov_b32_e32 v219, 0
	v_add_u32_e32 v217, s8, v217
	v_add_u32_e32 v242, 0x0, v217
	v_mov_b32_e32 v243, 0
	v_lshl_add_u64 v[246:247], v[242:243], 0, v[186:187]
	global_load_dwordx4 v[234:237], v[246:247], off
	global_load_dwordx4 v[238:241], v[246:247], off offset:256
	v_add_u32_e32 v242, 0x8000, v217
	v_mov_b32_e32 v243, 0
	v_lshl_add_u64 v[246:247], v[242:243], 0, v[186:187]
	global_load_dwordx4 v[180:183], v[246:247], off
	global_load_dwordx4 v[176:179], v[246:247], off offset:256
	v_add_u32_e32 v242, 0x10000, v217
	v_mov_b32_e32 v243, 0
	v_lshl_add_u64 v[246:247], v[242:243], 0, v[186:187]
	global_load_dwordx4 v[172:175], v[246:247], off
	global_load_dwordx4 v[168:171], v[246:247], off offset:256
	v_add_u32_e32 v242, 0x18000, v217
	v_mov_b32_e32 v243, 0
	v_lshl_add_u64 v[246:247], v[242:243], 0, v[186:187]
	global_load_dwordx4 v[164:167], v[246:247], off
	global_load_dwordx4 v[160:163], v[246:247], off offset:256
	v_add_u32_e32 v242, 0x40000, v217
	v_mov_b32_e32 v243, 0
	v_lshl_add_u64 v[246:247], v[242:243], 0, v[186:187]
	global_load_dwordx4 v[156:159], v[246:247], off
	global_load_dwordx4 v[152:155], v[246:247], off offset:256
	v_add_u32_e32 v242, 0x48000, v217
	v_mov_b32_e32 v243, 0
	v_lshl_add_u64 v[246:247], v[242:243], 0, v[186:187]
	global_load_dwordx4 v[148:151], v[246:247], off
	global_load_dwordx4 v[144:147], v[246:247], off offset:256
	v_add_u32_e32 v242, 0x50000, v217
	v_mov_b32_e32 v243, 0
	v_lshl_add_u64 v[246:247], v[242:243], 0, v[186:187]
	global_load_dwordx4 v[140:143], v[246:247], off
	global_load_dwordx4 v[136:139], v[246:247], off offset:256
	v_add_u32_e32 v242, 0x58000, v217
	v_mov_b32_e32 v243, 0
	v_lshl_add_u64 v[246:247], v[242:243], 0, v[186:187]
	global_load_dwordx4 v[132:135], v[246:247], off
	global_load_dwordx4 v[128:131], v[246:247], off offset:256
	v_lshlrev_b32_e32 v248, 2, v216
	s_waitcnt vmcnt(14)
	v_lshlrev_b32_e32 v242, 16, v234
	v_and_b32_e32 v243, 0xffff0000, v234
	v_pk_add_f32 v[120:121], v[120:121], v[242:243]
	v_lshlrev_b32_e32 v244, 16, v235
	v_and_b32_e32 v245, 0xffff0000, v235
	v_pk_add_f32 v[122:123], v[122:123], v[244:245]
	v_lshlrev_b32_e32 v242, 16, v236
	v_and_b32_e32 v243, 0xffff0000, v236
	v_pk_add_f32 v[124:125], v[124:125], v[242:243]
	v_lshlrev_b32_e32 v244, 16, v237
	v_and_b32_e32 v245, 0xffff0000, v237
	v_pk_add_f32 v[126:127], v[126:127], v[244:245]
	v_lshlrev_b32_e32 v242, 16, v238
	v_and_b32_e32 v243, 0xffff0000, v238
	v_pk_add_f32 v[116:117], v[116:117], v[242:243]
	v_lshlrev_b32_e32 v244, 16, v239
	v_and_b32_e32 v245, 0xffff0000, v239
	v_pk_add_f32 v[118:119], v[118:119], v[244:245]
	v_lshlrev_b32_e32 v242, 16, v240
	v_and_b32_e32 v243, 0xffff0000, v240
	v_pk_add_f32 v[112:113], v[112:113], v[242:243]
	v_lshlrev_b32_e32 v244, 16, v241
	v_and_b32_e32 v245, 0xffff0000, v241
	v_pk_add_f32 v[114:115], v[114:115], v[244:245]
	v_pk_mul_f32 v[234:235], v[120:121], v[120:121]
	v_pk_mul_f32 v[236:237], v[122:123], v[122:123]
	v_pk_fma_f32 v[234:235], v[124:125], v[124:125], v[234:235]
	v_pk_fma_f32 v[236:237], v[126:127], v[126:127], v[236:237]
	v_pk_fma_f32 v[234:235], v[116:117], v[116:117], v[234:235]
	v_pk_fma_f32 v[236:237], v[118:119], v[118:119], v[236:237]
	v_pk_fma_f32 v[234:235], v[112:113], v[112:113], v[234:235]
	v_pk_fma_f32 v[236:237], v[114:115], v[114:115], v[236:237]
	v_add_f32_e32 v234, v234, v235
	v_add_f32_e32 v236, v236, v237
	v_add_u32_e32 v246, 0x0, v248
	v_add_f32_e32 v208, v234, v236
	s_nop 0
	v_mov_b32_e32 v234, v208
	s_nop 1
	v_permlane16_swap_b32_e32 v208, v234
	v_add_f32_e32 v208, v208, v234
	v_mov_b32_e32 v234, v208
	s_nop 1
	v_permlane32_swap_b32_e32 v208, v234
	v_add_f32_e32 v208, v208, v234
	s_and_b64 exec, exec, s[4:5]
	global_atomic_add_f32 v234, v246, v208, s[12:13] sc0
	s_mov_b64 exec, -1
	s_waitcnt vmcnt(13)
	v_lshlrev_b32_e32 v242, 16, v180
	v_and_b32_e32 v243, 0xffff0000, v180
	v_pk_add_f32 v[108:109], v[108:109], v[242:243]
	v_lshlrev_b32_e32 v244, 16, v181
	v_and_b32_e32 v245, 0xffff0000, v181
	v_pk_add_f32 v[110:111], v[110:111], v[244:245]
	v_lshlrev_b32_e32 v242, 16, v182
	v_and_b32_e32 v243, 0xffff0000, v182
	v_pk_add_f32 v[104:105], v[104:105], v[242:243]
	v_lshlrev_b32_e32 v244, 16, v183
	v_and_b32_e32 v245, 0xffff0000, v183
	v_pk_add_f32 v[106:107], v[106:107], v[244:245]
	v_lshlrev_b32_e32 v242, 16, v176
	v_and_b32_e32 v243, 0xffff0000, v176
	v_pk_add_f32 v[100:101], v[100:101], v[242:243]
	v_lshlrev_b32_e32 v244, 16, v177
	v_and_b32_e32 v245, 0xffff0000, v177
	v_pk_add_f32 v[102:103], v[102:103], v[244:245]
	v_lshlrev_b32_e32 v242, 16, v178
	v_and_b32_e32 v243, 0xffff0000, v178
	v_pk_add_f32 v[96:97], v[96:97], v[242:243]
	v_lshlrev_b32_e32 v244, 16, v179
	v_and_b32_e32 v245, 0xffff0000, v179
	v_pk_add_f32 v[98:99], v[98:99], v[244:245]
	v_pk_mul_f32 v[180:181], v[108:109], v[108:109]
	v_pk_mul_f32 v[182:183], v[110:111], v[110:111]
	v_pk_fma_f32 v[180:181], v[104:105], v[104:105], v[180:181]
	v_pk_fma_f32 v[182:183], v[106:107], v[106:107], v[182:183]
	v_pk_fma_f32 v[180:181], v[100:101], v[100:101], v[180:181]
	v_pk_fma_f32 v[182:183], v[102:103], v[102:103], v[182:183]
	v_pk_fma_f32 v[180:181], v[96:97], v[96:97], v[180:181]
	v_pk_fma_f32 v[182:183], v[98:99], v[98:99], v[182:183]
	v_add_f32_e32 v180, v180, v181
	v_add_f32_e32 v182, v182, v183
	v_add_u32_e32 v246, 0x40, v248
	v_add_f32_e32 v209, v180, v182
	s_nop 0
	v_mov_b32_e32 v235, v209
	s_nop 1
	v_permlane16_swap_b32_e32 v209, v235
	v_add_f32_e32 v209, v209, v235
	v_mov_b32_e32 v235, v209
	s_nop 1
	v_permlane32_swap_b32_e32 v209, v235
	v_add_f32_e32 v209, v209, v235
	s_and_b64 exec, exec, s[4:5]
	global_atomic_add_f32 v235, v246, v209, s[12:13] sc0
	s_mov_b64 exec, -1
	s_waitcnt vmcnt(12)
; __device__ __forceinline__ unsigned cvt_pk_bf16(float lo, float hi) { unsigned r; asm volatile("v_cvt_pk_bf16_f32 %0, %1, %2" : "=v"(r) : "v"(lo), "v"(hi)); return r; }
; __device__ __forceinline__ float bf_lo(unsigned w) { return __uint_as_float(w << 16); }
; __device__ __forceinline__ float bf_hi(unsigned w) { return __uint_as_float(w & 0xffff0000u); }
;     __device__ __forceinline__ void operator()(const Acc& acc, const Unit& u, int wr, int wc, int fr, int fq, LAS unsigned char* lds, f32x4 epar) const {
;     ...
;         for (int ai = 0; ai < 2; ++ai)
; #pragma unroll
;             for (int m = 0; m < 4; ++m) { const int r = u.pm * BM + ai * HALF + wr * 64 + m * 16 + fr; float s = 0.f;
; #pragma unroll
;                 for (int bj = 0; bj < 2; ++bj) { const size_t off = (size_t)r * DM + u.pn * 256 + bj * 128 + wc * 32 + 8 * fq;
;                     const u32x4 q = hv[ai][m][bj];
;                     f32x4 v0 = (f32x4){bf_lo(q.x), bf_hi(q.x), bf_lo(q.y), bf_hi(q.y)}, v1 = (f32x4){bf_lo(q.z), bf_hi(q.z), bf_lo(q.w), bf_hi(q.w)};
;                     v0 += acc[ai][bj][m][0]; v1 += acc[ai][bj][m][1];
;                     u32x4 w; w.x = cvt_pk_bf16(v0[0], v0[1]); w.y = cvt_pk_bf16(v0[2], v0[3]); w.z = cvt_pk_bf16(v1[0], v1[1]); w.w = cvt_pk_bf16(v1[2], v1[3]);
;                     *(u32x4*)(HB + off) = w;
;                     s += (v0[0] * v0[0] + v0[1] * v0[1]) + (v0[2] * v0[2] + v0[3] * v0[3]) + (v1[0] * v1[0] + v1[1] * v1[1]) + (v1[2] * v1[2] + v1[3] * v1[3]); }
;                 s += __shfl_xor(s, 16); s += __shfl_xor(s, 32);
;                 if (fq == 0) unsafeAtomicAdd(ssq + r, s); }
	v_lshlrev_b32_e32 v242, 16, v172
	v_and_b32_e32 v243, 0xffff0000, v172
	v_pk_add_f32 v[92:93], v[92:93], v[242:243]
	v_lshlrev_b32_e32 v244, 16, v173
	v_and_b32_e32 v245, 0xffff0000, v173
	v_pk_add_f32 v[94:95], v[94:95], v[244:245]
	v_lshlrev_b32_e32 v242, 16, v174
	v_and_b32_e32 v243, 0xffff0000, v174
	v_pk_add_f32 v[88:89], v[88:89], v[242:243]
	v_lshlrev_b32_e32 v244, 16, v175
	v_and_b32_e32 v245, 0xffff0000, v175
	v_pk_add_f32 v[90:91], v[90:91], v[244:245]
	v_lshlrev_b32_e32 v242, 16, v168
	v_and_b32_e32 v243, 0xffff0000, v168
	v_pk_add_f32 v[84:85], v[84:85], v[242:243]
	v_lshlrev_b32_e32 v244, 16, v169
	v_and_b32_e32 v245, 0xffff0000, v169
	v_pk_add_f32 v[86:87], v[86:87], v[244:245]
	v_lshlrev_b32_e32 v242, 16, v170
	v_and_b32_e32 v243, 0xffff0000, v170
	v_pk_add_f32 v[80:81], v[80:81], v[242:243]
	v_lshlrev_b32_e32 v244, 16, v171
	v_and_b32_e32 v245, 0xffff0000, v171
	v_pk_add_f32 v[82:83], v[82:83], v[244:245]
	v_pk_mul_f32 v[172:173], v[92:93], v[92:93]
	v_pk_mul_f32 v[174:175], v[94:95], v[94:95]
	v_pk_fma_f32 v[172:173], v[88:89], v[88:89], v[172:173]
	v_pk_fma_f32 v[174:175], v[90:91], v[90:91], v[174:175]
	v_pk_fma_f32 v[172:173], v[84:85], v[84:85], v[172:173]
	v_pk_fma_f32 v[174:175], v[86:87], v[86:87], v[174:175]
	v_pk_fma_f32 v[172:173], v[80:81], v[80:81], v[172:173]
	v_pk_fma_f32 v[174:175], v[82:83], v[82:83], v[174:175]
	v_add_f32_e32 v172, v172, v173
	v_add_f32_e32 v174, v174, v175
	v_add_u32_e32 v246, 0x80, v248
	v_add_f32_e32 v210, v172, v174
	s_nop 0
	v_mov_b32_e32 v236, v210
	s_nop 1
	v_permlane16_swap_b32_e32 v210, v236
	v_add_f32_e32 v210, v210, v236
	v_mov_b32_e32 v236, v210
	s_nop 1
	v_permlane32_swap_b32_e32 v210, v236
	v_add_f32_e32 v210, v210, v236
	s_and_b64 exec, exec, s[4:5]
	global_atomic_add_f32 v236, v246, v210, s[12:13] sc0
	s_mov_b64 exec, -1
	s_waitcnt vmcnt(11)
	v_lshlrev_b32_e32 v242, 16, v164
	v_and_b32_e32 v243, 0xffff0000, v164
	v_pk_add_f32 v[76:77], v[76:77], v[242:243]
	v_lshlrev_b32_e32 v244, 16, v165
	v_and_b32_e32 v245, 0xffff0000, v165
	v_pk_add_f32 v[78:79], v[78:79], v[244:245]
	v_lshlrev_b32_e32 v242, 16, v166
	v_and_b32_e32 v243, 0xffff0000, v166
	v_pk_add_f32 v[72:73], v[72:73], v[242:243]
	v_lshlrev_b32_e32 v244, 16, v167
	v_and_b32_e32 v245, 0xffff0000, v167
	v_pk_add_f32 v[74:75], v[74:75], v[244:245]
	v_lshlrev_b32_e32 v242, 16, v160
	v_and_b32_e32 v243, 0xffff0000, v160
	v_pk_add_f32 v[68:69], v[68:69], v[242:243]
	v_lshlrev_b32_e32 v244, 16, v161
	v_and_b32_e32 v245, 0xffff0000, v161
	v_pk_add_f32 v[70:71], v[70:71], v[244:245]
	v_lshlrev_b32_e32 v242, 16, v162
	v_and_b32_e32 v243, 0xffff0000, v162
	v_pk_add_f32 v[64:65], v[64:65], v[242:243]
	v_lshlrev_b32_e32 v244, 16, v163
	v_and_b32_e32 v245, 0xffff0000, v163
	v_pk_add_f32 v[66:67], v[66:67], v[244:245]
	v_pk_mul_f32 v[164:165], v[76:77], v[76:77]
	v_pk_mul_f32 v[166:167], v[78:79], v[78:79]
	v_pk_fma_f32 v[164:165], v[72:73], v[72:73], v[164:165]
	v_pk_fma_f32 v[166:167], v[74:75], v[74:75], v[166:167]
	v_pk_fma_f32 v[164:165], v[68:69], v[68:69], v[164:165]
	v_pk_fma_f32 v[166:167], v[70:71], v[70:71], v[166:167]
	v_pk_fma_f32 v[164:165], v[64:65], v[64:65], v[164:165]
	v_pk_fma_f32 v[166:167], v[66:67], v[66:67], v[166:167]
	v_add_f32_e32 v164, v164, v165
	v_add_f32_e32 v166, v166, v167
	v_add_u32_e32 v246, 0xc0, v248
	v_add_f32_e32 v211, v164, v166
	s_nop 0
	v_mov_b32_e32 v237, v211
	s_nop 1
	v_permlane16_swap_b32_e32 v211, v237
	v_add_f32_e32 v211, v211, v237
	v_mov_b32_e32 v237, v211
	s_nop 1
	v_permlane32_swap_b32_e32 v211, v237
	v_add_f32_e32 v211, v211, v237
	s_and_b64 exec, exec, s[4:5]
	global_atomic_add_f32 v237, v246, v211, s[12:13] sc0
	s_mov_b64 exec, -1
	s_waitcnt vmcnt(10)
	v_lshlrev_b32_e32 v242, 16, v156
	v_and_b32_e32 v243, 0xffff0000, v156
	v_pk_add_f32 v[60:61], v[60:61], v[242:243]
	v_lshlrev_b32_e32 v244, 16, v157
	v_and_b32_e32 v245, 0xffff0000, v157
	v_pk_add_f32 v[62:63], v[62:63], v[244:245]
	v_lshlrev_b32_e32 v242, 16, v158
	v_and_b32_e32 v243, 0xffff0000, v158
	v_pk_add_f32 v[56:57], v[56:57], v[242:243]
	v_lshlrev_b32_e32 v244, 16, v159
	v_and_b32_e32 v245, 0xffff0000, v159
	v_pk_add_f32 v[58:59], v[58:59], v[244:245]
	v_lshlrev_b32_e32 v242, 16, v152
	v_and_b32_e32 v243, 0xffff0000, v152
	v_pk_add_f32 v[52:53], v[52:53], v[242:243]
	v_lshlrev_b32_e32 v244, 16, v153
	v_and_b32_e32 v245, 0xffff0000, v153
	v_pk_add_f32 v[54:55], v[54:55], v[244:245]
	v_lshlrev_b32_e32 v242, 16, v154
	v_and_b32_e32 v243, 0xffff0000, v154
	v_pk_add_f32 v[48:49], v[48:49], v[242:243]
	v_lshlrev_b32_e32 v244, 16, v155
	v_and_b32_e32 v245, 0xffff0000, v155
	v_pk_add_f32 v[50:51], v[50:51], v[244:245]
	v_pk_mul_f32 v[156:157], v[60:61], v[60:61]
	v_pk_mul_f32 v[158:159], v[62:63], v[62:63]
	v_pk_fma_f32 v[156:157], v[56:57], v[56:57], v[156:157]
	v_pk_fma_f32 v[158:159], v[58:59], v[58:59], v[158:159]
	v_pk_fma_f32 v[156:157], v[52:53], v[52:53], v[156:157]
	v_pk_fma_f32 v[158:159], v[54:55], v[54:55], v[158:159]
	v_pk_fma_f32 v[156:157], v[48:49], v[48:49], v[156:157]
	v_pk_fma_f32 v[158:159], v[50:51], v[50:51], v[158:159]
	v_add_f32_e32 v156, v156, v157
	v_add_f32_e32 v158, v158, v159
	v_add_u32_e32 v246, 0x200, v248
	v_add_f32_e32 v212, v156, v158
	s_nop 0
	v_mov_b32_e32 v238, v212
	s_nop 1
	v_permlane16_swap_b32_e32 v212, v238
	v_add_f32_e32 v212, v212, v238
	v_mov_b32_e32 v238, v212
	s_nop 1
	v_permlane32_swap_b32_e32 v212, v238
	v_add_f32_e32 v212, v212, v238
	s_and_b64 exec, exec, s[4:5]
	global_atomic_add_f32 v238, v246, v212, s[12:13] sc0
	s_mov_b64 exec, -1
	s_waitcnt vmcnt(9)
; __device__ __forceinline__ unsigned cvt_pk_bf16(float lo, float hi) { unsigned r; asm volatile("v_cvt_pk_bf16_f32 %0, %1, %2" : "=v"(r) : "v"(lo), "v"(hi)); return r; }
; __device__ __forceinline__ float bf_lo(unsigned w) { return __uint_as_float(w << 16); }
; __device__ __forceinline__ float bf_hi(unsigned w) { return __uint_as_float(w & 0xffff0000u); }
;     __device__ __forceinline__ void operator()(const Acc& acc, const Unit& u, int wr, int wc, int fr, int fq, LAS unsigned char* lds, f32x4 epar) const {
;     ...
;         for (int ai = 0; ai < 2; ++ai)
; #pragma unroll
;             for (int m = 0; m < 4; ++m) { const int r = u.pm * BM + ai * HALF + wr * 64 + m * 16 + fr; float s = 0.f;
; #pragma unroll
;                 for (int bj = 0; bj < 2; ++bj) { const size_t off = (size_t)r * DM + u.pn * 256 + bj * 128 + wc * 32 + 8 * fq;
;                     const u32x4 q = hv[ai][m][bj];
;                     f32x4 v0 = (f32x4){bf_lo(q.x), bf_hi(q.x), bf_lo(q.y), bf_hi(q.y)}, v1 = (f32x4){bf_lo(q.z), bf_hi(q.z), bf_lo(q.w), bf_hi(q.w)};
;                     v0 += acc[ai][bj][m][0]; v1 += acc[ai][bj][m][1];
;                     u32x4 w; w.x = cvt_pk_bf16(v0[0], v0[1]); w.y = cvt_pk_bf16(v0[2], v0[3]); w.z = cvt_pk_bf16(v1[0], v1[1]); w.w = cvt_pk_bf16(v1[2], v1[3]);
;                     *(u32x4*)(HB + off) = w;
;                     s += (v0[0] * v0[0] + v0[1] * v0[1]) + (v0[2] * v0[2] + v0[3] * v0[3]) + (v1[0] * v1[0] + v1[1] * v1[1]) + (v1[2] * v1[2] + v1[3] * v1[3]); }
;                 s += __shfl_xor(s, 16); s += __shfl_xor(s, 32);
;                 if (fq == 0) unsafeAtomicAdd(ssq + r, s); }
	v_lshlrev_b32_e32 v242, 16, v148
	v_and_b32_e32 v243, 0xffff0000, v148
	v_pk_add_f32 v[44:45], v[44:45], v[242:243]
	v_lshlrev_b32_e32 v244, 16, v149
	v_and_b32_e32 v245, 0xffff0000, v149
	v_pk_add_f32 v[46:47], v[46:47], v[244:245]
	v_lshlrev_b32_e32 v242, 16, v150
	v_and_b32_e32 v243, 0xffff0000, v150
	v_pk_add_f32 v[40:41], v[40:41], v[242:243]
	v_lshlrev_b32_e32 v244, 16, v151
	v_and_b32_e32 v245, 0xffff0000, v151
	v_pk_add_f32 v[42:43], v[42:43], v[244:245]
	v_lshlrev_b32_e32 v242, 16, v144
	v_and_b32_e32 v243, 0xffff0000, v144
	v_pk_add_f32 v[36:37], v[36:37], v[242:243]
	v_lshlrev_b32_e32 v244, 16, v145
	v_and_b32_e32 v245, 0xffff0000, v145
	v_pk_add_f32 v[38:39], v[38:39], v[244:245]
	v_lshlrev_b32_e32 v242, 16, v146
	v_and_b32_e32 v243, 0xffff0000, v146
	v_pk_add_f32 v[32:33], v[32:33], v[242:243]
	v_lshlrev_b32_e32 v244, 16, v147
	v_and_b32_e32 v245, 0xffff0000, v147
	v_pk_add_f32 v[34:35], v[34:35], v[244:245]
	v_pk_mul_f32 v[148:149], v[44:45], v[44:45]
	v_pk_mul_f32 v[150:151], v[46:47], v[46:47]
	v_pk_fma_f32 v[148:149], v[40:41], v[40:41], v[148:149]
	v_pk_fma_f32 v[150:151], v[42:43], v[42:43], v[150:151]
	v_pk_fma_f32 v[148:149], v[36:37], v[36:37], v[148:149]
	v_pk_fma_f32 v[150:151], v[38:39], v[38:39], v[150:151]
	v_pk_fma_f32 v[148:149], v[32:33], v[32:33], v[148:149]
	v_pk_fma_f32 v[150:151], v[34:35], v[34:35], v[150:151]
	v_add_f32_e32 v148, v148, v149
	v_add_f32_e32 v150, v150, v151
	v_add_u32_e32 v246, 0x240, v248
	v_add_f32_e32 v213, v148, v150
	s_nop 0
	v_mov_b32_e32 v239, v213
	s_nop 1
	v_permlane16_swap_b32_e32 v213, v239
	v_add_f32_e32 v213, v213, v239
	v_mov_b32_e32 v239, v213
	s_nop 1
	v_permlane32_swap_b32_e32 v213, v239
	v_add_f32_e32 v213, v213, v239
	s_and_b64 exec, exec, s[4:5]
	global_atomic_add_f32 v239, v246, v213, s[12:13] sc0
	s_mov_b64 exec, -1
	s_waitcnt vmcnt(8)
	v_lshlrev_b32_e32 v242, 16, v140
	v_and_b32_e32 v243, 0xffff0000, v140
	v_pk_add_f32 v[28:29], v[28:29], v[242:243]
	v_lshlrev_b32_e32 v244, 16, v141
	v_and_b32_e32 v245, 0xffff0000, v141
	v_pk_add_f32 v[30:31], v[30:31], v[244:245]
	v_lshlrev_b32_e32 v242, 16, v142
	v_and_b32_e32 v243, 0xffff0000, v142
	v_pk_add_f32 v[24:25], v[24:25], v[242:243]
	v_lshlrev_b32_e32 v244, 16, v143
	v_and_b32_e32 v245, 0xffff0000, v143
	v_pk_add_f32 v[26:27], v[26:27], v[244:245]
	v_lshlrev_b32_e32 v242, 16, v136
	v_and_b32_e32 v243, 0xffff0000, v136
	v_pk_add_f32 v[20:21], v[20:21], v[242:243]
	v_lshlrev_b32_e32 v244, 16, v137
	v_and_b32_e32 v245, 0xffff0000, v137
	v_pk_add_f32 v[22:23], v[22:23], v[244:245]
	v_lshlrev_b32_e32 v242, 16, v138
	v_and_b32_e32 v243, 0xffff0000, v138
	v_pk_add_f32 v[16:17], v[16:17], v[242:243]
	v_lshlrev_b32_e32 v244, 16, v139
	v_and_b32_e32 v245, 0xffff0000, v139
	v_pk_add_f32 v[18:19], v[18:19], v[244:245]
	v_pk_mul_f32 v[140:141], v[28:29], v[28:29]
	v_pk_mul_f32 v[142:143], v[30:31], v[30:31]
	v_pk_fma_f32 v[140:141], v[24:25], v[24:25], v[140:141]
	v_pk_fma_f32 v[142:143], v[26:27], v[26:27], v[142:143]
	v_pk_fma_f32 v[140:141], v[20:21], v[20:21], v[140:141]
	v_pk_fma_f32 v[142:143], v[22:23], v[22:23], v[142:143]
	v_pk_fma_f32 v[140:141], v[16:17], v[16:17], v[140:141]
	v_pk_fma_f32 v[142:143], v[18:19], v[18:19], v[142:143]
	v_add_f32_e32 v140, v140, v141
	v_add_f32_e32 v142, v142, v143
	v_add_u32_e32 v246, 0x280, v248
	v_add_f32_e32 v214, v140, v142
	s_nop 0
	v_mov_b32_e32 v240, v214
	s_nop 1
	v_permlane16_swap_b32_e32 v214, v240
	v_add_f32_e32 v214, v214, v240
	v_mov_b32_e32 v240, v214
	s_nop 1
	v_permlane32_swap_b32_e32 v214, v240
	v_add_f32_e32 v214, v214, v240
	s_and_b64 exec, exec, s[4:5]
	global_atomic_add_f32 v240, v246, v214, s[12:13] sc0
	s_mov_b64 exec, -1
	s_waitcnt vmcnt(7)
	v_lshlrev_b32_e32 v242, 16, v132
	v_and_b32_e32 v243, 0xffff0000, v132
	v_pk_add_f32 v[12:13], v[12:13], v[242:243]
	v_lshlrev_b32_e32 v244, 16, v133
	v_and_b32_e32 v245, 0xffff0000, v133
	v_pk_add_f32 v[14:15], v[14:15], v[244:245]
	v_lshlrev_b32_e32 v242, 16, v134
	v_and_b32_e32 v243, 0xffff0000, v134
	v_pk_add_f32 v[8:9], v[8:9], v[242:243]
	v_lshlrev_b32_e32 v244, 16, v135
	v_and_b32_e32 v245, 0xffff0000, v135
	v_pk_add_f32 v[10:11], v[10:11], v[244:245]
	v_lshlrev_b32_e32 v242, 16, v128
	v_and_b32_e32 v243, 0xffff0000, v128
	v_pk_add_f32 v[4:5], v[4:5], v[242:243]
	v_lshlrev_b32_e32 v244, 16, v129
	v_and_b32_e32 v245, 0xffff0000, v129
	v_pk_add_f32 v[6:7], v[6:7], v[244:245]
	v_lshlrev_b32_e32 v242, 16, v130
	v_and_b32_e32 v243, 0xffff0000, v130
	v_pk_add_f32 v[0:1], v[0:1], v[242:243]
	v_lshlrev_b32_e32 v244, 16, v131
	v_and_b32_e32 v245, 0xffff0000, v131
	v_pk_add_f32 v[2:3], v[2:3], v[244:245]
	v_pk_mul_f32 v[132:133], v[12:13], v[12:13]
	v_pk_mul_f32 v[134:135], v[14:15], v[14:15]
	v_pk_fma_f32 v[132:133], v[8:9], v[8:9], v[132:133]
	v_pk_fma_f32 v[134:135], v[10:11], v[10:11], v[134:135]
	v_pk_fma_f32 v[132:133], v[4:5], v[4:5], v[132:133]
	v_pk_fma_f32 v[134:135], v[6:7], v[6:7], v[134:135]
	v_pk_fma_f32 v[132:133], v[0:1], v[0:1], v[132:133]
	v_pk_fma_f32 v[134:135], v[2:3], v[2:3], v[134:135]
	v_add_f32_e32 v132, v132, v133
	v_add_f32_e32 v134, v134, v135
	v_add_u32_e32 v246, 0x2c0, v248
	v_add_f32_e32 v215, v132, v134
	s_nop 0
	v_mov_b32_e32 v241, v215
	s_nop 1
	v_permlane16_swap_b32_e32 v215, v241
	v_add_f32_e32 v215, v215, v241
	v_mov_b32_e32 v241, v215
	s_nop 1
	v_permlane32_swap_b32_e32 v215, v241
	v_add_f32_e32 v215, v215, v241
	s_and_b64 exec, exec, s[4:5]
	global_atomic_add_f32 v241, v246, v215, s[12:13] sc0
	s_mov_b64 exec, -1
	v_readfirstlane_b32 s9, v232
	s_lshl_b32 s8, s78, 3
	s_nop 1
	s_lshr_b32 s9, s9, 8
	s_lshl_b32 s9, s9, 2
	s_add_i32 s8, s8, s9
	s_add_i32 s8, s8, 0x3600
	v_mov_b32_e32 v251, s8
	v_mov_b32_e32 v218, 1
	s_waitcnt vmcnt(0)
	s_mov_b64 exec, 1
	global_atomic_add v251, v218, s[62:63]
	s_mov_b64 exec, -1
	s_mov_b32 s8, 0

; __device__ __forceinline__ float bf_lo(unsigned w) { return __uint_as_float(w << 16); }
; __device__ __forceinline__ float bf_hi(unsigned w) { return __uint_as_float(w & 0xffff0000u); }
; __device__ __forceinline__ int otid() { int t = threadIdx.x; asm volatile("" : "+v"(t)); return t; }
; __device__ __forceinline__ void final_phase(float* out, const bf16_t* HB, const float* ssq, const float* gf) {
;     for (int idx = blockIdx.x * 512 + otid(); idx < MTOK * 128; idx += gridDim.x * 512) {
;         const int r = idx >> 7, c = (idx & 127) * 8;
;         const float rs = rsqrtf(ssq[r] * (1.0f / DM) + RMS_EPS);
;         const u32x4 q = __builtin_nontemporal_load((const u32x4*)(HB + (size_t)idx * 8)); const f32x4 g0 = *(const f32x4*)(gf + c), g1 = *(const f32x4*)(gf + c + 4);
;         f32x4 v0 = (f32x4){bf_lo(q.x), bf_hi(q.x), bf_lo(q.y), bf_hi(q.y)}, v1 = (f32x4){bf_lo(q.z), bf_hi(q.z), bf_lo(q.w), bf_hi(q.w)};
;         v0 *= g0 * rs; v1 *= g1 * rs;
;         __builtin_nontemporal_store(v0, (f32x4*)(out + (size_t)idx * 8)); __builtin_nontemporal_store(v1, (f32x4*)(out + (size_t)idx * 8 + 4));
.Ldn1_go:
	s_and_b64 exec, exec, s[4:5]
	v_add_u32_e32 v246, 0x0, v248
	global_atomic_add_f32 v208, v246, v219, s[12:13] sc0
	v_add_u32_e32 v246, 0x40, v248
	global_atomic_add_f32 v209, v246, v219, s[12:13] sc0
	v_add_u32_e32 v246, 0x80, v248
	global_atomic_add_f32 v210, v246, v219, s[12:13] sc0
	v_add_u32_e32 v246, 0xc0, v248
	global_atomic_add_f32 v211, v246, v219, s[12:13] sc0
	v_add_u32_e32 v246, 0x200, v248
	global_atomic_add_f32 v212, v246, v219, s[12:13] sc0
	v_add_u32_e32 v246, 0x240, v248
	global_atomic_add_f32 v213, v246, v219, s[12:13] sc0
	v_add_u32_e32 v246, 0x280, v248
	global_atomic_add_f32 v214, v246, v219, s[12:13] sc0
	v_add_u32_e32 v246, 0x2c0, v248
	global_atomic_add_f32 v215, v246, v219, s[12:13] sc0
	s_mov_b64 exec, -1
	s_lshl_b32 s9, s77, 10
	v_lshl_add_u32 v249, v184, 1, s9
	v_bfe_u32 v242, v232, 6, 2
	v_lshl_add_u32 v249, v242, 7, v249
	v_lshlrev_b32_e32 v250, 12, v216
	global_load_dwordx4 v[192:195], v249, s[100:101]
	global_load_dwordx4 v[196:199], v249, s[100:101] offset:16
	global_load_dwordx4 v[200:203], v249, s[100:101] offset:512
	global_load_dwordx4 v[204:207], v249, s[100:101] offset:528
	v_add_u32_e32 v250, v250, v249
	v_mov_b32_e32 v245, 0x358637bd
	s_waitcnt vmcnt(0)
	v_mov_b32_e32 v234, v208
	v_mov_b32_e32 v235, v209
	v_mov_b32_e32 v236, v210
	v_mov_b32_e32 v237, v211
	v_mov_b32_e32 v238, v212
	v_mov_b32_e32 v239, v213
	v_mov_b32_e32 v240, v214
	v_mov_b32_e32 v241, v215
	s_nop 1
	v_permlane16_swap_b32_e32 v208, v234
	v_permlane16_swap_b32_e32 v209, v235
	v_permlane16_swap_b32_e32 v210, v236
	v_permlane16_swap_b32_e32 v211, v237
	v_permlane16_swap_b32_e32 v212, v238
	v_permlane16_swap_b32_e32 v213, v239
	v_permlane16_swap_b32_e32 v214, v240
	v_permlane16_swap_b32_e32 v215, v241
	v_mov_b32_e32 v234, v208
	v_mov_b32_e32 v235, v209
	v_mov_b32_e32 v236, v210
	v_mov_b32_e32 v237, v211
	v_mov_b32_e32 v238, v212
	v_mov_b32_e32 v239, v213
	v_mov_b32_e32 v240, v214
	v_mov_b32_e32 v241, v215
	s_nop 1
	v_permlane32_swap_b32_e32 v208, v234
	v_permlane32_swap_b32_e32 v209, v235
	v_permlane32_swap_b32_e32 v210, v236
	v_permlane32_swap_b32_e32 v211, v237
	v_permlane32_swap_b32_e32 v212, v238
	v_permlane32_swap_b32_e32 v213, v239
	v_permlane32_swap_b32_e32 v214, v240
	v_permlane32_swap_b32_e32 v215, v241
	s_nop 1
	v_fmamk_f32 v208, v208, 0x3a800000, v245
	v_fmamk_f32 v209, v209, 0x3a800000, v245
	v_fmamk_f32 v210, v210, 0x3a800000, v245
	v_fmamk_f32 v211, v211, 0x3a800000, v245
	v_fmamk_f32 v212, v212, 0x3a800000, v245
	v_fmamk_f32 v213, v213, 0x3a800000, v245
	v_fmamk_f32 v214, v214, 0x3a800000, v245
	v_fmamk_f32 v215, v215, 0x3a800000, v245
	v_rsq_f32_e32 v208, v208
	v_rsq_f32_e32 v209, v209
	v_rsq_f32_e32 v210, v210
	v_rsq_f32_e32 v211, v211
	v_rsq_f32_e32 v212, v212
	v_rsq_f32_e32 v213, v213
	v_rsq_f32_e32 v214, v214
	v_rsq_f32_e32 v215, v215
	s_nop 0
	v_pk_mul_f32 v[234:235], v[192:193], v[208:209] op_sel_hi:[1,0]
	v_pk_mul_f32 v[236:237], v[194:195], v[208:209] op_sel_hi:[1,0]
	v_pk_mul_f32 v[238:239], v[196:197], v[208:209] op_sel_hi:[1,0]
	v_pk_mul_f32 v[240:241], v[198:199], v[208:209] op_sel_hi:[1,0]
	v_pk_mul_f32 v[120:121], v[120:121], v[234:235]
	v_pk_mul_f32 v[122:123], v[122:123], v[236:237]
	v_pk_mul_f32 v[124:125], v[124:125], v[238:239]
	v_pk_mul_f32 v[126:127], v[126:127], v[240:241]
	v_pk_mul_f32 v[234:235], v[200:201], v[208:209] op_sel_hi:[1,0]
	v_pk_mul_f32 v[236:237], v[202:203], v[208:209] op_sel_hi:[1,0]
	v_pk_mul_f32 v[238:239], v[204:205], v[208:209] op_sel_hi:[1,0]
	v_pk_mul_f32 v[240:241], v[206:207], v[208:209] op_sel_hi:[1,0]
	v_pk_mul_f32 v[116:117], v[116:117], v[234:235]
	v_pk_mul_f32 v[118:119], v[118:119], v[236:237]
	v_pk_mul_f32 v[112:113], v[112:113], v[238:239]
	v_pk_mul_f32 v[114:115], v[114:115], v[240:241]
	v_add_u32_e32 v246, 0x0, v250
	global_store_dwordx4 v246, v[120:123], s[98:99] nt
	global_store_dwordx4 v246, v[124:127], s[98:99] offset:16 nt
	global_store_dwordx4 v246, v[116:119], s[98:99] offset:512 nt
	global_store_dwordx4 v246, v[112:115], s[98:99] offset:528 nt
	v_pk_mul_f32 v[234:235], v[192:193], v[208:209] op_sel:[0,1]
	v_pk_mul_f32 v[236:237], v[194:195], v[208:209] op_sel:[0,1]
	v_pk_mul_f32 v[238:239], v[196:197], v[208:209] op_sel:[0,1]
	v_pk_mul_f32 v[240:241], v[198:199], v[208:209] op_sel:[0,1]
	v_pk_mul_f32 v[108:109], v[108:109], v[234:235]
	v_pk_mul_f32 v[110:111], v[110:111], v[236:237]
	v_pk_mul_f32 v[104:105], v[104:105], v[238:239]
	v_pk_mul_f32 v[106:107], v[106:107], v[240:241]
	v_pk_mul_f32 v[234:235], v[200:201], v[208:209] op_sel:[0,1]
	v_pk_mul_f32 v[236:237], v[202:203], v[208:209] op_sel:[0,1]
	v_pk_mul_f32 v[238:239], v[204:205], v[208:209] op_sel:[0,1]
	v_pk_mul_f32 v[240:241], v[206:207], v[208:209] op_sel:[0,1]
	v_pk_mul_f32 v[100:101], v[100:101], v[234:235]
	v_pk_mul_f32 v[102:103], v[102:103], v[236:237]
	v_pk_mul_f32 v[96:97], v[96:97], v[238:239]
	v_pk_mul_f32 v[98:99], v[98:99], v[240:241]
	v_add_u32_e32 v246, 0x10000, v250
	global_store_dwordx4 v246, v[108:111], s[98:99] nt
	global_store_dwordx4 v246, v[104:107], s[98:99] offset:16 nt
	global_store_dwordx4 v246, v[100:103], s[98:99] offset:512 nt
	global_store_dwordx4 v246, v[96:99], s[98:99] offset:528 nt
	v_pk_mul_f32 v[234:235], v[192:193], v[210:211] op_sel_hi:[1,0]
	v_pk_mul_f32 v[236:237], v[194:195], v[210:211] op_sel_hi:[1,0]
	v_pk_mul_f32 v[238:239], v[196:197], v[210:211] op_sel_hi:[1,0]
	v_pk_mul_f32 v[240:241], v[198:199], v[210:211] op_sel_hi:[1,0]
	v_pk_mul_f32 v[92:93], v[92:93], v[234:235]
	v_pk_mul_f32 v[94:95], v[94:95], v[236:237]
	v_pk_mul_f32 v[88:89], v[88:89], v[238:239]
	v_pk_mul_f32 v[90:91], v[90:91], v[240:241]
	v_pk_mul_f32 v[234:235], v[200:201], v[210:211] op_sel_hi:[1,0]
; __device__ __forceinline__ float bf_lo(unsigned w) { return __uint_as_float(w << 16); }
; __device__ __forceinline__ float bf_hi(unsigned w) { return __uint_as_float(w & 0xffff0000u); }
; __device__ __forceinline__ int otid() { int t = threadIdx.x; asm volatile("" : "+v"(t)); return t; }
; __device__ __forceinline__ void final_phase(float* out, const bf16_t* HB, const float* ssq, const float* gf) {
;     for (int idx = blockIdx.x * 512 + otid(); idx < MTOK * 128; idx += gridDim.x * 512) {
;         const int r = idx >> 7, c = (idx & 127) * 8;
;         const float rs = rsqrtf(ssq[r] * (1.0f / DM) + RMS_EPS);
;         const u32x4 q = __builtin_nontemporal_load((const u32x4*)(HB + (size_t)idx * 8)); const f32x4 g0 = *(const f32x4*)(gf + c), g1 = *(const f32x4*)(gf + c + 4);
;         f32x4 v0 = (f32x4){bf_lo(q.x), bf_hi(q.x), bf_lo(q.y), bf_hi(q.y)}, v1 = (f32x4){bf_lo(q.z), bf_hi(q.z), bf_lo(q.w), bf_hi(q.w)};
;         v0 *= g0 * rs; v1 *= g1 * rs;
;         __builtin_nontemporal_store(v0, (f32x4*)(out + (size_t)idx * 8)); __builtin_nontemporal_store(v1, (f32x4*)(out + (size_t)idx * 8 + 4));
	v_pk_mul_f32 v[236:237], v[202:203], v[210:211] op_sel_hi:[1,0]
	v_pk_mul_f32 v[238:239], v[204:205], v[210:211] op_sel_hi:[1,0]
	v_pk_mul_f32 v[240:241], v[206:207], v[210:211] op_sel_hi:[1,0]
	v_pk_mul_f32 v[84:85], v[84:85], v[234:235]
	v_pk_mul_f32 v[86:87], v[86:87], v[236:237]
	v_pk_mul_f32 v[80:81], v[80:81], v[238:239]
	v_pk_mul_f32 v[82:83], v[82:83], v[240:241]
	v_add_u32_e32 v246, 0x20000, v250
	global_store_dwordx4 v246, v[92:95], s[98:99] nt
	global_store_dwordx4 v246, v[88:91], s[98:99] offset:16 nt
	global_store_dwordx4 v246, v[84:87], s[98:99] offset:512 nt
	global_store_dwordx4 v246, v[80:83], s[98:99] offset:528 nt
	v_pk_mul_f32 v[234:235], v[192:193], v[210:211] op_sel:[0,1]
	v_pk_mul_f32 v[236:237], v[194:195], v[210:211] op_sel:[0,1]
	v_pk_mul_f32 v[238:239], v[196:197], v[210:211] op_sel:[0,1]
	v_pk_mul_f32 v[240:241], v[198:199], v[210:211] op_sel:[0,1]
	v_pk_mul_f32 v[76:77], v[76:77], v[234:235]
	v_pk_mul_f32 v[78:79], v[78:79], v[236:237]
	v_pk_mul_f32 v[72:73], v[72:73], v[238:239]
	v_pk_mul_f32 v[74:75], v[74:75], v[240:241]
	v_pk_mul_f32 v[234:235], v[200:201], v[210:211] op_sel:[0,1]
	v_pk_mul_f32 v[236:237], v[202:203], v[210:211] op_sel:[0,1]
	v_pk_mul_f32 v[238:239], v[204:205], v[210:211] op_sel:[0,1]
	v_pk_mul_f32 v[240:241], v[206:207], v[210:211] op_sel:[0,1]
	v_pk_mul_f32 v[68:69], v[68:69], v[234:235]
	v_pk_mul_f32 v[70:71], v[70:71], v[236:237]
	v_pk_mul_f32 v[64:65], v[64:65], v[238:239]
	v_pk_mul_f32 v[66:67], v[66:67], v[240:241]
	v_add_u32_e32 v246, 0x30000, v250
	global_store_dwordx4 v246, v[76:79], s[98:99] nt
	global_store_dwordx4 v246, v[72:75], s[98:99] offset:16 nt
	global_store_dwordx4 v246, v[68:71], s[98:99] offset:512 nt
	global_store_dwordx4 v246, v[64:67], s[98:99] offset:528 nt
	v_pk_mul_f32 v[234:235], v[192:193], v[212:213] op_sel_hi:[1,0]
	v_pk_mul_f32 v[236:237], v[194:195], v[212:213] op_sel_hi:[1,0]
	v_pk_mul_f32 v[238:239], v[196:197], v[212:213] op_sel_hi:[1,0]
	v_pk_mul_f32 v[240:241], v[198:199], v[212:213] op_sel_hi:[1,0]
	v_pk_mul_f32 v[60:61], v[60:61], v[234:235]
	v_pk_mul_f32 v[62:63], v[62:63], v[236:237]
	v_pk_mul_f32 v[56:57], v[56:57], v[238:239]
	v_pk_mul_f32 v[58:59], v[58:59], v[240:241]
	v_pk_mul_f32 v[234:235], v[200:201], v[212:213] op_sel_hi:[1,0]
	v_pk_mul_f32 v[236:237], v[202:203], v[212:213] op_sel_hi:[1,0]
	v_pk_mul_f32 v[238:239], v[204:205], v[212:213] op_sel_hi:[1,0]
	v_pk_mul_f32 v[240:241], v[206:207], v[212:213] op_sel_hi:[1,0]
	v_pk_mul_f32 v[52:53], v[52:53], v[234:235]
	v_pk_mul_f32 v[54:55], v[54:55], v[236:237]
	v_pk_mul_f32 v[48:49], v[48:49], v[238:239]
	v_pk_mul_f32 v[50:51], v[50:51], v[240:241]
	v_add_u32_e32 v246, 0x80000, v250
	global_store_dwordx4 v246, v[60:63], s[98:99] nt
	global_store_dwordx4 v246, v[56:59], s[98:99] offset:16 nt
	global_store_dwordx4 v246, v[52:55], s[98:99] offset:512 nt
	global_store_dwordx4 v246, v[48:51], s[98:99] offset:528 nt
	v_pk_mul_f32 v[234:235], v[192:193], v[212:213] op_sel:[0,1]
	v_pk_mul_f32 v[236:237], v[194:195], v[212:213] op_sel:[0,1]
	v_pk_mul_f32 v[238:239], v[196:197], v[212:213] op_sel:[0,1]
	v_pk_mul_f32 v[240:241], v[198:199], v[212:213] op_sel:[0,1]
	v_pk_mul_f32 v[44:45], v[44:45], v[234:235]
	v_pk_mul_f32 v[46:47], v[46:47], v[236:237]
	v_pk_mul_f32 v[40:41], v[40:41], v[238:239]
	v_pk_mul_f32 v[42:43], v[42:43], v[240:241]
	v_pk_mul_f32 v[234:235], v[200:201], v[212:213] op_sel:[0,1]
	v_pk_mul_f32 v[236:237], v[202:203], v[212:213] op_sel:[0,1]
	v_pk_mul_f32 v[238:239], v[204:205], v[212:213] op_sel:[0,1]
	v_pk_mul_f32 v[240:241], v[206:207], v[212:213] op_sel:[0,1]
	v_pk_mul_f32 v[36:37], v[36:37], v[234:235]
	v_pk_mul_f32 v[38:39], v[38:39], v[236:237]
	v_pk_mul_f32 v[32:33], v[32:33], v[238:239]
	v_pk_mul_f32 v[34:35], v[34:35], v[240:241]
	v_add_u32_e32 v246, 0x90000, v250
	global_store_dwordx4 v246, v[44:47], s[98:99] nt
	global_store_dwordx4 v246, v[40:43], s[98:99] offset:16 nt
	global_store_dwordx4 v246, v[36:39], s[98:99] offset:512 nt
	global_store_dwordx4 v246, v[32:35], s[98:99] offset:528 nt
	v_pk_mul_f32 v[234:235], v[192:193], v[214:215] op_sel_hi:[1,0]
	v_pk_mul_f32 v[236:237], v[194:195], v[214:215] op_sel_hi:[1,0]
	v_pk_mul_f32 v[238:239], v[196:197], v[214:215] op_sel_hi:[1,0]
	v_pk_mul_f32 v[240:241], v[198:199], v[214:215] op_sel_hi:[1,0]
	v_pk_mul_f32 v[28:29], v[28:29], v[234:235]
	v_pk_mul_f32 v[30:31], v[30:31], v[236:237]
	v_pk_mul_f32 v[24:25], v[24:25], v[238:239]
	v_pk_mul_f32 v[26:27], v[26:27], v[240:241]
	v_pk_mul_f32 v[234:235], v[200:201], v[214:215] op_sel_hi:[1,0]
	v_pk_mul_f32 v[236:237], v[202:203], v[214:215] op_sel_hi:[1,0]
	v_pk_mul_f32 v[238:239], v[204:205], v[214:215] op_sel_hi:[1,0]
	v_pk_mul_f32 v[240:241], v[206:207], v[214:215] op_sel_hi:[1,0]
	v_pk_mul_f32 v[20:21], v[20:21], v[234:235]
	v_pk_mul_f32 v[22:23], v[22:23], v[236:237]
	v_pk_mul_f32 v[16:17], v[16:17], v[238:239]
	v_pk_mul_f32 v[18:19], v[18:19], v[240:241]
	v_add_u32_e32 v246, 0xa0000, v250
	global_store_dwordx4 v246, v[28:31], s[98:99] nt
	global_store_dwordx4 v246, v[24:27], s[98:99] offset:16 nt
	global_store_dwordx4 v246, v[20:23], s[98:99] offset:512 nt
	global_store_dwordx4 v246, v[16:19], s[98:99] offset:528 nt
	v_pk_mul_f32 v[234:235], v[192:193], v[214:215] op_sel:[0,1]
	v_pk_mul_f32 v[236:237], v[194:195], v[214:215] op_sel:[0,1]
	v_pk_mul_f32 v[238:239], v[196:197], v[214:215] op_sel:[0,1]
	v_pk_mul_f32 v[240:241], v[198:199], v[214:215] op_sel:[0,1]
	v_pk_mul_f32 v[12:13], v[12:13], v[234:235]
	v_pk_mul_f32 v[14:15], v[14:15], v[236:237]
	v_pk_mul_f32 v[8:9], v[8:9], v[238:239]
	v_pk_mul_f32 v[10:11], v[10:11], v[240:241]
	v_pk_mul_f32 v[234:235], v[200:201], v[214:215] op_sel:[0,1]
	v_pk_mul_f32 v[236:237], v[202:203], v[214:215] op_sel:[0,1]
	v_pk_mul_f32 v[238:239], v[204:205], v[214:215] op_sel:[0,1]
	v_pk_mul_f32 v[240:241], v[206:207], v[214:215] op_sel:[0,1]
	v_pk_mul_f32 v[4:5], v[4:5], v[234:235]
	v_pk_mul_f32 v[6:7], v[6:7], v[236:237]
	v_pk_mul_f32 v[0:1], v[0:1], v[238:239]
	v_pk_mul_f32 v[2:3], v[2:3], v[240:241]
	v_add_u32_e32 v246, 0xb0000, v250
	global_store_dwordx4 v246, v[12:15], s[98:99] nt
	global_store_dwordx4 v246, v[8:11], s[98:99] offset:16 nt
	global_store_dwordx4 v246, v[4:7], s[98:99] offset:512 nt
	global_store_dwordx4 v246, v[0:3], s[98:99] offset:528 nt
	s_branch .LBB0_1053

;     ...
;     f32x4 acc[2][2][4][2];
; #pragma unroll
;     for (int a = 0; a < 2; ++a)
; #pragma unroll
;         for (int b = 0; b < 2; ++b)
; #pragma unroll
;             for (int m = 0; m < 4; ++m)
; #pragma unroll
;                 for (int n = 0; n < 2; ++n) acc[a][b][m][n] = (f32x4){0.f, 0.f, 0.f, 0.f};
.LBB0_1118:
	s_endpgm
.Lkzero_575:
	v_mov_b32_e32 v135, 0
	v_mov_b32_e32 v134, v135
	v_mov_b32_e32 v133, v135
	v_mov_b32_e32 v132, v135
	v_mov_b32_e32 v123, v135
	v_mov_b32_e32 v122, v135
	v_mov_b32_e32 v121, v135
	v_mov_b32_e32 v120, v135
	v_mov_b32_e32 v119, v135
	v_mov_b32_e32 v118, v135
	v_mov_b32_e32 v117, v135
	v_mov_b32_e32 v116, v135
	v_mov_b32_e32 v115, v135
	v_mov_b32_e32 v114, v135
	v_mov_b32_e32 v113, v135
	v_mov_b32_e32 v112, v135
	v_mov_b32_e32 v95, v135
	v_mov_b32_e32 v94, v135
	v_mov_b32_e32 v93, v135
	v_mov_b32_e32 v92, v135
	v_mov_b32_e32 v91, v135
	v_mov_b32_e32 v90, v135
	v_mov_b32_e32 v89, v135
	v_mov_b32_e32 v88, v135
	v_mov_b32_e32 v79, v135
	v_mov_b32_e32 v78, v135
	v_mov_b32_e32 v77, v135
	v_mov_b32_e32 v76, v135
	v_mov_b32_e32 v75, v135
	v_mov_b32_e32 v74, v135
	v_mov_b32_e32 v73, v135
	v_mov_b32_e32 v72, v135
	v_mov_b32_e32 v131, v135
	v_mov_b32_e32 v130, v135
	v_mov_b32_e32 v129, v135
	v_mov_b32_e32 v128, v135
	v_mov_b32_e32 v127, v135
	v_mov_b32_e32 v126, v135
	v_mov_b32_e32 v125, v135
	v_mov_b32_e32 v124, v135
	v_mov_b32_e32 v111, v135
	v_mov_b32_e32 v110, v135
	v_mov_b32_e32 v109, v135
	v_mov_b32_e32 v108, v135
	v_mov_b32_e32 v107, v135
	v_mov_b32_e32 v106, v135
	v_mov_b32_e32 v105, v135
	v_mov_b32_e32 v104, v135
	v_mov_b32_e32 v87, v135
	v_mov_b32_e32 v86, v135
	v_mov_b32_e32 v85, v135
	v_mov_b32_e32 v84, v135
	v_mov_b32_e32 v83, v135
	v_mov_b32_e32 v82, v135
	v_mov_b32_e32 v81, v135
	v_mov_b32_e32 v80, v135
	v_mov_b32_e32 v71, v135
	v_mov_b32_e32 v70, v135
	v_mov_b32_e32 v69, v135
	v_mov_b32_e32 v68, v135
	v_mov_b32_e32 v67, v135
	v_mov_b32_e32 v66, v135
	v_mov_b32_e32 v65, v135
	v_mov_b32_e32 v64, v135
	v_mov_b32_e32 v63, v135
	v_mov_b32_e32 v62, v135
	v_mov_b32_e32 v61, v135
	v_mov_b32_e32 v60, v135
	v_mov_b32_e32 v59, v135
	v_mov_b32_e32 v58, v135
	v_mov_b32_e32 v57, v135
	v_mov_b32_e32 v56, v135
	v_mov_b32_e32 v47, v135
	v_mov_b32_e32 v46, v135
	v_mov_b32_e32 v45, v135
	v_mov_b32_e32 v44, v135
	v_mov_b32_e32 v43, v135
	v_mov_b32_e32 v42, v135
	v_mov_b32_e32 v41, v135
	v_mov_b32_e32 v40, v135
	v_mov_b32_e32 v31, v135
	v_mov_b32_e32 v30, v135
	v_mov_b32_e32 v29, v135
	v_mov_b32_e32 v28, v135
	v_mov_b32_e32 v27, v135
	v_mov_b32_e32 v26, v135
	v_mov_b32_e32 v25, v135
	v_mov_b32_e32 v24, v135
	v_mov_b32_e32 v15, v135
	v_mov_b32_e32 v14, v135
	v_mov_b32_e32 v13, v135
	v_mov_b32_e32 v12, v135
	v_mov_b32_e32 v11, v135
	v_mov_b32_e32 v10, v135
	v_mov_b32_e32 v9, v135
	v_mov_b32_e32 v8, v135
	v_mov_b32_e32 v55, v135
	v_mov_b32_e32 v54, v135
	v_mov_b32_e32 v53, v135
	v_mov_b32_e32 v52, v135
	v_mov_b32_e32 v51, v135
	v_mov_b32_e32 v50, v135
	v_mov_b32_e32 v49, v135
	v_mov_b32_e32 v48, v135
	v_mov_b32_e32 v39, v135
	v_mov_b32_e32 v38, v135
	v_mov_b32_e32 v37, v135
	v_mov_b32_e32 v36, v135
	v_mov_b32_e32 v35, v135
	v_mov_b32_e32 v34, v135
	v_mov_b32_e32 v33, v135
	v_mov_b32_e32 v32, v135
	v_mov_b32_e32 v23, v135
	v_mov_b32_e32 v22, v135
	v_mov_b32_e32 v21, v135
	v_mov_b32_e32 v20, v135
	v_mov_b32_e32 v19, v135
	v_mov_b32_e32 v18, v135
	v_mov_b32_e32 v17, v135
	v_mov_b32_e32 v16, v135
	v_mov_b32_e32 v7, v135
	v_mov_b32_e32 v6, v135
	v_mov_b32_e32 v5, v135
	v_mov_b32_e32 v4, v135
	v_mov_b32_e32 v3, v135
	v_mov_b32_e32 v2, v135
	v_mov_b32_e32 v1, v135
	v_mov_b32_e32 v0, v135
	s_branch .LBB0_568
